# GEMM epilogues: integer bf16 rounding sequences replaced by v_cvt_pk_bf16_f32; gate sigmoid 1/d by v_rcp_f32 instead of the div_scale/div_fmas sequence
# speedup vs baseline: 1.4544x; 1.0080x over previous
; __device__ __forceinline__ unsigned pk2(float lo, float hi) { return f2bf(lo) | (f2bf(hi) << 16); }
;     __device__ __forceinline__ void operator()(const f32x4 (&acc)[2][2][4][2], const pg8::Unit& u, int wr, int wc, int fr, int fq) const {
;     ...
;                 const size_t row = (size_t)(row0 + ai * 128 + m * 16);
;                 float ssq = 0.f, rstd = 1.f;
;                 if constexpr (MODE == 8) rstd = 1.f / sqrtf(rs[row] * (1.f / DM) + EPS);
;     ...
;                     } else if constexpr (MODE == 8) {
;                         const f32x4 b0 = *(const f32x4*)(vec + col), b1 = *(const f32x4*)(vec + col + 4);
;                         float r[8] = {v0[0] * rstd + b0[0], v0[1] * rstd + b0[1], v0[2] * rstd + b0[2], v0[3] * rstd + b0[3], v1[0] * rstd + b1[0], v1[1] * rstd + b1[1], v1[2] * rstd + b1[2], v1[3] * rstd + b1[3]};
; #pragma unroll
;                         for (int i = 0; i < 8; ++i) { const float q = fmaxf(r[i], 0.f); r[i] = q * q; }
;                         u32x4 w; w.x = pk2(r[0], r[1]); w.y = pk2(r[2], r[3]); w.z = pk2(r[4], r[5]); w.w = pk2(r[6], r[7]);
;                         *(u32x4*)(ob + row * HIDN + col) = w;
.LBB0_35:
	v_lshl_add_u32 v144, s9, 8, v148
	v_lshl_or_b32 v146, s8, 8, v150
	v_readlane_b32 s8, v251, 21
	v_ashrrev_i32_e32 v145, 31, v144
	v_readlane_b32 s9, v251, 22
	s_mov_b32 s10, 0xf800000
	s_nop 0
	v_lshl_add_u64 v[138:139], v[144:145], 2, s[8:9]
	global_load_dword v140, v[138:139], off
	s_waitcnt vmcnt(0)
	v_fmamk_f32 v140, v140, 0x3a000000, v205
	v_cmp_gt_f32_e32 vcc, s10, v140
	v_mul_f32_e32 v141, 0x4f800000, v140
	s_nop 0
	v_cndmask_b32_e32 v140, v140, v141, vcc
	v_sqrt_f32_e32 v141, v140
	s_nop 0
	v_add_u32_e32 v142, -1, v141
	v_fma_f32 v143, -v142, v141, v140
	v_cmp_ge_f32_e64 s[0:1], 0, v143
	v_add_u32_e32 v143, 1, v141
	s_nop 0
	v_cndmask_b32_e64 v142, v141, v142, s[0:1]
	v_fma_f32 v141, -v143, v141, v140
	v_cmp_lt_f32_e64 s[0:1], 0, v141
	s_nop 1
	v_cndmask_b32_e64 v141, v142, v143, s[0:1]
	v_mul_f32_e32 v142, 0x37800000, v141
	v_cndmask_b32_e32 v141, v141, v142, vcc
	v_cmp_class_f32_e32 vcc, v140, v206
	s_nop 1
	v_cndmask_b32_e32 v140, v141, v140, vcc
	v_div_scale_f32 v141, s[0:1], v140, v140, 1.0
	v_rcp_f32_e32 v142, v141
	v_readlane_b32 s0, v251, 23
	v_readlane_b32 s1, v251, 24
	v_fma_f32 v143, -v141, v142, 1.0
	v_fmac_f32_e32 v142, v143, v142
	v_div_scale_f32 v143, vcc, 1.0, v140, 1.0
	v_mul_f32_e32 v147, v143, v142
	v_fma_f32 v152, -v141, v147, v143
	v_fmac_f32_e32 v147, v152, v142
	v_fma_f32 v141, -v141, v147, v143
	v_div_fmas_f32 v141, v141, v142, v147
	v_ashrrev_i32_e32 v147, 31, v146
	v_div_fixup_f32 v152, v141, v140, 1.0
	v_lshl_add_u64 v[140:141], v[146:147], 2, s[0:1]
	global_load_dwordx4 v[154:157], v[140:141], off offset:16
	global_load_dwordx4 v[184:187], v[140:141], off
	v_lshlrev_b64 v[142:143], 14, v[144:145]
	s_waitcnt vmcnt(1)
	v_fma_f32 v145, v121, v152, v155
	s_waitcnt vmcnt(0)
	v_fma_f32 v124, v124, v152, v184
	v_fma_f32 v125, v125, v152, v185
	v_fma_f32 v126, v126, v152, v186
	v_fmac_f32_e32 v187, v127, v152
	v_fma_f32 v127, v120, v152, v154
	v_fmac_f32_e32 v157, v123, v152
	v_fma_f32 v153, v122, v152, v156
	v_max_f32_e32 v120, 0, v124
	v_max_f32_e32 v122, 0, v125
	v_max_f32_e32 v121, 0, v126
	v_max_f32_e32 v123, 0, v187
	v_max_f32_e32 v124, 0, v127
	v_max_f32_e32 v126, 0, v145
	v_max_f32_e32 v127, 0, v157
	v_max_f32_e32 v125, 0, v153
	v_pk_mul_f32 v[122:123], v[122:123], v[122:123]
	v_pk_mul_f32 v[126:127], v[126:127], v[126:127]
	v_pk_mul_f32 v[124:125], v[124:125], v[124:125]
	v_pk_mul_f32 v[120:121], v[120:121], v[120:121]
	v_cvt_pk_bf16_f32 v120, v120, v122
	v_cvt_pk_bf16_f32 v121, v121, v123
	v_cvt_pk_bf16_f32 v122, v124, v126
	v_cvt_pk_bf16_f32 v123, v125, v127
	v_lshl_add_u64 v[124:125], s[20:21], 0, v[142:143]
	v_lshlrev_b64 v[142:143], 1, v[146:147]
	v_lshl_add_u64 v[124:125], v[124:125], 0, v[142:143]
	global_store_dwordx4 v[124:125], v[120:123], off
	s_nop 1
	v_or_b32_e32 v120, 0x80, v146
	v_ashrrev_i32_e32 v121, 31, v120
	v_lshl_add_u64 v[126:127], v[120:121], 2, s[0:1]
	global_load_dwordx4 v[120:123], v[126:127], off offset:16
	global_load_dwordx4 v[154:157], v[126:127], off
	s_waitcnt vmcnt(1)
	v_fmac_f32_e32 v123, v115, v152
	s_waitcnt vmcnt(0)
	v_fma_f32 v116, v116, v152, v154
	v_fma_f32 v117, v117, v152, v155
	v_fma_f32 v118, v118, v152, v156
	v_fmac_f32_e32 v157, v119, v152
	v_fma_f32 v119, v112, v152, v120
	v_fma_f32 v120, v113, v152, v121
	v_fma_f32 v121, v114, v152, v122
	v_max_f32_e32 v112, 0, v116
	v_max_f32_e32 v114, 0, v117
	v_max_f32_e32 v113, 0, v118
	v_max_f32_e32 v115, 0, v157
	v_max_f32_e32 v116, 0, v119
	v_max_f32_e32 v118, 0, v120
	v_max_f32_e32 v119, 0, v123
	v_max_f32_e32 v117, 0, v121
	v_pk_mul_f32 v[114:115], v[114:115], v[114:115]
	v_pk_mul_f32 v[118:119], v[118:119], v[118:119]
	v_pk_mul_f32 v[112:113], v[112:113], v[112:113]
	v_pk_mul_f32 v[116:117], v[116:117], v[116:117]
	v_cvt_pk_bf16_f32 v112, v112, v114
	v_cvt_pk_bf16_f32 v113, v113, v115
	v_cvt_pk_bf16_f32 v114, v116, v118
	v_cvt_pk_bf16_f32 v115, v117, v119
	global_store_dwordx4 v[124:125], v[112:115], off offset:256
	s_nop 1
	v_or_b32_e32 v112, 16, v144
	v_ashrrev_i32_e32 v113, 31, v112
	v_lshl_add_u64 v[114:115], v[112:113], 2, s[8:9]
	global_load_dword v114, v[114:115], off
	v_lshlrev_b64 v[112:113], 14, v[112:113]
	s_waitcnt vmcnt(0)
	v_fmamk_f32 v114, v114, 0x3a000000, v205
	v_cmp_gt_f32_e32 vcc, s10, v114
	v_mul_f32_e32 v115, 0x4f800000, v114
	s_nop 0
	v_cndmask_b32_e32 v114, v114, v115, vcc
	v_sqrt_f32_e32 v115, v114
	s_nop 0
	v_add_u32_e32 v116, -1, v115
	v_fma_f32 v117, -v116, v115, v114
	v_cmp_ge_f32_e64 s[0:1], 0, v117
	v_add_u32_e32 v117, 1, v115
	s_nop 0
	v_cndmask_b32_e64 v116, v115, v116, s[0:1]
	v_fma_f32 v115, -v117, v115, v114
	v_cmp_lt_f32_e64 s[0:1], 0, v115
	s_nop 1
	v_cndmask_b32_e64 v115, v116, v117, s[0:1]
	v_mul_f32_e32 v116, 0x37800000, v115
	v_cndmask_b32_e32 v115, v115, v116, vcc
	v_cmp_class_f32_e32 vcc, v114, v206
	s_nop 1
	v_cndmask_b32_e32 v114, v115, v114, vcc
	v_div_scale_f32 v115, s[0:1], v114, v114, 1.0
	v_rcp_f32_e32 v116, v115
	s_nop 0
	v_fma_f32 v117, -v115, v116, 1.0
	v_fmac_f32_e32 v116, v117, v116
	v_div_scale_f32 v117, vcc, 1.0, v114, 1.0
	v_mul_f32_e32 v118, v117, v116
	v_fma_f32 v119, -v115, v118, v117
	v_fmac_f32_e32 v118, v119, v116
	v_fma_f32 v115, -v115, v118, v117
	v_div_fmas_f32 v115, v115, v116, v118
	global_load_dwordx4 v[116:119], v[140:141], off offset:16
	global_load_dwordx4 v[120:123], v[140:141], off
	v_div_fixup_f32 v114, v115, v114, 1.0
	s_waitcnt vmcnt(1)
	v_fma_f32 v115, v105, v114, v117
	s_waitcnt vmcnt(0)
; __device__ __forceinline__ unsigned pk2(float lo, float hi) { return f2bf(lo) | (f2bf(hi) << 16); }
;     __device__ __forceinline__ void operator()(const f32x4 (&acc)[2][2][4][2], const pg8::Unit& u, int wr, int wc, int fr, int fq) const {
;     ...
;                 const size_t row = (size_t)(row0 + ai * 128 + m * 16);
;                 float ssq = 0.f, rstd = 1.f;
;                 if constexpr (MODE == 8) rstd = 1.f / sqrtf(rs[row] * (1.f / DM) + EPS);
;     ...
;                     } else if constexpr (MODE == 8) {
;                         const f32x4 b0 = *(const f32x4*)(vec + col), b1 = *(const f32x4*)(vec + col + 4);
;                         float r[8] = {v0[0] * rstd + b0[0], v0[1] * rstd + b0[1], v0[2] * rstd + b0[2], v0[3] * rstd + b0[3], v1[0] * rstd + b1[0], v1[1] * rstd + b1[1], v1[2] * rstd + b1[2], v1[3] * rstd + b1[3]};
; #pragma unroll
;                         for (int i = 0; i < 8; ++i) { const float q = fmaxf(r[i], 0.f); r[i] = q * q; }
;                         u32x4 w; w.x = pk2(r[0], r[1]); w.y = pk2(r[2], r[3]); w.z = pk2(r[4], r[5]); w.w = pk2(r[6], r[7]);
;                         *(u32x4*)(ob + row * HIDN + col) = w;
	v_fma_f32 v108, v108, v114, v120
	v_fma_f32 v109, v109, v114, v121
	v_fma_f32 v110, v110, v114, v122
	v_fmac_f32_e32 v123, v111, v114
	v_fma_f32 v111, v104, v114, v116
	v_fmac_f32_e32 v119, v107, v114
	v_fma_f32 v116, v106, v114, v118
	v_max_f32_e32 v104, 0, v108
	v_max_f32_e32 v106, 0, v109
	v_max_f32_e32 v105, 0, v110
	v_max_f32_e32 v107, 0, v123
	v_max_f32_e32 v108, 0, v111
	v_max_f32_e32 v110, 0, v115
	v_max_f32_e32 v111, 0, v119
	v_max_f32_e32 v109, 0, v116
	v_pk_mul_f32 v[106:107], v[106:107], v[106:107]
	v_pk_mul_f32 v[110:111], v[110:111], v[110:111]
	v_pk_mul_f32 v[108:109], v[108:109], v[108:109]
	v_pk_mul_f32 v[104:105], v[104:105], v[104:105]
	v_cvt_pk_bf16_f32 v104, v104, v106
	v_cvt_pk_bf16_f32 v105, v105, v107
	v_cvt_pk_bf16_f32 v106, v108, v110
	v_cvt_pk_bf16_f32 v107, v109, v111
	v_lshl_add_u64 v[108:109], s[20:21], 0, v[112:113]
	v_lshl_add_u64 v[108:109], v[108:109], 0, v[142:143]
	global_store_dwordx4 v[108:109], v[104:107], off
	global_load_dwordx4 v[104:107], v[126:127], off offset:16
	s_nop 0
	global_load_dwordx4 v[110:113], v[126:127], off
	s_waitcnt vmcnt(1)
	v_fmac_f32_e32 v107, v99, v114
	s_waitcnt vmcnt(0)
	v_fma_f32 v100, v100, v114, v110
	v_fma_f32 v101, v101, v114, v111
	v_fma_f32 v102, v102, v114, v112
	v_fmac_f32_e32 v113, v103, v114
	v_fma_f32 v103, v96, v114, v104
	v_fma_f32 v104, v97, v114, v105
	v_fma_f32 v105, v98, v114, v106
	v_max_f32_e32 v96, 0, v100
	v_max_f32_e32 v98, 0, v101
	v_max_f32_e32 v97, 0, v102
	v_max_f32_e32 v99, 0, v113
	v_max_f32_e32 v100, 0, v103
	v_max_f32_e32 v102, 0, v104
	v_max_f32_e32 v103, 0, v107
	v_max_f32_e32 v101, 0, v105
	v_pk_mul_f32 v[98:99], v[98:99], v[98:99]
	v_pk_mul_f32 v[102:103], v[102:103], v[102:103]
	v_pk_mul_f32 v[96:97], v[96:97], v[96:97]
	v_pk_mul_f32 v[100:101], v[100:101], v[100:101]
	v_cvt_pk_bf16_f32 v96, v96, v98
	v_cvt_pk_bf16_f32 v97, v97, v99
	v_cvt_pk_bf16_f32 v98, v100, v102
	v_cvt_pk_bf16_f32 v99, v101, v103
	global_store_dwordx4 v[108:109], v[96:99], off offset:256
	s_nop 1
	v_or_b32_e32 v96, 32, v144
	v_ashrrev_i32_e32 v97, 31, v96
	v_lshl_add_u64 v[98:99], v[96:97], 2, s[8:9]
	global_load_dword v98, v[98:99], off
	v_lshlrev_b64 v[96:97], 14, v[96:97]
	s_waitcnt vmcnt(0)
	v_fmamk_f32 v98, v98, 0x3a000000, v205
	v_cmp_gt_f32_e32 vcc, s10, v98
	v_mul_f32_e32 v99, 0x4f800000, v98
	s_nop 0
	v_cndmask_b32_e32 v98, v98, v99, vcc
	v_sqrt_f32_e32 v99, v98
	s_nop 0
	v_add_u32_e32 v100, -1, v99
	v_fma_f32 v101, -v100, v99, v98
	v_cmp_ge_f32_e64 s[0:1], 0, v101
	v_add_u32_e32 v101, 1, v99
	s_nop 0
	v_cndmask_b32_e64 v100, v99, v100, s[0:1]
	v_fma_f32 v99, -v101, v99, v98
	v_cmp_lt_f32_e64 s[0:1], 0, v99
	s_nop 1
	v_cndmask_b32_e64 v99, v100, v101, s[0:1]
	v_mul_f32_e32 v100, 0x37800000, v99
	v_cndmask_b32_e32 v99, v99, v100, vcc
	v_cmp_class_f32_e32 vcc, v98, v206
	s_nop 1
	v_cndmask_b32_e32 v98, v99, v98, vcc
	v_div_scale_f32 v99, s[0:1], v98, v98, 1.0
	v_rcp_f32_e32 v100, v99
	s_nop 0
	v_fma_f32 v101, -v99, v100, 1.0
	v_fmac_f32_e32 v100, v101, v100
	v_div_scale_f32 v101, vcc, 1.0, v98, 1.0
	v_mul_f32_e32 v102, v101, v100
	v_fma_f32 v103, -v99, v102, v101
	v_fmac_f32_e32 v102, v103, v100
	v_fma_f32 v99, -v99, v102, v101
	v_div_fmas_f32 v99, v99, v100, v102
	global_load_dwordx4 v[100:103], v[140:141], off offset:16
	global_load_dwordx4 v[104:107], v[140:141], off
	v_div_fixup_f32 v98, v99, v98, 1.0
	s_waitcnt vmcnt(1)
	v_fma_f32 v99, v89, v98, v101
	s_waitcnt vmcnt(0)
	v_fma_f32 v92, v92, v98, v104
	v_fma_f32 v93, v93, v98, v105
	v_fma_f32 v94, v94, v98, v106
	v_fmac_f32_e32 v107, v95, v98
	v_fma_f32 v95, v88, v98, v100
	v_fmac_f32_e32 v103, v91, v98
	v_fma_f32 v100, v90, v98, v102
	v_max_f32_e32 v88, 0, v92
	v_max_f32_e32 v90, 0, v93
	v_max_f32_e32 v89, 0, v94
	v_max_f32_e32 v91, 0, v107
	v_max_f32_e32 v92, 0, v95
	v_max_f32_e32 v94, 0, v99
	v_max_f32_e32 v95, 0, v103
	v_max_f32_e32 v93, 0, v100
	v_pk_mul_f32 v[90:91], v[90:91], v[90:91]
	v_pk_mul_f32 v[94:95], v[94:95], v[94:95]
	v_pk_mul_f32 v[92:93], v[92:93], v[92:93]
	v_pk_mul_f32 v[88:89], v[88:89], v[88:89]
	v_cvt_pk_bf16_f32 v88, v88, v90
	v_cvt_pk_bf16_f32 v89, v89, v91
	v_cvt_pk_bf16_f32 v90, v92, v94
	v_cvt_pk_bf16_f32 v91, v93, v95
	v_lshl_add_u64 v[92:93], s[20:21], 0, v[96:97]
	v_lshl_add_u64 v[92:93], v[92:93], 0, v[142:143]
	global_store_dwordx4 v[92:93], v[88:91], off
	global_load_dwordx4 v[88:91], v[126:127], off offset:16
	s_nop 0
	global_load_dwordx4 v[94:97], v[126:127], off
	s_waitcnt vmcnt(1)
	v_fmac_f32_e32 v91, v83, v98
	s_waitcnt vmcnt(0)
	v_fma_f32 v84, v84, v98, v94
	v_fma_f32 v85, v85, v98, v95
	v_fma_f32 v86, v86, v98, v96
	v_fmac_f32_e32 v97, v87, v98
	v_fma_f32 v87, v80, v98, v88
	v_fma_f32 v88, v81, v98, v89
	v_fma_f32 v89, v82, v98, v90
	v_max_f32_e32 v80, 0, v84
	v_max_f32_e32 v82, 0, v85
	v_max_f32_e32 v81, 0, v86
	v_max_f32_e32 v83, 0, v97
	v_max_f32_e32 v84, 0, v87
	v_max_f32_e32 v86, 0, v88
	v_max_f32_e32 v87, 0, v91
	v_max_f32_e32 v85, 0, v89
	v_pk_mul_f32 v[82:83], v[82:83], v[82:83]
	v_pk_mul_f32 v[86:87], v[86:87], v[86:87]
	v_pk_mul_f32 v[80:81], v[80:81], v[80:81]
	v_pk_mul_f32 v[84:85], v[84:85], v[84:85]
	v_cvt_pk_bf16_f32 v80, v80, v82
	v_cvt_pk_bf16_f32 v81, v81, v83
	v_cvt_pk_bf16_f32 v82, v84, v86
	v_cvt_pk_bf16_f32 v83, v85, v87
	global_store_dwordx4 v[92:93], v[80:83], off offset:256
	s_nop 1
	v_or_b32_e32 v80, 48, v144
	v_ashrrev_i32_e32 v81, 31, v80
	v_lshl_add_u64 v[82:83], v[80:81], 2, s[8:9]
	global_load_dword v82, v[82:83], off
	v_lshlrev_b64 v[80:81], 14, v[80:81]
	s_waitcnt vmcnt(0)
; __device__ __forceinline__ unsigned pk2(float lo, float hi) { return f2bf(lo) | (f2bf(hi) << 16); }
;     __device__ __forceinline__ void operator()(const f32x4 (&acc)[2][2][4][2], const pg8::Unit& u, int wr, int wc, int fr, int fq) const {
;     ...
;                 const size_t row = (size_t)(row0 + ai * 128 + m * 16);
;                 float ssq = 0.f, rstd = 1.f;
;                 if constexpr (MODE == 8) rstd = 1.f / sqrtf(rs[row] * (1.f / DM) + EPS);
;     ...
;                     } else if constexpr (MODE == 8) {
;                         const f32x4 b0 = *(const f32x4*)(vec + col), b1 = *(const f32x4*)(vec + col + 4);
;                         float r[8] = {v0[0] * rstd + b0[0], v0[1] * rstd + b0[1], v0[2] * rstd + b0[2], v0[3] * rstd + b0[3], v1[0] * rstd + b1[0], v1[1] * rstd + b1[1], v1[2] * rstd + b1[2], v1[3] * rstd + b1[3]};
; #pragma unroll
;                         for (int i = 0; i < 8; ++i) { const float q = fmaxf(r[i], 0.f); r[i] = q * q; }
;                         u32x4 w; w.x = pk2(r[0], r[1]); w.y = pk2(r[2], r[3]); w.z = pk2(r[4], r[5]); w.w = pk2(r[6], r[7]);
;                         *(u32x4*)(ob + row * HIDN + col) = w;
	v_fmamk_f32 v82, v82, 0x3a000000, v205
	v_cmp_gt_f32_e32 vcc, s10, v82
	v_mul_f32_e32 v83, 0x4f800000, v82
	s_nop 0
	v_cndmask_b32_e32 v82, v82, v83, vcc
	v_sqrt_f32_e32 v83, v82
	s_nop 0
	v_add_u32_e32 v84, -1, v83
	v_fma_f32 v85, -v84, v83, v82
	v_cmp_ge_f32_e64 s[0:1], 0, v85
	v_add_u32_e32 v85, 1, v83
	s_nop 0
	v_cndmask_b32_e64 v84, v83, v84, s[0:1]
	v_fma_f32 v83, -v85, v83, v82
	v_cmp_lt_f32_e64 s[0:1], 0, v83
	s_nop 1
	v_cndmask_b32_e64 v83, v84, v85, s[0:1]
	v_mul_f32_e32 v84, 0x37800000, v83
	v_cndmask_b32_e32 v83, v83, v84, vcc
	v_cmp_class_f32_e32 vcc, v82, v206
	s_nop 1
	v_cndmask_b32_e32 v82, v83, v82, vcc
	v_div_scale_f32 v83, s[0:1], v82, v82, 1.0
	v_rcp_f32_e32 v84, v83
	s_nop 0
	v_fma_f32 v85, -v83, v84, 1.0
	v_fmac_f32_e32 v84, v85, v84
	v_div_scale_f32 v85, vcc, 1.0, v82, 1.0
	v_mul_f32_e32 v86, v85, v84
	v_fma_f32 v87, -v83, v86, v85
	v_fmac_f32_e32 v86, v87, v84
	v_fma_f32 v83, -v83, v86, v85
	v_div_fmas_f32 v83, v83, v84, v86
	global_load_dwordx4 v[84:87], v[140:141], off offset:16
	global_load_dwordx4 v[88:91], v[140:141], off
	v_div_fixup_f32 v82, v83, v82, 1.0
	s_waitcnt vmcnt(1)
	v_fma_f32 v83, v73, v82, v85
	s_waitcnt vmcnt(0)
	v_fma_f32 v76, v76, v82, v88
	v_fma_f32 v77, v77, v82, v89
	v_fma_f32 v78, v78, v82, v90
	v_fmac_f32_e32 v91, v79, v82
	v_fma_f32 v79, v72, v82, v84
	v_fmac_f32_e32 v87, v75, v82
	v_fma_f32 v84, v74, v82, v86
	v_max_f32_e32 v72, 0, v76
	v_max_f32_e32 v74, 0, v77
	v_max_f32_e32 v73, 0, v78
	v_max_f32_e32 v75, 0, v91
	v_max_f32_e32 v76, 0, v79
	v_max_f32_e32 v78, 0, v83
	v_max_f32_e32 v79, 0, v87
	v_max_f32_e32 v77, 0, v84
	v_pk_mul_f32 v[74:75], v[74:75], v[74:75]
	v_pk_mul_f32 v[78:79], v[78:79], v[78:79]
	v_pk_mul_f32 v[76:77], v[76:77], v[76:77]
	v_pk_mul_f32 v[72:73], v[72:73], v[72:73]
	v_cvt_pk_bf16_f32 v72, v72, v74
	v_cvt_pk_bf16_f32 v73, v73, v75
	v_cvt_pk_bf16_f32 v74, v76, v78
	v_cvt_pk_bf16_f32 v75, v77, v79
	v_lshl_add_u64 v[76:77], s[20:21], 0, v[80:81]
	v_lshl_add_u64 v[76:77], v[76:77], 0, v[142:143]
	global_store_dwordx4 v[76:77], v[72:75], off
	global_load_dwordx4 v[72:75], v[126:127], off offset:16
	s_nop 0
	global_load_dwordx4 v[78:81], v[126:127], off
	s_waitcnt vmcnt(1)
	v_fmac_f32_e32 v75, v67, v82
	s_waitcnt vmcnt(0)
	v_fma_f32 v68, v68, v82, v78
	v_fma_f32 v69, v69, v82, v79
	v_fma_f32 v70, v70, v82, v80
	v_fmac_f32_e32 v81, v71, v82
	v_fma_f32 v71, v64, v82, v72
	v_fma_f32 v72, v65, v82, v73
	v_fma_f32 v73, v66, v82, v74
	v_max_f32_e32 v64, 0, v68
	v_max_f32_e32 v66, 0, v69
	v_max_f32_e32 v65, 0, v70
	v_max_f32_e32 v67, 0, v81
	v_max_f32_e32 v68, 0, v71
	v_max_f32_e32 v70, 0, v72
	v_max_f32_e32 v71, 0, v75
	v_max_f32_e32 v69, 0, v73
	v_pk_mul_f32 v[66:67], v[66:67], v[66:67]
	v_pk_mul_f32 v[70:71], v[70:71], v[70:71]
	v_pk_mul_f32 v[64:65], v[64:65], v[64:65]
	v_pk_mul_f32 v[68:69], v[68:69], v[68:69]
	v_cvt_pk_bf16_f32 v64, v64, v66
	v_cvt_pk_bf16_f32 v65, v65, v67
	v_cvt_pk_bf16_f32 v66, v68, v70
	v_cvt_pk_bf16_f32 v67, v69, v71
	global_store_dwordx4 v[76:77], v[64:67], off offset:256
	global_load_dword v64, v[138:139], off offset:512
	s_waitcnt vmcnt(0)
	v_fmamk_f32 v64, v64, 0x3a000000, v205
	v_cmp_gt_f32_e32 vcc, s10, v64
	v_mul_f32_e32 v65, 0x4f800000, v64
	s_nop 0
	v_cndmask_b32_e32 v64, v64, v65, vcc
	v_sqrt_f32_e32 v65, v64
	s_nop 0
	v_add_u32_e32 v66, -1, v65
	v_fma_f32 v67, -v66, v65, v64
	v_cmp_ge_f32_e64 s[0:1], 0, v67
	v_add_u32_e32 v67, 1, v65
	s_nop 0
	v_cndmask_b32_e64 v66, v65, v66, s[0:1]
	v_fma_f32 v65, -v67, v65, v64
	v_cmp_lt_f32_e64 s[0:1], 0, v65
	s_nop 1
	v_cndmask_b32_e64 v65, v66, v67, s[0:1]
	v_mul_f32_e32 v66, 0x37800000, v65
	v_cndmask_b32_e32 v65, v65, v66, vcc
	v_cmp_class_f32_e32 vcc, v64, v206
	s_nop 1
	v_cndmask_b32_e32 v64, v65, v64, vcc
	v_div_scale_f32 v65, s[0:1], v64, v64, 1.0
	v_rcp_f32_e32 v66, v65
	s_mov_b64 s[0:1], 0x200000
	v_fma_f32 v67, -v65, v66, 1.0
	v_fmac_f32_e32 v66, v67, v66
	v_div_scale_f32 v67, vcc, 1.0, v64, 1.0
	v_mul_f32_e32 v68, v67, v66
	v_fma_f32 v69, -v65, v68, v67
	v_fmac_f32_e32 v68, v69, v66
	v_fma_f32 v65, -v65, v68, v67
	v_div_fmas_f32 v65, v65, v66, v68
	global_load_dwordx4 v[66:69], v[140:141], off offset:16
	global_load_dwordx4 v[70:73], v[140:141], off
	v_div_fixup_f32 v64, v65, v64, 1.0
	s_waitcnt vmcnt(1)
	v_fma_f32 v65, v57, v64, v67
	s_waitcnt vmcnt(0)
	v_fma_f32 v60, v60, v64, v70
	v_fma_f32 v61, v61, v64, v71
	v_fma_f32 v62, v62, v64, v72
	v_fmac_f32_e32 v73, v63, v64
	v_fma_f32 v63, v56, v64, v66
	v_fmac_f32_e32 v69, v59, v64
	v_fma_f32 v66, v58, v64, v68
	v_max_f32_e32 v56, 0, v60
	v_max_f32_e32 v58, 0, v61
	v_max_f32_e32 v57, 0, v62
	v_max_f32_e32 v59, 0, v73
	v_max_f32_e32 v60, 0, v63
	v_max_f32_e32 v62, 0, v65
	v_max_f32_e32 v63, 0, v69
	v_max_f32_e32 v61, 0, v66
	v_pk_mul_f32 v[58:59], v[58:59], v[58:59]
	v_pk_mul_f32 v[62:63], v[62:63], v[62:63]
	v_pk_mul_f32 v[60:61], v[60:61], v[60:61]
	v_bfe_u32 v67, v59, 16, 1
	v_bfe_u32 v68, v58, 16, 1
	v_add3_u32 v68, v58, v68, s33
	v_add3_u32 v67, v59, v67, s33
	v_pk_mul_f32 v[56:57], v[56:57], v[56:57]
	v_cvt_pk_bf16_f32 v59, v61, v63
	v_cvt_pk_bf16_f32 v58, v60, v62
	v_bfe_u32 v62, v56, 16, 1
	v_bfe_u32 v63, v57, 16, 1
	v_add3_u32 v57, v57, v63, s33
	v_add3_u32 v56, v56, v62, s33
	v_lshl_add_u64 v[60:61], v[124:125], 0, s[0:1]
	s_mov_b32 s0, 0x200000
	v_lshrrev_b32_e32 v56, 16, v56
	v_lshrrev_b32_e32 v57, 16, v57
	v_add_co_u32_e32 v62, vcc, s0, v124
	v_and_or_b32 v57, v67, s67, v57
	v_and_or_b32 v56, v68, s67, v56
	v_addc_co_u32_e32 v63, vcc, 0, v125, vcc
	global_store_dwordx4 v[62:63], v[56:59], off
	global_load_dwordx4 v[56:59], v[126:127], off offset:16
	s_nop 0
	global_load_dwordx4 v[66:69], v[126:127], off
	s_waitcnt vmcnt(1)
; __device__ __forceinline__ unsigned pk2(float lo, float hi) { return f2bf(lo) | (f2bf(hi) << 16); }
;     __device__ __forceinline__ void operator()(const f32x4 (&acc)[2][2][4][2], const pg8::Unit& u, int wr, int wc, int fr, int fq) const {
;     ...
;                 const size_t row = (size_t)(row0 + ai * 128 + m * 16);
;                 float ssq = 0.f, rstd = 1.f;
;                 if constexpr (MODE == 8) rstd = 1.f / sqrtf(rs[row] * (1.f / DM) + EPS);
;     ...
;                     } else if constexpr (MODE == 8) {
;                         const f32x4 b0 = *(const f32x4*)(vec + col), b1 = *(const f32x4*)(vec + col + 4);
;                         float r[8] = {v0[0] * rstd + b0[0], v0[1] * rstd + b0[1], v0[2] * rstd + b0[2], v0[3] * rstd + b0[3], v1[0] * rstd + b1[0], v1[1] * rstd + b1[1], v1[2] * rstd + b1[2], v1[3] * rstd + b1[3]};
; #pragma unroll
;                         for (int i = 0; i < 8; ++i) { const float q = fmaxf(r[i], 0.f); r[i] = q * q; }
;                         u32x4 w; w.x = pk2(r[0], r[1]); w.y = pk2(r[2], r[3]); w.z = pk2(r[4], r[5]); w.w = pk2(r[6], r[7]);
;                         *(u32x4*)(ob + row * HIDN + col) = w;
	v_fmac_f32_e32 v59, v51, v64
	s_waitcnt vmcnt(0)
	v_fma_f32 v52, v52, v64, v66
	v_fma_f32 v53, v53, v64, v67
	v_fma_f32 v54, v54, v64, v68
	v_fmac_f32_e32 v69, v55, v64
	v_fma_f32 v55, v48, v64, v56
	v_fma_f32 v56, v49, v64, v57
	v_fma_f32 v57, v50, v64, v58
	v_max_f32_e32 v48, 0, v52
	v_max_f32_e32 v50, 0, v53
	v_max_f32_e32 v49, 0, v54
	v_max_f32_e32 v51, 0, v69
	v_max_f32_e32 v52, 0, v55
	v_max_f32_e32 v54, 0, v56
	v_max_f32_e32 v55, 0, v59
	v_max_f32_e32 v53, 0, v57
	v_pk_mul_f32 v[50:51], v[50:51], v[50:51]
	v_pk_mul_f32 v[54:55], v[54:55], v[54:55]
	v_pk_mul_f32 v[48:49], v[48:49], v[48:49]
	v_pk_mul_f32 v[52:53], v[52:53], v[52:53]
	v_cvt_pk_bf16_f32 v48, v48, v50
	v_cvt_pk_bf16_f32 v49, v49, v51
	v_cvt_pk_bf16_f32 v50, v52, v54
	v_cvt_pk_bf16_f32 v51, v53, v55
	global_store_dwordx4 v[60:61], v[48:51], off offset:256
	global_load_dword v48, v[138:139], off offset:576
	s_waitcnt vmcnt(0)
	v_fmamk_f32 v48, v48, 0x3a000000, v205
	v_cmp_gt_f32_e32 vcc, s10, v48
	v_mul_f32_e32 v49, 0x4f800000, v48
	s_nop 0
	v_cndmask_b32_e32 v48, v48, v49, vcc
	v_sqrt_f32_e32 v49, v48
	s_nop 0
	v_add_u32_e32 v50, -1, v49
	v_fma_f32 v51, -v50, v49, v48
	v_cmp_ge_f32_e64 s[0:1], 0, v51
	v_add_u32_e32 v51, 1, v49
	s_nop 0
	v_cndmask_b32_e64 v50, v49, v50, s[0:1]
	v_fma_f32 v49, -v51, v49, v48
	v_cmp_lt_f32_e64 s[0:1], 0, v49
	s_nop 1
	v_cndmask_b32_e64 v49, v50, v51, s[0:1]
	v_mul_f32_e32 v50, 0x37800000, v49
	v_cndmask_b32_e32 v49, v49, v50, vcc
	v_cmp_class_f32_e32 vcc, v48, v206
	s_nop 1
	v_cndmask_b32_e32 v48, v49, v48, vcc
	v_div_scale_f32 v49, s[0:1], v48, v48, 1.0
	v_rcp_f32_e32 v50, v49
	s_mov_b64 s[0:1], 0x240000
	v_fma_f32 v51, -v49, v50, 1.0
	v_fmac_f32_e32 v50, v51, v50
	v_div_scale_f32 v51, vcc, 1.0, v48, 1.0
	v_mul_f32_e32 v52, v51, v50
	v_fma_f32 v53, -v49, v52, v51
	v_fmac_f32_e32 v52, v53, v50
	v_fma_f32 v49, -v49, v52, v51
	v_div_fmas_f32 v49, v49, v50, v52
	global_load_dwordx4 v[50:53], v[140:141], off offset:16
	global_load_dwordx4 v[54:57], v[140:141], off
	v_div_fixup_f32 v48, v49, v48, 1.0
	s_waitcnt vmcnt(1)
	v_fma_f32 v49, v41, v48, v51
	s_waitcnt vmcnt(0)
	v_fma_f32 v44, v44, v48, v54
	v_fma_f32 v45, v45, v48, v55
	v_fma_f32 v46, v46, v48, v56
	v_fmac_f32_e32 v57, v47, v48
	v_fma_f32 v47, v40, v48, v50
	v_fmac_f32_e32 v53, v43, v48
	v_fma_f32 v50, v42, v48, v52
	v_max_f32_e32 v40, 0, v44
	v_max_f32_e32 v42, 0, v45
	v_max_f32_e32 v41, 0, v46
	v_max_f32_e32 v43, 0, v57
	v_max_f32_e32 v44, 0, v47
	v_max_f32_e32 v46, 0, v49
	v_max_f32_e32 v47, 0, v53
	v_max_f32_e32 v45, 0, v50
	v_pk_mul_f32 v[42:43], v[42:43], v[42:43]
	v_pk_mul_f32 v[46:47], v[46:47], v[46:47]
	v_pk_mul_f32 v[44:45], v[44:45], v[44:45]
	v_bfe_u32 v51, v43, 16, 1
	v_bfe_u32 v52, v42, 16, 1
	v_add3_u32 v52, v42, v52, s33
	v_add3_u32 v51, v43, v51, s33
	v_pk_mul_f32 v[40:41], v[40:41], v[40:41]
	v_cvt_pk_bf16_f32 v43, v45, v47
	v_cvt_pk_bf16_f32 v42, v44, v46
	v_bfe_u32 v46, v40, 16, 1
	v_bfe_u32 v47, v41, 16, 1
	v_add3_u32 v41, v41, v47, s33
	v_add3_u32 v40, v40, v46, s33
	v_lshl_add_u64 v[44:45], v[124:125], 0, s[0:1]
	s_mov_b32 s0, 0x240000
	v_lshrrev_b32_e32 v40, 16, v40
	v_lshrrev_b32_e32 v41, 16, v41
	v_add_co_u32_e32 v46, vcc, s0, v124
	v_and_or_b32 v41, v51, s67, v41
	v_and_or_b32 v40, v52, s67, v40
	v_addc_co_u32_e32 v47, vcc, 0, v125, vcc
	global_store_dwordx4 v[46:47], v[40:43], off
	global_load_dwordx4 v[40:43], v[126:127], off offset:16
	s_nop 0
	global_load_dwordx4 v[50:53], v[126:127], off
	s_waitcnt vmcnt(1)
	v_fmac_f32_e32 v43, v35, v48
	s_waitcnt vmcnt(0)
	v_fma_f32 v36, v36, v48, v50
	v_fma_f32 v37, v37, v48, v51
	v_fma_f32 v38, v38, v48, v52
	v_fmac_f32_e32 v53, v39, v48
	v_fma_f32 v39, v32, v48, v40
	v_fma_f32 v40, v33, v48, v41
	v_fma_f32 v41, v34, v48, v42
	v_max_f32_e32 v32, 0, v36
	v_max_f32_e32 v34, 0, v37
	v_max_f32_e32 v33, 0, v38
	v_max_f32_e32 v35, 0, v53
	v_max_f32_e32 v36, 0, v39
	v_max_f32_e32 v38, 0, v40
	v_max_f32_e32 v39, 0, v43
	v_max_f32_e32 v37, 0, v41
	v_pk_mul_f32 v[34:35], v[34:35], v[34:35]
	v_pk_mul_f32 v[38:39], v[38:39], v[38:39]
	v_pk_mul_f32 v[32:33], v[32:33], v[32:33]
	v_pk_mul_f32 v[36:37], v[36:37], v[36:37]
	v_cvt_pk_bf16_f32 v32, v32, v34
	v_cvt_pk_bf16_f32 v33, v33, v35
	v_cvt_pk_bf16_f32 v34, v36, v38
	v_cvt_pk_bf16_f32 v35, v37, v39
	global_store_dwordx4 v[44:45], v[32:35], off offset:256
	global_load_dword v32, v[138:139], off offset:640
	s_waitcnt vmcnt(0)
	v_fmamk_f32 v32, v32, 0x3a000000, v205
	v_cmp_gt_f32_e32 vcc, s10, v32
	v_mul_f32_e32 v33, 0x4f800000, v32
	s_nop 0
	v_cndmask_b32_e32 v32, v32, v33, vcc
	v_sqrt_f32_e32 v33, v32
	s_nop 0
	v_add_u32_e32 v34, -1, v33
	v_fma_f32 v35, -v34, v33, v32
	v_cmp_ge_f32_e64 s[0:1], 0, v35
	v_add_u32_e32 v35, 1, v33
	s_nop 0
	v_cndmask_b32_e64 v34, v33, v34, s[0:1]
	v_fma_f32 v33, -v35, v33, v32
	v_cmp_lt_f32_e64 s[0:1], 0, v33
	s_nop 1
	v_cndmask_b32_e64 v33, v34, v35, s[0:1]
	v_mul_f32_e32 v34, 0x37800000, v33
	v_cndmask_b32_e32 v33, v33, v34, vcc
	v_cmp_class_f32_e32 vcc, v32, v206
	s_nop 1
	v_cndmask_b32_e32 v32, v33, v32, vcc
	v_div_scale_f32 v33, s[0:1], v32, v32, 1.0
	v_rcp_f32_e32 v34, v33
	s_mov_b64 s[0:1], 0x280000
	v_fma_f32 v35, -v33, v34, 1.0
	v_fmac_f32_e32 v34, v35, v34
	v_div_scale_f32 v35, vcc, 1.0, v32, 1.0
	v_mul_f32_e32 v36, v35, v34
	v_fma_f32 v37, -v33, v36, v35
	v_fmac_f32_e32 v36, v37, v34
	v_fma_f32 v33, -v33, v36, v35
	v_div_fmas_f32 v33, v33, v34, v36
	global_load_dwordx4 v[34:37], v[140:141], off offset:16
	global_load_dwordx4 v[38:41], v[140:141], off
	v_div_fixup_f32 v32, v33, v32, 1.0
	s_waitcnt vmcnt(1)
	v_fma_f32 v33, v25, v32, v35
	s_waitcnt vmcnt(0)
; __device__ __forceinline__ unsigned pk2(float lo, float hi) { return f2bf(lo) | (f2bf(hi) << 16); }
;     __device__ __forceinline__ void operator()(const f32x4 (&acc)[2][2][4][2], const pg8::Unit& u, int wr, int wc, int fr, int fq) const {
;     ...
;                 const size_t row = (size_t)(row0 + ai * 128 + m * 16);
;                 float ssq = 0.f, rstd = 1.f;
;                 if constexpr (MODE == 8) rstd = 1.f / sqrtf(rs[row] * (1.f / DM) + EPS);
;     ...
;                     } else if constexpr (MODE == 8) {
;                         const f32x4 b0 = *(const f32x4*)(vec + col), b1 = *(const f32x4*)(vec + col + 4);
;                         float r[8] = {v0[0] * rstd + b0[0], v0[1] * rstd + b0[1], v0[2] * rstd + b0[2], v0[3] * rstd + b0[3], v1[0] * rstd + b1[0], v1[1] * rstd + b1[1], v1[2] * rstd + b1[2], v1[3] * rstd + b1[3]};
; #pragma unroll
;                         for (int i = 0; i < 8; ++i) { const float q = fmaxf(r[i], 0.f); r[i] = q * q; }
;                         u32x4 w; w.x = pk2(r[0], r[1]); w.y = pk2(r[2], r[3]); w.z = pk2(r[4], r[5]); w.w = pk2(r[6], r[7]);
;                         *(u32x4*)(ob + row * HIDN + col) = w;
	v_fma_f32 v28, v28, v32, v38
	v_fma_f32 v29, v29, v32, v39
	v_fma_f32 v30, v30, v32, v40
	v_fmac_f32_e32 v41, v31, v32
	v_fma_f32 v31, v24, v32, v34
	v_fmac_f32_e32 v37, v27, v32
	v_fma_f32 v34, v26, v32, v36
	v_max_f32_e32 v24, 0, v28
	v_max_f32_e32 v26, 0, v29
	v_max_f32_e32 v25, 0, v30
	v_max_f32_e32 v27, 0, v41
	v_max_f32_e32 v28, 0, v31
	v_max_f32_e32 v30, 0, v33
	v_max_f32_e32 v31, 0, v37
	v_max_f32_e32 v29, 0, v34
	v_pk_mul_f32 v[26:27], v[26:27], v[26:27]
	v_pk_mul_f32 v[30:31], v[30:31], v[30:31]
	v_pk_mul_f32 v[28:29], v[28:29], v[28:29]
	v_bfe_u32 v35, v27, 16, 1
	v_bfe_u32 v36, v26, 16, 1
	v_add3_u32 v36, v26, v36, s33
	v_add3_u32 v35, v27, v35, s33
	v_pk_mul_f32 v[24:25], v[24:25], v[24:25]
	v_cvt_pk_bf16_f32 v27, v29, v31
	v_cvt_pk_bf16_f32 v26, v28, v30
	v_bfe_u32 v30, v24, 16, 1
	v_bfe_u32 v31, v25, 16, 1
	v_add3_u32 v25, v25, v31, s33
	v_add3_u32 v24, v24, v30, s33
	v_lshl_add_u64 v[28:29], v[124:125], 0, s[0:1]
	s_mov_b32 s0, 0x280000
	v_lshrrev_b32_e32 v24, 16, v24
	v_lshrrev_b32_e32 v25, 16, v25
	v_add_co_u32_e32 v30, vcc, s0, v124
	v_and_or_b32 v25, v35, s67, v25
	v_and_or_b32 v24, v36, s67, v24
	v_addc_co_u32_e32 v31, vcc, 0, v125, vcc
	global_store_dwordx4 v[30:31], v[24:27], off
	global_load_dwordx4 v[24:27], v[126:127], off offset:16
	s_nop 0
	global_load_dwordx4 v[34:37], v[126:127], off
	s_waitcnt vmcnt(1)
	v_fmac_f32_e32 v27, v19, v32
	s_waitcnt vmcnt(0)
	v_fma_f32 v20, v20, v32, v34
	v_fma_f32 v21, v21, v32, v35
	v_fma_f32 v22, v22, v32, v36
	v_fmac_f32_e32 v37, v23, v32
	v_fma_f32 v23, v16, v32, v24
	v_fma_f32 v24, v17, v32, v25
	v_fma_f32 v25, v18, v32, v26
	v_max_f32_e32 v16, 0, v20
	v_max_f32_e32 v18, 0, v21
	v_max_f32_e32 v17, 0, v22
	v_max_f32_e32 v19, 0, v37
	v_max_f32_e32 v20, 0, v23
	v_max_f32_e32 v22, 0, v24
	v_max_f32_e32 v23, 0, v27
	v_max_f32_e32 v21, 0, v25
	v_pk_mul_f32 v[18:19], v[18:19], v[18:19]
	v_pk_mul_f32 v[22:23], v[22:23], v[22:23]
	v_pk_mul_f32 v[16:17], v[16:17], v[16:17]
	v_pk_mul_f32 v[20:21], v[20:21], v[20:21]
	v_cvt_pk_bf16_f32 v16, v16, v18
	v_cvt_pk_bf16_f32 v17, v17, v19
	v_cvt_pk_bf16_f32 v18, v20, v22
	v_cvt_pk_bf16_f32 v19, v21, v23
	global_store_dwordx4 v[28:29], v[16:19], off offset:256
	global_load_dword v16, v[138:139], off offset:704
	s_waitcnt vmcnt(0)
	v_fmamk_f32 v16, v16, 0x3a000000, v205
	v_cmp_gt_f32_e32 vcc, s10, v16
	v_mul_f32_e32 v17, 0x4f800000, v16
	s_nop 0
	v_cndmask_b32_e32 v16, v16, v17, vcc
	v_sqrt_f32_e32 v17, v16
	s_nop 0
	v_add_u32_e32 v18, -1, v17
	v_fma_f32 v19, -v18, v17, v16
	v_cmp_ge_f32_e64 s[0:1], 0, v19
	v_add_u32_e32 v19, 1, v17
	s_nop 0
	v_cndmask_b32_e64 v18, v17, v18, s[0:1]
	v_fma_f32 v17, -v19, v17, v16
	v_cmp_lt_f32_e64 s[0:1], 0, v17
	s_nop 1
	v_cndmask_b32_e64 v17, v18, v19, s[0:1]
	v_mul_f32_e32 v18, 0x37800000, v17
	v_cndmask_b32_e32 v17, v17, v18, vcc
	v_cmp_class_f32_e32 vcc, v16, v206
	s_nop 1
	v_cndmask_b32_e32 v16, v17, v16, vcc
	v_div_scale_f32 v17, s[0:1], v16, v16, 1.0
	v_rcp_f32_e32 v18, v17
	s_mov_b64 s[0:1], 0x2c0000
	v_fma_f32 v19, -v17, v18, 1.0
	v_fmac_f32_e32 v18, v19, v18
	v_div_scale_f32 v19, vcc, 1.0, v16, 1.0
	v_mul_f32_e32 v20, v19, v18
	v_fma_f32 v21, -v17, v20, v19
	v_fmac_f32_e32 v20, v21, v18
	v_fma_f32 v17, -v17, v20, v19
	v_div_fmas_f32 v17, v17, v18, v20
	global_load_dwordx4 v[18:21], v[140:141], off offset:16
	global_load_dwordx4 v[22:25], v[140:141], off
	v_div_fixup_f32 v16, v17, v16, 1.0
	s_waitcnt vmcnt(1)
	v_fma_f32 v17, v9, v16, v19
	s_waitcnt vmcnt(0)
	v_fma_f32 v12, v12, v16, v22
	v_fma_f32 v13, v13, v16, v23
	v_fma_f32 v14, v14, v16, v24
	v_fmac_f32_e32 v25, v15, v16
	v_fma_f32 v15, v8, v16, v18
	v_fmac_f32_e32 v21, v11, v16
	v_fma_f32 v18, v10, v16, v20
	v_max_f32_e32 v8, 0, v12
	v_max_f32_e32 v10, 0, v13
	v_max_f32_e32 v9, 0, v14
	v_max_f32_e32 v11, 0, v25
	v_max_f32_e32 v12, 0, v15
	v_max_f32_e32 v14, 0, v17
	v_max_f32_e32 v15, 0, v21
	v_max_f32_e32 v13, 0, v18
	v_pk_mul_f32 v[10:11], v[10:11], v[10:11]
	v_pk_mul_f32 v[14:15], v[14:15], v[14:15]
	v_pk_mul_f32 v[12:13], v[12:13], v[12:13]
	v_bfe_u32 v19, v11, 16, 1
	v_bfe_u32 v20, v10, 16, 1
	v_add3_u32 v20, v10, v20, s33
	v_add3_u32 v19, v11, v19, s33
	v_pk_mul_f32 v[8:9], v[8:9], v[8:9]
	v_cvt_pk_bf16_f32 v11, v13, v15
	v_cvt_pk_bf16_f32 v10, v12, v14
	v_bfe_u32 v14, v8, 16, 1
	v_bfe_u32 v15, v9, 16, 1
	v_add3_u32 v9, v9, v15, s33
	v_add3_u32 v8, v8, v14, s33
	v_lshl_add_u64 v[12:13], v[124:125], 0, s[0:1]
	s_mov_b32 s0, 0x2c0000
	v_lshrrev_b32_e32 v8, 16, v8
	v_lshrrev_b32_e32 v9, 16, v9
	v_add_co_u32_e32 v14, vcc, s0, v124
	v_and_or_b32 v9, v19, s67, v9
	v_and_or_b32 v8, v20, s67, v8
	v_addc_co_u32_e32 v15, vcc, 0, v125, vcc
	global_store_dwordx4 v[14:15], v[8:11], off
	global_load_dwordx4 v[8:11], v[126:127], off offset:16
	s_nop 0
	global_load_dwordx4 v[18:21], v[126:127], off
	s_mov_b64 s[0:1], -1
	s_andn2_b64 vcc, exec, s[38:39]
	s_waitcnt vmcnt(1)
	v_fmac_f32_e32 v11, v3, v16
	s_waitcnt vmcnt(0)
	v_fma_f32 v4, v4, v16, v18
	v_fma_f32 v5, v5, v16, v19
	v_fma_f32 v6, v6, v16, v20
	v_fmac_f32_e32 v21, v7, v16
	v_fma_f32 v7, v0, v16, v8
	v_fma_f32 v8, v1, v16, v9
	v_fma_f32 v9, v2, v16, v10
	v_max_f32_e32 v0, 0, v4
	v_max_f32_e32 v2, 0, v5
	v_max_f32_e32 v1, 0, v6
	v_max_f32_e32 v3, 0, v21
	v_max_f32_e32 v4, 0, v7
	v_max_f32_e32 v6, 0, v8
	v_max_f32_e32 v7, 0, v11
	v_max_f32_e32 v5, 0, v9
	v_pk_mul_f32 v[2:3], v[2:3], v[2:3]
	v_pk_mul_f32 v[6:7], v[6:7], v[6:7]
	v_pk_mul_f32 v[0:1], v[0:1], v[0:1]
	v_pk_mul_f32 v[4:5], v[4:5], v[4:5]
	v_cvt_pk_bf16_f32 v0, v0, v2
	v_cvt_pk_bf16_f32 v1, v1, v3
	v_cvt_pk_bf16_f32 v2, v4, v6
	v_cvt_pk_bf16_f32 v3, v5, v7
	global_store_dwordx4 v[12:13], v[0:3], off offset:256
	s_cbranch_vccnz .LBB0_24
	s_andn2_b64 vcc, exec, s[42:43]
	s_cbranch_vccnz .LBB0_23
	s_barrier
	s_branch .LBB0_23

;     __device__ __forceinline__ void operator()(const f32x4 (&acc)[2][2][4][2], const pg8::Unit& u, int wr, int wc, int fr, int fq) const {
;     ...
;                     } else if constexpr (MODE == 7) {
;                         const f32x4 g0 = *(const f32x4*)(vec + col), g1 = *(const f32x4*)(vec + col + 4);
;                         const f32x4 x0 = *(const f32x4*)(xsrc + row * DM + col), x1 = *(const f32x4*)(xsrc + row * DM + col + 4);
;                         const f32x4 y0 = x0 + g0 * v0, y1 = x1 + g1 * v1;
;                         *(f32x4*)(of + row * DM + col) = y0; *(f32x4*)(of + row * DM + col + 4) = y1;
;                         ssq += (y0[0] * y0[0] + y0[1] * y0[1]) + (y0[2] * y0[2] + y0[3] * y0[3]) + (y1[0] * y1[0] + y1[1] * y1[1]) + (y1[2] * y1[2] + y1[3] * y1[3]);
;                         const f32x4 s0 = *(const f32x4*)(vec2 + col) + 1.f, s1 = *(const f32x4*)(vec2 + col + 4) + 1.f;
;                         const f32x4 a0 = y0 * s0, a1 = y1 * s1;
;                         u32x4 w; w.x = pk2(a0[0], a0[1]); w.y = pk2(a0[2], a0[3]); w.z = pk2(a1[0], a1[1]); w.w = pk2(a1[2], a1[3]);
;                         *(u32x4*)(ob + row * DM + col) = w;
;                     } else if constexpr (MODE == 8) {
;                         const f32x4 b0 = *(const f32x4*)(vec + col), b1 = *(const f32x4*)(vec + col + 4);
;                         float r[8] = {v0[0] * rstd + b0[0], v0[1] * rstd + b0[1], v0[2] * rstd + b0[2], v0[3] * rstd + b0[3], v1[0] * rstd + b1[0], v1[1] * rstd + b1[1], v1[2] * rstd + b1[2], v1[3] * rstd + b1[3]};
; #pragma unroll
;                         for (int i = 0; i < 8; ++i) { const float q = fmaxf(r[i], 0.f); r[i] = q * q; }
;                         u32x4 w; w.x = pk2(r[0], r[1]); w.y = pk2(r[2], r[3]); w.z = pk2(r[4], r[5]); w.w = pk2(r[6], r[7]);
;                         *(u32x4*)(ob + row * HIDN + col) = w;
;                     } else {
;                         float r[8] = {v0[0], v0[1], v0[2], v0[3], v1[0], v1[1], v1[2], v1[3]};
; #pragma unroll
;                         for (int i = 0; i < 8; ++i) { const float q = fmaxf(r[i], 0.f); r[i] = q * q; }
;                         u32x4 w; w.x = pk2(r[0], r[1]); w.y = pk2(r[2], r[3]); w.z = pk2(r[4], r[5]); w.w = pk2(r[6], r[7]);
;                         *(u32x4*)(ob + row * HIDN + col) = w;
;                     }
;                 }
;                 if constexpr (MODE == 7) {
.LBB0_62:
	v_lshl_add_u32 v144, s10, 8, v150
	v_lshl_or_b32 v138, s16, 8, v152
	v_ashrrev_i32_e32 v145, 31, v144
	v_ashrrev_i32_e32 v139, 31, v138
	v_lshlrev_b64 v[148:149], 13, v[144:145]
	v_lshlrev_b64 v[140:141], 2, v[138:139]
	v_lshl_add_u64 v[146:147], s[30:31], 0, v[148:149]
	v_lshl_add_u64 v[142:143], s[4:5], 0, v[140:141]
	v_lshl_add_u64 v[146:147], v[146:147], 0, v[140:141]
	global_load_dwordx4 v[154:157], v[142:143], off offset:16
	global_load_dwordx4 v[184:187], v[142:143], off
	global_load_dwordx4 v[188:191], v[146:147], off offset:16
	global_load_dwordx4 v[192:195], v[146:147], off
	v_readlane_b32 s28, v251, 7
	v_readlane_b32 s29, v251, 8
	s_waitcnt vmcnt(0)
	v_pk_fma_f32 v[186:187], v[126:127], v[186:187], v[194:195]
	v_pk_fma_f32 v[184:185], v[124:125], v[184:185], v[192:193]
	v_pk_fma_f32 v[124:125], v[122:123], v[156:157], v[190:191]
	v_pk_fma_f32 v[122:123], v[120:121], v[154:155], v[188:189]
	v_lshl_add_u64 v[120:121], s[6:7], 0, v[148:149]
	v_lshl_add_u64 v[126:127], v[120:121], 0, v[140:141]
	v_mul_f32_e32 v120, v185, v185
	v_mul_f32_e32 v121, v187, v187
	v_fmac_f32_e32 v120, v184, v184
	v_fmac_f32_e32 v121, v186, v186
	v_add_f32_e32 v120, v120, v121
	v_mul_f32_e32 v121, v123, v123
	v_fmac_f32_e32 v121, v122, v122
	v_add_f32_e32 v120, v120, v121
	v_mul_f32_e32 v121, v125, v125
	v_fmac_f32_e32 v121, v124, v124
	global_store_dwordx4 v[126:127], v[184:187], off
	global_store_dwordx4 v[126:127], v[122:125], off offset:16
	v_add_f32_e32 v162, v121, v120
	v_lshl_add_u64 v[120:121], s[42:43], 0, v[140:141]
	global_load_dwordx4 v[154:157], v[120:121], off offset:16
	global_load_dwordx4 v[188:191], v[120:121], off
	s_waitcnt vmcnt(1)
	v_pk_add_f32 v[154:155], v[154:155], 1.0 op_sel_hi:[1,0]
	s_waitcnt vmcnt(0)
	v_pk_add_f32 v[158:159], v[188:189], 1.0 op_sel_hi:[1,0]
	v_pk_mul_f32 v[122:123], v[122:123], v[154:155]
	v_pk_mul_f32 v[158:159], v[184:185], v[158:159]
	v_pk_add_f32 v[148:149], v[190:191], 1.0 op_sel_hi:[1,0]
	v_pk_mul_f32 v[148:149], v[186:187], v[148:149]
	v_cvt_pk_bf16_f32 v154, v158, v159
	v_cvt_pk_bf16_f32 v155, v148, v149
	v_pk_add_f32 v[156:157], v[156:157], 1.0 op_sel_hi:[1,0]
	v_pk_mul_f32 v[124:125], v[124:125], v[156:157]
	v_cvt_pk_bf16_f32 v156, v122, v123
	v_cvt_pk_bf16_f32 v157, v124, v125
	v_lshlrev_b64 v[122:123], 12, v[144:145]
	v_lshl_add_u64 v[122:123], s[28:29], 0, v[122:123]
	v_lshl_add_u64 v[124:125], v[138:139], 1, v[122:123]
	v_or_b32_e32 v122, 0x80, v138
	v_ashrrev_i32_e32 v123, 31, v122
	v_lshlrev_b64 v[148:149], 2, v[122:123]
	global_store_dwordx4 v[124:125], v[154:157], off
	v_lshl_add_u64 v[122:123], s[4:5], 0, v[148:149]
	global_load_dwordx4 v[154:157], v[122:123], off offset:16
	global_load_dwordx4 v[184:187], v[122:123], off
	global_load_dwordx4 v[188:191], v[146:147], off offset:528
	global_load_dwordx4 v[192:195], v[146:147], off offset:512
	s_waitcnt vmcnt(1)
	v_pk_fma_f32 v[154:155], v[112:113], v[154:155], v[188:189]
	s_waitcnt vmcnt(0)
	v_pk_fma_f32 v[118:119], v[118:119], v[186:187], v[194:195]
	v_pk_fma_f32 v[116:117], v[116:117], v[184:185], v[192:193]
	v_mul_f32_e32 v113, v119, v119
	v_mul_f32_e32 v112, v117, v117
	v_fmac_f32_e32 v112, v116, v116
	v_fmac_f32_e32 v113, v118, v118
	v_add_f32_e32 v112, v112, v113
	v_mul_f32_e32 v113, v155, v155
	v_pk_fma_f32 v[156:157], v[114:115], v[156:157], v[190:191]
	v_fmac_f32_e32 v113, v154, v154
	v_add_f32_e32 v112, v112, v113
	v_mul_f32_e32 v113, v157, v157
	v_fmac_f32_e32 v113, v156, v156
	v_add_f32_e32 v112, v113, v112
	global_store_dwordx4 v[126:127], v[116:119], off offset:512
	global_store_dwordx4 v[126:127], v[154:157], off offset:528
	v_add_f32_e32 v114, v162, v112
	v_lshl_add_u64 v[112:113], s[42:43], 0, v[148:149]
	global_load_dwordx4 v[146:149], v[112:113], off offset:16
	global_load_dwordx4 v[184:187], v[112:113], off
	s_waitcnt vmcnt(1)
	v_pk_add_f32 v[146:147], v[146:147], 1.0 op_sel_hi:[1,0]
	s_waitcnt vmcnt(0)
	v_pk_add_f32 v[158:159], v[184:185], 1.0 op_sel_hi:[1,0]
	v_pk_add_f32 v[126:127], v[186:187], 1.0 op_sel_hi:[1,0]
	v_pk_mul_f32 v[116:117], v[116:117], v[158:159]
	v_pk_mul_f32 v[118:119], v[118:119], v[126:127]
	v_cvt_pk_bf16_f32 v116, v116, v117
	v_pk_mul_f32 v[146:147], v[154:155], v[146:147]
	v_cvt_pk_bf16_f32 v117, v118, v119
	v_pk_add_f32 v[148:149], v[148:149], 1.0 op_sel_hi:[1,0]
	v_pk_mul_f32 v[126:127], v[156:157], v[148:149]
	v_cvt_pk_bf16_f32 v118, v146, v147
	v_cvt_pk_bf16_f32 v119, v126, v127
	v_mov_b32_e32 v115, v114
	global_store_dwordx4 v[124:125], v[116:119], off offset:256
	s_nop 0
	v_permlane16_swap_b32_e32 v114, v115
	s_nop 0
	v_add_f32_e32 v114, v114, v115
	v_mov_b32_e32 v115, v114
	s_nop 1
	v_permlane32_swap_b32_e32 v114, v115
	s_and_saveexec_b64 s[10:11], s[38:39]
	s_cbranch_execz .LBB0_64
	v_lshl_add_u64 v[116:117], v[144:145], 2, s[62:63]
	v_add_f32_e32 v114, v114, v115
	global_atomic_add_f32 v[116:117], v114, off
;     __device__ __forceinline__ void operator()(const f32x4 (&acc)[2][2][4][2], const pg8::Unit& u, int wr, int wc, int fr, int fq) const {
;     ...
;                     } else if constexpr (MODE == 7) {
;                         const f32x4 g0 = *(const f32x4*)(vec + col), g1 = *(const f32x4*)(vec + col + 4);
;                         const f32x4 x0 = *(const f32x4*)(xsrc + row * DM + col), x1 = *(const f32x4*)(xsrc + row * DM + col + 4);
;                         const f32x4 y0 = x0 + g0 * v0, y1 = x1 + g1 * v1;
;                         *(f32x4*)(of + row * DM + col) = y0; *(f32x4*)(of + row * DM + col + 4) = y1;
;                         ssq += (y0[0] * y0[0] + y0[1] * y0[1]) + (y0[2] * y0[2] + y0[3] * y0[3]) + (y1[0] * y1[0] + y1[1] * y1[1]) + (y1[2] * y1[2] + y1[3] * y1[3]);
;                         const f32x4 s0 = *(const f32x4*)(vec2 + col) + 1.f, s1 = *(const f32x4*)(vec2 + col + 4) + 1.f;
;                         const f32x4 a0 = y0 * s0, a1 = y1 * s1;
;                         u32x4 w; w.x = pk2(a0[0], a0[1]); w.y = pk2(a0[2], a0[3]); w.z = pk2(a1[0], a1[1]); w.w = pk2(a1[2], a1[3]);
;                         *(u32x4*)(ob + row * DM + col) = w;
;                     } else if constexpr (MODE == 8) {
;                         const f32x4 b0 = *(const f32x4*)(vec + col), b1 = *(const f32x4*)(vec + col + 4);
;                         float r[8] = {v0[0] * rstd + b0[0], v0[1] * rstd + b0[1], v0[2] * rstd + b0[2], v0[3] * rstd + b0[3], v1[0] * rstd + b1[0], v1[1] * rstd + b1[1], v1[2] * rstd + b1[2], v1[3] * rstd + b1[3]};
; #pragma unroll
;                         for (int i = 0; i < 8; ++i) { const float q = fmaxf(r[i], 0.f); r[i] = q * q; }
;                         u32x4 w; w.x = pk2(r[0], r[1]); w.y = pk2(r[2], r[3]); w.z = pk2(r[4], r[5]); w.w = pk2(r[6], r[7]);
;                         *(u32x4*)(ob + row * HIDN + col) = w;
;                     } else {
;                         float r[8] = {v0[0], v0[1], v0[2], v0[3], v1[0], v1[1], v1[2], v1[3]};
; #pragma unroll
;                         for (int i = 0; i < 8; ++i) { const float q = fmaxf(r[i], 0.f); r[i] = q * q; }
;                         u32x4 w; w.x = pk2(r[0], r[1]); w.y = pk2(r[2], r[3]); w.z = pk2(r[4], r[5]); w.w = pk2(r[6], r[7]);
;                         *(u32x4*)(ob + row * HIDN + col) = w;
;                     }
;                 }
;                 if constexpr (MODE == 7) {
.LBB0_64:
	s_or_b64 exec, exec, s[10:11]
	v_or_b32_e32 v114, 16, v144
	v_ashrrev_i32_e32 v115, 31, v114
	v_lshlrev_b64 v[118:119], 13, v[114:115]
	v_lshl_add_u64 v[116:117], s[30:31], 0, v[118:119]
	v_lshl_add_u64 v[116:117], v[116:117], 0, v[140:141]
	global_load_dwordx4 v[124:127], v[142:143], off offset:16
	global_load_dwordx4 v[146:149], v[142:143], off
	global_load_dwordx4 v[154:157], v[116:117], off offset:16
	global_load_dwordx4 v[184:187], v[116:117], off
	s_waitcnt vmcnt(1)
	v_pk_fma_f32 v[106:107], v[106:107], v[126:127], v[156:157]
	s_waitcnt vmcnt(0)
	v_pk_fma_f32 v[146:147], v[108:109], v[146:147], v[184:185]
	v_lshl_add_u64 v[108:109], s[6:7], 0, v[118:119]
	v_pk_fma_f32 v[148:149], v[110:111], v[148:149], v[186:187]
	v_lshl_add_u64 v[108:109], v[108:109], 0, v[140:141]
	v_pk_fma_f32 v[104:105], v[104:105], v[124:125], v[154:155]
	global_store_dwordx4 v[108:109], v[146:149], off
	global_store_dwordx4 v[108:109], v[104:107], off offset:16
	global_load_dwordx4 v[124:127], v[120:121], off offset:16
	global_load_dwordx4 v[154:157], v[120:121], off
	v_mul_f32_e32 v110, v147, v147
	v_mul_f32_e32 v111, v149, v149
	v_fmac_f32_e32 v110, v146, v146
	v_fmac_f32_e32 v111, v148, v148
	v_add_f32_e32 v110, v110, v111
	v_mul_f32_e32 v111, v105, v105
	v_fmac_f32_e32 v111, v104, v104
	v_add_f32_e32 v110, v110, v111
	v_mul_f32_e32 v111, v107, v107
	v_fmac_f32_e32 v111, v106, v106
	v_add_f32_e32 v145, v111, v110
	s_waitcnt vmcnt(1)
	v_pk_add_f32 v[126:127], v[126:127], 1.0 op_sel_hi:[1,0]
	s_waitcnt vmcnt(0)
	v_pk_add_f32 v[118:119], v[154:155], 1.0 op_sel_hi:[1,0]
	v_pk_add_f32 v[124:125], v[124:125], 1.0 op_sel_hi:[1,0]
	v_pk_mul_f32 v[118:119], v[146:147], v[118:119]
	v_pk_mul_f32 v[126:127], v[106:107], v[126:127]
	v_pk_mul_f32 v[106:107], v[104:105], v[124:125]
	v_pk_add_f32 v[110:111], v[156:157], 1.0 op_sel_hi:[1,0]
	v_pk_mul_f32 v[110:111], v[148:149], v[110:111]
	v_cvt_pk_bf16_f32 v104, v118, v119
	v_cvt_pk_bf16_f32 v105, v110, v111
	v_cvt_pk_bf16_f32 v106, v106, v107
	v_cvt_pk_bf16_f32 v107, v126, v127
	v_lshlrev_b64 v[110:111], 12, v[114:115]
	v_lshl_add_u64 v[110:111], s[28:29], 0, v[110:111]
	v_lshl_add_u64 v[110:111], v[138:139], 1, v[110:111]
	global_store_dwordx4 v[110:111], v[104:107], off
	global_load_dwordx4 v[104:107], v[122:123], off offset:16
	s_nop 0
	global_load_dwordx4 v[124:127], v[122:123], off
	global_load_dwordx4 v[146:149], v[116:117], off offset:528
	s_nop 0
	global_load_dwordx4 v[116:119], v[116:117], off offset:512
	s_waitcnt vmcnt(1)
	v_pk_fma_f32 v[96:97], v[96:97], v[104:105], v[146:147]
	s_waitcnt vmcnt(0)
	v_pk_fma_f32 v[102:103], v[102:103], v[126:127], v[118:119]
	v_pk_fma_f32 v[100:101], v[100:101], v[124:125], v[116:117]
	v_mul_f32_e32 v105, v103, v103
	v_mul_f32_e32 v104, v101, v101
	v_fmac_f32_e32 v104, v100, v100
	v_fmac_f32_e32 v105, v102, v102
	v_add_f32_e32 v104, v104, v105
	v_mul_f32_e32 v105, v97, v97
	v_pk_fma_f32 v[98:99], v[98:99], v[106:107], v[148:149]
	v_fmac_f32_e32 v105, v96, v96
	v_add_f32_e32 v104, v104, v105
	v_mul_f32_e32 v105, v99, v99
	v_fmac_f32_e32 v105, v98, v98
	global_store_dwordx4 v[108:109], v[100:103], off offset:512
	global_store_dwordx4 v[108:109], v[96:99], off offset:528
	v_add_f32_e32 v104, v105, v104
	v_add_f32_e32 v124, v145, v104
	global_load_dwordx4 v[104:107], v[112:113], off offset:16
	global_load_dwordx4 v[116:119], v[112:113], off
	s_waitcnt vmcnt(1)
	v_pk_add_f32 v[106:107], v[106:107], 1.0 op_sel_hi:[1,0]
	s_waitcnt vmcnt(0)
	v_pk_add_f32 v[116:117], v[116:117], 1.0 op_sel_hi:[1,0]
	v_pk_add_f32 v[104:105], v[104:105], 1.0 op_sel_hi:[1,0]
	v_pk_mul_f32 v[100:101], v[100:101], v[116:117]
	v_pk_mul_f32 v[106:107], v[98:99], v[106:107]
	v_pk_mul_f32 v[98:99], v[96:97], v[104:105]
	v_pk_add_f32 v[108:109], v[118:119], 1.0 op_sel_hi:[1,0]
	v_pk_mul_f32 v[102:103], v[102:103], v[108:109]
	v_cvt_pk_bf16_f32 v96, v100, v101
	v_cvt_pk_bf16_f32 v97, v102, v103
	v_cvt_pk_bf16_f32 v98, v98, v99
	v_cvt_pk_bf16_f32 v99, v106, v107
	global_store_dwordx4 v[110:111], v[96:99], off offset:256
	s_nop 1
	v_mov_b32_e32 v96, v124
	s_nop 1
	v_permlane16_swap_b32_e32 v124, v96
	s_nop 0
	v_add_f32_e32 v96, v124, v96
	v_mov_b32_e32 v97, v96
	s_nop 1
	v_permlane32_swap_b32_e32 v96, v97
	s_and_saveexec_b64 s[10:11], s[38:39]
	s_cbranch_execz .LBB0_66
	v_lshl_add_u64 v[98:99], v[114:115], 2, s[62:63]
	v_add_f32_e32 v96, v96, v97
	global_atomic_add_f32 v[98:99], v96, off
;     __device__ __forceinline__ void operator()(const f32x4 (&acc)[2][2][4][2], const pg8::Unit& u, int wr, int wc, int fr, int fq) const {
;     ...
;                     } else if constexpr (MODE == 7) {
;                         const f32x4 g0 = *(const f32x4*)(vec + col), g1 = *(const f32x4*)(vec + col + 4);
;                         const f32x4 x0 = *(const f32x4*)(xsrc + row * DM + col), x1 = *(const f32x4*)(xsrc + row * DM + col + 4);
;                         const f32x4 y0 = x0 + g0 * v0, y1 = x1 + g1 * v1;
;                         *(f32x4*)(of + row * DM + col) = y0; *(f32x4*)(of + row * DM + col + 4) = y1;
;                         ssq += (y0[0] * y0[0] + y0[1] * y0[1]) + (y0[2] * y0[2] + y0[3] * y0[3]) + (y1[0] * y1[0] + y1[1] * y1[1]) + (y1[2] * y1[2] + y1[3] * y1[3]);
;                         const f32x4 s0 = *(const f32x4*)(vec2 + col) + 1.f, s1 = *(const f32x4*)(vec2 + col + 4) + 1.f;
;                         const f32x4 a0 = y0 * s0, a1 = y1 * s1;
;                         u32x4 w; w.x = pk2(a0[0], a0[1]); w.y = pk2(a0[2], a0[3]); w.z = pk2(a1[0], a1[1]); w.w = pk2(a1[2], a1[3]);
;                         *(u32x4*)(ob + row * DM + col) = w;
;                     } else if constexpr (MODE == 8) {
;                         const f32x4 b0 = *(const f32x4*)(vec + col), b1 = *(const f32x4*)(vec + col + 4);
;                         float r[8] = {v0[0] * rstd + b0[0], v0[1] * rstd + b0[1], v0[2] * rstd + b0[2], v0[3] * rstd + b0[3], v1[0] * rstd + b1[0], v1[1] * rstd + b1[1], v1[2] * rstd + b1[2], v1[3] * rstd + b1[3]};
; #pragma unroll
;                         for (int i = 0; i < 8; ++i) { const float q = fmaxf(r[i], 0.f); r[i] = q * q; }
;                         u32x4 w; w.x = pk2(r[0], r[1]); w.y = pk2(r[2], r[3]); w.z = pk2(r[4], r[5]); w.w = pk2(r[6], r[7]);
;                         *(u32x4*)(ob + row * HIDN + col) = w;
;                     } else {
;                         float r[8] = {v0[0], v0[1], v0[2], v0[3], v1[0], v1[1], v1[2], v1[3]};
; #pragma unroll
;                         for (int i = 0; i < 8; ++i) { const float q = fmaxf(r[i], 0.f); r[i] = q * q; }
;                         u32x4 w; w.x = pk2(r[0], r[1]); w.y = pk2(r[2], r[3]); w.z = pk2(r[4], r[5]); w.w = pk2(r[6], r[7]);
;                         *(u32x4*)(ob + row * HIDN + col) = w;
;                     }
;                 }
;                 if constexpr (MODE == 7) {
.LBB0_66:
	s_or_b64 exec, exec, s[10:11]
	v_or_b32_e32 v96, 32, v144
	v_ashrrev_i32_e32 v97, 31, v96
	v_lshlrev_b64 v[118:119], 13, v[96:97]
	v_lshl_add_u64 v[98:99], s[30:31], 0, v[118:119]
	v_lshl_add_u64 v[98:99], v[98:99], 0, v[140:141]
	global_load_dwordx4 v[100:103], v[142:143], off offset:16
	global_load_dwordx4 v[104:107], v[142:143], off
	global_load_dwordx4 v[108:111], v[98:99], off offset:16
	global_load_dwordx4 v[114:117], v[98:99], off
	s_waitcnt vmcnt(1)
	v_pk_fma_f32 v[90:91], v[90:91], v[102:103], v[110:111]
	s_waitcnt vmcnt(0)
	v_pk_fma_f32 v[104:105], v[92:93], v[104:105], v[114:115]
	v_lshl_add_u64 v[92:93], s[6:7], 0, v[118:119]
	v_pk_fma_f32 v[106:107], v[94:95], v[106:107], v[116:117]
	v_lshl_add_u64 v[92:93], v[92:93], 0, v[140:141]
	v_pk_fma_f32 v[88:89], v[88:89], v[100:101], v[108:109]
	global_store_dwordx4 v[92:93], v[104:107], off
	global_store_dwordx4 v[92:93], v[88:91], off offset:16
	global_load_dwordx4 v[100:103], v[120:121], off offset:16
	global_load_dwordx4 v[108:111], v[120:121], off
	v_mul_f32_e32 v94, v105, v105
	v_mul_f32_e32 v95, v107, v107
	v_fmac_f32_e32 v94, v104, v104
	v_fmac_f32_e32 v95, v106, v106
	v_add_f32_e32 v94, v94, v95
	v_mul_f32_e32 v95, v89, v89
	v_fmac_f32_e32 v95, v88, v88
	v_add_f32_e32 v94, v94, v95
	v_mul_f32_e32 v95, v91, v91
	v_fmac_f32_e32 v95, v90, v90
	v_add_f32_e32 v114, v95, v94
	s_waitcnt vmcnt(1)
	v_pk_add_f32 v[102:103], v[102:103], 1.0 op_sel_hi:[1,0]
	s_waitcnt vmcnt(0)
	v_pk_add_f32 v[108:109], v[108:109], 1.0 op_sel_hi:[1,0]
	v_pk_add_f32 v[100:101], v[100:101], 1.0 op_sel_hi:[1,0]
	v_pk_mul_f32 v[104:105], v[104:105], v[108:109]
	v_pk_mul_f32 v[102:103], v[90:91], v[102:103]
	v_pk_mul_f32 v[90:91], v[88:89], v[100:101]
	v_pk_add_f32 v[94:95], v[110:111], 1.0 op_sel_hi:[1,0]
	v_pk_mul_f32 v[94:95], v[106:107], v[94:95]
	v_cvt_pk_bf16_f32 v88, v104, v105
	v_cvt_pk_bf16_f32 v89, v94, v95
	v_cvt_pk_bf16_f32 v90, v90, v91
	v_cvt_pk_bf16_f32 v91, v102, v103
	v_lshlrev_b64 v[94:95], 12, v[96:97]
	v_lshl_add_u64 v[94:95], s[28:29], 0, v[94:95]
	v_lshl_add_u64 v[94:95], v[138:139], 1, v[94:95]
	global_store_dwordx4 v[94:95], v[88:91], off
	global_load_dwordx4 v[88:91], v[122:123], off offset:16
	s_nop 0
	global_load_dwordx4 v[100:103], v[122:123], off
	global_load_dwordx4 v[104:107], v[98:99], off offset:528
	global_load_dwordx4 v[108:111], v[98:99], off offset:512
	s_waitcnt vmcnt(1)
	v_pk_fma_f32 v[80:81], v[80:81], v[88:89], v[104:105]
	s_waitcnt vmcnt(0)
	v_pk_fma_f32 v[86:87], v[86:87], v[102:103], v[110:111]
	v_pk_fma_f32 v[84:85], v[84:85], v[100:101], v[108:109]
	v_mul_f32_e32 v89, v87, v87
	v_mul_f32_e32 v88, v85, v85
	v_fmac_f32_e32 v88, v84, v84
	v_fmac_f32_e32 v89, v86, v86
	v_add_f32_e32 v88, v88, v89
	v_mul_f32_e32 v89, v81, v81
	v_pk_fma_f32 v[82:83], v[82:83], v[90:91], v[106:107]
	v_fmac_f32_e32 v89, v80, v80
	v_add_f32_e32 v88, v88, v89
	v_mul_f32_e32 v89, v83, v83
	v_fmac_f32_e32 v89, v82, v82
	global_store_dwordx4 v[92:93], v[84:87], off offset:512
	global_store_dwordx4 v[92:93], v[80:83], off offset:528
	v_add_f32_e32 v88, v89, v88
	v_add_f32_e32 v102, v114, v88
	global_load_dwordx4 v[88:91], v[112:113], off offset:16
	global_load_dwordx4 v[98:101], v[112:113], off
	s_waitcnt vmcnt(1)
	v_pk_add_f32 v[90:91], v[90:91], 1.0 op_sel_hi:[1,0]
	s_waitcnt vmcnt(0)
	v_pk_add_f32 v[98:99], v[98:99], 1.0 op_sel_hi:[1,0]
	v_pk_add_f32 v[88:89], v[88:89], 1.0 op_sel_hi:[1,0]
	v_pk_mul_f32 v[84:85], v[84:85], v[98:99]
	v_pk_mul_f32 v[90:91], v[82:83], v[90:91]
	v_pk_mul_f32 v[82:83], v[80:81], v[88:89]
	v_pk_add_f32 v[92:93], v[100:101], 1.0 op_sel_hi:[1,0]
	v_pk_mul_f32 v[86:87], v[86:87], v[92:93]
	v_cvt_pk_bf16_f32 v80, v84, v85
	v_cvt_pk_bf16_f32 v81, v86, v87
	v_cvt_pk_bf16_f32 v82, v82, v83
	v_cvt_pk_bf16_f32 v83, v90, v91
	global_store_dwordx4 v[94:95], v[80:83], off offset:256
	s_nop 1
	v_mov_b32_e32 v80, v102
	s_nop 1
	v_permlane16_swap_b32_e32 v102, v80
	s_nop 0
	v_add_f32_e32 v80, v102, v80
	v_mov_b32_e32 v81, v80
	s_nop 1
	v_permlane32_swap_b32_e32 v80, v81
	s_and_saveexec_b64 s[10:11], s[38:39]
	s_cbranch_execz .LBB0_68
	v_lshl_add_u64 v[82:83], v[96:97], 2, s[62:63]
	v_add_f32_e32 v80, v80, v81
	global_atomic_add_f32 v[82:83], v80, off
.LBB0_68:
	s_or_b64 exec, exec, s[10:11]
	v_or_b32_e32 v80, 48, v144
	v_ashrrev_i32_e32 v81, 31, v80
	v_lshlrev_b64 v[100:101], 13, v[80:81]
	v_lshl_add_u64 v[82:83], s[30:31], 0, v[100:101]
	v_lshl_add_u64 v[82:83], v[82:83], 0, v[140:141]
	global_load_dwordx4 v[84:87], v[142:143], off offset:16
	global_load_dwordx4 v[88:91], v[142:143], off
	global_load_dwordx4 v[92:95], v[82:83], off offset:16
	global_load_dwordx4 v[96:99], v[82:83], off
	s_waitcnt vmcnt(1)
	v_pk_fma_f32 v[74:75], v[74:75], v[86:87], v[94:95]
	s_waitcnt vmcnt(0)
	v_pk_fma_f32 v[88:89], v[76:77], v[88:89], v[96:97]
	v_lshl_add_u64 v[76:77], s[6:7], 0, v[100:101]
	v_pk_fma_f32 v[90:91], v[78:79], v[90:91], v[98:99]
	v_lshl_add_u64 v[76:77], v[76:77], 0, v[140:141]
	v_pk_fma_f32 v[72:73], v[72:73], v[84:85], v[92:93]
	global_store_dwordx4 v[76:77], v[88:91], off
	global_store_dwordx4 v[76:77], v[72:75], off offset:16
	global_load_dwordx4 v[84:87], v[120:121], off offset:16
	global_load_dwordx4 v[92:95], v[120:121], off
	v_mul_f32_e32 v78, v89, v89
	v_mul_f32_e32 v79, v91, v91
	v_fmac_f32_e32 v78, v88, v88
	v_fmac_f32_e32 v79, v90, v90
	v_add_f32_e32 v78, v78, v79
	v_mul_f32_e32 v79, v73, v73
	v_fmac_f32_e32 v79, v72, v72
	v_add_f32_e32 v78, v78, v79
	v_mul_f32_e32 v79, v75, v75
	v_fmac_f32_e32 v79, v74, v74
	v_add_f32_e32 v96, v79, v78
	s_waitcnt vmcnt(1)
	v_pk_add_f32 v[86:87], v[86:87], 1.0 op_sel_hi:[1,0]
	s_waitcnt vmcnt(0)
;     __device__ __forceinline__ void operator()(const f32x4 (&acc)[2][2][4][2], const pg8::Unit& u, int wr, int wc, int fr, int fq) const {
;     ...
;                     } else if constexpr (MODE == 7) {
;                         const f32x4 g0 = *(const f32x4*)(vec + col), g1 = *(const f32x4*)(vec + col + 4);
;                         const f32x4 x0 = *(const f32x4*)(xsrc + row * DM + col), x1 = *(const f32x4*)(xsrc + row * DM + col + 4);
;                         const f32x4 y0 = x0 + g0 * v0, y1 = x1 + g1 * v1;
;                         *(f32x4*)(of + row * DM + col) = y0; *(f32x4*)(of + row * DM + col + 4) = y1;
;                         ssq += (y0[0] * y0[0] + y0[1] * y0[1]) + (y0[2] * y0[2] + y0[3] * y0[3]) + (y1[0] * y1[0] + y1[1] * y1[1]) + (y1[2] * y1[2] + y1[3] * y1[3]);
;                         const f32x4 s0 = *(const f32x4*)(vec2 + col) + 1.f, s1 = *(const f32x4*)(vec2 + col + 4) + 1.f;
;                         const f32x4 a0 = y0 * s0, a1 = y1 * s1;
;                         u32x4 w; w.x = pk2(a0[0], a0[1]); w.y = pk2(a0[2], a0[3]); w.z = pk2(a1[0], a1[1]); w.w = pk2(a1[2], a1[3]);
;                         *(u32x4*)(ob + row * DM + col) = w;
;                     } else if constexpr (MODE == 8) {
;                         const f32x4 b0 = *(const f32x4*)(vec + col), b1 = *(const f32x4*)(vec + col + 4);
;                         float r[8] = {v0[0] * rstd + b0[0], v0[1] * rstd + b0[1], v0[2] * rstd + b0[2], v0[3] * rstd + b0[3], v1[0] * rstd + b1[0], v1[1] * rstd + b1[1], v1[2] * rstd + b1[2], v1[3] * rstd + b1[3]};
; #pragma unroll
;                         for (int i = 0; i < 8; ++i) { const float q = fmaxf(r[i], 0.f); r[i] = q * q; }
;                         u32x4 w; w.x = pk2(r[0], r[1]); w.y = pk2(r[2], r[3]); w.z = pk2(r[4], r[5]); w.w = pk2(r[6], r[7]);
;                         *(u32x4*)(ob + row * HIDN + col) = w;
;                     } else {
;                         float r[8] = {v0[0], v0[1], v0[2], v0[3], v1[0], v1[1], v1[2], v1[3]};
; #pragma unroll
;                         for (int i = 0; i < 8; ++i) { const float q = fmaxf(r[i], 0.f); r[i] = q * q; }
;                         u32x4 w; w.x = pk2(r[0], r[1]); w.y = pk2(r[2], r[3]); w.z = pk2(r[4], r[5]); w.w = pk2(r[6], r[7]);
;                         *(u32x4*)(ob + row * HIDN + col) = w;
;                     }
;                 }
;                 if constexpr (MODE == 7) {
	v_pk_add_f32 v[92:93], v[92:93], 1.0 op_sel_hi:[1,0]
	v_pk_add_f32 v[84:85], v[84:85], 1.0 op_sel_hi:[1,0]
	v_pk_mul_f32 v[88:89], v[88:89], v[92:93]
	v_pk_mul_f32 v[86:87], v[74:75], v[86:87]
	v_pk_mul_f32 v[74:75], v[72:73], v[84:85]
	v_pk_add_f32 v[78:79], v[94:95], 1.0 op_sel_hi:[1,0]
	v_pk_mul_f32 v[78:79], v[90:91], v[78:79]
	v_cvt_pk_bf16_f32 v72, v88, v89
	v_cvt_pk_bf16_f32 v73, v78, v79
	v_cvt_pk_bf16_f32 v74, v74, v75
	v_cvt_pk_bf16_f32 v75, v86, v87
	v_lshlrev_b64 v[78:79], 12, v[80:81]
	v_lshl_add_u64 v[78:79], s[28:29], 0, v[78:79]
	v_lshl_add_u64 v[78:79], v[138:139], 1, v[78:79]
	global_store_dwordx4 v[78:79], v[72:75], off
	global_load_dwordx4 v[72:75], v[122:123], off offset:16
	s_nop 0
	global_load_dwordx4 v[84:87], v[122:123], off
	global_load_dwordx4 v[88:91], v[82:83], off offset:528
	global_load_dwordx4 v[92:95], v[82:83], off offset:512
	s_waitcnt vmcnt(1)
	v_pk_fma_f32 v[64:65], v[64:65], v[72:73], v[88:89]
	s_waitcnt vmcnt(0)
	v_pk_fma_f32 v[70:71], v[70:71], v[86:87], v[94:95]
	v_pk_fma_f32 v[68:69], v[68:69], v[84:85], v[92:93]
	v_mul_f32_e32 v73, v71, v71
	v_mul_f32_e32 v72, v69, v69
	v_fmac_f32_e32 v72, v68, v68
	v_fmac_f32_e32 v73, v70, v70
	v_add_f32_e32 v72, v72, v73
	v_mul_f32_e32 v73, v65, v65
	v_pk_fma_f32 v[66:67], v[66:67], v[74:75], v[90:91]
	v_fmac_f32_e32 v73, v64, v64
	v_add_f32_e32 v72, v72, v73
	v_mul_f32_e32 v73, v67, v67
	v_fmac_f32_e32 v73, v66, v66
	global_store_dwordx4 v[76:77], v[68:71], off offset:512
	global_store_dwordx4 v[76:77], v[64:67], off offset:528
	v_add_f32_e32 v72, v73, v72
	v_add_f32_e32 v86, v96, v72
	global_load_dwordx4 v[72:75], v[112:113], off offset:16
	global_load_dwordx4 v[82:85], v[112:113], off
	s_waitcnt vmcnt(1)
	v_pk_add_f32 v[74:75], v[74:75], 1.0 op_sel_hi:[1,0]
	s_waitcnt vmcnt(0)
	v_pk_add_f32 v[82:83], v[82:83], 1.0 op_sel_hi:[1,0]
	v_pk_add_f32 v[72:73], v[72:73], 1.0 op_sel_hi:[1,0]
	v_pk_mul_f32 v[68:69], v[68:69], v[82:83]
	v_pk_mul_f32 v[74:75], v[66:67], v[74:75]
	v_pk_mul_f32 v[66:67], v[64:65], v[72:73]
	v_pk_add_f32 v[76:77], v[84:85], 1.0 op_sel_hi:[1,0]
	v_pk_mul_f32 v[70:71], v[70:71], v[76:77]
	v_cvt_pk_bf16_f32 v64, v68, v69
	v_cvt_pk_bf16_f32 v65, v70, v71
	v_cvt_pk_bf16_f32 v66, v66, v67
	v_cvt_pk_bf16_f32 v67, v74, v75
	global_store_dwordx4 v[78:79], v[64:67], off offset:256
	s_nop 1
	v_mov_b32_e32 v64, v86
	s_nop 1
	v_permlane16_swap_b32_e32 v86, v64
	s_nop 0
	v_add_f32_e32 v64, v86, v64
	v_mov_b32_e32 v65, v64
	s_nop 1
	v_permlane32_swap_b32_e32 v64, v65
	s_and_saveexec_b64 s[10:11], s[38:39]
	s_cbranch_execz .LBB0_70
	v_lshl_add_u64 v[66:67], v[80:81], 2, s[62:63]
	v_add_f32_e32 v64, v64, v65
	global_atomic_add_f32 v[66:67], v64, off
.LBB0_70:
	s_or_b64 exec, exec, s[10:11]
	v_add_u32_e32 v64, 0x80, v144
	v_ashrrev_i32_e32 v65, 31, v64
	v_lshlrev_b64 v[84:85], 13, v[64:65]
	v_lshl_add_u64 v[66:67], s[30:31], 0, v[84:85]
	v_lshl_add_u64 v[66:67], v[66:67], 0, v[140:141]
	global_load_dwordx4 v[68:71], v[142:143], off offset:16
	global_load_dwordx4 v[72:75], v[142:143], off
	global_load_dwordx4 v[76:79], v[66:67], off offset:16
	global_load_dwordx4 v[80:83], v[66:67], off
	s_waitcnt vmcnt(1)
	v_pk_fma_f32 v[58:59], v[58:59], v[70:71], v[78:79]
	s_waitcnt vmcnt(0)
	v_pk_fma_f32 v[72:73], v[60:61], v[72:73], v[80:81]
	v_lshl_add_u64 v[60:61], s[6:7], 0, v[84:85]
	v_pk_fma_f32 v[74:75], v[62:63], v[74:75], v[82:83]
	v_lshl_add_u64 v[60:61], v[60:61], 0, v[140:141]
	v_pk_fma_f32 v[56:57], v[56:57], v[68:69], v[76:77]
	global_store_dwordx4 v[60:61], v[72:75], off
	global_store_dwordx4 v[60:61], v[56:59], off offset:16
	global_load_dwordx4 v[68:71], v[120:121], off offset:16
	global_load_dwordx4 v[76:79], v[120:121], off
	v_mul_f32_e32 v62, v73, v73
	v_mul_f32_e32 v63, v75, v75
	v_fmac_f32_e32 v62, v72, v72
	v_fmac_f32_e32 v63, v74, v74
	v_add_f32_e32 v62, v62, v63
	v_mul_f32_e32 v63, v57, v57
	v_fmac_f32_e32 v63, v56, v56
	v_add_f32_e32 v62, v62, v63
	v_mul_f32_e32 v63, v59, v59
	v_fmac_f32_e32 v63, v58, v58
	v_add_f32_e32 v80, v63, v62
	s_waitcnt vmcnt(1)
	v_pk_add_f32 v[70:71], v[70:71], 1.0 op_sel_hi:[1,0]
	s_waitcnt vmcnt(0)
	v_pk_add_f32 v[76:77], v[76:77], 1.0 op_sel_hi:[1,0]
	v_pk_add_f32 v[68:69], v[68:69], 1.0 op_sel_hi:[1,0]
	v_pk_mul_f32 v[72:73], v[72:73], v[76:77]
	v_pk_mul_f32 v[70:71], v[58:59], v[70:71]
	v_pk_mul_f32 v[58:59], v[56:57], v[68:69]
	v_pk_add_f32 v[62:63], v[78:79], 1.0 op_sel_hi:[1,0]
	v_pk_mul_f32 v[62:63], v[74:75], v[62:63]
	v_cvt_pk_bf16_f32 v56, v72, v73
	v_cvt_pk_bf16_f32 v57, v62, v63
	v_cvt_pk_bf16_f32 v58, v58, v59
	v_cvt_pk_bf16_f32 v59, v70, v71
	v_lshlrev_b64 v[62:63], 12, v[64:65]
	v_lshl_add_u64 v[62:63], s[28:29], 0, v[62:63]
	v_lshl_add_u64 v[62:63], v[138:139], 1, v[62:63]
	global_store_dwordx4 v[62:63], v[56:59], off
	global_load_dwordx4 v[56:59], v[122:123], off offset:16
	s_nop 0
	global_load_dwordx4 v[68:71], v[122:123], off
	global_load_dwordx4 v[72:75], v[66:67], off offset:528
	global_load_dwordx4 v[76:79], v[66:67], off offset:512
	s_waitcnt vmcnt(1)
	v_pk_fma_f32 v[48:49], v[48:49], v[56:57], v[72:73]
	s_waitcnt vmcnt(0)
	v_pk_fma_f32 v[54:55], v[54:55], v[70:71], v[78:79]
	v_pk_fma_f32 v[52:53], v[52:53], v[68:69], v[76:77]
	v_mul_f32_e32 v57, v55, v55
	v_mul_f32_e32 v56, v53, v53
	v_fmac_f32_e32 v56, v52, v52
	v_fmac_f32_e32 v57, v54, v54
	v_add_f32_e32 v56, v56, v57
	v_mul_f32_e32 v57, v49, v49
	v_pk_fma_f32 v[50:51], v[50:51], v[58:59], v[74:75]
	v_fmac_f32_e32 v57, v48, v48
	v_add_f32_e32 v56, v56, v57
	v_mul_f32_e32 v57, v51, v51
	v_fmac_f32_e32 v57, v50, v50
	global_store_dwordx4 v[60:61], v[52:55], off offset:512
	global_store_dwordx4 v[60:61], v[48:51], off offset:528
	v_add_f32_e32 v56, v57, v56
	v_add_f32_e32 v70, v80, v56
	global_load_dwordx4 v[56:59], v[112:113], off offset:16
	global_load_dwordx4 v[66:69], v[112:113], off
	s_waitcnt vmcnt(1)
	v_pk_add_f32 v[58:59], v[58:59], 1.0 op_sel_hi:[1,0]
	s_waitcnt vmcnt(0)
	v_pk_add_f32 v[66:67], v[66:67], 1.0 op_sel_hi:[1,0]
	v_pk_add_f32 v[56:57], v[56:57], 1.0 op_sel_hi:[1,0]
	v_pk_mul_f32 v[52:53], v[52:53], v[66:67]
	v_pk_mul_f32 v[58:59], v[50:51], v[58:59]
	v_pk_mul_f32 v[50:51], v[48:49], v[56:57]
	v_pk_add_f32 v[60:61], v[68:69], 1.0 op_sel_hi:[1,0]
	v_pk_mul_f32 v[54:55], v[54:55], v[60:61]
	v_cvt_pk_bf16_f32 v48, v52, v53
	v_cvt_pk_bf16_f32 v49, v54, v55
	v_cvt_pk_bf16_f32 v50, v50, v51
	v_cvt_pk_bf16_f32 v51, v58, v59
	global_store_dwordx4 v[62:63], v[48:51], off offset:256
	s_nop 1
	v_mov_b32_e32 v48, v70
	s_nop 1
	v_permlane16_swap_b32_e32 v70, v48
	s_nop 0
	v_add_f32_e32 v48, v70, v48
	v_mov_b32_e32 v49, v48
	s_nop 1
	v_permlane32_swap_b32_e32 v48, v49
	s_and_saveexec_b64 s[10:11], s[38:39]
	s_cbranch_execz .LBB0_72
	v_lshl_add_u64 v[50:51], v[64:65], 2, s[62:63]
	v_add_f32_e32 v48, v48, v49
	global_atomic_add_f32 v[50:51], v48, off
;     __device__ __forceinline__ void operator()(const f32x4 (&acc)[2][2][4][2], const pg8::Unit& u, int wr, int wc, int fr, int fq) const {
;     ...
;                     } else if constexpr (MODE == 7) {
;                         const f32x4 g0 = *(const f32x4*)(vec + col), g1 = *(const f32x4*)(vec + col + 4);
;                         const f32x4 x0 = *(const f32x4*)(xsrc + row * DM + col), x1 = *(const f32x4*)(xsrc + row * DM + col + 4);
;                         const f32x4 y0 = x0 + g0 * v0, y1 = x1 + g1 * v1;
;                         *(f32x4*)(of + row * DM + col) = y0; *(f32x4*)(of + row * DM + col + 4) = y1;
;                         ssq += (y0[0] * y0[0] + y0[1] * y0[1]) + (y0[2] * y0[2] + y0[3] * y0[3]) + (y1[0] * y1[0] + y1[1] * y1[1]) + (y1[2] * y1[2] + y1[3] * y1[3]);
;                         const f32x4 s0 = *(const f32x4*)(vec2 + col) + 1.f, s1 = *(const f32x4*)(vec2 + col + 4) + 1.f;
;                         const f32x4 a0 = y0 * s0, a1 = y1 * s1;
;                         u32x4 w; w.x = pk2(a0[0], a0[1]); w.y = pk2(a0[2], a0[3]); w.z = pk2(a1[0], a1[1]); w.w = pk2(a1[2], a1[3]);
;                         *(u32x4*)(ob + row * DM + col) = w;
;                     } else if constexpr (MODE == 8) {
;                         const f32x4 b0 = *(const f32x4*)(vec + col), b1 = *(const f32x4*)(vec + col + 4);
;                         float r[8] = {v0[0] * rstd + b0[0], v0[1] * rstd + b0[1], v0[2] * rstd + b0[2], v0[3] * rstd + b0[3], v1[0] * rstd + b1[0], v1[1] * rstd + b1[1], v1[2] * rstd + b1[2], v1[3] * rstd + b1[3]};
; #pragma unroll
;                         for (int i = 0; i < 8; ++i) { const float q = fmaxf(r[i], 0.f); r[i] = q * q; }
;                         u32x4 w; w.x = pk2(r[0], r[1]); w.y = pk2(r[2], r[3]); w.z = pk2(r[4], r[5]); w.w = pk2(r[6], r[7]);
;                         *(u32x4*)(ob + row * HIDN + col) = w;
;                     } else {
;                         float r[8] = {v0[0], v0[1], v0[2], v0[3], v1[0], v1[1], v1[2], v1[3]};
; #pragma unroll
;                         for (int i = 0; i < 8; ++i) { const float q = fmaxf(r[i], 0.f); r[i] = q * q; }
;                         u32x4 w; w.x = pk2(r[0], r[1]); w.y = pk2(r[2], r[3]); w.z = pk2(r[4], r[5]); w.w = pk2(r[6], r[7]);
;                         *(u32x4*)(ob + row * HIDN + col) = w;
;                     }
;                 }
;                 if constexpr (MODE == 7) {
.LBB0_72:
	s_or_b64 exec, exec, s[10:11]
	v_add_u32_e32 v48, 0x90, v144
	v_ashrrev_i32_e32 v49, 31, v48
	v_lshlrev_b64 v[68:69], 13, v[48:49]
	v_lshl_add_u64 v[50:51], s[30:31], 0, v[68:69]
	v_lshl_add_u64 v[50:51], v[50:51], 0, v[140:141]
	global_load_dwordx4 v[52:55], v[142:143], off offset:16
	global_load_dwordx4 v[56:59], v[142:143], off
	global_load_dwordx4 v[60:63], v[50:51], off offset:16
	global_load_dwordx4 v[64:67], v[50:51], off
	s_waitcnt vmcnt(1)
	v_pk_fma_f32 v[42:43], v[42:43], v[54:55], v[62:63]
	s_waitcnt vmcnt(0)
	v_pk_fma_f32 v[56:57], v[44:45], v[56:57], v[64:65]
	v_lshl_add_u64 v[44:45], s[6:7], 0, v[68:69]
	v_pk_fma_f32 v[58:59], v[46:47], v[58:59], v[66:67]
	v_lshl_add_u64 v[44:45], v[44:45], 0, v[140:141]
	v_pk_fma_f32 v[40:41], v[40:41], v[52:53], v[60:61]
	global_store_dwordx4 v[44:45], v[56:59], off
	global_store_dwordx4 v[44:45], v[40:43], off offset:16
	global_load_dwordx4 v[52:55], v[120:121], off offset:16
	global_load_dwordx4 v[60:63], v[120:121], off
	v_mul_f32_e32 v46, v57, v57
	v_mul_f32_e32 v47, v59, v59
	v_fmac_f32_e32 v46, v56, v56
	v_fmac_f32_e32 v47, v58, v58
	v_add_f32_e32 v46, v46, v47
	v_mul_f32_e32 v47, v41, v41
	v_fmac_f32_e32 v47, v40, v40
	v_add_f32_e32 v46, v46, v47
	v_mul_f32_e32 v47, v43, v43
	v_fmac_f32_e32 v47, v42, v42
	v_add_f32_e32 v64, v47, v46
	s_waitcnt vmcnt(1)
	v_pk_add_f32 v[54:55], v[54:55], 1.0 op_sel_hi:[1,0]
	s_waitcnt vmcnt(0)
	v_pk_add_f32 v[60:61], v[60:61], 1.0 op_sel_hi:[1,0]
	v_pk_add_f32 v[52:53], v[52:53], 1.0 op_sel_hi:[1,0]
	v_pk_mul_f32 v[56:57], v[56:57], v[60:61]
	v_pk_mul_f32 v[54:55], v[42:43], v[54:55]
	v_pk_mul_f32 v[42:43], v[40:41], v[52:53]
	v_pk_add_f32 v[46:47], v[62:63], 1.0 op_sel_hi:[1,0]
	v_pk_mul_f32 v[46:47], v[58:59], v[46:47]
	v_cvt_pk_bf16_f32 v40, v56, v57
	v_cvt_pk_bf16_f32 v41, v46, v47
	v_cvt_pk_bf16_f32 v42, v42, v43
	v_cvt_pk_bf16_f32 v43, v54, v55
	v_lshlrev_b64 v[46:47], 12, v[48:49]
	v_lshl_add_u64 v[46:47], s[28:29], 0, v[46:47]
	v_lshl_add_u64 v[46:47], v[138:139], 1, v[46:47]
	global_store_dwordx4 v[46:47], v[40:43], off
	global_load_dwordx4 v[40:43], v[122:123], off offset:16
	s_nop 0
	global_load_dwordx4 v[52:55], v[122:123], off
	global_load_dwordx4 v[56:59], v[50:51], off offset:528
	global_load_dwordx4 v[60:63], v[50:51], off offset:512
	s_waitcnt vmcnt(1)
	v_pk_fma_f32 v[32:33], v[32:33], v[40:41], v[56:57]
	s_waitcnt vmcnt(0)
	v_pk_fma_f32 v[38:39], v[38:39], v[54:55], v[62:63]
	v_pk_fma_f32 v[36:37], v[36:37], v[52:53], v[60:61]
	v_mul_f32_e32 v41, v39, v39
	v_mul_f32_e32 v40, v37, v37
	v_fmac_f32_e32 v40, v36, v36
	v_fmac_f32_e32 v41, v38, v38
	v_add_f32_e32 v40, v40, v41
	v_mul_f32_e32 v41, v33, v33
	v_pk_fma_f32 v[34:35], v[34:35], v[42:43], v[58:59]
	v_fmac_f32_e32 v41, v32, v32
	v_add_f32_e32 v40, v40, v41
	v_mul_f32_e32 v41, v35, v35
	v_fmac_f32_e32 v41, v34, v34
	global_store_dwordx4 v[44:45], v[36:39], off offset:512
	global_store_dwordx4 v[44:45], v[32:35], off offset:528
	v_add_f32_e32 v40, v41, v40
	v_add_f32_e32 v54, v64, v40
	global_load_dwordx4 v[40:43], v[112:113], off offset:16
	global_load_dwordx4 v[50:53], v[112:113], off
	s_waitcnt vmcnt(1)
	v_pk_add_f32 v[42:43], v[42:43], 1.0 op_sel_hi:[1,0]
	s_waitcnt vmcnt(0)
	v_pk_add_f32 v[50:51], v[50:51], 1.0 op_sel_hi:[1,0]
	v_pk_add_f32 v[40:41], v[40:41], 1.0 op_sel_hi:[1,0]
	v_pk_mul_f32 v[36:37], v[36:37], v[50:51]
	v_pk_mul_f32 v[42:43], v[34:35], v[42:43]
	v_pk_mul_f32 v[34:35], v[32:33], v[40:41]
	v_pk_add_f32 v[44:45], v[52:53], 1.0 op_sel_hi:[1,0]
	v_pk_mul_f32 v[38:39], v[38:39], v[44:45]
	v_cvt_pk_bf16_f32 v32, v36, v37
	v_cvt_pk_bf16_f32 v33, v38, v39
	v_cvt_pk_bf16_f32 v34, v34, v35
	v_cvt_pk_bf16_f32 v35, v42, v43
	global_store_dwordx4 v[46:47], v[32:35], off offset:256
	s_nop 1
	v_mov_b32_e32 v32, v54
	s_nop 1
	v_permlane16_swap_b32_e32 v54, v32
	s_nop 0
	v_add_f32_e32 v32, v54, v32
	v_mov_b32_e32 v33, v32
	s_nop 1
	v_permlane32_swap_b32_e32 v32, v33
	s_and_saveexec_b64 s[10:11], s[38:39]
	s_cbranch_execz .LBB0_74
	v_lshl_add_u64 v[34:35], v[48:49], 2, s[62:63]
	v_add_f32_e32 v32, v32, v33
	global_atomic_add_f32 v[34:35], v32, off
.LBB0_74:
	s_or_b64 exec, exec, s[10:11]
	v_add_u32_e32 v32, 0xa0, v144
	v_ashrrev_i32_e32 v33, 31, v32
	v_lshlrev_b64 v[52:53], 13, v[32:33]
	v_lshl_add_u64 v[34:35], s[30:31], 0, v[52:53]
	v_lshl_add_u64 v[34:35], v[34:35], 0, v[140:141]
	global_load_dwordx4 v[36:39], v[142:143], off offset:16
	global_load_dwordx4 v[40:43], v[142:143], off
	global_load_dwordx4 v[44:47], v[34:35], off offset:16
	global_load_dwordx4 v[48:51], v[34:35], off
	s_waitcnt vmcnt(1)
	v_pk_fma_f32 v[26:27], v[26:27], v[38:39], v[46:47]
	s_waitcnt vmcnt(0)
	v_pk_fma_f32 v[40:41], v[28:29], v[40:41], v[48:49]
	v_lshl_add_u64 v[28:29], s[6:7], 0, v[52:53]
	v_pk_fma_f32 v[42:43], v[30:31], v[42:43], v[50:51]
	v_lshl_add_u64 v[28:29], v[28:29], 0, v[140:141]
	v_pk_fma_f32 v[24:25], v[24:25], v[36:37], v[44:45]
	global_store_dwordx4 v[28:29], v[40:43], off
	global_store_dwordx4 v[28:29], v[24:27], off offset:16
	global_load_dwordx4 v[36:39], v[120:121], off offset:16
	global_load_dwordx4 v[44:47], v[120:121], off
	v_mul_f32_e32 v30, v41, v41
	v_mul_f32_e32 v31, v43, v43
	v_fmac_f32_e32 v30, v40, v40
	v_fmac_f32_e32 v31, v42, v42
	v_add_f32_e32 v30, v30, v31
	v_mul_f32_e32 v31, v25, v25
	v_fmac_f32_e32 v31, v24, v24
	v_add_f32_e32 v30, v30, v31
	v_mul_f32_e32 v31, v27, v27
	v_fmac_f32_e32 v31, v26, v26
	v_add_f32_e32 v48, v31, v30
	s_waitcnt vmcnt(1)
	v_pk_add_f32 v[38:39], v[38:39], 1.0 op_sel_hi:[1,0]
	s_waitcnt vmcnt(0)
;     __device__ __forceinline__ void operator()(const f32x4 (&acc)[2][2][4][2], const pg8::Unit& u, int wr, int wc, int fr, int fq) const {
;     ...
;                     } else if constexpr (MODE == 7) {
;                         const f32x4 g0 = *(const f32x4*)(vec + col), g1 = *(const f32x4*)(vec + col + 4);
;                         const f32x4 x0 = *(const f32x4*)(xsrc + row * DM + col), x1 = *(const f32x4*)(xsrc + row * DM + col + 4);
;                         const f32x4 y0 = x0 + g0 * v0, y1 = x1 + g1 * v1;
;                         *(f32x4*)(of + row * DM + col) = y0; *(f32x4*)(of + row * DM + col + 4) = y1;
;                         ssq += (y0[0] * y0[0] + y0[1] * y0[1]) + (y0[2] * y0[2] + y0[3] * y0[3]) + (y1[0] * y1[0] + y1[1] * y1[1]) + (y1[2] * y1[2] + y1[3] * y1[3]);
;                         const f32x4 s0 = *(const f32x4*)(vec2 + col) + 1.f, s1 = *(const f32x4*)(vec2 + col + 4) + 1.f;
;                         const f32x4 a0 = y0 * s0, a1 = y1 * s1;
;                         u32x4 w; w.x = pk2(a0[0], a0[1]); w.y = pk2(a0[2], a0[3]); w.z = pk2(a1[0], a1[1]); w.w = pk2(a1[2], a1[3]);
;                         *(u32x4*)(ob + row * DM + col) = w;
;                     } else if constexpr (MODE == 8) {
;                         const f32x4 b0 = *(const f32x4*)(vec + col), b1 = *(const f32x4*)(vec + col + 4);
;                         float r[8] = {v0[0] * rstd + b0[0], v0[1] * rstd + b0[1], v0[2] * rstd + b0[2], v0[3] * rstd + b0[3], v1[0] * rstd + b1[0], v1[1] * rstd + b1[1], v1[2] * rstd + b1[2], v1[3] * rstd + b1[3]};
; #pragma unroll
;                         for (int i = 0; i < 8; ++i) { const float q = fmaxf(r[i], 0.f); r[i] = q * q; }
;                         u32x4 w; w.x = pk2(r[0], r[1]); w.y = pk2(r[2], r[3]); w.z = pk2(r[4], r[5]); w.w = pk2(r[6], r[7]);
;                         *(u32x4*)(ob + row * HIDN + col) = w;
;                     } else {
;                         float r[8] = {v0[0], v0[1], v0[2], v0[3], v1[0], v1[1], v1[2], v1[3]};
; #pragma unroll
;                         for (int i = 0; i < 8; ++i) { const float q = fmaxf(r[i], 0.f); r[i] = q * q; }
;                         u32x4 w; w.x = pk2(r[0], r[1]); w.y = pk2(r[2], r[3]); w.z = pk2(r[4], r[5]); w.w = pk2(r[6], r[7]);
;                         *(u32x4*)(ob + row * HIDN + col) = w;
;                     }
;                 }
;                 if constexpr (MODE == 7) {
	v_pk_add_f32 v[44:45], v[44:45], 1.0 op_sel_hi:[1,0]
	v_pk_add_f32 v[36:37], v[36:37], 1.0 op_sel_hi:[1,0]
	v_pk_mul_f32 v[40:41], v[40:41], v[44:45]
	v_pk_mul_f32 v[38:39], v[26:27], v[38:39]
	v_pk_mul_f32 v[26:27], v[24:25], v[36:37]
	v_pk_add_f32 v[30:31], v[46:47], 1.0 op_sel_hi:[1,0]
	v_pk_mul_f32 v[30:31], v[42:43], v[30:31]
	v_cvt_pk_bf16_f32 v24, v40, v41
	v_cvt_pk_bf16_f32 v25, v30, v31
	v_cvt_pk_bf16_f32 v26, v26, v27
	v_cvt_pk_bf16_f32 v27, v38, v39
	v_lshlrev_b64 v[30:31], 12, v[32:33]
	v_lshl_add_u64 v[30:31], s[28:29], 0, v[30:31]
	v_lshl_add_u64 v[30:31], v[138:139], 1, v[30:31]
	global_store_dwordx4 v[30:31], v[24:27], off
	global_load_dwordx4 v[24:27], v[122:123], off offset:16
	s_nop 0
	global_load_dwordx4 v[36:39], v[122:123], off
	global_load_dwordx4 v[40:43], v[34:35], off offset:528
	global_load_dwordx4 v[44:47], v[34:35], off offset:512
	s_waitcnt vmcnt(1)
	v_pk_fma_f32 v[16:17], v[16:17], v[24:25], v[40:41]
	s_waitcnt vmcnt(0)
	v_pk_fma_f32 v[22:23], v[22:23], v[38:39], v[46:47]
	v_pk_fma_f32 v[20:21], v[20:21], v[36:37], v[44:45]
	v_mul_f32_e32 v25, v23, v23
	v_mul_f32_e32 v24, v21, v21
	v_fmac_f32_e32 v24, v20, v20
	v_fmac_f32_e32 v25, v22, v22
	v_add_f32_e32 v24, v24, v25
	v_mul_f32_e32 v25, v17, v17
	v_pk_fma_f32 v[18:19], v[18:19], v[26:27], v[42:43]
	v_fmac_f32_e32 v25, v16, v16
	v_add_f32_e32 v24, v24, v25
	v_mul_f32_e32 v25, v19, v19
	v_fmac_f32_e32 v25, v18, v18
	global_store_dwordx4 v[28:29], v[20:23], off offset:512
	global_store_dwordx4 v[28:29], v[16:19], off offset:528
	v_add_f32_e32 v24, v25, v24
	v_add_f32_e32 v38, v48, v24
	global_load_dwordx4 v[24:27], v[112:113], off offset:16
	global_load_dwordx4 v[34:37], v[112:113], off
	s_waitcnt vmcnt(1)
	v_pk_add_f32 v[26:27], v[26:27], 1.0 op_sel_hi:[1,0]
	s_waitcnt vmcnt(0)
	v_pk_add_f32 v[34:35], v[34:35], 1.0 op_sel_hi:[1,0]
	v_pk_add_f32 v[24:25], v[24:25], 1.0 op_sel_hi:[1,0]
	v_pk_mul_f32 v[20:21], v[20:21], v[34:35]
	v_pk_mul_f32 v[26:27], v[18:19], v[26:27]
	v_pk_mul_f32 v[18:19], v[16:17], v[24:25]
	v_pk_add_f32 v[28:29], v[36:37], 1.0 op_sel_hi:[1,0]
	v_pk_mul_f32 v[22:23], v[22:23], v[28:29]
	v_cvt_pk_bf16_f32 v16, v20, v21
	v_cvt_pk_bf16_f32 v17, v22, v23
	v_cvt_pk_bf16_f32 v18, v18, v19
	v_cvt_pk_bf16_f32 v19, v26, v27
	global_store_dwordx4 v[30:31], v[16:19], off offset:256
	s_nop 1
	v_mov_b32_e32 v16, v38
	s_nop 1
	v_permlane16_swap_b32_e32 v38, v16
	s_nop 0
	v_add_f32_e32 v16, v38, v16
	v_mov_b32_e32 v17, v16
	s_nop 1
	v_permlane32_swap_b32_e32 v16, v17
	s_and_saveexec_b64 s[10:11], s[38:39]
	s_cbranch_execz .LBB0_76
	v_lshl_add_u64 v[18:19], v[32:33], 2, s[62:63]
	v_add_f32_e32 v16, v16, v17
	global_atomic_add_f32 v[18:19], v16, off
.LBB0_76:
	s_or_b64 exec, exec, s[10:11]
	v_add_u32_e32 v16, 0xb0, v144
	v_ashrrev_i32_e32 v17, 31, v16
	v_lshlrev_b64 v[34:35], 13, v[16:17]
	v_lshl_add_u64 v[18:19], s[30:31], 0, v[34:35]
	v_lshl_add_u64 v[36:37], v[18:19], 0, v[140:141]
	global_load_dwordx4 v[18:21], v[36:37], off
	global_load_dwordx4 v[22:25], v[142:143], off
	global_load_dwordx4 v[26:29], v[142:143], off offset:16
	global_load_dwordx4 v[30:33], v[36:37], off offset:16
	v_lshl_add_u64 v[34:35], s[6:7], 0, v[34:35]
	v_lshl_add_u64 v[34:35], v[34:35], 0, v[140:141]
	s_waitcnt vmcnt(2)
	v_pk_fma_f32 v[14:15], v[14:15], v[24:25], v[20:21]
	v_pk_fma_f32 v[12:13], v[12:13], v[22:23], v[18:19]
	s_waitcnt vmcnt(0)
	v_pk_fma_f32 v[10:11], v[10:11], v[28:29], v[32:33]
	v_pk_fma_f32 v[8:9], v[8:9], v[26:27], v[30:31]
	global_store_dwordx4 v[34:35], v[12:15], off
	global_store_dwordx4 v[34:35], v[8:11], off offset:16
	global_load_dwordx4 v[18:21], v[120:121], off
	global_load_dwordx4 v[22:25], v[120:121], off offset:16
	v_lshlrev_b64 v[26:27], 12, v[16:17]
	v_lshl_add_u64 v[26:27], s[28:29], 0, v[26:27]
	v_lshl_add_u64 v[38:39], v[138:139], 1, v[26:27]
	s_waitcnt vmcnt(1)
	v_pk_add_f32 v[20:21], v[20:21], 1.0 op_sel_hi:[1,0]
	v_pk_add_f32 v[18:19], v[18:19], 1.0 op_sel_hi:[1,0]
	s_waitcnt vmcnt(0)
	v_pk_add_f32 v[24:25], v[24:25], 1.0 op_sel_hi:[1,0]
	v_pk_add_f32 v[22:23], v[22:23], 1.0 op_sel_hi:[1,0]
	v_pk_mul_f32 v[20:21], v[14:15], v[20:21]
	v_pk_mul_f32 v[18:19], v[12:13], v[18:19]
	v_pk_mul_f32 v[24:25], v[10:11], v[24:25]
	v_pk_mul_f32 v[22:23], v[8:9], v[22:23]
	v_cvt_pk_bf16_f32 v18, v18, v19
	v_cvt_pk_bf16_f32 v19, v20, v21
	v_cvt_pk_bf16_f32 v20, v22, v23
	v_cvt_pk_bf16_f32 v21, v24, v25
	global_store_dwordx4 v[38:39], v[18:21], off
	global_load_dwordx4 v[18:21], v[36:37], off offset:512
	s_nop 0
	global_load_dwordx4 v[22:25], v[122:123], off
	global_load_dwordx4 v[26:29], v[122:123], off offset:16
	global_load_dwordx4 v[30:33], v[36:37], off offset:528
	v_mul_f32_e32 v13, v13, v13
	v_mul_f32_e32 v15, v15, v15
	v_mul_f32_e32 v9, v9, v9
	v_fmac_f32_e32 v13, v12, v12
	v_fmac_f32_e32 v15, v14, v14
	v_mul_f32_e32 v11, v11, v11
	v_fmac_f32_e32 v9, v8, v8
	v_add_f32_e32 v8, v13, v15
	v_fmac_f32_e32 v11, v10, v10
	v_add_f32_e32 v8, v8, v9
	v_add_f32_e32 v8, v11, v8
	s_waitcnt vmcnt(2)
	v_pk_fma_f32 v[6:7], v[6:7], v[24:25], v[20:21]
	v_pk_fma_f32 v[4:5], v[4:5], v[22:23], v[18:19]
	s_waitcnt vmcnt(0)
	v_pk_fma_f32 v[2:3], v[2:3], v[28:29], v[32:33]
	v_pk_fma_f32 v[0:1], v[0:1], v[26:27], v[30:31]
	global_store_dwordx4 v[34:35], v[4:7], off offset:512
	global_store_dwordx4 v[34:35], v[0:3], off offset:528
	global_load_dwordx4 v[18:21], v[112:113], off
	global_load_dwordx4 v[22:25], v[112:113], off offset:16
	v_mul_f32_e32 v9, v5, v5
	v_mul_f32_e32 v10, v7, v7
	v_mul_f32_e32 v11, v1, v1
	v_fmac_f32_e32 v9, v4, v4
	v_fmac_f32_e32 v10, v6, v6
	v_mul_f32_e32 v12, v3, v3
	v_fmac_f32_e32 v11, v0, v0
	v_add_f32_e32 v9, v9, v10
	v_fmac_f32_e32 v12, v2, v2
	v_add_f32_e32 v9, v9, v11
	v_add_f32_e32 v9, v12, v9
	v_add_f32_e32 v26, v8, v9
	v_mov_b32_e32 v27, v26
	s_waitcnt vmcnt(1)
	v_pk_add_f32 v[8:9], v[20:21], 1.0 op_sel_hi:[1,0]
	v_pk_add_f32 v[10:11], v[18:19], 1.0 op_sel_hi:[1,0]
	s_waitcnt vmcnt(0)
	v_pk_add_f32 v[12:13], v[24:25], 1.0 op_sel_hi:[1,0]
	v_pk_add_f32 v[14:15], v[22:23], 1.0 op_sel_hi:[1,0]
	v_pk_mul_f32 v[6:7], v[6:7], v[8:9]
	v_pk_mul_f32 v[4:5], v[4:5], v[10:11]
	v_pk_mul_f32 v[2:3], v[2:3], v[12:13]
	v_pk_mul_f32 v[0:1], v[0:1], v[14:15]
	v_bfe_u32 v12, v0, 16, 1
	v_bfe_u32 v13, v1, 16, 1
	v_add3_u32 v0, v0, v12, s33
	v_add3_u32 v8, v1, v13, s33
	v_cvt_pk_bf16_f32 v1, v6, v7
	v_cvt_pk_bf16_f32 v3, v2, v3
	v_lshrrev_b32_e32 v6, 16, v0
	v_cvt_pk_bf16_f32 v0, v4, v5
	v_and_or_b32 v2, v8, s67, v6
	global_store_dwordx4 v[38:39], v[0:3], off offset:256
	s_nop 0
	v_permlane16_swap_b32_e32 v26, v27
	s_nop 0
	v_add_f32_e32 v0, v26, v27
	v_mov_b32_e32 v1, v0
	s_nop 1
	v_permlane32_swap_b32_e32 v0, v1
	s_and_saveexec_b64 s[10:11], s[38:39]
	s_cbranch_execz .LBB0_78
	v_lshl_add_u64 v[2:3], v[16:17], 2, s[62:63]
	v_add_f32_e32 v0, v0, v1
	global_atomic_add_f32 v[2:3], v0, off

; __device__ __forceinline__ unsigned pk2(float lo, float hi) { return f2bf(lo) | (f2bf(hi) << 16); }
;     __device__ __forceinline__ void operator()(const f32x4 (&acc)[2][2][4][2], const pg8::Unit& u, int wr, int wc, int fr, int fq) const {
;     ...
;                     } else if constexpr (MODE == 2 || MODE == 3) {
;                         const u32x4 g = *(const u32x4*)(aux + row * 4096 + (MODE == 3 ? 2048 : 0) + col);
;                         float r[8] = {v0[0], v0[1], v0[2], v0[3], v1[0], v1[1], v1[2], v1[3]};
;                         const unsigned gw[4] = {g.x, g.y, g.z, g.w};
; #pragma unroll
;                         for (int i = 0; i < 4; ++i) { r[2 * i] *= bf2f(gw[i] & 0xffffu); r[2 * i + 1] *= __builtin_bit_cast(float, gw[i] & 0xffff0000u); }
;                         if constexpr (MODE == 3) { const u32x4 pv = *(const u32x4*)(ob + row * 2048 + col); const unsigned pw[4] = {pv.x, pv.y, pv.z, pv.w};
; #pragma unroll
;                             for (int i = 0; i < 4; ++i) { r[2 * i] += bf2f(pw[i] & 0xffffu); r[2 * i + 1] += __builtin_bit_cast(float, pw[i] & 0xffff0000u); } }
;                         u32x4 w; w.x = pk2(r[0], r[1]); w.y = pk2(r[2], r[3]); w.z = pk2(r[4], r[5]); w.w = pk2(r[6], r[7]);
;                         *(u32x4*)(ob + row * 2048 + col) = w;
.LBB0_100:
	v_lshl_add_u32 v140, s9, 8, v142
	v_lshl_or_b32 v138, s8, 8, v144
	v_ashrrev_i32_e32 v141, 31, v140
	v_lshlrev_b64 v[146:147], 13, v[140:141]
	v_ashrrev_i32_e32 v139, 31, v138
	v_lshl_add_u64 v[146:147], s[24:25], 0, v[146:147]
	v_lshlrev_b64 v[138:139], 1, v[138:139]
	v_lshl_add_u64 v[152:153], v[146:147], 0, v[138:139]
	global_load_dwordx4 v[146:149], v[152:153], off
	v_mov_b32_e32 v157, v126
	v_mov_b32_e32 v126, v125
	v_mov_b32_e32 v156, v124
	v_lshlrev_b64 v[150:151], 12, v[140:141]
	s_mov_b64 s[42:43], -1
	s_andn2_b64 vcc, exec, s[38:39]
	s_waitcnt vmcnt(0)
	v_lshlrev_b32_e32 v155, 16, v147
	v_lshlrev_b32_e32 v154, 16, v146
	v_and_b32_e32 v147, 0xffff0000, v147
	v_and_b32_e32 v146, 0xffff0000, v146
	v_pk_mul_f32 v[124:125], v[126:127], v[146:147]
	v_lshlrev_b32_e32 v127, 16, v149
	v_lshlrev_b32_e32 v126, 16, v148
	v_mov_b32_e32 v146, v120
	v_mov_b32_e32 v147, v122
	v_pk_mul_f32 v[126:127], v[146:147], v[126:127]
	v_and_b32_e32 v147, 0xffff0000, v149
	v_and_b32_e32 v146, 0xffff0000, v148
	v_mov_b32_e32 v122, v121
	v_pk_mul_f32 v[120:121], v[122:123], v[146:147]
	v_pk_mul_f32 v[154:155], v[156:157], v[154:155]
	v_cvt_pk_bf16_f32 v123, v155, v125
	v_cvt_pk_bf16_f32 v122, v154, v124
	v_cvt_pk_bf16_f32 v125, v127, v121
	v_cvt_pk_bf16_f32 v124, v126, v120
	v_lshl_add_u64 v[120:121], s[26:27], 0, v[150:151]
	v_lshl_add_u64 v[120:121], v[120:121], 0, v[138:139]
	global_store_dwordx4 v[120:121], v[122:125], off
	global_load_dwordx4 v[124:127], v[152:153], off offset:256
	v_mov_b32_e32 v147, v118
	v_mov_b32_e32 v118, v117
	v_mov_b32_e32 v146, v116
	s_waitcnt vmcnt(0)
	v_lshlrev_b32_e32 v123, 16, v125
	v_lshlrev_b32_e32 v122, 16, v124
	v_and_b32_e32 v125, 0xffff0000, v125
	v_and_b32_e32 v124, 0xffff0000, v124
	v_pk_mul_f32 v[116:117], v[118:119], v[124:125]
	v_lshlrev_b32_e32 v119, 16, v127
	v_lshlrev_b32_e32 v118, 16, v126
	v_mov_b32_e32 v124, v112
	v_mov_b32_e32 v125, v114
	v_pk_mul_f32 v[118:119], v[124:125], v[118:119]
	v_and_b32_e32 v125, 0xffff0000, v127
	v_and_b32_e32 v124, 0xffff0000, v126
	v_mov_b32_e32 v114, v113
	v_pk_mul_f32 v[112:113], v[114:115], v[124:125]
	v_pk_mul_f32 v[122:123], v[146:147], v[122:123]
	v_cvt_pk_bf16_f32 v115, v119, v113
	v_cvt_pk_bf16_f32 v114, v118, v112
	v_cvt_pk_bf16_f32 v113, v123, v117
	v_cvt_pk_bf16_f32 v112, v122, v116
	global_store_dwordx4 v[120:121], v[112:115], off offset:256
	v_mov_b32_e32 v123, v110
	v_mov_b32_e32 v110, v109
	v_or_b32_e32 v112, 16, v140
	v_ashrrev_i32_e32 v113, 31, v112
	v_lshlrev_b64 v[114:115], 13, v[112:113]
	v_lshlrev_b64 v[118:119], 12, v[112:113]
	v_lshl_add_u64 v[112:113], s[24:25], 0, v[114:115]
	v_lshl_add_u64 v[112:113], v[112:113], 0, v[138:139]
	global_load_dwordx4 v[114:117], v[112:113], off
	v_mov_b32_e32 v122, v108
	s_waitcnt vmcnt(0)
	v_lshlrev_b32_e32 v121, 16, v115
	v_lshlrev_b32_e32 v120, 16, v114
	v_and_b32_e32 v115, 0xffff0000, v115
	v_and_b32_e32 v114, 0xffff0000, v114
	v_pk_mul_f32 v[108:109], v[110:111], v[114:115]
	v_lshlrev_b32_e32 v111, 16, v117
	v_lshlrev_b32_e32 v110, 16, v116
	v_mov_b32_e32 v114, v104
	v_mov_b32_e32 v115, v106
	v_pk_mul_f32 v[110:111], v[114:115], v[110:111]
	v_and_b32_e32 v115, 0xffff0000, v117
	v_and_b32_e32 v114, 0xffff0000, v116
	v_mov_b32_e32 v106, v105
	v_pk_mul_f32 v[104:105], v[106:107], v[114:115]
	v_pk_mul_f32 v[120:121], v[122:123], v[120:121]
	v_cvt_pk_bf16_f32 v107, v121, v109
	v_cvt_pk_bf16_f32 v106, v120, v108
	v_cvt_pk_bf16_f32 v109, v111, v105
	v_cvt_pk_bf16_f32 v108, v110, v104
	v_lshl_add_u64 v[104:105], s[26:27], 0, v[118:119]
	v_lshl_add_u64 v[104:105], v[104:105], 0, v[138:139]
	global_store_dwordx4 v[104:105], v[106:109], off
	global_load_dwordx4 v[108:111], v[112:113], off offset:256
	v_mov_b32_e32 v113, v102
	v_mov_b32_e32 v102, v101
	v_mov_b32_e32 v112, v100
	s_waitcnt vmcnt(0)
	v_lshlrev_b32_e32 v107, 16, v109
	v_lshlrev_b32_e32 v106, 16, v108
	v_and_b32_e32 v109, 0xffff0000, v109
	v_and_b32_e32 v108, 0xffff0000, v108
	v_pk_mul_f32 v[102:103], v[102:103], v[108:109]
	v_lshlrev_b32_e32 v101, 16, v111
	v_lshlrev_b32_e32 v100, 16, v110
	v_mov_b32_e32 v108, v96
	v_mov_b32_e32 v109, v98
	v_pk_mul_f32 v[100:101], v[108:109], v[100:101]
	v_and_b32_e32 v109, 0xffff0000, v111
	v_and_b32_e32 v108, 0xffff0000, v110
	v_mov_b32_e32 v98, v97
	v_pk_mul_f32 v[96:97], v[98:99], v[108:109]
	v_pk_mul_f32 v[106:107], v[112:113], v[106:107]
	v_cvt_pk_bf16_f32 v99, v101, v97
	v_cvt_pk_bf16_f32 v98, v100, v96
	v_cvt_pk_bf16_f32 v97, v107, v103
	v_cvt_pk_bf16_f32 v96, v106, v102
	global_store_dwordx4 v[104:105], v[96:99], off offset:256
	v_mov_b32_e32 v107, v94
	v_mov_b32_e32 v94, v93
	v_or_b32_e32 v96, 32, v140
	v_ashrrev_i32_e32 v97, 31, v96
	v_lshlrev_b64 v[98:99], 13, v[96:97]
	v_lshlrev_b64 v[102:103], 12, v[96:97]
	v_lshl_add_u64 v[96:97], s[24:25], 0, v[98:99]
	v_lshl_add_u64 v[96:97], v[96:97], 0, v[138:139]
	global_load_dwordx4 v[98:101], v[96:97], off
	v_mov_b32_e32 v106, v92
	s_waitcnt vmcnt(0)
	v_lshlrev_b32_e32 v105, 16, v99
	v_lshlrev_b32_e32 v104, 16, v98
	v_and_b32_e32 v99, 0xffff0000, v99
	v_and_b32_e32 v98, 0xffff0000, v98
	v_pk_mul_f32 v[92:93], v[94:95], v[98:99]
	v_lshlrev_b32_e32 v95, 16, v101
	v_lshlrev_b32_e32 v94, 16, v100
	v_mov_b32_e32 v98, v88
	v_mov_b32_e32 v99, v90
	v_pk_mul_f32 v[94:95], v[98:99], v[94:95]
	v_and_b32_e32 v99, 0xffff0000, v101
	v_and_b32_e32 v98, 0xffff0000, v100
	v_mov_b32_e32 v90, v89
	v_pk_mul_f32 v[88:89], v[90:91], v[98:99]
	v_pk_mul_f32 v[104:105], v[106:107], v[104:105]
	v_cvt_pk_bf16_f32 v91, v105, v93
	v_cvt_pk_bf16_f32 v90, v104, v92
	v_cvt_pk_bf16_f32 v93, v95, v89
	v_cvt_pk_bf16_f32 v92, v94, v88
	v_lshl_add_u64 v[88:89], s[26:27], 0, v[102:103]
	v_lshl_add_u64 v[88:89], v[88:89], 0, v[138:139]
	global_store_dwordx4 v[88:89], v[90:93], off
	global_load_dwordx4 v[92:95], v[96:97], off offset:256
	v_mov_b32_e32 v97, v86
	v_mov_b32_e32 v86, v85
	v_mov_b32_e32 v96, v84
	s_waitcnt vmcnt(0)
; __device__ __forceinline__ unsigned pk2(float lo, float hi) { return f2bf(lo) | (f2bf(hi) << 16); }
;     __device__ __forceinline__ void operator()(const f32x4 (&acc)[2][2][4][2], const pg8::Unit& u, int wr, int wc, int fr, int fq) const {
;     ...
;                     } else if constexpr (MODE == 2 || MODE == 3) {
;                         const u32x4 g = *(const u32x4*)(aux + row * 4096 + (MODE == 3 ? 2048 : 0) + col);
;                         float r[8] = {v0[0], v0[1], v0[2], v0[3], v1[0], v1[1], v1[2], v1[3]};
;                         const unsigned gw[4] = {g.x, g.y, g.z, g.w};
; #pragma unroll
;                         for (int i = 0; i < 4; ++i) { r[2 * i] *= bf2f(gw[i] & 0xffffu); r[2 * i + 1] *= __builtin_bit_cast(float, gw[i] & 0xffff0000u); }
;                         if constexpr (MODE == 3) { const u32x4 pv = *(const u32x4*)(ob + row * 2048 + col); const unsigned pw[4] = {pv.x, pv.y, pv.z, pv.w};
; #pragma unroll
;                             for (int i = 0; i < 4; ++i) { r[2 * i] += bf2f(pw[i] & 0xffffu); r[2 * i + 1] += __builtin_bit_cast(float, pw[i] & 0xffff0000u); } }
;                         u32x4 w; w.x = pk2(r[0], r[1]); w.y = pk2(r[2], r[3]); w.z = pk2(r[4], r[5]); w.w = pk2(r[6], r[7]);
;                         *(u32x4*)(ob + row * 2048 + col) = w;
	v_lshlrev_b32_e32 v91, 16, v93
	v_lshlrev_b32_e32 v90, 16, v92
	v_and_b32_e32 v93, 0xffff0000, v93
	v_and_b32_e32 v92, 0xffff0000, v92
	v_pk_mul_f32 v[84:85], v[86:87], v[92:93]
	v_lshlrev_b32_e32 v87, 16, v95
	v_lshlrev_b32_e32 v86, 16, v94
	v_mov_b32_e32 v92, v80
	v_mov_b32_e32 v93, v82
	v_pk_mul_f32 v[86:87], v[92:93], v[86:87]
	v_and_b32_e32 v93, 0xffff0000, v95
	v_and_b32_e32 v92, 0xffff0000, v94
	v_mov_b32_e32 v82, v81
	v_pk_mul_f32 v[80:81], v[82:83], v[92:93]
	v_pk_mul_f32 v[90:91], v[96:97], v[90:91]
	v_cvt_pk_bf16_f32 v83, v87, v81
	v_cvt_pk_bf16_f32 v82, v86, v80
	v_cvt_pk_bf16_f32 v81, v91, v85
	v_cvt_pk_bf16_f32 v80, v90, v84
	global_store_dwordx4 v[88:89], v[80:83], off offset:256
	v_mov_b32_e32 v91, v78
	v_mov_b32_e32 v78, v77
	v_or_b32_e32 v80, 48, v140
	v_ashrrev_i32_e32 v81, 31, v80
	v_lshlrev_b64 v[82:83], 13, v[80:81]
	v_lshlrev_b64 v[86:87], 12, v[80:81]
	v_lshl_add_u64 v[80:81], s[24:25], 0, v[82:83]
	v_lshl_add_u64 v[80:81], v[80:81], 0, v[138:139]
	global_load_dwordx4 v[82:85], v[80:81], off
	v_mov_b32_e32 v90, v76
	s_waitcnt vmcnt(0)
	v_lshlrev_b32_e32 v89, 16, v83
	v_lshlrev_b32_e32 v88, 16, v82
	v_and_b32_e32 v83, 0xffff0000, v83
	v_and_b32_e32 v82, 0xffff0000, v82
	v_pk_mul_f32 v[76:77], v[78:79], v[82:83]
	v_lshlrev_b32_e32 v79, 16, v85
	v_lshlrev_b32_e32 v78, 16, v84
	v_mov_b32_e32 v82, v72
	v_mov_b32_e32 v83, v74
	v_pk_mul_f32 v[78:79], v[82:83], v[78:79]
	v_and_b32_e32 v83, 0xffff0000, v85
	v_and_b32_e32 v82, 0xffff0000, v84
	v_mov_b32_e32 v74, v73
	v_pk_mul_f32 v[72:73], v[74:75], v[82:83]
	v_pk_mul_f32 v[88:89], v[90:91], v[88:89]
	v_cvt_pk_bf16_f32 v75, v89, v77
	v_cvt_pk_bf16_f32 v74, v88, v76
	v_cvt_pk_bf16_f32 v77, v79, v73
	v_cvt_pk_bf16_f32 v76, v78, v72
	v_lshl_add_u64 v[72:73], s[26:27], 0, v[86:87]
	v_lshl_add_u64 v[72:73], v[72:73], 0, v[138:139]
	global_store_dwordx4 v[72:73], v[74:77], off
	global_load_dwordx4 v[74:77], v[80:81], off offset:256
	v_mov_b32_e32 v81, v70
	v_mov_b32_e32 v70, v69
	v_mov_b32_e32 v80, v68
	s_waitcnt vmcnt(0)
	v_lshlrev_b32_e32 v79, 16, v75
	v_lshlrev_b32_e32 v78, 16, v74
	v_and_b32_e32 v75, 0xffff0000, v75
	v_and_b32_e32 v74, 0xffff0000, v74
	v_pk_mul_f32 v[68:69], v[70:71], v[74:75]
	v_lshlrev_b32_e32 v71, 16, v77
	v_lshlrev_b32_e32 v70, 16, v76
	v_mov_b32_e32 v74, v64
	v_mov_b32_e32 v75, v66
	v_pk_mul_f32 v[70:71], v[74:75], v[70:71]
	v_and_b32_e32 v75, 0xffff0000, v77
	v_and_b32_e32 v74, 0xffff0000, v76
	v_mov_b32_e32 v66, v65
	v_pk_mul_f32 v[64:65], v[66:67], v[74:75]
	v_pk_mul_f32 v[78:79], v[80:81], v[78:79]
	v_cvt_pk_bf16_f32 v67, v71, v65
	v_cvt_pk_bf16_f32 v66, v70, v64
	v_cvt_pk_bf16_f32 v65, v79, v69
	v_cvt_pk_bf16_f32 v64, v78, v68
	global_store_dwordx4 v[72:73], v[64:67], off offset:256
	v_mov_b32_e32 v75, v62
	v_mov_b32_e32 v62, v61
	v_add_u32_e32 v64, 0x80, v140
	v_ashrrev_i32_e32 v65, 31, v64
	v_lshlrev_b64 v[66:67], 13, v[64:65]
	v_lshlrev_b64 v[70:71], 12, v[64:65]
	v_lshl_add_u64 v[64:65], s[24:25], 0, v[66:67]
	v_lshl_add_u64 v[64:65], v[64:65], 0, v[138:139]
	global_load_dwordx4 v[66:69], v[64:65], off
	v_mov_b32_e32 v74, v60
	s_waitcnt vmcnt(0)
	v_lshlrev_b32_e32 v73, 16, v67
	v_lshlrev_b32_e32 v72, 16, v66
	v_and_b32_e32 v67, 0xffff0000, v67
	v_and_b32_e32 v66, 0xffff0000, v66
	v_pk_mul_f32 v[60:61], v[62:63], v[66:67]
	v_lshlrev_b32_e32 v63, 16, v69
	v_lshlrev_b32_e32 v62, 16, v68
	v_mov_b32_e32 v66, v56
	v_mov_b32_e32 v67, v58
	v_pk_mul_f32 v[62:63], v[66:67], v[62:63]
	v_and_b32_e32 v67, 0xffff0000, v69
	v_and_b32_e32 v66, 0xffff0000, v68
	v_mov_b32_e32 v58, v57
	v_pk_mul_f32 v[56:57], v[58:59], v[66:67]
	v_pk_mul_f32 v[72:73], v[74:75], v[72:73]
	v_cvt_pk_bf16_f32 v59, v73, v61
	v_cvt_pk_bf16_f32 v58, v72, v60
	v_cvt_pk_bf16_f32 v61, v63, v57
	v_cvt_pk_bf16_f32 v60, v62, v56
	v_lshl_add_u64 v[56:57], s[26:27], 0, v[70:71]
	v_lshl_add_u64 v[56:57], v[56:57], 0, v[138:139]
	global_store_dwordx4 v[56:57], v[58:61], off
	global_load_dwordx4 v[58:61], v[64:65], off offset:256
	v_mov_b32_e32 v65, v54
	v_mov_b32_e32 v54, v53
	v_mov_b32_e32 v64, v52
	s_waitcnt vmcnt(0)
	v_lshlrev_b32_e32 v63, 16, v59
	v_lshlrev_b32_e32 v62, 16, v58
	v_and_b32_e32 v59, 0xffff0000, v59
	v_and_b32_e32 v58, 0xffff0000, v58
	v_pk_mul_f32 v[52:53], v[54:55], v[58:59]
	v_lshlrev_b32_e32 v55, 16, v61
	v_lshlrev_b32_e32 v54, 16, v60
	v_mov_b32_e32 v58, v48
	v_mov_b32_e32 v59, v50
	v_pk_mul_f32 v[54:55], v[58:59], v[54:55]
	v_and_b32_e32 v59, 0xffff0000, v61
	v_and_b32_e32 v58, 0xffff0000, v60
	v_mov_b32_e32 v50, v49
	v_pk_mul_f32 v[48:49], v[50:51], v[58:59]
	v_pk_mul_f32 v[62:63], v[64:65], v[62:63]
	v_cvt_pk_bf16_f32 v51, v55, v49
	v_cvt_pk_bf16_f32 v50, v54, v48
	v_cvt_pk_bf16_f32 v49, v63, v53
	v_cvt_pk_bf16_f32 v48, v62, v52
	global_store_dwordx4 v[56:57], v[48:51], off offset:256
	v_mov_b32_e32 v59, v46
	v_mov_b32_e32 v46, v45
	v_add_u32_e32 v48, 0x90, v140
	v_ashrrev_i32_e32 v49, 31, v48
	v_lshlrev_b64 v[50:51], 13, v[48:49]
	v_lshlrev_b64 v[54:55], 12, v[48:49]
	v_lshl_add_u64 v[48:49], s[24:25], 0, v[50:51]
	v_lshl_add_u64 v[48:49], v[48:49], 0, v[138:139]
	global_load_dwordx4 v[50:53], v[48:49], off
	v_mov_b32_e32 v58, v44
	s_waitcnt vmcnt(0)
; #define PG8_BAR __builtin_amdgcn_s_barrier()
; __device__ __forceinline__ unsigned pk2(float lo, float hi) { return f2bf(lo) | (f2bf(hi) << 16); }
; template <class Epi, class Sched, bool ALIGN_EPI = false, bool SP2 = false, bool F8 = false>
; __device__ __forceinline__ void gemm_phase(PG8_LAS unsigned char* lds, const Gemm g, const Sched& S, const Epi& E) {
;     ...
;         if constexpr (ALIGN_EPI) { if (wr == 0) PG8_BAR; }
;         if constexpr (F8) asm volatile("s_nop 15\n\ts_nop 15" : "+v"(acc[1][1][0][0]), "+v"(acc[1][1][0][1]), "+v"(acc[1][1][1][0]), "+v"(acc[1][1][1][1]), "+v"(acc[1][1][2][0]), "+v"(acc[1][1][2][1]), "+v"(acc[1][1][3][0]), "+v"(acc[1][1][3][1]));
;         if constexpr (!Epi::AFTER_DRAIN) { E(acc, cur, wr, wc, fr, fq); S.done(cur); }
;         if (!has_next) break;
; #pragma unroll
;         for (int a = 0; a < 2; ++a)
; #pragma unroll
;             for (int b = 0; b < 2; ++b)
; #pragma unroll
;                 for (int m = 0; m < 4; ++m)
; #pragma unroll
;                     for (int n = 0; n < 2; ++n) acc[a][b][m][n] = (f32x4){0.f, 0.f, 0.f, 0.f};
;         cur = nxt; cA = nA; cB = nB; ++ui;
;         if constexpr (ALIGN_EPI) { if (wr == 1) PG8_BAR; }
;     __device__ __forceinline__ void operator()(const f32x4 (&acc)[2][2][4][2], const pg8::Unit& u, int wr, int wc, int fr, int fq) const {
;     ...
;                     } else if constexpr (MODE == 2 || MODE == 3) {
;                         const u32x4 g = *(const u32x4*)(aux + row * 4096 + (MODE == 3 ? 2048 : 0) + col);
;                         float r[8] = {v0[0], v0[1], v0[2], v0[3], v1[0], v1[1], v1[2], v1[3]};
;                         const unsigned gw[4] = {g.x, g.y, g.z, g.w};
; #pragma unroll
;                         for (int i = 0; i < 4; ++i) { r[2 * i] *= bf2f(gw[i] & 0xffffu); r[2 * i + 1] *= __builtin_bit_cast(float, gw[i] & 0xffff0000u); }
;                         if constexpr (MODE == 3) { const u32x4 pv = *(const u32x4*)(ob + row * 2048 + col); const unsigned pw[4] = {pv.x, pv.y, pv.z, pv.w};
; #pragma unroll
;                             for (int i = 0; i < 4; ++i) { r[2 * i] += bf2f(pw[i] & 0xffffu); r[2 * i + 1] += __builtin_bit_cast(float, pw[i] & 0xffff0000u); } }
;                         u32x4 w; w.x = pk2(r[0], r[1]); w.y = pk2(r[2], r[3]); w.z = pk2(r[4], r[5]); w.w = pk2(r[6], r[7]);
;                         *(u32x4*)(ob + row * 2048 + col) = w;
	v_lshlrev_b32_e32 v57, 16, v51
	v_lshlrev_b32_e32 v56, 16, v50
	v_and_b32_e32 v51, 0xffff0000, v51
	v_and_b32_e32 v50, 0xffff0000, v50
	v_pk_mul_f32 v[44:45], v[46:47], v[50:51]
	v_lshlrev_b32_e32 v47, 16, v53
	v_lshlrev_b32_e32 v46, 16, v52
	v_mov_b32_e32 v50, v40
	v_mov_b32_e32 v51, v42
	v_pk_mul_f32 v[46:47], v[50:51], v[46:47]
	v_and_b32_e32 v51, 0xffff0000, v53
	v_and_b32_e32 v50, 0xffff0000, v52
	v_mov_b32_e32 v42, v41
	v_pk_mul_f32 v[40:41], v[42:43], v[50:51]
	v_pk_mul_f32 v[56:57], v[58:59], v[56:57]
	v_cvt_pk_bf16_f32 v43, v57, v45
	v_cvt_pk_bf16_f32 v42, v56, v44
	v_cvt_pk_bf16_f32 v45, v47, v41
	v_cvt_pk_bf16_f32 v44, v46, v40
	v_lshl_add_u64 v[40:41], s[26:27], 0, v[54:55]
	v_lshl_add_u64 v[40:41], v[40:41], 0, v[138:139]
	global_store_dwordx4 v[40:41], v[42:45], off
	global_load_dwordx4 v[42:45], v[48:49], off offset:256
	v_mov_b32_e32 v49, v38
	v_mov_b32_e32 v38, v37
	v_mov_b32_e32 v48, v36
	s_waitcnt vmcnt(0)
	v_lshlrev_b32_e32 v47, 16, v43
	v_lshlrev_b32_e32 v46, 16, v42
	v_and_b32_e32 v43, 0xffff0000, v43
	v_and_b32_e32 v42, 0xffff0000, v42
	v_pk_mul_f32 v[36:37], v[38:39], v[42:43]
	v_lshlrev_b32_e32 v39, 16, v45
	v_lshlrev_b32_e32 v38, 16, v44
	v_mov_b32_e32 v42, v32
	v_mov_b32_e32 v43, v34
	v_pk_mul_f32 v[38:39], v[42:43], v[38:39]
	v_and_b32_e32 v43, 0xffff0000, v45
	v_and_b32_e32 v42, 0xffff0000, v44
	v_mov_b32_e32 v34, v33
	v_pk_mul_f32 v[32:33], v[34:35], v[42:43]
	v_pk_mul_f32 v[46:47], v[48:49], v[46:47]
	v_cvt_pk_bf16_f32 v35, v39, v33
	v_cvt_pk_bf16_f32 v34, v38, v32
	v_cvt_pk_bf16_f32 v33, v47, v37
	v_cvt_pk_bf16_f32 v32, v46, v36
	global_store_dwordx4 v[40:41], v[32:35], off offset:256
	v_mov_b32_e32 v43, v30
	v_mov_b32_e32 v30, v29
	v_add_u32_e32 v32, 0xa0, v140
	v_ashrrev_i32_e32 v33, 31, v32
	v_lshlrev_b64 v[34:35], 13, v[32:33]
	v_lshlrev_b64 v[38:39], 12, v[32:33]
	v_lshl_add_u64 v[32:33], s[24:25], 0, v[34:35]
	v_lshl_add_u64 v[32:33], v[32:33], 0, v[138:139]
	global_load_dwordx4 v[34:37], v[32:33], off
	v_mov_b32_e32 v42, v28
	s_waitcnt vmcnt(0)
	v_lshlrev_b32_e32 v41, 16, v35
	v_lshlrev_b32_e32 v40, 16, v34
	v_and_b32_e32 v35, 0xffff0000, v35
	v_and_b32_e32 v34, 0xffff0000, v34
	v_pk_mul_f32 v[28:29], v[30:31], v[34:35]
	v_lshlrev_b32_e32 v31, 16, v37
	v_lshlrev_b32_e32 v30, 16, v36
	v_mov_b32_e32 v34, v24
	v_mov_b32_e32 v35, v26
	v_pk_mul_f32 v[30:31], v[34:35], v[30:31]
	v_and_b32_e32 v35, 0xffff0000, v37
	v_and_b32_e32 v34, 0xffff0000, v36
	v_mov_b32_e32 v26, v25
	v_pk_mul_f32 v[24:25], v[26:27], v[34:35]
	v_pk_mul_f32 v[40:41], v[42:43], v[40:41]
	v_cvt_pk_bf16_f32 v27, v41, v29
	v_cvt_pk_bf16_f32 v26, v40, v28
	v_cvt_pk_bf16_f32 v29, v31, v25
	v_cvt_pk_bf16_f32 v28, v30, v24
	v_lshl_add_u64 v[24:25], s[26:27], 0, v[38:39]
	v_lshl_add_u64 v[24:25], v[24:25], 0, v[138:139]
	global_store_dwordx4 v[24:25], v[26:29], off
	global_load_dwordx4 v[26:29], v[32:33], off offset:256
	v_mov_b32_e32 v33, v22
	v_mov_b32_e32 v22, v21
	v_mov_b32_e32 v32, v20
	s_waitcnt vmcnt(0)
	v_lshlrev_b32_e32 v31, 16, v27
	v_lshlrev_b32_e32 v30, 16, v26
	v_and_b32_e32 v27, 0xffff0000, v27
	v_and_b32_e32 v26, 0xffff0000, v26
	v_pk_mul_f32 v[20:21], v[22:23], v[26:27]
	v_lshlrev_b32_e32 v23, 16, v29
	v_lshlrev_b32_e32 v22, 16, v28
	v_mov_b32_e32 v26, v16
	v_mov_b32_e32 v27, v18
	v_pk_mul_f32 v[22:23], v[26:27], v[22:23]
	v_and_b32_e32 v27, 0xffff0000, v29
	v_and_b32_e32 v26, 0xffff0000, v28
	v_mov_b32_e32 v18, v17
	v_pk_mul_f32 v[16:17], v[18:19], v[26:27]
	v_pk_mul_f32 v[30:31], v[32:33], v[30:31]
	v_cvt_pk_bf16_f32 v19, v23, v17
	v_cvt_pk_bf16_f32 v18, v22, v16
	v_cvt_pk_bf16_f32 v17, v31, v21
	v_cvt_pk_bf16_f32 v16, v30, v20
	global_store_dwordx4 v[24:25], v[16:19], off offset:256
	v_mov_b32_e32 v27, v14
	v_mov_b32_e32 v14, v13
	v_add_u32_e32 v16, 0xb0, v140
	v_ashrrev_i32_e32 v17, 31, v16
	v_lshlrev_b64 v[18:19], 13, v[16:17]
	v_lshlrev_b64 v[22:23], 12, v[16:17]
	v_lshl_add_u64 v[16:17], s[24:25], 0, v[18:19]
	v_lshl_add_u64 v[16:17], v[16:17], 0, v[138:139]
	global_load_dwordx4 v[18:21], v[16:17], off
	v_mov_b32_e32 v26, v12
	s_waitcnt vmcnt(0)
	v_lshlrev_b32_e32 v25, 16, v19
	v_lshlrev_b32_e32 v24, 16, v18
	v_and_b32_e32 v19, 0xffff0000, v19
	v_and_b32_e32 v18, 0xffff0000, v18
	v_pk_mul_f32 v[12:13], v[14:15], v[18:19]
	v_lshlrev_b32_e32 v15, 16, v21
	v_lshlrev_b32_e32 v14, 16, v20
	v_mov_b32_e32 v18, v8
	v_mov_b32_e32 v19, v10
	v_pk_mul_f32 v[14:15], v[18:19], v[14:15]
	v_and_b32_e32 v19, 0xffff0000, v21
	v_and_b32_e32 v18, 0xffff0000, v20
	v_mov_b32_e32 v10, v9
	v_pk_mul_f32 v[8:9], v[10:11], v[18:19]
	v_pk_mul_f32 v[24:25], v[26:27], v[24:25]
	v_cvt_pk_bf16_f32 v11, v25, v13
	v_cvt_pk_bf16_f32 v10, v24, v12
	v_cvt_pk_bf16_f32 v13, v15, v9
	v_cvt_pk_bf16_f32 v12, v14, v8
	v_lshl_add_u64 v[8:9], s[26:27], 0, v[22:23]
	v_lshl_add_u64 v[8:9], v[8:9], 0, v[138:139]
	global_store_dwordx4 v[8:9], v[10:13], off
	global_load_dwordx4 v[10:13], v[16:17], off offset:256
	v_mov_b32_e32 v17, v6
	v_mov_b32_e32 v6, v5
	v_mov_b32_e32 v16, v4
	s_waitcnt vmcnt(0)
	v_lshlrev_b32_e32 v15, 16, v11
	v_lshlrev_b32_e32 v14, 16, v10
	v_and_b32_e32 v11, 0xffff0000, v11
	v_and_b32_e32 v10, 0xffff0000, v10
	v_pk_mul_f32 v[4:5], v[6:7], v[10:11]
	v_lshlrev_b32_e32 v7, 16, v13
	v_lshlrev_b32_e32 v6, 16, v12
	v_mov_b32_e32 v10, v0
	v_mov_b32_e32 v11, v2
	v_pk_mul_f32 v[6:7], v[10:11], v[6:7]
	v_and_b32_e32 v11, 0xffff0000, v13
	v_and_b32_e32 v10, 0xffff0000, v12
	v_mov_b32_e32 v2, v1
	v_pk_mul_f32 v[0:1], v[2:3], v[10:11]
	v_pk_mul_f32 v[14:15], v[16:17], v[14:15]
	v_cvt_pk_bf16_f32 v3, v7, v1
	v_cvt_pk_bf16_f32 v2, v6, v0
	v_cvt_pk_bf16_f32 v1, v15, v5
	v_cvt_pk_bf16_f32 v0, v14, v4
	global_store_dwordx4 v[8:9], v[0:3], off offset:256
	s_cbranch_vccnz .LBB0_89
	s_andn2_b64 vcc, exec, s[0:1]
	s_cbranch_vccnz .LBB0_88
	s_barrier
	s_branch .LBB0_88

; __device__ __forceinline__ unsigned pk2(float lo, float hi) { return f2bf(lo) | (f2bf(hi) << 16); }
;     __device__ __forceinline__ void operator()(const f32x4 (&acc)[2][2][4][2], const pg8::Unit& u, int wr, int wc, int fr, int fq) const {
;     ...
;                     } else if constexpr (MODE == 2 || MODE == 3) {
;                         const u32x4 g = *(const u32x4*)(aux + row * 4096 + (MODE == 3 ? 2048 : 0) + col);
;                         float r[8] = {v0[0], v0[1], v0[2], v0[3], v1[0], v1[1], v1[2], v1[3]};
;                         const unsigned gw[4] = {g.x, g.y, g.z, g.w};
; #pragma unroll
;                         for (int i = 0; i < 4; ++i) { r[2 * i] *= bf2f(gw[i] & 0xffffu); r[2 * i + 1] *= __builtin_bit_cast(float, gw[i] & 0xffff0000u); }
;                         if constexpr (MODE == 3) { const u32x4 pv = *(const u32x4*)(ob + row * 2048 + col); const unsigned pw[4] = {pv.x, pv.y, pv.z, pv.w};
; #pragma unroll
;                             for (int i = 0; i < 4; ++i) { r[2 * i] += bf2f(pw[i] & 0xffffu); r[2 * i + 1] += __builtin_bit_cast(float, pw[i] & 0xffff0000u); } }
;                         u32x4 w; w.x = pk2(r[0], r[1]); w.y = pk2(r[2], r[3]); w.z = pk2(r[4], r[5]); w.w = pk2(r[6], r[7]);
;                         *(u32x4*)(ob + row * 2048 + col) = w;
.LBB0_120:
	v_lshl_add_u32 v140, s9, 8, v144
	v_ashrrev_i32_e32 v141, 31, v140
	v_lshl_or_b32 v156, s8, 8, v146
	v_lshlrev_b64 v[138:139], 13, v[140:141]
	v_lshlrev_b64 v[142:143], 12, v[140:141]
	v_lshl_add_u64 v[138:139], s[24:25], 0, v[138:139]
	s_mov_b64 s[8:9], 0x1000
	v_ashrrev_i32_e32 v157, 31, v156
	v_lshl_add_u64 v[158:159], v[138:139], 0, s[8:9]
	v_lshlrev_b64 v[138:139], 1, v[156:157]
	v_lshl_add_u64 v[142:143], s[26:27], 0, v[142:143]
	v_lshl_add_u64 v[148:149], v[158:159], 0, v[138:139]
	v_lshl_add_u64 v[142:143], v[142:143], 0, v[138:139]
	global_load_dwordx4 v[148:151], v[148:149], off
	v_mov_b32_e32 v184, v124
	global_load_dwordx4 v[152:155], v[142:143], off
	v_mov_b32_e32 v185, v126
	v_mov_b32_e32 v126, v125
	s_mov_b64 s[10:11], -1
	s_andn2_b64 vcc, exec, s[38:39]
	s_waitcnt vmcnt(0)
	v_lshlrev_b32_e32 v163, 16, v149
	v_lshlrev_b32_e32 v162, 16, v148
	v_and_b32_e32 v149, 0xffff0000, v149
	v_and_b32_e32 v148, 0xffff0000, v148
	v_lshlrev_b32_e32 v125, 16, v153
	v_lshlrev_b32_e32 v124, 16, v152
	v_and_b32_e32 v153, 0xffff0000, v153
	v_and_b32_e32 v152, 0xffff0000, v152
	v_pk_fma_f32 v[126:127], v[126:127], v[148:149], v[152:153]
	v_lshlrev_b32_e32 v149, 16, v151
	v_lshlrev_b32_e32 v148, 16, v150
	v_mov_b32_e32 v152, v120
	v_mov_b32_e32 v153, v122
	v_mov_b32_e32 v122, v121
	v_lshlrev_b32_e32 v121, 16, v155
	v_lshlrev_b32_e32 v120, 16, v154
	v_and_b32_e32 v151, 0xffff0000, v151
	v_and_b32_e32 v150, 0xffff0000, v150
	v_pk_fma_f32 v[120:121], v[152:153], v[148:149], v[120:121]
	v_and_b32_e32 v149, 0xffff0000, v155
	v_and_b32_e32 v148, 0xffff0000, v154
	v_pk_fma_f32 v[122:123], v[122:123], v[150:151], v[148:149]
	v_pk_fma_f32 v[124:125], v[184:185], v[162:163], v[124:125]
	v_cvt_pk_bf16_f32 v123, v121, v123
	v_cvt_pk_bf16_f32 v122, v120, v122
	v_cvt_pk_bf16_f32 v121, v125, v127
	v_cvt_pk_bf16_f32 v120, v124, v126
	global_store_dwordx4 v[142:143], v[120:123], off
	v_mov_b32_e32 v152, v116
	v_mov_b32_e32 v153, v118
	v_or_b32_e32 v120, 0x80, v156
	v_ashrrev_i32_e32 v121, 31, v120
	v_lshlrev_b64 v[124:125], 1, v[120:121]
	v_lshl_add_u64 v[120:121], v[158:159], 0, v[124:125]
	global_load_dwordx4 v[120:123], v[120:121], off
	s_nop 0
	global_load_dwordx4 v[148:151], v[142:143], off offset:256
	v_mov_b32_e32 v118, v117
	s_waitcnt vmcnt(1)
	v_lshlrev_b32_e32 v127, 16, v121
	v_lshlrev_b32_e32 v126, 16, v120
	s_waitcnt vmcnt(0)
	v_lshlrev_b32_e32 v117, 16, v149
	v_lshlrev_b32_e32 v116, 16, v148
	v_and_b32_e32 v121, 0xffff0000, v121
	v_and_b32_e32 v120, 0xffff0000, v120
	v_pk_fma_f32 v[116:117], v[152:153], v[126:127], v[116:117]
	v_and_b32_e32 v127, 0xffff0000, v149
	v_and_b32_e32 v126, 0xffff0000, v148
	v_pk_fma_f32 v[118:119], v[118:119], v[120:121], v[126:127]
	v_lshlrev_b32_e32 v121, 16, v123
	v_lshlrev_b32_e32 v120, 16, v122
	v_mov_b32_e32 v126, v112
	v_mov_b32_e32 v127, v114
	v_mov_b32_e32 v114, v113
	v_lshlrev_b32_e32 v113, 16, v151
	v_lshlrev_b32_e32 v112, 16, v150
	v_and_b32_e32 v123, 0xffff0000, v123
	v_and_b32_e32 v122, 0xffff0000, v122
	v_pk_fma_f32 v[112:113], v[126:127], v[120:121], v[112:113]
	v_and_b32_e32 v121, 0xffff0000, v151
	v_and_b32_e32 v120, 0xffff0000, v150
	v_pk_fma_f32 v[114:115], v[114:115], v[122:123], v[120:121]
	v_cvt_pk_bf16_f32 v115, v113, v115
	v_cvt_pk_bf16_f32 v114, v112, v114
	v_cvt_pk_bf16_f32 v113, v117, v119
	v_cvt_pk_bf16_f32 v112, v116, v118
	global_store_dwordx4 v[142:143], v[112:115], off offset:256
	v_mov_b32_e32 v142, v108
	v_mov_b32_e32 v143, v110
	v_or_b32_e32 v112, 16, v140
	v_ashrrev_i32_e32 v113, 31, v112
	v_lshlrev_b64 v[114:115], 13, v[112:113]
	v_lshlrev_b64 v[112:113], 12, v[112:113]
	v_lshl_add_u64 v[114:115], s[24:25], 0, v[114:115]
	v_lshl_add_u64 v[114:115], v[114:115], 0, s[8:9]
	v_lshl_add_u64 v[112:113], s[26:27], 0, v[112:113]
	v_lshl_add_u64 v[116:117], v[114:115], 0, v[138:139]
	v_lshl_add_u64 v[112:113], v[112:113], 0, v[138:139]
	global_load_dwordx4 v[116:119], v[116:117], off
	v_mov_b32_e32 v110, v109
	global_load_dwordx4 v[120:123], v[112:113], off
	s_waitcnt vmcnt(1)
	v_lshlrev_b32_e32 v127, 16, v117
	v_lshlrev_b32_e32 v126, 16, v116
	v_and_b32_e32 v117, 0xffff0000, v117
	v_and_b32_e32 v116, 0xffff0000, v116
	s_waitcnt vmcnt(0)
	v_lshlrev_b32_e32 v109, 16, v121
	v_lshlrev_b32_e32 v108, 16, v120
	v_and_b32_e32 v121, 0xffff0000, v121
	v_and_b32_e32 v120, 0xffff0000, v120
	v_pk_fma_f32 v[110:111], v[110:111], v[116:117], v[120:121]
	v_lshlrev_b32_e32 v117, 16, v119
	v_lshlrev_b32_e32 v116, 16, v118
	v_mov_b32_e32 v120, v104
	v_mov_b32_e32 v121, v106
	v_mov_b32_e32 v106, v105
	v_lshlrev_b32_e32 v105, 16, v123
	v_lshlrev_b32_e32 v104, 16, v122
	v_and_b32_e32 v119, 0xffff0000, v119
	v_and_b32_e32 v118, 0xffff0000, v118
	v_pk_fma_f32 v[104:105], v[120:121], v[116:117], v[104:105]
	v_and_b32_e32 v117, 0xffff0000, v123
	v_and_b32_e32 v116, 0xffff0000, v122
	v_pk_fma_f32 v[106:107], v[106:107], v[118:119], v[116:117]
	v_pk_fma_f32 v[108:109], v[142:143], v[126:127], v[108:109]
	v_cvt_pk_bf16_f32 v107, v105, v107
	v_cvt_pk_bf16_f32 v106, v104, v106
	v_cvt_pk_bf16_f32 v105, v109, v111
	v_cvt_pk_bf16_f32 v104, v108, v110
	global_store_dwordx4 v[112:113], v[104:107], off
	v_mov_b32_e32 v116, v100
	v_mov_b32_e32 v117, v102
	v_lshl_add_u64 v[104:105], v[114:115], 0, v[124:125]
	global_load_dwordx4 v[104:107], v[104:105], off
	s_nop 0
	global_load_dwordx4 v[108:111], v[112:113], off offset:256
	v_mov_b32_e32 v102, v101
	s_waitcnt vmcnt(1)
	v_lshlrev_b32_e32 v115, 16, v105
	v_lshlrev_b32_e32 v114, 16, v104
	v_and_b32_e32 v105, 0xffff0000, v105
	v_and_b32_e32 v104, 0xffff0000, v104
	s_waitcnt vmcnt(0)
; __device__ __forceinline__ unsigned pk2(float lo, float hi) { return f2bf(lo) | (f2bf(hi) << 16); }
;     __device__ __forceinline__ void operator()(const f32x4 (&acc)[2][2][4][2], const pg8::Unit& u, int wr, int wc, int fr, int fq) const {
;     ...
;                     } else if constexpr (MODE == 2 || MODE == 3) {
;                         const u32x4 g = *(const u32x4*)(aux + row * 4096 + (MODE == 3 ? 2048 : 0) + col);
;                         float r[8] = {v0[0], v0[1], v0[2], v0[3], v1[0], v1[1], v1[2], v1[3]};
;                         const unsigned gw[4] = {g.x, g.y, g.z, g.w};
; #pragma unroll
;                         for (int i = 0; i < 4; ++i) { r[2 * i] *= bf2f(gw[i] & 0xffffu); r[2 * i + 1] *= __builtin_bit_cast(float, gw[i] & 0xffff0000u); }
;                         if constexpr (MODE == 3) { const u32x4 pv = *(const u32x4*)(ob + row * 2048 + col); const unsigned pw[4] = {pv.x, pv.y, pv.z, pv.w};
; #pragma unroll
;                             for (int i = 0; i < 4; ++i) { r[2 * i] += bf2f(pw[i] & 0xffffu); r[2 * i + 1] += __builtin_bit_cast(float, pw[i] & 0xffff0000u); } }
;                         u32x4 w; w.x = pk2(r[0], r[1]); w.y = pk2(r[2], r[3]); w.z = pk2(r[4], r[5]); w.w = pk2(r[6], r[7]);
;                         *(u32x4*)(ob + row * 2048 + col) = w;
	v_lshlrev_b32_e32 v101, 16, v109
	v_lshlrev_b32_e32 v100, 16, v108
	v_and_b32_e32 v109, 0xffff0000, v109
	v_and_b32_e32 v108, 0xffff0000, v108
	v_pk_fma_f32 v[102:103], v[102:103], v[104:105], v[108:109]
	v_lshlrev_b32_e32 v105, 16, v107
	v_lshlrev_b32_e32 v104, 16, v106
	v_mov_b32_e32 v108, v96
	v_mov_b32_e32 v109, v98
	v_mov_b32_e32 v98, v97
	v_lshlrev_b32_e32 v97, 16, v111
	v_lshlrev_b32_e32 v96, 16, v110
	v_and_b32_e32 v107, 0xffff0000, v107
	v_and_b32_e32 v106, 0xffff0000, v106
	v_pk_fma_f32 v[96:97], v[108:109], v[104:105], v[96:97]
	v_and_b32_e32 v105, 0xffff0000, v111
	v_and_b32_e32 v104, 0xffff0000, v110
	v_pk_fma_f32 v[98:99], v[98:99], v[106:107], v[104:105]
	v_pk_fma_f32 v[100:101], v[116:117], v[114:115], v[100:101]
	v_cvt_pk_bf16_f32 v99, v97, v99
	v_cvt_pk_bf16_f32 v98, v96, v98
	v_cvt_pk_bf16_f32 v97, v101, v103
	v_cvt_pk_bf16_f32 v96, v100, v102
	global_store_dwordx4 v[112:113], v[96:99], off offset:256
	v_mov_b32_e32 v110, v92
	v_mov_b32_e32 v111, v94
	v_or_b32_e32 v96, 32, v140
	v_ashrrev_i32_e32 v97, 31, v96
	v_lshlrev_b64 v[98:99], 13, v[96:97]
	v_lshlrev_b64 v[96:97], 12, v[96:97]
	v_lshl_add_u64 v[98:99], s[24:25], 0, v[98:99]
	v_lshl_add_u64 v[98:99], v[98:99], 0, s[8:9]
	v_lshl_add_u64 v[96:97], s[26:27], 0, v[96:97]
	v_lshl_add_u64 v[100:101], v[98:99], 0, v[138:139]
	v_lshl_add_u64 v[96:97], v[96:97], 0, v[138:139]
	global_load_dwordx4 v[100:103], v[100:101], off
	v_mov_b32_e32 v94, v93
	global_load_dwordx4 v[104:107], v[96:97], off
	s_waitcnt vmcnt(1)
	v_lshlrev_b32_e32 v109, 16, v101
	v_lshlrev_b32_e32 v108, 16, v100
	v_and_b32_e32 v101, 0xffff0000, v101
	v_and_b32_e32 v100, 0xffff0000, v100
	s_waitcnt vmcnt(0)
	v_lshlrev_b32_e32 v93, 16, v105
	v_lshlrev_b32_e32 v92, 16, v104
	v_and_b32_e32 v105, 0xffff0000, v105
	v_and_b32_e32 v104, 0xffff0000, v104
	v_pk_fma_f32 v[94:95], v[94:95], v[100:101], v[104:105]
	v_lshlrev_b32_e32 v101, 16, v103
	v_lshlrev_b32_e32 v100, 16, v102
	v_mov_b32_e32 v104, v88
	v_mov_b32_e32 v105, v90
	v_mov_b32_e32 v90, v89
	v_lshlrev_b32_e32 v89, 16, v107
	v_lshlrev_b32_e32 v88, 16, v106
	v_and_b32_e32 v103, 0xffff0000, v103
	v_and_b32_e32 v102, 0xffff0000, v102
	v_pk_fma_f32 v[88:89], v[104:105], v[100:101], v[88:89]
	v_and_b32_e32 v101, 0xffff0000, v107
	v_and_b32_e32 v100, 0xffff0000, v106
	v_pk_fma_f32 v[90:91], v[90:91], v[102:103], v[100:101]
	v_pk_fma_f32 v[92:93], v[110:111], v[108:109], v[92:93]
	v_cvt_pk_bf16_f32 v91, v89, v91
	v_cvt_pk_bf16_f32 v90, v88, v90
	v_cvt_pk_bf16_f32 v89, v93, v95
	v_cvt_pk_bf16_f32 v88, v92, v94
	global_store_dwordx4 v[96:97], v[88:91], off
	v_mov_b32_e32 v100, v84
	v_mov_b32_e32 v101, v86
	v_lshl_add_u64 v[88:89], v[98:99], 0, v[124:125]
	global_load_dwordx4 v[88:91], v[88:89], off
	s_nop 0
	global_load_dwordx4 v[92:95], v[96:97], off offset:256
	v_mov_b32_e32 v86, v85
	s_waitcnt vmcnt(1)
	v_lshlrev_b32_e32 v99, 16, v89
	v_lshlrev_b32_e32 v98, 16, v88
	v_and_b32_e32 v89, 0xffff0000, v89
	v_and_b32_e32 v88, 0xffff0000, v88
	s_waitcnt vmcnt(0)
	v_lshlrev_b32_e32 v85, 16, v93
	v_lshlrev_b32_e32 v84, 16, v92
	v_and_b32_e32 v93, 0xffff0000, v93
	v_and_b32_e32 v92, 0xffff0000, v92
	v_pk_fma_f32 v[86:87], v[86:87], v[88:89], v[92:93]
	v_lshlrev_b32_e32 v89, 16, v91
	v_lshlrev_b32_e32 v88, 16, v90
	v_mov_b32_e32 v92, v80
	v_mov_b32_e32 v93, v82
	v_mov_b32_e32 v82, v81
	v_lshlrev_b32_e32 v81, 16, v95
	v_lshlrev_b32_e32 v80, 16, v94
	v_and_b32_e32 v91, 0xffff0000, v91
	v_and_b32_e32 v90, 0xffff0000, v90
	v_pk_fma_f32 v[80:81], v[92:93], v[88:89], v[80:81]
	v_and_b32_e32 v89, 0xffff0000, v95
	v_and_b32_e32 v88, 0xffff0000, v94
	v_pk_fma_f32 v[82:83], v[82:83], v[90:91], v[88:89]
	v_pk_fma_f32 v[84:85], v[100:101], v[98:99], v[84:85]
	v_cvt_pk_bf16_f32 v83, v81, v83
	v_cvt_pk_bf16_f32 v82, v80, v82
	v_cvt_pk_bf16_f32 v81, v85, v87
	v_cvt_pk_bf16_f32 v80, v84, v86
	global_store_dwordx4 v[96:97], v[80:83], off offset:256
	v_mov_b32_e32 v94, v76
	v_mov_b32_e32 v95, v78
	v_or_b32_e32 v80, 48, v140
	v_ashrrev_i32_e32 v81, 31, v80
	v_lshlrev_b64 v[82:83], 13, v[80:81]
	v_lshlrev_b64 v[80:81], 12, v[80:81]
	v_lshl_add_u64 v[82:83], s[24:25], 0, v[82:83]
	v_lshl_add_u64 v[82:83], v[82:83], 0, s[8:9]
	v_lshl_add_u64 v[80:81], s[26:27], 0, v[80:81]
	v_lshl_add_u64 v[84:85], v[82:83], 0, v[138:139]
	v_lshl_add_u64 v[80:81], v[80:81], 0, v[138:139]
	global_load_dwordx4 v[84:87], v[84:85], off
	v_mov_b32_e32 v78, v77
	global_load_dwordx4 v[88:91], v[80:81], off
	s_waitcnt vmcnt(1)
	v_lshlrev_b32_e32 v93, 16, v85
	v_lshlrev_b32_e32 v92, 16, v84
	v_and_b32_e32 v85, 0xffff0000, v85
	v_and_b32_e32 v84, 0xffff0000, v84
	s_waitcnt vmcnt(0)
	v_lshlrev_b32_e32 v77, 16, v89
	v_lshlrev_b32_e32 v76, 16, v88
	v_and_b32_e32 v89, 0xffff0000, v89
	v_and_b32_e32 v88, 0xffff0000, v88
	v_pk_fma_f32 v[78:79], v[78:79], v[84:85], v[88:89]
	v_lshlrev_b32_e32 v85, 16, v87
	v_lshlrev_b32_e32 v84, 16, v86
	v_mov_b32_e32 v88, v72
	v_mov_b32_e32 v89, v74
	v_mov_b32_e32 v74, v73
	v_lshlrev_b32_e32 v73, 16, v91
	v_lshlrev_b32_e32 v72, 16, v90
	v_and_b32_e32 v87, 0xffff0000, v87
	v_and_b32_e32 v86, 0xffff0000, v86
	v_pk_fma_f32 v[72:73], v[88:89], v[84:85], v[72:73]
	v_and_b32_e32 v85, 0xffff0000, v91
	v_and_b32_e32 v84, 0xffff0000, v90
	v_pk_fma_f32 v[74:75], v[74:75], v[86:87], v[84:85]
	v_pk_fma_f32 v[76:77], v[94:95], v[92:93], v[76:77]
	v_cvt_pk_bf16_f32 v75, v73, v75
	v_cvt_pk_bf16_f32 v74, v72, v74
	v_cvt_pk_bf16_f32 v73, v77, v79
	v_cvt_pk_bf16_f32 v72, v76, v78
	global_store_dwordx4 v[80:81], v[72:75], off
	v_mov_b32_e32 v84, v68
	v_mov_b32_e32 v85, v70
	v_lshl_add_u64 v[72:73], v[82:83], 0, v[124:125]
	global_load_dwordx4 v[72:75], v[72:73], off
	s_nop 0
	global_load_dwordx4 v[76:79], v[80:81], off offset:256
	v_mov_b32_e32 v70, v69
	s_waitcnt vmcnt(1)
; __device__ __forceinline__ unsigned pk2(float lo, float hi) { return f2bf(lo) | (f2bf(hi) << 16); }
;     __device__ __forceinline__ void operator()(const f32x4 (&acc)[2][2][4][2], const pg8::Unit& u, int wr, int wc, int fr, int fq) const {
;     ...
;                     } else if constexpr (MODE == 2 || MODE == 3) {
;                         const u32x4 g = *(const u32x4*)(aux + row * 4096 + (MODE == 3 ? 2048 : 0) + col);
;                         float r[8] = {v0[0], v0[1], v0[2], v0[3], v1[0], v1[1], v1[2], v1[3]};
;                         const unsigned gw[4] = {g.x, g.y, g.z, g.w};
; #pragma unroll
;                         for (int i = 0; i < 4; ++i) { r[2 * i] *= bf2f(gw[i] & 0xffffu); r[2 * i + 1] *= __builtin_bit_cast(float, gw[i] & 0xffff0000u); }
;                         if constexpr (MODE == 3) { const u32x4 pv = *(const u32x4*)(ob + row * 2048 + col); const unsigned pw[4] = {pv.x, pv.y, pv.z, pv.w};
; #pragma unroll
;                             for (int i = 0; i < 4; ++i) { r[2 * i] += bf2f(pw[i] & 0xffffu); r[2 * i + 1] += __builtin_bit_cast(float, pw[i] & 0xffff0000u); } }
;                         u32x4 w; w.x = pk2(r[0], r[1]); w.y = pk2(r[2], r[3]); w.z = pk2(r[4], r[5]); w.w = pk2(r[6], r[7]);
;                         *(u32x4*)(ob + row * 2048 + col) = w;
	v_lshlrev_b32_e32 v83, 16, v73
	v_lshlrev_b32_e32 v82, 16, v72
	v_and_b32_e32 v73, 0xffff0000, v73
	v_and_b32_e32 v72, 0xffff0000, v72
	s_waitcnt vmcnt(0)
	v_lshlrev_b32_e32 v69, 16, v77
	v_lshlrev_b32_e32 v68, 16, v76
	v_and_b32_e32 v77, 0xffff0000, v77
	v_and_b32_e32 v76, 0xffff0000, v76
	v_pk_fma_f32 v[70:71], v[70:71], v[72:73], v[76:77]
	v_lshlrev_b32_e32 v73, 16, v75
	v_lshlrev_b32_e32 v72, 16, v74
	v_mov_b32_e32 v76, v64
	v_mov_b32_e32 v77, v66
	v_mov_b32_e32 v66, v65
	v_lshlrev_b32_e32 v65, 16, v79
	v_lshlrev_b32_e32 v64, 16, v78
	v_and_b32_e32 v75, 0xffff0000, v75
	v_and_b32_e32 v74, 0xffff0000, v74
	v_pk_fma_f32 v[64:65], v[76:77], v[72:73], v[64:65]
	v_and_b32_e32 v73, 0xffff0000, v79
	v_and_b32_e32 v72, 0xffff0000, v78
	v_pk_fma_f32 v[66:67], v[66:67], v[74:75], v[72:73]
	v_pk_fma_f32 v[68:69], v[84:85], v[82:83], v[68:69]
	v_cvt_pk_bf16_f32 v67, v65, v67
	v_cvt_pk_bf16_f32 v66, v64, v66
	v_cvt_pk_bf16_f32 v65, v69, v71
	v_cvt_pk_bf16_f32 v64, v68, v70
	global_store_dwordx4 v[80:81], v[64:67], off offset:256
	v_mov_b32_e32 v78, v60
	v_mov_b32_e32 v79, v62
	v_add_u32_e32 v64, 0x80, v140
	v_ashrrev_i32_e32 v65, 31, v64
	v_lshlrev_b64 v[66:67], 13, v[64:65]
	v_lshlrev_b64 v[64:65], 12, v[64:65]
	v_lshl_add_u64 v[66:67], s[24:25], 0, v[66:67]
	v_lshl_add_u64 v[66:67], v[66:67], 0, s[8:9]
	v_lshl_add_u64 v[64:65], s[26:27], 0, v[64:65]
	v_lshl_add_u64 v[68:69], v[66:67], 0, v[138:139]
	v_lshl_add_u64 v[64:65], v[64:65], 0, v[138:139]
	global_load_dwordx4 v[68:71], v[68:69], off
	v_mov_b32_e32 v62, v61
	global_load_dwordx4 v[72:75], v[64:65], off
	s_waitcnt vmcnt(1)
	v_lshlrev_b32_e32 v77, 16, v69
	v_lshlrev_b32_e32 v76, 16, v68
	v_and_b32_e32 v69, 0xffff0000, v69
	v_and_b32_e32 v68, 0xffff0000, v68
	s_waitcnt vmcnt(0)
	v_lshlrev_b32_e32 v61, 16, v73
	v_lshlrev_b32_e32 v60, 16, v72
	v_and_b32_e32 v73, 0xffff0000, v73
	v_and_b32_e32 v72, 0xffff0000, v72
	v_pk_fma_f32 v[62:63], v[62:63], v[68:69], v[72:73]
	v_lshlrev_b32_e32 v69, 16, v71
	v_lshlrev_b32_e32 v68, 16, v70
	v_mov_b32_e32 v72, v56
	v_mov_b32_e32 v73, v58
	v_mov_b32_e32 v58, v57
	v_lshlrev_b32_e32 v57, 16, v75
	v_lshlrev_b32_e32 v56, 16, v74
	v_and_b32_e32 v71, 0xffff0000, v71
	v_and_b32_e32 v70, 0xffff0000, v70
	v_pk_fma_f32 v[56:57], v[72:73], v[68:69], v[56:57]
	v_and_b32_e32 v69, 0xffff0000, v75
	v_and_b32_e32 v68, 0xffff0000, v74
	v_pk_fma_f32 v[58:59], v[58:59], v[70:71], v[68:69]
	v_pk_fma_f32 v[60:61], v[78:79], v[76:77], v[60:61]
	v_cvt_pk_bf16_f32 v59, v57, v59
	v_cvt_pk_bf16_f32 v58, v56, v58
	v_cvt_pk_bf16_f32 v57, v61, v63
	v_cvt_pk_bf16_f32 v56, v60, v62
	global_store_dwordx4 v[64:65], v[56:59], off
	v_mov_b32_e32 v68, v52
	v_mov_b32_e32 v69, v54
	v_lshl_add_u64 v[56:57], v[66:67], 0, v[124:125]
	global_load_dwordx4 v[56:59], v[56:57], off
	s_nop 0
	global_load_dwordx4 v[60:63], v[64:65], off offset:256
	v_mov_b32_e32 v54, v53
	s_waitcnt vmcnt(1)
	v_lshlrev_b32_e32 v67, 16, v57
	v_lshlrev_b32_e32 v66, 16, v56
	v_and_b32_e32 v57, 0xffff0000, v57
	v_and_b32_e32 v56, 0xffff0000, v56
	s_waitcnt vmcnt(0)
	v_lshlrev_b32_e32 v53, 16, v61
	v_lshlrev_b32_e32 v52, 16, v60
	v_and_b32_e32 v61, 0xffff0000, v61
	v_and_b32_e32 v60, 0xffff0000, v60
	v_pk_fma_f32 v[54:55], v[54:55], v[56:57], v[60:61]
	v_lshlrev_b32_e32 v57, 16, v59
	v_lshlrev_b32_e32 v56, 16, v58
	v_mov_b32_e32 v60, v48
	v_mov_b32_e32 v61, v50
	v_mov_b32_e32 v50, v49
	v_lshlrev_b32_e32 v49, 16, v63
	v_lshlrev_b32_e32 v48, 16, v62
	v_and_b32_e32 v59, 0xffff0000, v59
	v_and_b32_e32 v58, 0xffff0000, v58
	v_pk_fma_f32 v[48:49], v[60:61], v[56:57], v[48:49]
	v_and_b32_e32 v57, 0xffff0000, v63
	v_and_b32_e32 v56, 0xffff0000, v62
	v_pk_fma_f32 v[50:51], v[50:51], v[58:59], v[56:57]
	v_pk_fma_f32 v[52:53], v[68:69], v[66:67], v[52:53]
	v_cvt_pk_bf16_f32 v51, v49, v51
	v_cvt_pk_bf16_f32 v50, v48, v50
	v_cvt_pk_bf16_f32 v49, v53, v55
	v_cvt_pk_bf16_f32 v48, v52, v54
	global_store_dwordx4 v[64:65], v[48:51], off offset:256
	v_mov_b32_e32 v62, v44
	v_mov_b32_e32 v63, v46
	v_add_u32_e32 v48, 0x90, v140
	v_ashrrev_i32_e32 v49, 31, v48
	v_lshlrev_b64 v[50:51], 13, v[48:49]
	v_lshlrev_b64 v[48:49], 12, v[48:49]
	v_lshl_add_u64 v[50:51], s[24:25], 0, v[50:51]
	v_lshl_add_u64 v[50:51], v[50:51], 0, s[8:9]
	v_lshl_add_u64 v[48:49], s[26:27], 0, v[48:49]
	v_lshl_add_u64 v[52:53], v[50:51], 0, v[138:139]
	v_lshl_add_u64 v[48:49], v[48:49], 0, v[138:139]
	global_load_dwordx4 v[52:55], v[52:53], off
	v_mov_b32_e32 v46, v45
	global_load_dwordx4 v[56:59], v[48:49], off
	s_waitcnt vmcnt(1)
	v_lshlrev_b32_e32 v61, 16, v53
	v_lshlrev_b32_e32 v60, 16, v52
	v_and_b32_e32 v53, 0xffff0000, v53
	v_and_b32_e32 v52, 0xffff0000, v52
	s_waitcnt vmcnt(0)
	v_lshlrev_b32_e32 v45, 16, v57
	v_lshlrev_b32_e32 v44, 16, v56
	v_and_b32_e32 v57, 0xffff0000, v57
	v_and_b32_e32 v56, 0xffff0000, v56
	v_pk_fma_f32 v[46:47], v[46:47], v[52:53], v[56:57]
	v_lshlrev_b32_e32 v53, 16, v55
	v_lshlrev_b32_e32 v52, 16, v54
	v_mov_b32_e32 v56, v40
	v_mov_b32_e32 v57, v42
	v_mov_b32_e32 v42, v41
	v_lshlrev_b32_e32 v41, 16, v59
	v_lshlrev_b32_e32 v40, 16, v58
	v_and_b32_e32 v55, 0xffff0000, v55
	v_and_b32_e32 v54, 0xffff0000, v54
	v_pk_fma_f32 v[40:41], v[56:57], v[52:53], v[40:41]
	v_and_b32_e32 v53, 0xffff0000, v59
	v_and_b32_e32 v52, 0xffff0000, v58
	v_pk_fma_f32 v[42:43], v[42:43], v[54:55], v[52:53]
	v_pk_fma_f32 v[44:45], v[62:63], v[60:61], v[44:45]
	v_cvt_pk_bf16_f32 v43, v41, v43
	v_cvt_pk_bf16_f32 v42, v40, v42
	v_cvt_pk_bf16_f32 v41, v45, v47
	v_cvt_pk_bf16_f32 v40, v44, v46
	global_store_dwordx4 v[48:49], v[40:43], off
	v_mov_b32_e32 v52, v36
	v_mov_b32_e32 v53, v38
	v_lshl_add_u64 v[40:41], v[50:51], 0, v[124:125]
	global_load_dwordx4 v[40:43], v[40:41], off
	s_nop 0
	global_load_dwordx4 v[44:47], v[48:49], off offset:256
	v_mov_b32_e32 v38, v37
	s_waitcnt vmcnt(1)
; #define PG8_BAR __builtin_amdgcn_s_barrier()
; __device__ __forceinline__ unsigned pk2(float lo, float hi) { return f2bf(lo) | (f2bf(hi) << 16); }
; template <class Epi, class Sched, bool ALIGN_EPI = false, bool SP2 = false, bool F8 = false>
; __device__ __forceinline__ void gemm_phase(PG8_LAS unsigned char* lds, const Gemm g, const Sched& S, const Epi& E) {
;     ...
;         if constexpr (ALIGN_EPI) { if (wr == 0) PG8_BAR; }
;         if constexpr (F8) asm volatile("s_nop 15\n\ts_nop 15" : "+v"(acc[1][1][0][0]), "+v"(acc[1][1][0][1]), "+v"(acc[1][1][1][0]), "+v"(acc[1][1][1][1]), "+v"(acc[1][1][2][0]), "+v"(acc[1][1][2][1]), "+v"(acc[1][1][3][0]), "+v"(acc[1][1][3][1]));
;         if constexpr (!Epi::AFTER_DRAIN) { E(acc, cur, wr, wc, fr, fq); S.done(cur); }
;         if (!has_next) break;
; #pragma unroll
;         for (int a = 0; a < 2; ++a)
; #pragma unroll
;             for (int b = 0; b < 2; ++b)
; #pragma unroll
;                 for (int m = 0; m < 4; ++m)
; #pragma unroll
;                     for (int n = 0; n < 2; ++n) acc[a][b][m][n] = (f32x4){0.f, 0.f, 0.f, 0.f};
;         cur = nxt; cA = nA; cB = nB; ++ui;
;         if constexpr (ALIGN_EPI) { if (wr == 1) PG8_BAR; }
;     __device__ __forceinline__ void operator()(const f32x4 (&acc)[2][2][4][2], const pg8::Unit& u, int wr, int wc, int fr, int fq) const {
;     ...
;                     } else if constexpr (MODE == 2 || MODE == 3) {
;                         const u32x4 g = *(const u32x4*)(aux + row * 4096 + (MODE == 3 ? 2048 : 0) + col);
;                         float r[8] = {v0[0], v0[1], v0[2], v0[3], v1[0], v1[1], v1[2], v1[3]};
;                         const unsigned gw[4] = {g.x, g.y, g.z, g.w};
; #pragma unroll
;                         for (int i = 0; i < 4; ++i) { r[2 * i] *= bf2f(gw[i] & 0xffffu); r[2 * i + 1] *= __builtin_bit_cast(float, gw[i] & 0xffff0000u); }
;                         if constexpr (MODE == 3) { const u32x4 pv = *(const u32x4*)(ob + row * 2048 + col); const unsigned pw[4] = {pv.x, pv.y, pv.z, pv.w};
; #pragma unroll
;                             for (int i = 0; i < 4; ++i) { r[2 * i] += bf2f(pw[i] & 0xffffu); r[2 * i + 1] += __builtin_bit_cast(float, pw[i] & 0xffff0000u); } }
;                         u32x4 w; w.x = pk2(r[0], r[1]); w.y = pk2(r[2], r[3]); w.z = pk2(r[4], r[5]); w.w = pk2(r[6], r[7]);
;                         *(u32x4*)(ob + row * 2048 + col) = w;
	v_lshlrev_b32_e32 v51, 16, v41
	v_lshlrev_b32_e32 v50, 16, v40
	v_and_b32_e32 v41, 0xffff0000, v41
	v_and_b32_e32 v40, 0xffff0000, v40
	s_waitcnt vmcnt(0)
	v_lshlrev_b32_e32 v37, 16, v45
	v_lshlrev_b32_e32 v36, 16, v44
	v_and_b32_e32 v45, 0xffff0000, v45
	v_and_b32_e32 v44, 0xffff0000, v44
	v_pk_fma_f32 v[38:39], v[38:39], v[40:41], v[44:45]
	v_lshlrev_b32_e32 v41, 16, v43
	v_lshlrev_b32_e32 v40, 16, v42
	v_mov_b32_e32 v44, v32
	v_mov_b32_e32 v45, v34
	v_mov_b32_e32 v34, v33
	v_lshlrev_b32_e32 v33, 16, v47
	v_lshlrev_b32_e32 v32, 16, v46
	v_and_b32_e32 v43, 0xffff0000, v43
	v_and_b32_e32 v42, 0xffff0000, v42
	v_pk_fma_f32 v[32:33], v[44:45], v[40:41], v[32:33]
	v_and_b32_e32 v41, 0xffff0000, v47
	v_and_b32_e32 v40, 0xffff0000, v46
	v_pk_fma_f32 v[34:35], v[34:35], v[42:43], v[40:41]
	v_pk_fma_f32 v[36:37], v[52:53], v[50:51], v[36:37]
	v_cvt_pk_bf16_f32 v35, v33, v35
	v_cvt_pk_bf16_f32 v34, v32, v34
	v_cvt_pk_bf16_f32 v33, v37, v39
	v_cvt_pk_bf16_f32 v32, v36, v38
	global_store_dwordx4 v[48:49], v[32:35], off offset:256
	v_mov_b32_e32 v46, v28
	v_mov_b32_e32 v47, v30
	v_add_u32_e32 v32, 0xa0, v140
	v_ashrrev_i32_e32 v33, 31, v32
	v_lshlrev_b64 v[34:35], 13, v[32:33]
	v_lshlrev_b64 v[32:33], 12, v[32:33]
	v_lshl_add_u64 v[34:35], s[24:25], 0, v[34:35]
	v_lshl_add_u64 v[34:35], v[34:35], 0, s[8:9]
	v_lshl_add_u64 v[32:33], s[26:27], 0, v[32:33]
	v_lshl_add_u64 v[36:37], v[34:35], 0, v[138:139]
	v_lshl_add_u64 v[32:33], v[32:33], 0, v[138:139]
	global_load_dwordx4 v[36:39], v[36:37], off
	v_mov_b32_e32 v30, v29
	global_load_dwordx4 v[40:43], v[32:33], off
	s_waitcnt vmcnt(1)
	v_lshlrev_b32_e32 v45, 16, v37
	v_lshlrev_b32_e32 v44, 16, v36
	v_and_b32_e32 v37, 0xffff0000, v37
	v_and_b32_e32 v36, 0xffff0000, v36
	s_waitcnt vmcnt(0)
	v_lshlrev_b32_e32 v29, 16, v41
	v_lshlrev_b32_e32 v28, 16, v40
	v_and_b32_e32 v41, 0xffff0000, v41
	v_and_b32_e32 v40, 0xffff0000, v40
	v_pk_fma_f32 v[30:31], v[30:31], v[36:37], v[40:41]
	v_lshlrev_b32_e32 v37, 16, v39
	v_lshlrev_b32_e32 v36, 16, v38
	v_mov_b32_e32 v40, v24
	v_mov_b32_e32 v41, v26
	v_mov_b32_e32 v26, v25
	v_lshlrev_b32_e32 v25, 16, v43
	v_lshlrev_b32_e32 v24, 16, v42
	v_and_b32_e32 v39, 0xffff0000, v39
	v_and_b32_e32 v38, 0xffff0000, v38
	v_pk_fma_f32 v[24:25], v[40:41], v[36:37], v[24:25]
	v_and_b32_e32 v37, 0xffff0000, v43
	v_and_b32_e32 v36, 0xffff0000, v42
	v_pk_fma_f32 v[26:27], v[26:27], v[38:39], v[36:37]
	v_pk_fma_f32 v[28:29], v[46:47], v[44:45], v[28:29]
	v_cvt_pk_bf16_f32 v27, v25, v27
	v_cvt_pk_bf16_f32 v26, v24, v26
	v_cvt_pk_bf16_f32 v25, v29, v31
	v_cvt_pk_bf16_f32 v24, v28, v30
	global_store_dwordx4 v[32:33], v[24:27], off
	v_mov_b32_e32 v36, v20
	v_mov_b32_e32 v37, v22
	v_lshl_add_u64 v[24:25], v[34:35], 0, v[124:125]
	global_load_dwordx4 v[24:27], v[24:25], off
	s_nop 0
	global_load_dwordx4 v[28:31], v[32:33], off offset:256
	v_mov_b32_e32 v22, v21
	s_waitcnt vmcnt(1)
	v_lshlrev_b32_e32 v35, 16, v25
	v_lshlrev_b32_e32 v34, 16, v24
	v_and_b32_e32 v25, 0xffff0000, v25
	v_and_b32_e32 v24, 0xffff0000, v24
	s_waitcnt vmcnt(0)
	v_lshlrev_b32_e32 v21, 16, v29
	v_lshlrev_b32_e32 v20, 16, v28
	v_and_b32_e32 v29, 0xffff0000, v29
	v_and_b32_e32 v28, 0xffff0000, v28
	v_pk_fma_f32 v[22:23], v[22:23], v[24:25], v[28:29]
	v_lshlrev_b32_e32 v25, 16, v27
	v_lshlrev_b32_e32 v24, 16, v26
	v_mov_b32_e32 v28, v16
	v_mov_b32_e32 v29, v18
	v_mov_b32_e32 v18, v17
	v_lshlrev_b32_e32 v17, 16, v31
	v_lshlrev_b32_e32 v16, 16, v30
	v_and_b32_e32 v27, 0xffff0000, v27
	v_and_b32_e32 v26, 0xffff0000, v26
	v_pk_fma_f32 v[16:17], v[28:29], v[24:25], v[16:17]
	v_and_b32_e32 v25, 0xffff0000, v31
	v_and_b32_e32 v24, 0xffff0000, v30
	v_pk_fma_f32 v[18:19], v[18:19], v[26:27], v[24:25]
	v_pk_fma_f32 v[20:21], v[36:37], v[34:35], v[20:21]
	v_cvt_pk_bf16_f32 v19, v17, v19
	v_cvt_pk_bf16_f32 v18, v16, v18
	v_cvt_pk_bf16_f32 v17, v21, v23
	v_cvt_pk_bf16_f32 v16, v20, v22
	global_store_dwordx4 v[32:33], v[16:19], off offset:256
	v_mov_b32_e32 v30, v12
	v_mov_b32_e32 v31, v14
	v_add_u32_e32 v16, 0xb0, v140
	v_ashrrev_i32_e32 v17, 31, v16
	v_lshlrev_b64 v[18:19], 13, v[16:17]
	v_lshlrev_b64 v[16:17], 12, v[16:17]
	v_lshl_add_u64 v[18:19], s[24:25], 0, v[18:19]
	v_lshl_add_u64 v[18:19], v[18:19], 0, s[8:9]
	v_lshl_add_u64 v[16:17], s[26:27], 0, v[16:17]
	v_lshl_add_u64 v[20:21], v[18:19], 0, v[138:139]
	v_lshl_add_u64 v[16:17], v[16:17], 0, v[138:139]
	global_load_dwordx4 v[20:23], v[20:21], off
	v_mov_b32_e32 v14, v13
	global_load_dwordx4 v[24:27], v[16:17], off
	s_waitcnt vmcnt(1)
	v_lshlrev_b32_e32 v29, 16, v21
	v_lshlrev_b32_e32 v28, 16, v20
	v_and_b32_e32 v21, 0xffff0000, v21
	v_and_b32_e32 v20, 0xffff0000, v20
	s_waitcnt vmcnt(0)
	v_lshlrev_b32_e32 v13, 16, v25
	v_lshlrev_b32_e32 v12, 16, v24
	v_and_b32_e32 v25, 0xffff0000, v25
	v_and_b32_e32 v24, 0xffff0000, v24
	v_pk_fma_f32 v[14:15], v[14:15], v[20:21], v[24:25]
	v_lshlrev_b32_e32 v21, 16, v23
	v_lshlrev_b32_e32 v20, 16, v22
	v_mov_b32_e32 v24, v8
	v_mov_b32_e32 v25, v10
	v_mov_b32_e32 v10, v9
	v_lshlrev_b32_e32 v9, 16, v27
	v_lshlrev_b32_e32 v8, 16, v26
	v_and_b32_e32 v23, 0xffff0000, v23
	v_and_b32_e32 v22, 0xffff0000, v22
	v_pk_fma_f32 v[8:9], v[24:25], v[20:21], v[8:9]
	v_and_b32_e32 v21, 0xffff0000, v27
	v_and_b32_e32 v20, 0xffff0000, v26
	v_pk_fma_f32 v[10:11], v[10:11], v[22:23], v[20:21]
	v_pk_fma_f32 v[12:13], v[30:31], v[28:29], v[12:13]
	v_cvt_pk_bf16_f32 v11, v9, v11
	v_cvt_pk_bf16_f32 v10, v8, v10
	v_cvt_pk_bf16_f32 v9, v13, v15
	v_cvt_pk_bf16_f32 v8, v12, v14
	global_store_dwordx4 v[16:17], v[8:11], off
	v_mov_b32_e32 v20, v4
	v_mov_b32_e32 v21, v6
	v_lshl_add_u64 v[8:9], v[18:19], 0, v[124:125]
	global_load_dwordx4 v[12:15], v[8:9], off
	s_nop 0
	global_load_dwordx4 v[8:11], v[16:17], off offset:256
	v_mov_b32_e32 v6, v5
	s_waitcnt vmcnt(1)
	v_lshlrev_b32_e32 v19, 16, v13
	v_lshlrev_b32_e32 v18, 16, v12
	v_and_b32_e32 v13, 0xffff0000, v13
	v_and_b32_e32 v12, 0xffff0000, v12
	s_waitcnt vmcnt(0)
	v_lshlrev_b32_e32 v5, 16, v9
	v_lshlrev_b32_e32 v4, 16, v8
	v_and_b32_e32 v9, 0xffff0000, v9
	v_and_b32_e32 v8, 0xffff0000, v8
	v_pk_fma_f32 v[6:7], v[6:7], v[12:13], v[8:9]
	v_lshlrev_b32_e32 v9, 16, v15
	v_lshlrev_b32_e32 v8, 16, v14
	v_mov_b32_e32 v12, v0
	v_mov_b32_e32 v13, v2
	v_mov_b32_e32 v2, v1
	v_lshlrev_b32_e32 v1, 16, v11
	v_lshlrev_b32_e32 v0, 16, v10
	v_and_b32_e32 v15, 0xffff0000, v15
	v_and_b32_e32 v14, 0xffff0000, v14
	v_pk_fma_f32 v[0:1], v[12:13], v[8:9], v[0:1]
	v_and_b32_e32 v9, 0xffff0000, v11
	v_and_b32_e32 v8, 0xffff0000, v10
	v_pk_fma_f32 v[2:3], v[2:3], v[14:15], v[8:9]
	v_pk_fma_f32 v[4:5], v[20:21], v[18:19], v[4:5]
	v_cvt_pk_bf16_f32 v3, v1, v3
	v_cvt_pk_bf16_f32 v2, v0, v2
	v_cvt_pk_bf16_f32 v1, v5, v7
	v_cvt_pk_bf16_f32 v0, v4, v6
	global_store_dwordx4 v[16:17], v[0:3], off offset:256
	s_cbranch_vccnz .LBB0_109
	s_andn2_b64 vcc, exec, s[0:1]
	s_cbranch_vccnz .LBB0_108
	s_barrier
	s_branch .LBB0_108

; #define LAS __attribute__((address_space(3)))
; __device__ __forceinline__ unsigned pk2(float lo, float hi) { return f2bf(lo) | (f2bf(hi) << 16); }
; __device__ __forceinline__ void dilated_block(const bf16_t* QKV, bf16_t* OG, float* LSE, LAS unsigned char* lds, int u, int tid) {
;     ...
;     const int q4 = n16 >> 2, p4 = lane & 3;
; #pragma unroll
;     for (int u2 = 0; u2 < 5; ++u2) {
;         u32x4 pw; pw.x = pk2(sacc[2 * u2][0], sacc[2 * u2][1]); pw.y = pk2(sacc[2 * u2][2], sacc[2 * u2][3]); pw.z = pk2(sacc[2 * u2 + 1][0], sacc[2 * u2 + 1][1]); pw.w = pk2(sacc[2 * u2 + 1][2], sacc[2 * u2 + 1][3]);
;         const bf16x8 pf = __builtin_bit_cast(bf16x8, pw);
;         const int r0 = min(i0 + 32 * u2 + 4 * slab + q4, 255), r1 = min(i0 + 32 * u2 + 16 + 4 * slab + q4, 255);
;         LAS unsigned char* a0p = lds + r0 * VRS + 8 * p4; LAS unsigned char* a1p = lds + r1 * VRS + 8 * p4;
; #pragma unroll
;         for (int c = 0; c < 8; ++c) {
;             const v4i16_t lo = __builtin_amdgcn_ds_read_tr16_b64_v4i16((LAS v4i16_t*)(a0p + c * 32)), hi = __builtin_amdgcn_ds_read_tr16_b64_v4i16((LAS v4i16_t*)(a1p + c * 32));
;             const bf16x8 vf = __builtin_shufflevector(lo, hi, 0, 1, 2, 3, 4, 5, 6, 7);
;             oacc[c] = __builtin_amdgcn_mfma_f32_16x16x32_bf16(vf, pf, oacc[c], 0, 0, 0);
;         }
;     }
.LBB0_196:
	s_or_b64 exec, exec, s[10:11]
	v_bfe_u32 v38, v35, 16, 1
	v_bfe_u32 v39, v33, 16, 1
	v_bfe_u32 v40, v31, 16, 1
	v_add3_u32 v40, v31, v40, s33
	v_add3_u32 v39, v33, v39, s33
	v_add3_u32 v35, v35, v38, s33
	v_bfe_u32 v31, v29, 16, 1
	v_bfe_u32 v33, v30, 16, 1
	v_bfe_u32 v37, v32, 16, 1
	v_add3_u32 v38, v30, v33, s33
	v_add3_u32 v29, v29, v31, s33
	v_or_b32_e32 v30, s1, v63
	v_add_u32_e32 v31, s1, v64
	v_add3_u32 v37, v32, v37, s33
	v_min_i32_e32 v30, 0xff, v30
	v_min_i32_e32 v31, 0xff, v31
	s_movk_i32 s10, 0x110
	v_lshrrev_b32_e32 v29, 16, v29
	v_mad_u64_u32 v[46:47], s[4:5], v30, s10, v[50:51]
	v_mad_u64_u32 v[54:55], s[4:5], v31, s10, v[50:51]
	v_lshrrev_b32_e32 v38, 16, v38
	v_lshrrev_b32_e32 v41, 16, v37
	ds_read_b64_tr_b16 v[32:33], v54
	ds_read_b64_tr_b16 v[30:31], v46
	v_cvt_pk_bf16_f32 v37, v34, v36
	v_and_or_b32 v36, v35, s67, v41
	v_and_or_b32 v35, v39, s67, v38
	v_and_or_b32 v34, v40, s67, v29
	ds_read_b64_tr_b16 v[40:41], v54 offset:32
	ds_read_b64_tr_b16 v[38:39], v46 offset:32
	ds_read_b64_tr_b16 v[42:43], v46 offset:64
	ds_read_b64_tr_b16 v[44:45], v54 offset:64
	ds_read_b64_tr_b16 v[74:75], v46 offset:96
	ds_read_b64_tr_b16 v[76:77], v54 offset:96
	ds_read_b64_tr_b16 v[78:79], v46 offset:128
	ds_read_b64_tr_b16 v[80:81], v54 offset:128
	ds_read_b64_tr_b16 v[82:83], v46 offset:160
	ds_read_b64_tr_b16 v[84:85], v54 offset:160
	ds_read_b64_tr_b16 v[86:87], v46 offset:192
	ds_read_b64_tr_b16 v[88:89], v54 offset:192
	ds_read_b64_tr_b16 v[90:91], v46 offset:224
	ds_read_b64_tr_b16 v[92:93], v54 offset:224
	v_bfe_u32 v47, v25, 16, 1
	v_bfe_u32 v54, v23, 16, 1
	s_waitcnt lgkmcnt(14)
	v_mfma_f32_16x16x32_bf16 v[30:33], v[30:33], v[34:37], 0
	v_add3_u32 v73, v23, v54, s33
	v_bfe_u32 v23, v21, 16, 1
	s_add_i32 s4, s1, 32
	s_waitcnt lgkmcnt(12)
	v_mfma_f32_16x16x32_bf16 v[38:41], v[38:41], v[34:37], 0
	v_bfe_u32 v46, v27, 16, 1
	v_add3_u32 v21, v21, v23, s33
	s_waitcnt lgkmcnt(10)
	v_mfma_f32_16x16x32_bf16 v[42:45], v[42:45], v[34:37], 0
	v_add_u32_e32 v23, s4, v64
	v_add3_u32 v27, v27, v46, s33
	s_waitcnt lgkmcnt(8)
	v_mfma_f32_16x16x32_bf16 v[74:77], v[74:77], v[34:37], 0
	v_bfe_u32 v29, v24, 16, 1
	v_min_i32_e32 v23, 0xff, v23
	s_waitcnt lgkmcnt(6)
	v_mfma_f32_16x16x32_bf16 v[78:81], v[78:81], v[34:37], 0
	v_add3_u32 v29, v24, v29, s33
	s_waitcnt lgkmcnt(4)
	v_mfma_f32_16x16x32_bf16 v[82:85], v[82:85], v[34:37], 0
	v_lshrrev_b32_e32 v21, 16, v21
	s_waitcnt lgkmcnt(2)
	v_mfma_f32_16x16x32_bf16 v[86:89], v[86:89], v[34:37], 0
	s_waitcnt lgkmcnt(0)
	v_mfma_f32_16x16x32_bf16 v[34:37], v[90:93], v[34:37], 0
	v_add3_u32 v90, v25, v47, s33
	v_bfe_u32 v25, v22, 16, 1
	v_add3_u32 v91, v22, v25, s33
	v_or_b32_e32 v22, s4, v63
	v_min_i32_e32 v22, 0xff, v22
	v_mad_u64_u32 v[46:47], s[4:5], v22, s10, v[50:51]
	v_mad_u64_u32 v[54:55], s[4:5], v23, s10, v[50:51]
	v_lshrrev_b32_e32 v47, 16, v91
	v_lshrrev_b32_e32 v55, 16, v29
	ds_read_b64_tr_b16 v[24:25], v54
	ds_read_b64_tr_b16 v[22:23], v46
	v_cvt_pk_bf16_f32 v29, v26, v28
	v_and_or_b32 v28, v27, s67, v55
	v_and_or_b32 v27, v90, s67, v47
	ds_read_b64_tr_b16 v[92:93], v54 offset:32
	ds_read_b64_tr_b16 v[90:91], v46 offset:32
	v_and_or_b32 v26, v73, s67, v21
	s_add_i32 s4, s1, 64
	s_waitcnt lgkmcnt(2)
	v_mfma_f32_16x16x32_bf16 v[22:25], v[22:25], v[26:29], v[30:33]
	v_bfe_u32 v21, v16, 16, 1
	v_add3_u32 v21, v16, v21, s33
	s_waitcnt lgkmcnt(0)
	v_mfma_f32_16x16x32_bf16 v[30:33], v[90:93], v[26:29], v[38:41]
	s_nop 2
	ds_read_b64_tr_b16 v[38:39], v46 offset:64
	ds_read_b64_tr_b16 v[40:41], v54 offset:64
	s_waitcnt lgkmcnt(0)
	v_mfma_f32_16x16x32_bf16 v[38:41], v[38:41], v[26:29], v[42:45]
	s_nop 2
	ds_read_b64_tr_b16 v[42:43], v46 offset:96
	ds_read_b64_tr_b16 v[44:45], v54 offset:96
	s_waitcnt lgkmcnt(0)
	v_mfma_f32_16x16x32_bf16 v[42:45], v[42:45], v[26:29], v[74:77]
	s_nop 2
	ds_read_b64_tr_b16 v[74:75], v46 offset:128
	ds_read_b64_tr_b16 v[76:77], v54 offset:128
	s_waitcnt lgkmcnt(0)
	v_mfma_f32_16x16x32_bf16 v[74:77], v[74:77], v[26:29], v[78:81]
	s_nop 2
	ds_read_b64_tr_b16 v[78:79], v46 offset:160
	ds_read_b64_tr_b16 v[80:81], v54 offset:160
	s_waitcnt lgkmcnt(0)
	v_mfma_f32_16x16x32_bf16 v[78:81], v[78:81], v[26:29], v[82:85]
	s_nop 2
	ds_read_b64_tr_b16 v[82:83], v46 offset:192
	ds_read_b64_tr_b16 v[84:85], v54 offset:192
	s_waitcnt lgkmcnt(0)
	v_mfma_f32_16x16x32_bf16 v[82:85], v[82:85], v[26:29], v[86:89]
	s_nop 2
	ds_read_b64_tr_b16 v[86:87], v46 offset:224
	ds_read_b64_tr_b16 v[88:89], v54 offset:224
	s_waitcnt lgkmcnt(0)
	v_mfma_f32_16x16x32_bf16 v[26:29], v[86:89], v[26:29], v[34:37]
	s_nop 2
	v_bfe_u32 v34, v19, 16, 1
	v_bfe_u32 v35, v17, 16, 1
	v_bfe_u32 v36, v15, 16, 1
	v_add3_u32 v36, v15, v36, s33
	v_add3_u32 v35, v17, v35, s33
	v_add3_u32 v19, v19, v34, s33
	v_bfe_u32 v15, v13, 16, 1
	v_bfe_u32 v17, v14, 16, 1
	v_add3_u32 v34, v14, v17, s33
	v_add3_u32 v13, v13, v15, s33
	v_or_b32_e32 v14, s4, v63
	v_add_u32_e32 v15, s4, v64
	v_min_i32_e32 v14, 0xff, v14
	v_min_i32_e32 v15, 0xff, v15
	v_lshrrev_b32_e32 v13, 16, v13
	v_mad_u64_u32 v[46:47], s[4:5], v14, s10, v[50:51]
	v_mad_u64_u32 v[54:55], s[4:5], v15, s10, v[50:51]
	v_lshrrev_b32_e32 v34, 16, v34
	v_lshrrev_b32_e32 v37, 16, v21
	ds_read_b64_tr_b16 v[16:17], v54
	ds_read_b64_tr_b16 v[14:15], v46
	v_cvt_pk_bf16_f32 v21, v18, v20
	v_and_or_b32 v20, v19, s67, v37
	v_and_or_b32 v19, v35, s67, v34
	v_and_or_b32 v18, v36, s67, v13
	ds_read_b64_tr_b16 v[36:37], v54 offset:32
	ds_read_b64_tr_b16 v[34:35], v46 offset:32
	s_waitcnt lgkmcnt(2)
	v_mfma_f32_16x16x32_bf16 v[14:17], v[14:17], v[18:21], v[22:25]
	s_add_i32 s4, s1, 0x60
	s_waitcnt lgkmcnt(0)
; #define LAS __attribute__((address_space(3)))
; __device__ __forceinline__ unsigned pk2(float lo, float hi) { return f2bf(lo) | (f2bf(hi) << 16); }
; __device__ __forceinline__ void dilated_block(const bf16_t* QKV, bf16_t* OG, float* LSE, LAS unsigned char* lds, int u, int tid) {
;     ...
;     const int q4 = n16 >> 2, p4 = lane & 3;
; #pragma unroll
;     for (int u2 = 0; u2 < 5; ++u2) {
;         u32x4 pw; pw.x = pk2(sacc[2 * u2][0], sacc[2 * u2][1]); pw.y = pk2(sacc[2 * u2][2], sacc[2 * u2][3]); pw.z = pk2(sacc[2 * u2 + 1][0], sacc[2 * u2 + 1][1]); pw.w = pk2(sacc[2 * u2 + 1][2], sacc[2 * u2 + 1][3]);
;         const bf16x8 pf = __builtin_bit_cast(bf16x8, pw);
;         const int r0 = min(i0 + 32 * u2 + 4 * slab + q4, 255), r1 = min(i0 + 32 * u2 + 16 + 4 * slab + q4, 255);
;         LAS unsigned char* a0p = lds + r0 * VRS + 8 * p4; LAS unsigned char* a1p = lds + r1 * VRS + 8 * p4;
; #pragma unroll
;         for (int c = 0; c < 8; ++c) {
;             const v4i16_t lo = __builtin_amdgcn_ds_read_tr16_b64_v4i16((LAS v4i16_t*)(a0p + c * 32)), hi = __builtin_amdgcn_ds_read_tr16_b64_v4i16((LAS v4i16_t*)(a1p + c * 32));
;             const bf16x8 vf = __builtin_shufflevector(lo, hi, 0, 1, 2, 3, 4, 5, 6, 7);
;             oacc[c] = __builtin_amdgcn_mfma_f32_16x16x32_bf16(vf, pf, oacc[c], 0, 0, 0);
;         }
;     }
	v_mfma_f32_16x16x32_bf16 v[22:25], v[34:37], v[18:21], v[30:33]
	s_nop 2
	ds_read_b64_tr_b16 v[30:31], v46 offset:64
	ds_read_b64_tr_b16 v[32:33], v54 offset:64
	ds_read_b64_tr_b16 v[34:35], v46 offset:96
	ds_read_b64_tr_b16 v[36:37], v54 offset:96
	v_bfe_u32 v13, v8, 16, 1
	s_waitcnt lgkmcnt(2)
	v_mfma_f32_16x16x32_bf16 v[30:33], v[30:33], v[18:21], v[38:41]
	s_nop 2
	ds_read_b64_tr_b16 v[38:39], v46 offset:128
	ds_read_b64_tr_b16 v[40:41], v54 offset:128
	v_add3_u32 v13, v8, v13, s33
	s_addk_i32 s1, 0x80
	s_waitcnt lgkmcnt(2)
	v_mfma_f32_16x16x32_bf16 v[34:37], v[34:37], v[18:21], v[42:45]
	s_nop 2
	ds_read_b64_tr_b16 v[42:43], v46 offset:160
	ds_read_b64_tr_b16 v[44:45], v54 offset:160
	s_waitcnt lgkmcnt(2)
	v_mfma_f32_16x16x32_bf16 v[38:41], v[38:41], v[18:21], v[74:77]
	s_nop 2
	ds_read_b64_tr_b16 v[74:75], v46 offset:192
	ds_read_b64_tr_b16 v[76:77], v54 offset:192
	s_waitcnt lgkmcnt(2)
	v_mfma_f32_16x16x32_bf16 v[42:45], v[42:45], v[18:21], v[78:81]
	s_nop 2
	ds_read_b64_tr_b16 v[78:79], v46 offset:224
	ds_read_b64_tr_b16 v[80:81], v54 offset:224
	s_waitcnt lgkmcnt(2)
	v_mfma_f32_16x16x32_bf16 v[74:77], v[74:77], v[18:21], v[82:85]
	s_waitcnt lgkmcnt(0)
	v_mfma_f32_16x16x32_bf16 v[18:21], v[78:81], v[18:21], v[26:29]
	s_nop 2
	v_bfe_u32 v26, v11, 16, 1
	v_bfe_u32 v27, v9, 16, 1
	v_bfe_u32 v28, v7, 16, 1
	v_add3_u32 v28, v7, v28, s33
	v_add3_u32 v27, v9, v27, s33
	v_add3_u32 v11, v11, v26, s33
	v_bfe_u32 v7, v5, 16, 1
	v_bfe_u32 v9, v6, 16, 1
	v_add3_u32 v26, v6, v9, s33
	v_add3_u32 v5, v5, v7, s33
	v_or_b32_e32 v6, s4, v63
	v_add_u32_e32 v7, s4, v64
	v_min_i32_e32 v6, 0xff, v6
	v_min_i32_e32 v7, 0xff, v7
	v_lshrrev_b32_e32 v5, 16, v5
	v_mad_u64_u32 v[46:47], s[4:5], v6, s10, v[50:51]
	v_mad_u64_u32 v[54:55], s[4:5], v7, s10, v[50:51]
	v_lshrrev_b32_e32 v26, 16, v26
	v_lshrrev_b32_e32 v29, 16, v13
	ds_read_b64_tr_b16 v[8:9], v54
	ds_read_b64_tr_b16 v[6:7], v46
	v_cvt_pk_bf16_f32 v13, v10, v12
	v_and_or_b32 v12, v11, s67, v29
	v_and_or_b32 v11, v27, s67, v26
	v_and_or_b32 v10, v28, s67, v5
	ds_read_b64_tr_b16 v[28:29], v54 offset:32
	ds_read_b64_tr_b16 v[26:27], v46 offset:32
	s_waitcnt lgkmcnt(2)
	v_mfma_f32_16x16x32_bf16 v[6:9], v[6:9], v[10:13], v[14:17]
	v_and_b32_sdwa v5, v3, v207 dst_sel:DWORD dst_unused:UNUSED_PAD src0_sel:WORD_1 src1_sel:DWORD
	s_waitcnt lgkmcnt(0)
	v_mfma_f32_16x16x32_bf16 v[14:17], v[26:29], v[10:13], v[22:25]
	s_nop 2
	ds_read_b64_tr_b16 v[22:23], v46 offset:64
	ds_read_b64_tr_b16 v[24:25], v54 offset:64
	ds_read_b64_tr_b16 v[26:27], v46 offset:96
	ds_read_b64_tr_b16 v[28:29], v54 offset:96
	s_waitcnt lgkmcnt(2)
	v_mfma_f32_16x16x32_bf16 v[22:25], v[22:25], v[10:13], v[30:33]
	s_nop 2
	ds_read_b64_tr_b16 v[30:31], v46 offset:128
	ds_read_b64_tr_b16 v[32:33], v54 offset:128
	s_waitcnt lgkmcnt(2)
	v_mfma_f32_16x16x32_bf16 v[26:29], v[26:29], v[10:13], v[34:37]
	s_nop 2
	ds_read_b64_tr_b16 v[34:35], v46 offset:160
	ds_read_b64_tr_b16 v[36:37], v54 offset:160
	s_waitcnt lgkmcnt(2)
	v_mfma_f32_16x16x32_bf16 v[30:33], v[30:33], v[10:13], v[38:41]
	s_nop 2
	ds_read_b64_tr_b16 v[38:39], v46 offset:192
	ds_read_b64_tr_b16 v[40:41], v54 offset:192
	s_waitcnt lgkmcnt(2)
	v_mfma_f32_16x16x32_bf16 v[34:37], v[34:37], v[10:13], v[42:45]
	s_nop 2
	ds_read_b64_tr_b16 v[42:43], v46 offset:224
	ds_read_b64_tr_b16 v[44:45], v54 offset:224
	s_waitcnt lgkmcnt(2)
	v_mfma_f32_16x16x32_bf16 v[38:41], v[38:41], v[10:13], v[74:77]
	s_waitcnt lgkmcnt(0)
	v_mfma_f32_16x16x32_bf16 v[10:13], v[42:45], v[10:13], v[18:21]
	s_nop 2
	v_and_b32_sdwa v18, v2, v207 dst_sel:DWORD dst_unused:UNUSED_PAD src0_sel:WORD_1 src1_sel:DWORD
	v_add3_u32 v19, v3, v5, s33
	v_and_b32_sdwa v3, v1, v207 dst_sel:DWORD dst_unused:UNUSED_PAD src0_sel:WORD_1 src1_sel:DWORD
	v_add3_u32 v18, v2, v18, s33
	v_and_b32_sdwa v2, v4, v207 dst_sel:DWORD dst_unused:UNUSED_PAD src0_sel:WORD_1 src1_sel:DWORD
	v_add3_u32 v1, v1, v3, s33
	v_add_u32_e32 v3, s1, v64
	v_add3_u32 v20, v4, v2, s33
	v_or_b32_e32 v2, s1, v63
	v_min_i32_e32 v3, 0xff, v3
	v_min_i32_e32 v2, 0xff, v2
	v_mad_u64_u32 v[54:55], s[4:5], v3, s10, v[50:51]
	v_mad_u64_u32 v[46:47], s[4:5], v2, s10, v[50:51]
	ds_read_b64_tr_b16 v[4:5], v54
	ds_read_b64_tr_b16 v[2:3], v46
	v_and_b32_e32 v20, 0xffff0000, v20
	v_and_b32_e32 v1, 0xffff0000, v1
	v_or_b32_sdwa v19, v20, v19 dst_sel:DWORD dst_unused:UNUSED_PAD src0_sel:DWORD src1_sel:WORD_1
	v_or_b32_sdwa v18, v1, v18 dst_sel:DWORD dst_unused:UNUSED_PAD src0_sel:DWORD src1_sel:WORD_1
	ds_read_b64_tr_b16 v[44:45], v54 offset:32
	ds_read_b64_tr_b16 v[42:43], v46 offset:32
	v_mov_b32_e32 v20, v161
	v_mov_b32_e32 v21, v161
	v_div_scale_f32 v1, s[4:5], v0, v0, 1.0
	s_waitcnt lgkmcnt(2)
	v_mfma_f32_16x16x32_bf16 v[2:5], v[2:5], v[18:21], v[6:9]
	s_nop 2
	ds_read_b64_tr_b16 v[6:7], v46 offset:64
	ds_read_b64_tr_b16 v[8:9], v54 offset:64
	s_ashr_i32 s1, s0, 31
	s_lshl_b64 s[0:1], s[0:1], 24
	s_waitcnt lgkmcnt(2)
	v_mfma_f32_16x16x32_bf16 v[14:17], v[42:45], v[18:21], v[14:17]
	ds_read_b64_tr_b16 v[42:43], v46 offset:96
	ds_read_b64_tr_b16 v[44:45], v54 offset:96
	s_add_u32 s0, s30, s0
	s_addc_u32 s1, s31, s1
	s_waitcnt lgkmcnt(2)
	v_mfma_f32_16x16x32_bf16 v[6:9], v[6:9], v[18:21], v[22:25]
	s_nop 2
	ds_read_b64_tr_b16 v[22:23], v46 offset:128
	ds_read_b64_tr_b16 v[24:25], v54 offset:128
	s_lshl_b32 s4, s9, 8
	s_add_i32 s8, s8, s94
	s_waitcnt lgkmcnt(2)
	v_mfma_f32_16x16x32_bf16 v[26:29], v[42:45], v[18:21], v[26:29]
	ds_read_b64_tr_b16 v[42:43], v46 offset:160
	ds_read_b64_tr_b16 v[44:45], v54 offset:160
	s_cmpk_gt_i32 s8, 0x5ff
	s_waitcnt lgkmcnt(2)
	v_mfma_f32_16x16x32_bf16 v[22:25], v[22:25], v[18:21], v[30:33]
	s_nop 2
	ds_read_b64_tr_b16 v[30:31], v46 offset:192
	ds_read_b64_tr_b16 v[32:33], v54 offset:192
	s_waitcnt lgkmcnt(2)
; __device__ __forceinline__ unsigned pk2(float lo, float hi) { return f2bf(lo) | (f2bf(hi) << 16); }
; __device__ __forceinline__ void dilated_block(const bf16_t* QKV, bf16_t* OG, float* LSE, LAS unsigned char* lds, int u, int tid) {
;     ...
;             oacc[c] = __builtin_amdgcn_mfma_f32_16x16x32_bf16(vf, pf, oacc[c], 0, 0, 0);
;         }
;     }
;     const float inv = 1.f / lsum;
;     bf16_t* op = OG + ((size_t)g * SEQ + tq) * 512 + hs * 128 + 4 * slab;
; #pragma unroll
;     for (int c = 0; c < 8; ++c) { u32x2 o; o.x = pk2(oacc[c][0] * inv, oacc[c][1] * inv); o.y = pk2(oacc[c][2] * inv, oacc[c][3] * inv); *(u32x2*)(op + 16 * c) = o; }
	v_mfma_f32_16x16x32_bf16 v[34:37], v[42:45], v[18:21], v[34:37]
	ds_read_b64_tr_b16 v[42:43], v46 offset:224
	ds_read_b64_tr_b16 v[44:45], v54 offset:224
	s_waitcnt lgkmcnt(2)
	v_mfma_f32_16x16x32_bf16 v[30:33], v[30:33], v[18:21], v[38:41]
	s_nop 2
	v_rcp_f32_e32 v38, v1
	s_waitcnt lgkmcnt(0)
	v_mfma_f32_16x16x32_bf16 v[10:13], v[42:45], v[18:21], v[10:13]
	v_fma_f32 v18, -v1, v38, 1.0
	v_fmac_f32_e32 v38, v18, v38
	v_div_scale_f32 v18, vcc, 1.0, v0, 1.0
	v_mul_f32_e32 v19, v18, v38
	v_fma_f32 v20, -v1, v19, v18
	v_fmac_f32_e32 v19, v20, v38
	v_fma_f32 v1, -v1, v19, v18
	v_div_fmas_f32 v1, v1, v38, v19
	v_lshlrev_b64 v[18:19], 10, v[52:53]
	v_lshl_add_u64 v[18:19], s[0:1], 0, v[18:19]
	v_readlane_b32 s0, v252, 56
	v_readlane_b32 s1, v252, 57
	s_mov_b32 s5, s1
	v_lshl_add_u64 v[18:19], v[18:19], 0, s[4:5]
	v_lshlrev_b32_e32 v20, 1, v49
	v_div_fixup_f32 v0, v1, v0, 1.0
	v_lshl_add_u64 v[18:19], v[18:19], 0, v[20:21]
	v_mov_b32_e32 v20, v2
	v_mov_b32_e32 v21, v4
	v_pk_mul_f32 v[20:21], v[0:1], v[20:21] op_sel_hi:[0,1]
	v_mov_b32_e32 v4, v3
	v_pk_mul_f32 v[2:3], v[0:1], v[4:5] op_sel_hi:[0,1]
	v_and_b32_sdwa v4, v20, v207 dst_sel:DWORD dst_unused:UNUSED_PAD src0_sel:WORD_1 src1_sel:DWORD
	v_add3_u32 v4, v20, v4, s33
	v_and_b32_sdwa v5, v3, v207 dst_sel:DWORD dst_unused:UNUSED_PAD src0_sel:WORD_1 src1_sel:DWORD
	v_and_b32_sdwa v20, v2, v207 dst_sel:DWORD dst_unused:UNUSED_PAD src0_sel:WORD_1 src1_sel:DWORD
	v_and_b32_sdwa v1, v21, v207 dst_sel:DWORD dst_unused:UNUSED_PAD src0_sel:WORD_1 src1_sel:DWORD
	v_add3_u32 v3, v3, v5, s33
	v_add3_u32 v2, v2, v20, s33
	v_add3_u32 v1, v21, v1, s33
	v_and_b32_e32 v3, 0xffff0000, v3
	v_and_b32_e32 v2, 0xffff0000, v2
	v_or_b32_sdwa v3, v3, v1 dst_sel:DWORD dst_unused:UNUSED_PAD src0_sel:DWORD src1_sel:WORD_1
	v_or_b32_sdwa v2, v2, v4 dst_sel:DWORD dst_unused:UNUSED_PAD src0_sel:DWORD src1_sel:WORD_1
	global_store_dwordx2 v[18:19], v[2:3], off
	v_mov_b32_e32 v2, v14
	v_mov_b32_e32 v3, v16
	v_pk_mul_f32 v[2:3], v[0:1], v[2:3] op_sel_hi:[0,1]
	v_mov_b32_e32 v16, v15
	v_pk_mul_f32 v[4:5], v[0:1], v[16:17] op_sel_hi:[0,1]
	v_and_b32_sdwa v1, v3, v207 dst_sel:DWORD dst_unused:UNUSED_PAD src0_sel:WORD_1 src1_sel:DWORD
	v_and_b32_sdwa v14, v2, v207 dst_sel:DWORD dst_unused:UNUSED_PAD src0_sel:WORD_1 src1_sel:DWORD
	v_add3_u32 v2, v2, v14, s33
	v_add3_u32 v1, v3, v1, s33
	v_and_b32_sdwa v3, v5, v207 dst_sel:DWORD dst_unused:UNUSED_PAD src0_sel:WORD_1 src1_sel:DWORD
	v_and_b32_sdwa v14, v4, v207 dst_sel:DWORD dst_unused:UNUSED_PAD src0_sel:WORD_1 src1_sel:DWORD
	v_add3_u32 v3, v5, v3, s33
	v_add3_u32 v4, v4, v14, s33
	v_and_b32_e32 v3, 0xffff0000, v3
	v_and_b32_e32 v4, 0xffff0000, v4
	v_or_b32_sdwa v3, v3, v1 dst_sel:DWORD dst_unused:UNUSED_PAD src0_sel:DWORD src1_sel:WORD_1
	v_or_b32_sdwa v2, v4, v2 dst_sel:DWORD dst_unused:UNUSED_PAD src0_sel:DWORD src1_sel:WORD_1
	global_store_dwordx2 v[18:19], v[2:3], off offset:32
	v_mov_b32_e32 v2, v6
	v_mov_b32_e32 v3, v8
	v_pk_mul_f32 v[2:3], v[0:1], v[2:3] op_sel_hi:[0,1]
	v_mov_b32_e32 v8, v7
	v_pk_mul_f32 v[4:5], v[0:1], v[8:9] op_sel_hi:[0,1]
	v_and_b32_sdwa v1, v3, v207 dst_sel:DWORD dst_unused:UNUSED_PAD src0_sel:WORD_1 src1_sel:DWORD
	v_and_b32_sdwa v6, v2, v207 dst_sel:DWORD dst_unused:UNUSED_PAD src0_sel:WORD_1 src1_sel:DWORD
	v_add3_u32 v2, v2, v6, s33
	v_add3_u32 v1, v3, v1, s33
	v_and_b32_sdwa v3, v5, v207 dst_sel:DWORD dst_unused:UNUSED_PAD src0_sel:WORD_1 src1_sel:DWORD
	v_and_b32_sdwa v6, v4, v207 dst_sel:DWORD dst_unused:UNUSED_PAD src0_sel:WORD_1 src1_sel:DWORD
	v_add3_u32 v3, v5, v3, s33
	v_add3_u32 v4, v4, v6, s33
	v_and_b32_e32 v3, 0xffff0000, v3
	v_and_b32_e32 v4, 0xffff0000, v4
	v_or_b32_sdwa v3, v3, v1 dst_sel:DWORD dst_unused:UNUSED_PAD src0_sel:DWORD src1_sel:WORD_1
	v_or_b32_sdwa v2, v4, v2 dst_sel:DWORD dst_unused:UNUSED_PAD src0_sel:DWORD src1_sel:WORD_1
	global_store_dwordx2 v[18:19], v[2:3], off offset:64
	v_mov_b32_e32 v2, v26
	v_mov_b32_e32 v3, v28
	v_pk_mul_f32 v[2:3], v[0:1], v[2:3] op_sel_hi:[0,1]
	v_mov_b32_e32 v28, v27
	v_pk_mul_f32 v[4:5], v[0:1], v[28:29] op_sel_hi:[0,1]
	v_and_b32_sdwa v1, v3, v207 dst_sel:DWORD dst_unused:UNUSED_PAD src0_sel:WORD_1 src1_sel:DWORD
	v_and_b32_sdwa v6, v2, v207 dst_sel:DWORD dst_unused:UNUSED_PAD src0_sel:WORD_1 src1_sel:DWORD
	v_add3_u32 v2, v2, v6, s33
	v_add3_u32 v1, v3, v1, s33
	v_and_b32_sdwa v3, v5, v207 dst_sel:DWORD dst_unused:UNUSED_PAD src0_sel:WORD_1 src1_sel:DWORD
; __device__ __forceinline__ unsigned pk2(float lo, float hi) { return f2bf(lo) | (f2bf(hi) << 16); }
; __device__ __forceinline__ void dilated_block(const bf16_t* QKV, bf16_t* OG, float* LSE, LAS unsigned char* lds, int u, int tid) {
;     ...
;     const float inv = 1.f / lsum;
;     bf16_t* op = OG + ((size_t)g * SEQ + tq) * 512 + hs * 128 + 4 * slab;
; #pragma unroll
;     for (int c = 0; c < 8; ++c) { u32x2 o; o.x = pk2(oacc[c][0] * inv, oacc[c][1] * inv); o.y = pk2(oacc[c][2] * inv, oacc[c][3] * inv); *(u32x2*)(op + 16 * c) = o; }
	v_and_b32_sdwa v6, v4, v207 dst_sel:DWORD dst_unused:UNUSED_PAD src0_sel:WORD_1 src1_sel:DWORD
	v_add3_u32 v3, v5, v3, s33
	v_add3_u32 v4, v4, v6, s33
	v_and_b32_e32 v3, 0xffff0000, v3
	v_and_b32_e32 v4, 0xffff0000, v4
	v_or_b32_sdwa v3, v3, v1 dst_sel:DWORD dst_unused:UNUSED_PAD src0_sel:DWORD src1_sel:WORD_1
	v_or_b32_sdwa v2, v4, v2 dst_sel:DWORD dst_unused:UNUSED_PAD src0_sel:DWORD src1_sel:WORD_1
	global_store_dwordx2 v[18:19], v[2:3], off offset:96
	v_mov_b32_e32 v2, v22
	v_mov_b32_e32 v3, v24
	v_pk_mul_f32 v[2:3], v[0:1], v[2:3] op_sel_hi:[0,1]
	v_mov_b32_e32 v24, v23
	v_pk_mul_f32 v[4:5], v[0:1], v[24:25] op_sel_hi:[0,1]
	v_and_b32_sdwa v1, v3, v207 dst_sel:DWORD dst_unused:UNUSED_PAD src0_sel:WORD_1 src1_sel:DWORD
	v_and_b32_sdwa v6, v2, v207 dst_sel:DWORD dst_unused:UNUSED_PAD src0_sel:WORD_1 src1_sel:DWORD
	v_add3_u32 v2, v2, v6, s33
	v_add3_u32 v1, v3, v1, s33
	v_and_b32_sdwa v3, v5, v207 dst_sel:DWORD dst_unused:UNUSED_PAD src0_sel:WORD_1 src1_sel:DWORD
	v_and_b32_sdwa v6, v4, v207 dst_sel:DWORD dst_unused:UNUSED_PAD src0_sel:WORD_1 src1_sel:DWORD
	v_add3_u32 v3, v5, v3, s33
	v_add3_u32 v4, v4, v6, s33
	v_and_b32_e32 v3, 0xffff0000, v3
	v_and_b32_e32 v4, 0xffff0000, v4
	v_or_b32_sdwa v3, v3, v1 dst_sel:DWORD dst_unused:UNUSED_PAD src0_sel:DWORD src1_sel:WORD_1
	v_or_b32_sdwa v2, v4, v2 dst_sel:DWORD dst_unused:UNUSED_PAD src0_sel:DWORD src1_sel:WORD_1
	global_store_dwordx2 v[18:19], v[2:3], off offset:128
	v_mov_b32_e32 v2, v34
	v_mov_b32_e32 v3, v36
	v_pk_mul_f32 v[2:3], v[0:1], v[2:3] op_sel_hi:[0,1]
	v_mov_b32_e32 v36, v35
	v_pk_mul_f32 v[4:5], v[0:1], v[36:37] op_sel_hi:[0,1]
	v_and_b32_sdwa v1, v3, v207 dst_sel:DWORD dst_unused:UNUSED_PAD src0_sel:WORD_1 src1_sel:DWORD
	v_and_b32_sdwa v6, v2, v207 dst_sel:DWORD dst_unused:UNUSED_PAD src0_sel:WORD_1 src1_sel:DWORD
	v_add3_u32 v2, v2, v6, s33
	v_add3_u32 v1, v3, v1, s33
	v_and_b32_sdwa v3, v5, v207 dst_sel:DWORD dst_unused:UNUSED_PAD src0_sel:WORD_1 src1_sel:DWORD
	v_and_b32_sdwa v6, v4, v207 dst_sel:DWORD dst_unused:UNUSED_PAD src0_sel:WORD_1 src1_sel:DWORD
	v_add3_u32 v3, v5, v3, s33
	v_add3_u32 v4, v4, v6, s33
	v_and_b32_e32 v3, 0xffff0000, v3
	v_and_b32_e32 v4, 0xffff0000, v4
	v_or_b32_sdwa v3, v3, v1 dst_sel:DWORD dst_unused:UNUSED_PAD src0_sel:DWORD src1_sel:WORD_1
	v_or_b32_sdwa v2, v4, v2 dst_sel:DWORD dst_unused:UNUSED_PAD src0_sel:DWORD src1_sel:WORD_1
	global_store_dwordx2 v[18:19], v[2:3], off offset:160
	v_mov_b32_e32 v2, v30
	v_mov_b32_e32 v3, v32
	v_pk_mul_f32 v[2:3], v[0:1], v[2:3] op_sel_hi:[0,1]
	v_mov_b32_e32 v32, v31
	v_pk_mul_f32 v[4:5], v[0:1], v[32:33] op_sel_hi:[0,1]
	v_and_b32_sdwa v1, v3, v207 dst_sel:DWORD dst_unused:UNUSED_PAD src0_sel:WORD_1 src1_sel:DWORD
	v_and_b32_sdwa v6, v2, v207 dst_sel:DWORD dst_unused:UNUSED_PAD src0_sel:WORD_1 src1_sel:DWORD
	v_add3_u32 v2, v2, v6, s33
	v_add3_u32 v1, v3, v1, s33
	v_and_b32_sdwa v3, v5, v207 dst_sel:DWORD dst_unused:UNUSED_PAD src0_sel:WORD_1 src1_sel:DWORD
	v_and_b32_sdwa v6, v4, v207 dst_sel:DWORD dst_unused:UNUSED_PAD src0_sel:WORD_1 src1_sel:DWORD
	v_add3_u32 v3, v5, v3, s33
	v_add3_u32 v4, v4, v6, s33
	v_and_b32_e32 v3, 0xffff0000, v3
	v_and_b32_e32 v4, 0xffff0000, v4
	v_or_b32_sdwa v3, v3, v1 dst_sel:DWORD dst_unused:UNUSED_PAD src0_sel:DWORD src1_sel:WORD_1
	v_or_b32_sdwa v2, v4, v2 dst_sel:DWORD dst_unused:UNUSED_PAD src0_sel:DWORD src1_sel:WORD_1
	global_store_dwordx2 v[18:19], v[2:3], off offset:192
	v_mov_b32_e32 v2, v10
	v_mov_b32_e32 v3, v12
	v_pk_mul_f32 v[2:3], v[0:1], v[2:3] op_sel_hi:[0,1]
	v_mov_b32_e32 v12, v11
	v_pk_mul_f32 v[0:1], v[0:1], v[12:13] op_sel_hi:[0,1]
	v_and_b32_sdwa v4, v3, v207 dst_sel:DWORD dst_unused:UNUSED_PAD src0_sel:WORD_1 src1_sel:DWORD
	v_and_b32_sdwa v5, v2, v207 dst_sel:DWORD dst_unused:UNUSED_PAD src0_sel:WORD_1 src1_sel:DWORD
	v_add3_u32 v2, v2, v5, s33
	v_add3_u32 v3, v3, v4, s33
	v_and_b32_sdwa v4, v1, v207 dst_sel:DWORD dst_unused:UNUSED_PAD src0_sel:WORD_1 src1_sel:DWORD
	v_and_b32_sdwa v5, v0, v207 dst_sel:DWORD dst_unused:UNUSED_PAD src0_sel:WORD_1 src1_sel:DWORD
	v_add3_u32 v1, v1, v4, s33
	v_add3_u32 v0, v0, v5, s33
	v_writelane_b32 v252, s0, 56
	v_and_b32_e32 v1, 0xffff0000, v1
	v_and_b32_e32 v0, 0xffff0000, v0
	v_writelane_b32 v252, s1, 57
	v_or_b32_sdwa v1, v1, v3 dst_sel:DWORD dst_unused:UNUSED_PAD src0_sel:DWORD src1_sel:WORD_1
	v_or_b32_sdwa v0, v0, v2 dst_sel:DWORD dst_unused:UNUSED_PAD src0_sel:DWORD src1_sel:WORD_1
	global_store_dwordx2 v[18:19], v[0:1], off offset:224
	s_cbranch_scc1 .LBB0_220

; __device__ __forceinline__ float row16_sum(float v) { v += dpp_f<0x128>(v); v += dpp_f<0x124>(v); v += dpp_f<0x4E>(v); v += dpp_f<0xB1>(v); return v; }
; template <int NIT, bool F8>
; __device__ __forceinline__ void post_segment(bf16_t* seg, const float* gain, const float (&cs)[8], const float (&sn)[8], int c, int grp, unsigned char* k8 = nullptr) {
;     const f32x4 g0 = *(const f32x4*)(gain + 8 * c), g1 = *(const f32x4*)(gain + 8 * c + 4);
;     const float g[8] = {g0[0], g0[1], g0[2], g0[3], g1[0], g1[1], g1[2], g1[3]};
;     u32x4 raw[NIT];
; #pragma unroll
;     for (int it = 0; it < NIT; ++it) raw[it] = *(const u32x4*)(seg + (it * 4 + grp) * 128 + c * 8);
; #pragma unroll
;     for (int it = 0; it < NIT; ++it) {
;         const unsigned w[4] = {raw[it].x, raw[it].y, raw[it].z, raw[it].w}; float x[8];
; #pragma unroll
;         for (int i = 0; i < 4; ++i) { x[2 * i] = bf2f(w[i] & 0xffffu); x[2 * i + 1] = __builtin_bit_cast(float, w[i] & 0xffff0000u); }
;         float ss = 0.f;
; #pragma unroll
;         for (int e = 0; e < 8; ++e) ss += x[e] * x[e];
;         ss = row16_sum(ss); const float r = 1.f / sqrtf(ss * (1.f / 128.f) + EPS);
; __device__ __forceinline__ void post_token(int pos, const float* gaq, const float* gak, const float* gbq, const float* gbk, const float* gik, ...
;     const float pf = (float)pos; const int c = lane & 15, grp = lane >> 4; const float sgn = (c < 8) ? -1.f : 1.f;
;     float cs[8], sn[8];
; #pragma unroll
;     for (int e = 0; e < 8; ++e) { float s_; rope_cs(pf * INVF[8 * (c & 7) + e], cs[e], s_); sn[e] = s_ * sgn; }
.LBB0_1008:
	global_load_dword v52, v161, s[4:5]
	v_lshl_add_u64 v[20:21], s[90:91], 0, v[40:41]
	s_mov_b32 s0, 0x12302000
	v_add_co_u32_e32 v64, vcc, s0, v20
	s_mov_b32 s0, 0x12300000
	s_nop 0
	v_addc_co_u32_e32 v65, vcc, 0, v21, vcc
	global_load_dwordx4 v[16:19], v[64:65], off offset:3072
	global_load_dwordx4 v[8:11], v[24:25], off offset:16
	global_load_dwordx4 v[12:15], v[24:25], off
	v_add_co_u32_e32 v76, vcc, s0, v20
	s_mov_b32 s0, 0x12303000
	v_add_co_u32_e64 v22, s[0:1], s0, v20
	v_addc_co_u32_e32 v77, vcc, 0, v21, vcc
	s_nop 0
	v_addc_co_u32_e64 v23, vcc, 0, v21, s[0:1]
	global_load_dwordx4 v[54:57], v[22:23], off
	s_mov_b32 s0, 0x6dc9c883
	s_mov_b32 s1, 0x3fc45f30
	s_mov_b32 s8, 0xf800000
	s_waitcnt vmcnt(4)
	v_cvt_f32_i32_e32 v22, v52
	v_mul_f32_e32 v23, v2, v22
	v_mul_f32_e32 v52, v3, v22
	s_waitcnt vmcnt(3)
	v_lshlrev_b32_e32 v78, 16, v16
	v_and_b32_e32 v79, 0xffff0000, v16
	v_lshlrev_b32_e32 v82, 16, v18
	v_and_b32_e32 v83, 0xffff0000, v18
	v_mul_f32_e32 v16, v0, v22
	v_mul_f32_e32 v18, v1, v22
	v_mul_f32_e32 v58, v4, v22
	v_mul_f32_e32 v60, v5, v22
	v_mul_f32_e32 v62, v6, v22
	v_mul_f32_e32 v66, v7, v22
	v_lshlrev_b32_e32 v80, 16, v17
	v_and_b32_e32 v81, 0xffff0000, v17
	v_lshlrev_b32_e32 v84, 16, v19
	v_and_b32_e32 v85, 0xffff0000, v19
	v_cvt_f64_f32_e32 v[16:17], v16
	v_cvt_f64_f32_e32 v[18:19], v18
	v_cvt_f64_f32_e32 v[22:23], v23
	v_cvt_f64_f32_e32 v[52:53], v52
	v_cvt_f64_f32_e32 v[58:59], v58
	v_cvt_f64_f32_e32 v[60:61], v60
	v_cvt_f64_f32_e32 v[62:63], v62
	v_cvt_f64_f32_e32 v[66:67], v66
	v_mul_f64 v[68:69], v[16:17], s[0:1]
	v_mul_f64 v[70:71], v[18:19], s[0:1]
	v_mul_f64 v[72:73], v[22:23], s[0:1]
	v_mul_f64 v[74:75], v[52:53], s[0:1]
	v_mul_f64 v[86:87], v[58:59], s[0:1]
	v_mul_f64 v[88:89], v[60:61], s[0:1]
	v_mul_f64 v[90:91], v[62:63], s[0:1]
	v_mul_f64 v[92:93], v[66:67], s[0:1]
	v_rndne_f64_e32 v[68:69], v[68:69]
	v_rndne_f64_e32 v[70:71], v[70:71]
	v_rndne_f64_e32 v[72:73], v[72:73]
	v_rndne_f64_e32 v[74:75], v[74:75]
	v_rndne_f64_e32 v[86:87], v[86:87]
	v_rndne_f64_e32 v[88:89], v[88:89]
	v_rndne_f64_e32 v[90:91], v[90:91]
	v_rndne_f64_e32 v[92:93], v[92:93]
	v_fma_f64 v[16:17], v[16:17], s[0:1], -v[68:69]
	v_fma_f64 v[18:19], v[18:19], s[0:1], -v[70:71]
	v_fma_f64 v[22:23], v[22:23], s[0:1], -v[72:73]
	v_fma_f64 v[52:53], v[52:53], s[0:1], -v[74:75]
	v_fma_f64 v[58:59], v[58:59], s[0:1], -v[86:87]
	v_fma_f64 v[60:61], v[60:61], s[0:1], -v[88:89]
	v_fma_f64 v[62:63], v[62:63], s[0:1], -v[90:91]
	v_fma_f64 v[66:67], v[66:67], s[0:1], -v[92:93]
	s_mov_b32 s0, 0x12301000
	v_add_co_u32_e64 v74, s[0:1], s0, v20
	v_cvt_f32_f64_e32 v16, v[16:17]
	s_nop 0
	v_addc_co_u32_e64 v75, s[0:1], 0, v21, s[0:1]
	global_load_dwordx4 v[68:71], v[74:75], off offset:-4096
	v_cvt_f32_f64_e32 v17, v[18:19]
	v_cvt_f32_f64_e32 v18, v[22:23]
	v_cvt_f32_f64_e32 v22, v[58:59]
	v_cvt_f32_f64_e32 v23, v[60:61]
	v_cvt_f32_f64_e32 v61, v[66:67]
	v_sin_f32_e32 v66, v16
	v_cos_f32_e32 v58, v16
	v_mul_f32_e32 v16, v79, v79
	v_fmac_f32_e32 v16, v78, v78
	v_fmac_f32_e32 v16, v80, v80
	v_fmac_f32_e32 v16, v81, v81
	v_fmac_f32_e32 v16, v82, v82
	v_fmac_f32_e32 v16, v83, v83
	v_fmac_f32_e32 v16, v84, v84
	v_fmac_f32_e32 v16, v85, v85
	v_cvt_f32_f64_e32 v19, v[52:53]
	v_cvt_f32_f64_e32 v53, v[62:63]
	v_add_f32_dpp v16, v16, v16 row_ror:8 row_mask:0xf bank_mask:0xf bound_ctrl:1
	v_sin_f32_e32 v72, v17
	v_cos_f32_e32 v62, v17
	v_add_f32_dpp v16, v16, v16 row_ror:4 row_mask:0xf bank_mask:0xf bound_ctrl:1
	v_sin_f32_e32 v102, v18
	v_cos_f32_e32 v59, v18
	v_add_f32_dpp v16, v16, v16 quad_perm:[2,3,0,1] row_mask:0xf bank_mask:0xf bound_ctrl:1
	v_sin_f32_e32 v73, v19
	v_cos_f32_e32 v63, v19
	v_add_f32_dpp v16, v16, v16 quad_perm:[1,0,3,2] row_mask:0xf bank_mask:0xf bound_ctrl:1
	v_fmamk_f32 v16, v16, 0x3c000000, v205
	v_mul_f32_e32 v17, 0x4f800000, v16
	v_cmp_gt_f32_e32 vcc, s8, v16
	s_waitcnt vmcnt(1)
	v_and_b32_e32 v87, 0xffff0000, v54
	v_lshlrev_b32_e32 v88, 16, v55
	v_cndmask_b32_e32 v16, v16, v17, vcc
	v_sqrt_f32_e32 v17, v16
	v_and_b32_e32 v89, 0xffff0000, v55
	v_lshlrev_b32_e32 v90, 16, v56
	v_and_b32_e32 v91, 0xffff0000, v56
	v_add_u32_e32 v18, -1, v17
	v_fma_f32 v19, -v18, v17, v16
	v_cmp_ge_f32_e64 s[0:1], 0, v19
	v_add_u32_e32 v19, 1, v17
	v_lshlrev_b32_e32 v92, 16, v57
	v_cndmask_b32_e64 v18, v17, v18, s[0:1]
	v_fma_f32 v17, -v19, v17, v16
	v_cmp_lt_f32_e64 s[0:1], 0, v17
	v_and_b32_e32 v93, 0xffff0000, v57
	v_sin_f32_e32 v67, v22
	v_cndmask_b32_e64 v17, v18, v19, s[0:1]
	v_mul_f32_e32 v18, 0x37800000, v17
	v_cndmask_b32_e32 v17, v17, v18, vcc
	v_cmp_class_f32_e32 vcc, v16, v206
	v_cos_f32_e32 v52, v22
	v_sin_f32_e32 v104, v23
	v_cndmask_b32_e32 v94, v17, v16, vcc
	v_div_scale_f32 v96, s[0:1], v94, v94, 1.0
	v_rcp_f32_e32 v97, v96
	v_cos_f32_e32 v60, v23
	global_load_dwordx4 v[98:101], v[76:77], off offset:1024
	global_load_dwordx4 v[20:23], v[76:77], off offset:2048
	global_load_dwordx4 v[16:19], v[76:77], off offset:3072
	v_div_scale_f32 v106, vcc, 1.0, v94, 1.0
	v_fma_f32 v86, -v96, v97, 1.0
	v_fmac_f32_e32 v97, v86, v97
	v_lshlrev_b32_e32 v86, 16, v54
	v_mul_f32_e32 v54, v87, v87
	v_fmac_f32_e32 v54, v86, v86
	v_fmac_f32_e32 v54, v88, v88
	v_fmac_f32_e32 v54, v89, v89
	v_fmac_f32_e32 v54, v90, v90
	v_fmac_f32_e32 v54, v91, v91
	v_fmac_f32_e32 v54, v92, v92
	v_fmac_f32_e32 v54, v93, v93
	v_mul_f32_e32 v56, v106, v97
	v_fma_f32 v57, -v96, v56, v106
	v_add_f32_dpp v54, v54, v54 row_ror:8 row_mask:0xf bank_mask:0xf bound_ctrl:1
	v_fmac_f32_e32 v56, v57, v97
	v_sin_f32_e32 v103, v53
	v_add_f32_dpp v54, v54, v54 row_ror:4 row_mask:0xf bank_mask:0xf bound_ctrl:1
	v_sin_f32_e32 v105, v61
	s_waitcnt vmcnt(3)
; __device__ __forceinline__ unsigned pk2(float lo, float hi) { return f2bf(lo) | (f2bf(hi) << 16); }
; template <int CTRL> __device__ __forceinline__ float dpp_f(float v) { return __builtin_bit_cast(float, __builtin_amdgcn_update_dpp(0, __builtin_bit_cast(int, v), CTRL, 0xF, 0xF, true)); }
; __device__ __forceinline__ float row16_sum(float v) { v += dpp_f<0x128>(v); v += dpp_f<0x124>(v); v += dpp_f<0x4E>(v); v += dpp_f<0xB1>(v); return v; }
; template <int NIT, bool F8>
; __device__ __forceinline__ void post_segment(bf16_t* seg, const float* gain, const float (&cs)[8], const float (&sn)[8], int c, int grp, unsigned char* k8 = nullptr) {
;     ...
;     for (int it = 0; it < NIT; ++it) {
;         const unsigned w[4] = {raw[it].x, raw[it].y, raw[it].z, raw[it].w}; float x[8];
; #pragma unroll
;         for (int i = 0; i < 4; ++i) { x[2 * i] = bf2f(w[i] & 0xffffu); x[2 * i + 1] = __builtin_bit_cast(float, w[i] & 0xffff0000u); }
;         float ss = 0.f;
; #pragma unroll
;         for (int e = 0; e < 8; ++e) ss += x[e] * x[e];
;         ss = row16_sum(ss); const float r = 1.f / sqrtf(ss * (1.f / 128.f) + EPS);
;         float o[8];
; #pragma unroll
;         for (int e = 0; e < 8; ++e) { const float y = x[e] * r * g[e]; const float py = dpp_f<0x128>(y); o[e] = y * cs[e] + py * sn[e]; }
;         u32x4 ow; ow.x = pk2(o[0], o[1]); ow.y = pk2(o[2], o[3]); ow.z = pk2(o[4], o[5]); ow.w = pk2(o[6], o[7]);
;         if constexpr (F8) *(u32x2*)(k8 + (it * 4 + grp) * 128 + c * 8) = to_fp8x8(o);
;         else *(u32x4*)(seg + (it * 4 + grp) * 128 + c * 8) = ow;
	v_lshlrev_b32_e32 v108, 16, v70
	v_add_f32_dpp v54, v54, v54 quad_perm:[2,3,0,1] row_mask:0xf bank_mask:0xf bound_ctrl:1
	v_and_b32_e32 v110, 0xffff0000, v70
	v_lshlrev_b32_e32 v109, 16, v71
	v_add_f32_dpp v54, v54, v54 quad_perm:[1,0,3,2] row_mask:0xf bank_mask:0xf bound_ctrl:1
	v_fmamk_f32 v54, v54, 0x3c000000, v205
	v_mul_f32_e32 v55, 0x4f800000, v54
	v_cmp_gt_f32_e64 s[0:1], s8, v54
	v_and_b32_e32 v111, 0xffff0000, v71
	v_mov_b32_e32 v70, v110
	v_cndmask_b32_e64 v54, v54, v55, s[0:1]
	v_sqrt_f32_e32 v55, v54
	v_mov_b32_e32 v71, v108
	v_pk_mul_f32 v[70:71], v[70:71], v[70:71]
	v_mov_b32_e32 v112, v111
	v_add_u32_e32 v57, -1, v55
	v_fma_f32 v95, -v57, v55, v54
	v_cmp_ge_f32_e64 s[40:41], 0, v95
	v_add_u32_e32 v95, 1, v55
	v_mov_b32_e32 v113, v109
	v_cndmask_b32_e64 v57, v55, v57, s[40:41]
	v_fma_f32 v55, -v95, v55, v54
	v_cmp_lt_f32_e64 s[40:41], 0, v55
	v_pk_mul_f32 v[112:113], v[112:113], v[112:113]
	v_cos_f32_e32 v61, v61
	v_cndmask_b32_e64 v55, v57, v95, s[40:41]
	v_mul_f32_e32 v57, 0x37800000, v55
	v_cndmask_b32_e64 v55, v55, v57, s[0:1]
	v_cmp_class_f32_e64 s[0:1], v54, v206
	v_fma_f32 v57, -v96, v56, v106
	v_div_fmas_f32 v97, v57, v97, v56
	v_cndmask_b32_e64 v95, v55, v54, s[0:1]
	v_div_scale_f32 v54, s[0:1], v95, v95, 1.0
	v_rcp_f32_e32 v55, v54
	v_cos_f32_e32 v53, v53
	v_fma_f32 v56, -v54, v55, 1.0
	v_fmac_f32_e32 v55, v56, v55
	v_div_scale_f32 v56, vcc, 1.0, v95, 1.0
	v_mul_f32_e32 v57, v56, v55
	v_fma_f32 v96, -v54, v57, v56
	v_fmac_f32_e32 v57, v96, v55
	v_fma_f32 v54, -v54, v57, v56
	v_div_fmas_f32 v96, v54, v55, v57
	v_pk_mul_f32 v[54:55], v[34:35], v[66:67]
	v_pk_mul_f32 v[56:57], v[34:35], v[102:103]
	v_pk_mul_f32 v[66:67], v[34:35], v[72:73]
	v_lshlrev_b32_e32 v73, 16, v69
	v_lshlrev_b32_e32 v72, 16, v68
	v_and_b32_e32 v103, 0xffff0000, v69
	v_and_b32_e32 v102, 0xffff0000, v68
	v_pk_mul_f32 v[68:69], v[72:73], v[72:73]
	v_pk_mul_f32 v[106:107], v[102:103], v[102:103]
	s_nop 0
	v_add_f32_e32 v68, v68, v106
	v_add_f32_e32 v68, v69, v68
	v_add_f32_e32 v68, v107, v68
	v_add_f32_e32 v68, v71, v68
	v_add_f32_e32 v68, v70, v68
	v_add_f32_e32 v68, v113, v68
	v_add_f32_e32 v68, v112, v68
	v_mov_b32_e32 v106, v12
	v_mov_b32_e32 v107, v14
	v_add_f32_dpp v68, v68, v68 row_ror:8 row_mask:0xf bank_mask:0xf bound_ctrl:1
	v_mov_b32_e32 v14, v13
	v_mov_b32_e32 v70, v54
	v_add_f32_dpp v68, v68, v68 row_ror:4 row_mask:0xf bank_mask:0xf bound_ctrl:1
	v_mov_b32_e32 v71, v56
	s_nop 0
	v_add_f32_dpp v68, v68, v68 quad_perm:[2,3,0,1] row_mask:0xf bank_mask:0xf bound_ctrl:1
	s_nop 1
	v_add_f32_dpp v68, v68, v68 quad_perm:[1,0,3,2] row_mask:0xf bank_mask:0xf bound_ctrl:1
	v_fmamk_f32 v68, v68, 0x3c000000, v205
	v_mul_f32_e32 v69, 0x4f800000, v68
	v_cmp_gt_f32_e32 vcc, s8, v68
	s_nop 1
	v_cndmask_b32_e32 v68, v68, v69, vcc
	v_sqrt_f32_e32 v69, v68
	s_nop 0
	v_add_u32_e32 v12, -1, v69
	v_fma_f32 v13, -v12, v69, v68
	v_cmp_ge_f32_e64 s[0:1], 0, v13
	v_add_u32_e32 v13, 1, v69
	s_nop 0
	v_cndmask_b32_e64 v12, v69, v12, s[0:1]
	v_fma_f32 v69, -v13, v69, v68
	v_cmp_lt_f32_e64 s[0:1], 0, v69
	s_nop 1
	v_cndmask_b32_e64 v12, v12, v13, s[0:1]
	v_mul_f32_e32 v13, 0x37800000, v12
	v_cndmask_b32_e32 v12, v12, v13, vcc
	v_cmp_class_f32_e32 vcc, v68, v206
	s_nop 1
	v_cndmask_b32_e32 v12, v12, v68, vcc
	v_div_scale_f32 v13, s[0:1], v12, v12, 1.0
	v_rcp_f32_e32 v112, v13
	v_pk_mul_f32 v[68:69], v[34:35], v[104:105]
	v_fma_f32 v104, -v13, v112, 1.0
	v_fmac_f32_e32 v112, v104, v112
	v_div_scale_f32 v104, vcc, 1.0, v12, 1.0
	v_mul_f32_e32 v105, v104, v112
	v_fma_f32 v113, -v13, v105, v104
	v_fmac_f32_e32 v105, v113, v112
	v_fma_f32 v13, -v13, v105, v104
	v_div_fmas_f32 v13, v13, v112, v105
	v_div_fixup_f32 v12, v13, v12, 1.0
	v_pk_mul_f32 v[102:103], v[12:13], v[102:103] op_sel_hi:[0,1]
	v_pk_mul_f32 v[102:103], v[14:15], v[102:103]
	v_pk_mul_f32 v[72:73], v[12:13], v[72:73] op_sel_hi:[0,1]
	v_pk_mul_f32 v[108:109], v[12:13], v[108:109] op_sel_hi:[0,1]
	v_mov_b32_dpp v112, v102 row_ror:8 row_mask:0xf bank_mask:0xf bound_ctrl:1
	v_mov_b32_dpp v113, v103 row_ror:8 row_mask:0xf bank_mask:0xf bound_ctrl:1
	v_pk_mul_f32 v[102:103], v[62:63], v[102:103]
	v_pk_mul_f32 v[12:13], v[12:13], v[110:111] op_sel_hi:[0,1]
	v_pk_fma_f32 v[102:103], v[66:67], v[112:113], v[102:103]
	v_mov_b32_e32 v113, v10
	v_mov_b32_e32 v10, v9
	v_pk_mul_f32 v[72:73], v[106:107], v[72:73]
	v_mov_b32_e32 v112, v8
	v_pk_mul_f32 v[12:13], v[10:11], v[12:13]
	v_mov_b32_dpp v104, v72 row_ror:8 row_mask:0xf bank_mask:0xf bound_ctrl:1
	v_mov_b32_dpp v105, v73 row_ror:8 row_mask:0xf bank_mask:0xf bound_ctrl:1
	v_pk_mul_f32 v[72:73], v[58:59], v[72:73]
	v_pk_mul_f32 v[108:109], v[112:113], v[108:109]
	v_mov_b32_dpp v110, v12 row_ror:8 row_mask:0xf bank_mask:0xf bound_ctrl:1
	v_mov_b32_dpp v111, v13 row_ror:8 row_mask:0xf bank_mask:0xf bound_ctrl:1
	v_pk_mul_f32 v[12:13], v[60:61], v[12:13]
	v_mov_b32_dpp v8, v108 row_ror:8 row_mask:0xf bank_mask:0xf bound_ctrl:1
	v_mov_b32_dpp v9, v109 row_ror:8 row_mask:0xf bank_mask:0xf bound_ctrl:1
	v_pk_mul_f32 v[108:109], v[52:53], v[108:109]
	v_pk_fma_f32 v[12:13], v[68:69], v[110:111], v[12:13]
	v_pk_fma_f32 v[104:105], v[70:71], v[104:105], v[72:73]
	v_mov_b32_e32 v72, v55
	v_mov_b32_e32 v73, v57
	v_pk_fma_f32 v[8:9], v[72:73], v[8:9], v[108:109]
	v_bfe_u32 v108, v13, 16, 1
	v_bfe_u32 v109, v12, 16, 1
	v_bfe_u32 v110, v103, 16, 1
	v_bfe_u32 v111, v102, 16, 1
	v_add3_u32 v114, v102, v111, s33
	v_add3_u32 v115, v103, v110, s33
	v_add3_u32 v116, v12, v109, s33
	v_add3_u32 v117, v13, v108, s33
	v_bfe_u32 v12, v104, 16, 1
	v_bfe_u32 v13, v105, 16, 1
	v_bfe_u32 v102, v8, 16, 1
	v_bfe_u32 v103, v9, 16, 1
	v_add3_u32 v118, v9, v103, s33
	v_add3_u32 v8, v8, v102, s33
	v_add3_u32 v9, v105, v13, s33
	v_add3_u32 v12, v104, v12, s33
	v_lshrrev_b32_e32 v119, 16, v12
	v_lshrrev_b32_e32 v120, 16, v9
	v_lshrrev_b32_e32 v121, 16, v8
	s_waitcnt vmcnt(2)
; __device__ __forceinline__ unsigned pk2(float lo, float hi) { return f2bf(lo) | (f2bf(hi) << 16); }
; template <int CTRL> __device__ __forceinline__ float dpp_f(float v) { return __builtin_bit_cast(float, __builtin_amdgcn_update_dpp(0, __builtin_bit_cast(int, v), CTRL, 0xF, 0xF, true)); }
; __device__ __forceinline__ float row16_sum(float v) { v += dpp_f<0x128>(v); v += dpp_f<0x124>(v); v += dpp_f<0x4E>(v); v += dpp_f<0xB1>(v); return v; }
; template <int NIT, bool F8>
; __device__ __forceinline__ void post_segment(bf16_t* seg, const float* gain, const float (&cs)[8], const float (&sn)[8], int c, int grp, unsigned char* k8 = nullptr) {
;     ...
;     for (int it = 0; it < NIT; ++it) {
;         const unsigned w[4] = {raw[it].x, raw[it].y, raw[it].z, raw[it].w}; float x[8];
; #pragma unroll
;         for (int i = 0; i < 4; ++i) { x[2 * i] = bf2f(w[i] & 0xffffu); x[2 * i + 1] = __builtin_bit_cast(float, w[i] & 0xffff0000u); }
;         float ss = 0.f;
; #pragma unroll
;         for (int e = 0; e < 8; ++e) ss += x[e] * x[e];
;         ss = row16_sum(ss); const float r = 1.f / sqrtf(ss * (1.f / 128.f) + EPS);
;         float o[8];
; #pragma unroll
;         for (int e = 0; e < 8; ++e) { const float y = x[e] * r * g[e]; const float py = dpp_f<0x128>(y); o[e] = y * cs[e] + py * sn[e]; }
;         u32x4 ow; ow.x = pk2(o[0], o[1]); ow.y = pk2(o[2], o[3]); ow.z = pk2(o[4], o[5]); ow.w = pk2(o[6], o[7]);
;         if constexpr (F8) *(u32x2*)(k8 + (it * 4 + grp) * 128 + c * 8) = to_fp8x8(o);
;         else *(u32x4*)(seg + (it * 4 + grp) * 128 + c * 8) = ow;
	v_lshlrev_b32_e32 v9, 16, v99
	v_lshlrev_b32_e32 v8, 16, v98
	v_and_b32_e32 v13, 0xffff0000, v99
	v_and_b32_e32 v12, 0xffff0000, v98
	v_pk_mul_f32 v[98:99], v[8:9], v[8:9]
	v_pk_mul_f32 v[102:103], v[12:13], v[12:13]
	v_lshlrev_b32_e32 v104, 16, v100
	v_and_b32_e32 v108, 0xffff0000, v100
	v_add_f32_e32 v98, v98, v102
	v_lshlrev_b32_e32 v105, 16, v101
	v_and_b32_e32 v109, 0xffff0000, v101
	v_mov_b32_e32 v100, v108
	v_mov_b32_e32 v101, v104
	v_add_f32_e32 v98, v99, v98
	v_pk_mul_f32 v[100:101], v[100:101], v[100:101]
	v_add_f32_e32 v98, v103, v98
	v_mov_b32_e32 v110, v109
	v_mov_b32_e32 v111, v105
	v_add_f32_e32 v98, v101, v98
	v_pk_mul_f32 v[110:111], v[110:111], v[110:111]
	v_add_f32_e32 v98, v100, v98
	v_add_f32_e32 v98, v111, v98
	v_add_f32_e32 v98, v110, v98
	v_lshrrev_b32_e32 v100, 16, v118
	v_and_or_b32 v101, v117, s67, v100
	v_add_f32_dpp v98, v98, v98 row_ror:8 row_mask:0xf bank_mask:0xf bound_ctrl:1
	v_and_or_b32 v100, v116, s67, v121
	s_nop 0
	v_add_f32_dpp v98, v98, v98 row_ror:4 row_mask:0xf bank_mask:0xf bound_ctrl:1
	s_nop 1
	v_add_f32_dpp v98, v98, v98 quad_perm:[2,3,0,1] row_mask:0xf bank_mask:0xf bound_ctrl:1
	s_nop 1
	v_add_f32_dpp v98, v98, v98 quad_perm:[1,0,3,2] row_mask:0xf bank_mask:0xf bound_ctrl:1
	v_fmamk_f32 v98, v98, 0x3c000000, v205
	v_mul_f32_e32 v99, 0x4f800000, v98
	v_cmp_gt_f32_e32 vcc, s8, v98
	s_nop 1
	v_cndmask_b32_e32 v98, v98, v99, vcc
	v_sqrt_f32_e32 v99, v98
	s_nop 0
	v_add_u32_e32 v102, -1, v99
	v_fma_f32 v103, -v102, v99, v98
	v_cmp_ge_f32_e64 s[0:1], 0, v103
	v_add_u32_e32 v103, 1, v99
	s_nop 0
	v_cndmask_b32_e64 v102, v99, v102, s[0:1]
	v_fma_f32 v99, -v103, v99, v98
	v_cmp_lt_f32_e64 s[0:1], 0, v99
	s_nop 1
	v_cndmask_b32_e64 v99, v102, v103, s[0:1]
	v_mul_f32_e32 v102, 0x37800000, v99
	v_cndmask_b32_e32 v99, v99, v102, vcc
	v_cmp_class_f32_e32 vcc, v98, v206
	s_nop 1
	v_cndmask_b32_e32 v102, v99, v98, vcc
	v_div_scale_f32 v103, s[0:1], v102, v102, 1.0
	v_rcp_f32_e32 v110, v103
	v_and_or_b32 v99, v115, s67, v120
	v_and_or_b32 v98, v114, s67, v119
	global_store_dwordx4 v[74:75], v[98:101], off offset:-4096
	s_nop 1
	v_fma_f32 v98, -v103, v110, 1.0
	v_fmac_f32_e32 v110, v98, v110
	v_div_scale_f32 v98, vcc, 1.0, v102, 1.0
	v_mul_f32_e32 v99, v98, v110
	v_fma_f32 v100, -v103, v99, v98
	v_fmac_f32_e32 v99, v100, v110
	v_fma_f32 v98, -v103, v99, v98
	v_div_fmas_f32 v98, v98, v110, v99
	v_div_fixup_f32 v98, v98, v102, 1.0
	v_pk_mul_f32 v[8:9], v[98:99], v[8:9] op_sel_hi:[0,1]
	v_pk_mul_f32 v[12:13], v[98:99], v[12:13] op_sel_hi:[0,1]
	v_pk_mul_f32 v[104:105], v[98:99], v[104:105] op_sel_hi:[0,1]
	v_pk_mul_f32 v[98:99], v[98:99], v[108:109] op_sel_hi:[0,1]
	v_pk_mul_f32 v[12:13], v[14:15], v[12:13]
	v_pk_mul_f32 v[98:99], v[10:11], v[98:99]
	v_pk_mul_f32 v[8:9], v[106:107], v[8:9]
	v_mov_b32_dpp v102, v12 row_ror:8 row_mask:0xf bank_mask:0xf bound_ctrl:1
	v_mov_b32_dpp v103, v13 row_ror:8 row_mask:0xf bank_mask:0xf bound_ctrl:1
	v_pk_mul_f32 v[12:13], v[62:63], v[12:13]
	v_pk_mul_f32 v[104:105], v[112:113], v[104:105]
	v_mov_b32_dpp v108, v98 row_ror:8 row_mask:0xf bank_mask:0xf bound_ctrl:1
	v_mov_b32_dpp v109, v99 row_ror:8 row_mask:0xf bank_mask:0xf bound_ctrl:1
	v_mov_b32_dpp v100, v8 row_ror:8 row_mask:0xf bank_mask:0xf bound_ctrl:1
	v_mov_b32_dpp v101, v9 row_ror:8 row_mask:0xf bank_mask:0xf bound_ctrl:1
	v_pk_mul_f32 v[8:9], v[58:59], v[8:9]
	v_mov_b32_dpp v110, v104 row_ror:8 row_mask:0xf bank_mask:0xf bound_ctrl:1
	v_mov_b32_dpp v111, v105 row_ror:8 row_mask:0xf bank_mask:0xf bound_ctrl:1
	v_pk_fma_f32 v[12:13], v[66:67], v[102:103], v[12:13]
	v_pk_mul_f32 v[102:103], v[68:69], v[108:109]
	v_pk_fma_f32 v[8:9], v[70:71], v[100:101], v[8:9]
	v_pk_fma_f32 v[98:99], v[60:61], v[98:99], v[102:103]
	v_pk_mul_f32 v[100:101], v[72:73], v[110:111]
	v_bfe_u32 v102, v13, 16, 1
	v_pk_fma_f32 v[100:101], v[52:53], v[104:105], v[100:101]
	v_bfe_u32 v103, v12, 16, 1
	v_bfe_u32 v104, v99, 16, 1
	v_bfe_u32 v105, v98, 16, 1
	v_add3_u32 v108, v98, v105, s33
	v_add3_u32 v109, v99, v104, s33
	v_add3_u32 v110, v12, v103, s33
	v_add3_u32 v111, v13, v102, s33
	v_bfe_u32 v12, v100, 16, 1
	v_bfe_u32 v13, v101, 16, 1
	v_bfe_u32 v98, v8, 16, 1
	v_bfe_u32 v99, v9, 16, 1
	v_add3_u32 v114, v9, v99, s33
	v_add3_u32 v8, v8, v98, s33
	v_add3_u32 v9, v101, v13, s33
	v_add3_u32 v12, v100, v12, s33
	v_lshrrev_b32_e32 v115, 16, v12
	v_lshrrev_b32_e32 v116, 16, v9
	v_lshrrev_b32_e32 v117, 16, v8
	s_waitcnt vmcnt(2)
	v_lshlrev_b32_e32 v9, 16, v21
	v_lshlrev_b32_e32 v8, 16, v20
	v_and_b32_e32 v13, 0xffff0000, v21
	v_and_b32_e32 v12, 0xffff0000, v20
	v_pk_mul_f32 v[20:21], v[8:9], v[8:9]
	v_pk_mul_f32 v[98:99], v[12:13], v[12:13]
	v_lshlrev_b32_e32 v100, 16, v22
	v_and_b32_e32 v102, 0xffff0000, v22
	v_add_f32_e32 v20, v20, v98
	v_lshlrev_b32_e32 v101, 16, v23
	v_and_b32_e32 v103, 0xffff0000, v23
	v_mov_b32_e32 v22, v102
	v_mov_b32_e32 v23, v100
	v_add_f32_e32 v20, v21, v20
	v_pk_mul_f32 v[22:23], v[22:23], v[22:23]
	v_add_f32_e32 v20, v99, v20
	v_mov_b32_e32 v104, v103
	v_mov_b32_e32 v105, v101
	v_add_f32_e32 v20, v23, v20
	v_pk_mul_f32 v[104:105], v[104:105], v[104:105]
	v_add_f32_e32 v20, v22, v20
	v_add_f32_e32 v20, v105, v20
	v_add_f32_e32 v20, v104, v20
	s_waitcnt vmcnt(1)
; __device__ __forceinline__ unsigned pk2(float lo, float hi) { return f2bf(lo) | (f2bf(hi) << 16); }
; template <int CTRL> __device__ __forceinline__ float dpp_f(float v) { return __builtin_bit_cast(float, __builtin_amdgcn_update_dpp(0, __builtin_bit_cast(int, v), CTRL, 0xF, 0xF, true)); }
; __device__ __forceinline__ float row16_sum(float v) { v += dpp_f<0x128>(v); v += dpp_f<0x124>(v); v += dpp_f<0x4E>(v); v += dpp_f<0xB1>(v); return v; }
; template <int NIT, bool F8>
; __device__ __forceinline__ void post_segment(bf16_t* seg, const float* gain, const float (&cs)[8], const float (&sn)[8], int c, int grp, unsigned char* k8 = nullptr) {
;     ...
;     for (int it = 0; it < NIT; ++it) {
;         const unsigned w[4] = {raw[it].x, raw[it].y, raw[it].z, raw[it].w}; float x[8];
; #pragma unroll
;         for (int i = 0; i < 4; ++i) { x[2 * i] = bf2f(w[i] & 0xffffu); x[2 * i + 1] = __builtin_bit_cast(float, w[i] & 0xffff0000u); }
;         float ss = 0.f;
; #pragma unroll
;         for (int e = 0; e < 8; ++e) ss += x[e] * x[e];
;         ss = row16_sum(ss); const float r = 1.f / sqrtf(ss * (1.f / 128.f) + EPS);
;         float o[8];
; #pragma unroll
;         for (int e = 0; e < 8; ++e) { const float y = x[e] * r * g[e]; const float py = dpp_f<0x128>(y); o[e] = y * cs[e] + py * sn[e]; }
;         u32x4 ow; ow.x = pk2(o[0], o[1]); ow.y = pk2(o[2], o[3]); ow.z = pk2(o[4], o[5]); ow.w = pk2(o[6], o[7]);
;         if constexpr (F8) *(u32x2*)(k8 + (it * 4 + grp) * 128 + c * 8) = to_fp8x8(o);
;         else *(u32x4*)(seg + (it * 4 + grp) * 128 + c * 8) = ow;
	v_and_b32_e32 v105, 0xffff0000, v17
	v_add_f32_dpp v20, v20, v20 row_ror:8 row_mask:0xf bank_mask:0xf bound_ctrl:1
	s_nop 1
	v_add_f32_dpp v20, v20, v20 row_ror:4 row_mask:0xf bank_mask:0xf bound_ctrl:1
	s_nop 1
	v_add_f32_dpp v20, v20, v20 quad_perm:[2,3,0,1] row_mask:0xf bank_mask:0xf bound_ctrl:1
	s_nop 1
	v_add_f32_dpp v20, v20, v20 quad_perm:[1,0,3,2] row_mask:0xf bank_mask:0xf bound_ctrl:1
	v_fmamk_f32 v20, v20, 0x3c000000, v205
	v_mul_f32_e32 v21, 0x4f800000, v20
	v_cmp_gt_f32_e32 vcc, s8, v20
	s_nop 1
	v_cndmask_b32_e32 v22, v20, v21, vcc
	v_sqrt_f32_e32 v23, v22
	v_lshrrev_b32_e32 v20, 16, v114
	v_and_or_b32 v21, v111, s67, v20
	v_and_or_b32 v20, v110, s67, v117
	v_add_u32_e32 v98, -1, v23
	v_fma_f32 v99, -v98, v23, v22
	v_cmp_ge_f32_e64 s[0:1], 0, v99
	v_add_u32_e32 v99, 1, v23
	s_nop 0
	v_cndmask_b32_e64 v98, v23, v98, s[0:1]
	v_fma_f32 v23, -v99, v23, v22
	v_cmp_lt_f32_e64 s[0:1], 0, v23
	s_nop 1
	v_cndmask_b32_e64 v23, v98, v99, s[0:1]
	v_mul_f32_e32 v98, 0x37800000, v23
	v_cndmask_b32_e32 v23, v23, v98, vcc
	v_cmp_class_f32_e32 vcc, v22, v206
	s_nop 1
	v_cndmask_b32_e32 v98, v23, v22, vcc
	v_div_scale_f32 v99, s[0:1], v98, v98, 1.0
	v_rcp_f32_e32 v104, v99
	v_and_or_b32 v23, v109, s67, v116
	v_and_or_b32 v22, v108, s67, v115
	global_store_dwordx4 v[76:77], v[20:23], off offset:1024
	v_and_b32_e32 v108, 0xffff0000, v18
	v_and_b32_e32 v109, 0xffff0000, v19
	v_fma_f32 v20, -v99, v104, 1.0
	v_fmac_f32_e32 v104, v20, v104
	v_div_scale_f32 v20, vcc, 1.0, v98, 1.0
	v_mul_f32_e32 v21, v20, v104
	v_fma_f32 v22, -v99, v21, v20
	v_fmac_f32_e32 v21, v22, v104
	v_fma_f32 v20, -v99, v21, v20
	v_div_fmas_f32 v20, v20, v104, v21
	v_div_fixup_f32 v20, v20, v98, 1.0
	v_pk_mul_f32 v[8:9], v[20:21], v[8:9] op_sel_hi:[0,1]
	v_pk_mul_f32 v[12:13], v[20:21], v[12:13] op_sel_hi:[0,1]
	v_pk_mul_f32 v[98:99], v[20:21], v[100:101] op_sel_hi:[0,1]
	v_pk_mul_f32 v[20:21], v[20:21], v[102:103] op_sel_hi:[0,1]
	v_pk_mul_f32 v[12:13], v[14:15], v[12:13]
	v_pk_mul_f32 v[10:11], v[10:11], v[20:21]
	v_pk_mul_f32 v[98:99], v[112:113], v[98:99]
	v_mov_b32_dpp v14, v12 row_ror:8 row_mask:0xf bank_mask:0xf bound_ctrl:1
	v_mov_b32_dpp v15, v13 row_ror:8 row_mask:0xf bank_mask:0xf bound_ctrl:1
	v_pk_mul_f32 v[12:13], v[62:63], v[12:13]
	v_mov_b32_dpp v20, v10 row_ror:8 row_mask:0xf bank_mask:0xf bound_ctrl:1
	v_mov_b32_dpp v21, v11 row_ror:8 row_mask:0xf bank_mask:0xf bound_ctrl:1
	v_pk_mul_f32 v[8:9], v[106:107], v[8:9]
	v_mov_b32_dpp v100, v98 row_ror:8 row_mask:0xf bank_mask:0xf bound_ctrl:1
	v_mov_b32_dpp v101, v99 row_ror:8 row_mask:0xf bank_mask:0xf bound_ctrl:1
	v_pk_fma_f32 v[12:13], v[66:67], v[14:15], v[12:13]
	v_pk_mul_f32 v[14:15], v[68:69], v[20:21]
	v_mov_b32_dpp v22, v8 row_ror:8 row_mask:0xf bank_mask:0xf bound_ctrl:1
	v_mov_b32_dpp v23, v9 row_ror:8 row_mask:0xf bank_mask:0xf bound_ctrl:1
	v_pk_mul_f32 v[8:9], v[58:59], v[8:9]
	v_pk_fma_f32 v[10:11], v[60:61], v[10:11], v[14:15]
	v_pk_mul_f32 v[14:15], v[72:73], v[100:101]
	v_pk_fma_f32 v[8:9], v[70:71], v[22:23], v[8:9]
	v_pk_fma_f32 v[14:15], v[52:53], v[98:99], v[14:15]
	v_cvt_pk_bf16_f32 v9, v9, v13
	v_cvt_pk_bf16_f32 v8, v8, v12
	v_cvt_pk_bf16_f32 v11, v15, v11
	v_cvt_pk_bf16_f32 v10, v14, v10
	global_store_dwordx4 v[76:77], v[8:11], off offset:2048
	global_load_dwordx4 v[20:23], v[26:27], off
	global_load_dwordx4 v[12:15], v[26:27], off offset:16
	global_load_dwordx4 v[98:101], v[74:75], off
	v_lshlrev_b32_e32 v103, 16, v17
	v_lshlrev_b32_e32 v102, 16, v16
	v_and_b32_e32 v104, 0xffff0000, v16
	v_pk_mul_f32 v[8:9], v[102:103], v[102:103]
	v_pk_mul_f32 v[10:11], v[104:105], v[104:105]
	v_lshlrev_b32_e32 v106, 16, v18
	v_add_f32_e32 v8, v8, v10
	v_mov_b32_e32 v16, v108
	v_mov_b32_e32 v17, v106
	v_add_f32_e32 v8, v9, v8
	v_lshlrev_b32_e32 v107, 16, v19
	v_pk_mul_f32 v[16:17], v[16:17], v[16:17]
	v_add_f32_e32 v8, v11, v8
	v_mov_b32_e32 v18, v109
	v_mov_b32_e32 v19, v107
	v_add_f32_e32 v8, v17, v8
	v_pk_mul_f32 v[18:19], v[18:19], v[18:19]
	v_add_f32_e32 v8, v16, v8
	v_add_f32_e32 v8, v19, v8
	v_add_f32_e32 v8, v18, v8
	s_nop 1
	v_add_f32_dpp v8, v8, v8 row_ror:8 row_mask:0xf bank_mask:0xf bound_ctrl:1
	s_nop 1
	v_add_f32_dpp v8, v8, v8 row_ror:4 row_mask:0xf bank_mask:0xf bound_ctrl:1
	s_nop 1
	v_add_f32_dpp v8, v8, v8 quad_perm:[2,3,0,1] row_mask:0xf bank_mask:0xf bound_ctrl:1
	s_nop 1
	v_add_f32_dpp v8, v8, v8 quad_perm:[1,0,3,2] row_mask:0xf bank_mask:0xf bound_ctrl:1
	v_fmamk_f32 v8, v8, 0x3c000000, v205
	v_mul_f32_e32 v9, 0x4f800000, v8
	v_cmp_gt_f32_e32 vcc, s8, v8
	s_nop 1
	v_cndmask_b32_e32 v110, v8, v9, vcc
	v_sqrt_f32_e32 v111, v110
	global_load_dwordx4 v[8:11], v[64:65], off offset:1024
	global_load_dwordx4 v[16:19], v[74:75], off offset:1024
	v_add_u32_e32 v112, -1, v111
	v_fma_f32 v113, -v112, v111, v110
	v_cmp_ge_f32_e64 s[0:1], 0, v113
	v_add_u32_e32 v113, 1, v111
	s_nop 0
	v_cndmask_b32_e64 v112, v111, v112, s[0:1]
	v_fma_f32 v111, -v113, v111, v110
	v_cmp_lt_f32_e64 s[0:1], 0, v111
	s_nop 1
	v_cndmask_b32_e64 v111, v112, v113, s[0:1]
	v_mul_f32_e32 v112, 0x37800000, v111
	v_cndmask_b32_e32 v111, v111, v112, vcc
	v_cmp_class_f32_e32 vcc, v110, v206
	s_nop 1
	v_cndmask_b32_e32 v112, v111, v110, vcc
	v_div_scale_f32 v113, s[0:1], v112, v112, 1.0
	v_rcp_f32_e32 v114, v113
	s_waitcnt vmcnt(4)
; __device__ __forceinline__ unsigned pk2(float lo, float hi) { return f2bf(lo) | (f2bf(hi) << 16); }
; template <int CTRL> __device__ __forceinline__ float dpp_f(float v) { return __builtin_bit_cast(float, __builtin_amdgcn_update_dpp(0, __builtin_bit_cast(int, v), CTRL, 0xF, 0xF, true)); }
; __device__ __forceinline__ float row16_sum(float v) { v += dpp_f<0x128>(v); v += dpp_f<0x124>(v); v += dpp_f<0x4E>(v); v += dpp_f<0xB1>(v); return v; }
; template <int NIT, bool F8>
; __device__ __forceinline__ void post_segment(bf16_t* seg, const float* gain, const float (&cs)[8], const float (&sn)[8], int c, int grp, unsigned char* k8 = nullptr) {
;     ...
;     for (int it = 0; it < NIT; ++it) {
;         const unsigned w[4] = {raw[it].x, raw[it].y, raw[it].z, raw[it].w}; float x[8];
; #pragma unroll
;         for (int i = 0; i < 4; ++i) { x[2 * i] = bf2f(w[i] & 0xffffu); x[2 * i + 1] = __builtin_bit_cast(float, w[i] & 0xffff0000u); }
;         float ss = 0.f;
; #pragma unroll
;         for (int e = 0; e < 8; ++e) ss += x[e] * x[e];
;         ss = row16_sum(ss); const float r = 1.f / sqrtf(ss * (1.f / 128.f) + EPS);
;         float o[8];
; #pragma unroll
;         for (int e = 0; e < 8; ++e) { const float y = x[e] * r * g[e]; const float py = dpp_f<0x128>(y); o[e] = y * cs[e] + py * sn[e]; }
;         u32x4 ow; ow.x = pk2(o[0], o[1]); ow.y = pk2(o[2], o[3]); ow.z = pk2(o[4], o[5]); ow.w = pk2(o[6], o[7]);
;         if constexpr (F8) *(u32x2*)(k8 + (it * 4 + grp) * 128 + c * 8) = to_fp8x8(o);
;         else *(u32x4*)(seg + (it * 4 + grp) * 128 + c * 8) = ow;
	v_mov_b32_e32 v110, v20
	v_fma_f32 v20, -v113, v114, 1.0
	v_fmac_f32_e32 v114, v20, v114
	v_div_scale_f32 v20, vcc, 1.0, v112, 1.0
	v_mov_b32_e32 v111, v22
	v_mov_b32_e32 v22, v21
	v_mul_f32_e32 v21, v20, v114
	v_fma_f32 v115, -v113, v21, v20
	v_fmac_f32_e32 v21, v115, v114
	v_fma_f32 v20, -v113, v21, v20
	v_div_fmas_f32 v20, v20, v114, v21
	v_div_fixup_f32 v20, v20, v112, 1.0
	v_pk_mul_f32 v[102:103], v[20:21], v[102:103] op_sel_hi:[0,1]
	v_pk_mul_f32 v[102:103], v[110:111], v[102:103]
	v_pk_mul_f32 v[104:105], v[20:21], v[104:105] op_sel_hi:[0,1]
	v_pk_mul_f32 v[106:107], v[20:21], v[106:107] op_sel_hi:[0,1]
	v_pk_mul_f32 v[20:21], v[20:21], v[108:109] op_sel_hi:[0,1]
	v_mov_b32_dpp v108, v102 row_ror:8 row_mask:0xf bank_mask:0xf bound_ctrl:1
	v_mov_b32_dpp v109, v103 row_ror:8 row_mask:0xf bank_mask:0xf bound_ctrl:1
	v_pk_mul_f32 v[102:103], v[58:59], v[102:103]
	v_pk_mul_f32 v[104:105], v[22:23], v[104:105]
	v_pk_fma_f32 v[102:103], v[70:71], v[108:109], v[102:103]
	s_waitcnt vmcnt(3)
	v_mov_b32_e32 v109, v14
	v_mov_b32_e32 v14, v13
	v_mov_b32_dpp v112, v104 row_ror:8 row_mask:0xf bank_mask:0xf bound_ctrl:1
	v_mov_b32_dpp v113, v105 row_ror:8 row_mask:0xf bank_mask:0xf bound_ctrl:1
	v_pk_mul_f32 v[104:105], v[62:63], v[104:105]
	v_mov_b32_e32 v108, v12
	v_pk_mul_f32 v[20:21], v[14:15], v[20:21]
	v_pk_fma_f32 v[104:105], v[66:67], v[112:113], v[104:105]
	v_pk_mul_f32 v[106:107], v[108:109], v[106:107]
	v_mov_b32_dpp v112, v20 row_ror:8 row_mask:0xf bank_mask:0xf bound_ctrl:1
	v_mov_b32_dpp v113, v21 row_ror:8 row_mask:0xf bank_mask:0xf bound_ctrl:1
	v_pk_mul_f32 v[20:21], v[60:61], v[20:21]
	v_mov_b32_dpp v12, v106 row_ror:8 row_mask:0xf bank_mask:0xf bound_ctrl:1
	v_mov_b32_dpp v13, v107 row_ror:8 row_mask:0xf bank_mask:0xf bound_ctrl:1
	v_pk_mul_f32 v[106:107], v[52:53], v[106:107]
	v_pk_fma_f32 v[20:21], v[68:69], v[112:113], v[20:21]
	v_pk_fma_f32 v[12:13], v[72:73], v[12:13], v[106:107]
	v_bfe_u32 v106, v21, 16, 1
	v_bfe_u32 v107, v20, 16, 1
	v_bfe_u32 v112, v105, 16, 1
	v_bfe_u32 v113, v104, 16, 1
	v_add3_u32 v114, v104, v113, s33
	v_add3_u32 v115, v105, v112, s33
	v_add3_u32 v116, v20, v107, s33
	v_add3_u32 v117, v21, v106, s33
	v_bfe_u32 v20, v102, 16, 1
	v_bfe_u32 v21, v103, 16, 1
	v_bfe_u32 v104, v12, 16, 1
	v_bfe_u32 v105, v13, 16, 1
	v_add3_u32 v118, v13, v105, s33
	v_add3_u32 v12, v12, v104, s33
	v_add3_u32 v13, v103, v21, s33
	v_add3_u32 v20, v102, v20, s33
	v_lshrrev_b32_e32 v119, 16, v20
	v_lshrrev_b32_e32 v120, 16, v13
	v_lshrrev_b32_e32 v121, 16, v12
	s_waitcnt vmcnt(2)
	v_lshlrev_b32_e32 v13, 16, v99
	v_lshlrev_b32_e32 v12, 16, v98
	v_and_b32_e32 v21, 0xffff0000, v99
	v_and_b32_e32 v20, 0xffff0000, v98
	v_pk_mul_f32 v[98:99], v[12:13], v[12:13]
	v_pk_mul_f32 v[102:103], v[20:21], v[20:21]
	v_lshlrev_b32_e32 v104, 16, v100
	v_and_b32_e32 v106, 0xffff0000, v100
	v_add_f32_e32 v98, v98, v102
	v_lshlrev_b32_e32 v105, 16, v101
	v_and_b32_e32 v107, 0xffff0000, v101
	v_mov_b32_e32 v100, v106
	v_mov_b32_e32 v101, v104
	v_add_f32_e32 v98, v99, v98
	v_pk_mul_f32 v[100:101], v[100:101], v[100:101]
	v_add_f32_e32 v98, v103, v98
	v_mov_b32_e32 v112, v107
	v_mov_b32_e32 v113, v105
	v_add_f32_e32 v98, v101, v98
	v_pk_mul_f32 v[112:113], v[112:113], v[112:113]
	v_add_f32_e32 v98, v100, v98
	v_add_f32_e32 v98, v113, v98
	v_add_f32_e32 v98, v112, v98
	v_lshrrev_b32_e32 v100, 16, v118
	v_and_or_b32 v101, v117, s67, v100
	v_add_f32_dpp v98, v98, v98 row_ror:8 row_mask:0xf bank_mask:0xf bound_ctrl:1
	v_and_or_b32 v100, v116, s67, v121
	s_nop 0
	v_add_f32_dpp v98, v98, v98 row_ror:4 row_mask:0xf bank_mask:0xf bound_ctrl:1
	s_nop 1
	v_add_f32_dpp v98, v98, v98 quad_perm:[2,3,0,1] row_mask:0xf bank_mask:0xf bound_ctrl:1
	s_nop 1
	v_add_f32_dpp v98, v98, v98 quad_perm:[1,0,3,2] row_mask:0xf bank_mask:0xf bound_ctrl:1
	v_fmamk_f32 v98, v98, 0x3c000000, v205
	v_mul_f32_e32 v99, 0x4f800000, v98
	v_cmp_gt_f32_e32 vcc, s8, v98
	s_nop 1
	v_cndmask_b32_e32 v98, v98, v99, vcc
	v_sqrt_f32_e32 v99, v98
	s_nop 0
	v_add_u32_e32 v102, -1, v99
	v_fma_f32 v103, -v102, v99, v98
	v_cmp_ge_f32_e64 s[0:1], 0, v103
	v_add_u32_e32 v103, 1, v99
	s_nop 0
	v_cndmask_b32_e64 v102, v99, v102, s[0:1]
	v_fma_f32 v99, -v103, v99, v98
	v_cmp_lt_f32_e64 s[0:1], 0, v99
	s_nop 1
	v_cndmask_b32_e64 v99, v102, v103, s[0:1]
	v_mul_f32_e32 v102, 0x37800000, v99
	v_cndmask_b32_e32 v99, v99, v102, vcc
	v_cmp_class_f32_e32 vcc, v98, v206
	s_nop 1
	v_cndmask_b32_e32 v102, v99, v98, vcc
	v_div_scale_f32 v103, s[0:1], v102, v102, 1.0
	v_rcp_f32_e32 v112, v103
	v_and_or_b32 v99, v115, s67, v120
	v_and_or_b32 v98, v114, s67, v119
	global_store_dwordx4 v[76:77], v[98:101], off offset:3072
	v_fma_f32 v76, -v103, v112, 1.0
	v_fmac_f32_e32 v112, v76, v112
	v_div_scale_f32 v76, vcc, 1.0, v102, 1.0
	v_mul_f32_e32 v77, v76, v112
	v_fma_f32 v98, -v103, v77, v76
	v_fmac_f32_e32 v77, v98, v112
	v_fma_f32 v76, -v103, v77, v76
	v_div_fmas_f32 v76, v76, v112, v77
	v_div_fixup_f32 v76, v76, v102, 1.0
	v_pk_mul_f32 v[12:13], v[76:77], v[12:13] op_sel_hi:[0,1]
	v_pk_mul_f32 v[20:21], v[76:77], v[20:21] op_sel_hi:[0,1]
	v_pk_mul_f32 v[98:99], v[76:77], v[104:105] op_sel_hi:[0,1]
	v_pk_mul_f32 v[12:13], v[110:111], v[12:13]
	v_pk_mul_f32 v[76:77], v[76:77], v[106:107] op_sel_hi:[0,1]
	v_pk_mul_f32 v[20:21], v[22:23], v[20:21]
	v_mov_b32_dpp v100, v12 row_ror:8 row_mask:0xf bank_mask:0xf bound_ctrl:1
	v_mov_b32_dpp v101, v13 row_ror:8 row_mask:0xf bank_mask:0xf bound_ctrl:1
	v_pk_mul_f32 v[12:13], v[58:59], v[12:13]
	v_pk_mul_f32 v[98:99], v[108:109], v[98:99]
	v_mov_b32_dpp v102, v20 row_ror:8 row_mask:0xf bank_mask:0xf bound_ctrl:1
	v_pk_fma_f32 v[12:13], v[70:71], v[100:101], v[12:13]
	v_mov_b32_dpp v103, v21 row_ror:8 row_mask:0xf bank_mask:0xf bound_ctrl:1
	v_pk_mul_f32 v[20:21], v[62:63], v[20:21]
	v_mov_b32_dpp v100, v98 row_ror:8 row_mask:0xf bank_mask:0xf bound_ctrl:1
	v_pk_mul_f32 v[76:77], v[14:15], v[76:77]
	v_mov_b32_dpp v101, v99 row_ror:8 row_mask:0xf bank_mask:0xf bound_ctrl:1
	v_pk_fma_f32 v[20:21], v[66:67], v[102:103], v[20:21]
	v_mov_b32_dpp v102, v76 row_ror:8 row_mask:0xf bank_mask:0xf bound_ctrl:1
	v_pk_mul_f32 v[100:101], v[72:73], v[100:101]
	v_mov_b32_dpp v103, v77 row_ror:8 row_mask:0xf bank_mask:0xf bound_ctrl:1
	v_pk_fma_f32 v[98:99], v[52:53], v[98:99], v[100:101]
	v_pk_mul_f32 v[100:101], v[68:69], v[102:103]
	s_nop 0
	v_pk_fma_f32 v[76:77], v[60:61], v[76:77], v[100:101]
	v_bfe_u32 v100, v21, 16, 1
	v_bfe_u32 v101, v20, 16, 1
	v_bfe_u32 v102, v77, 16, 1
	v_bfe_u32 v103, v76, 16, 1
	v_add3_u32 v104, v76, v103, s33
	v_add3_u32 v105, v77, v102, s33
	v_add3_u32 v106, v20, v101, s33
	v_add3_u32 v107, v21, v100, s33
	v_bfe_u32 v20, v98, 16, 1
	v_bfe_u32 v21, v99, 16, 1
	v_bfe_u32 v76, v12, 16, 1
	v_bfe_u32 v77, v13, 16, 1
	v_add3_u32 v112, v13, v77, s33
	v_add3_u32 v12, v12, v76, s33
	v_add3_u32 v13, v99, v21, s33
	v_add3_u32 v20, v98, v20, s33
	v_lshrrev_b32_e32 v113, 16, v20
	v_lshrrev_b32_e32 v114, 16, v13
	v_lshrrev_b32_e32 v115, 16, v12
	s_waitcnt vmcnt(1)
; __device__ __forceinline__ unsigned pk2(float lo, float hi) { return f2bf(lo) | (f2bf(hi) << 16); }
; template <int CTRL> __device__ __forceinline__ float dpp_f(float v) { return __builtin_bit_cast(float, __builtin_amdgcn_update_dpp(0, __builtin_bit_cast(int, v), CTRL, 0xF, 0xF, true)); }
; __device__ __forceinline__ float row16_sum(float v) { v += dpp_f<0x128>(v); v += dpp_f<0x124>(v); v += dpp_f<0x4E>(v); v += dpp_f<0xB1>(v); return v; }
; template <int NIT, bool F8>
; __device__ __forceinline__ void post_segment(bf16_t* seg, const float* gain, const float (&cs)[8], const float (&sn)[8], int c, int grp, unsigned char* k8 = nullptr) {
;     ...
;     for (int it = 0; it < NIT; ++it) {
;         const unsigned w[4] = {raw[it].x, raw[it].y, raw[it].z, raw[it].w}; float x[8];
; #pragma unroll
;         for (int i = 0; i < 4; ++i) { x[2 * i] = bf2f(w[i] & 0xffffu); x[2 * i + 1] = __builtin_bit_cast(float, w[i] & 0xffff0000u); }
;         float ss = 0.f;
; #pragma unroll
;         for (int e = 0; e < 8; ++e) ss += x[e] * x[e];
;         ss = row16_sum(ss); const float r = 1.f / sqrtf(ss * (1.f / 128.f) + EPS);
;         float o[8];
; #pragma unroll
;         for (int e = 0; e < 8; ++e) { const float y = x[e] * r * g[e]; const float py = dpp_f<0x128>(y); o[e] = y * cs[e] + py * sn[e]; }
;         u32x4 ow; ow.x = pk2(o[0], o[1]); ow.y = pk2(o[2], o[3]); ow.z = pk2(o[4], o[5]); ow.w = pk2(o[6], o[7]);
;         if constexpr (F8) *(u32x2*)(k8 + (it * 4 + grp) * 128 + c * 8) = to_fp8x8(o);
;         else *(u32x4*)(seg + (it * 4 + grp) * 128 + c * 8) = ow;
	v_lshlrev_b32_e32 v13, 16, v17
	v_lshlrev_b32_e32 v12, 16, v16
	v_and_b32_e32 v21, 0xffff0000, v17
	v_and_b32_e32 v20, 0xffff0000, v16
	v_pk_mul_f32 v[16:17], v[12:13], v[12:13]
	v_pk_mul_f32 v[76:77], v[20:21], v[20:21]
	v_lshlrev_b32_e32 v98, 16, v18
	v_and_b32_e32 v100, 0xffff0000, v18
	v_add_f32_e32 v16, v16, v76
	v_lshlrev_b32_e32 v99, 16, v19
	v_and_b32_e32 v101, 0xffff0000, v19
	v_mov_b32_e32 v18, v100
	v_mov_b32_e32 v19, v98
	v_add_f32_e32 v16, v17, v16
	v_pk_mul_f32 v[18:19], v[18:19], v[18:19]
	v_add_f32_e32 v16, v77, v16
	v_mov_b32_e32 v102, v101
	v_mov_b32_e32 v103, v99
	v_add_f32_e32 v16, v19, v16
	v_pk_mul_f32 v[102:103], v[102:103], v[102:103]
	v_add_f32_e32 v16, v18, v16
	v_add_f32_e32 v16, v103, v16
	v_add_f32_e32 v16, v102, v16
	s_nop 1
	v_add_f32_dpp v16, v16, v16 row_ror:8 row_mask:0xf bank_mask:0xf bound_ctrl:1
	s_nop 1
	v_add_f32_dpp v16, v16, v16 row_ror:4 row_mask:0xf bank_mask:0xf bound_ctrl:1
	s_nop 1
	v_add_f32_dpp v16, v16, v16 quad_perm:[2,3,0,1] row_mask:0xf bank_mask:0xf bound_ctrl:1
	s_nop 1
	v_add_f32_dpp v16, v16, v16 quad_perm:[1,0,3,2] row_mask:0xf bank_mask:0xf bound_ctrl:1
	v_fmamk_f32 v16, v16, 0x3c000000, v205
	v_mul_f32_e32 v17, 0x4f800000, v16
	v_cmp_gt_f32_e32 vcc, s8, v16
	s_nop 1
	v_cndmask_b32_e32 v18, v16, v17, vcc
	v_sqrt_f32_e32 v19, v18
	v_lshrrev_b32_e32 v16, 16, v112
	v_and_or_b32 v17, v107, s67, v16
	v_and_or_b32 v16, v106, s67, v115
	v_add_u32_e32 v76, -1, v19
	v_fma_f32 v77, -v76, v19, v18
	v_cmp_ge_f32_e64 s[0:1], 0, v77
	v_add_u32_e32 v77, 1, v19
	s_nop 0
	v_cndmask_b32_e64 v76, v19, v76, s[0:1]
	v_fma_f32 v19, -v77, v19, v18
	v_cmp_lt_f32_e64 s[0:1], 0, v19
	s_nop 1
	v_cndmask_b32_e64 v19, v76, v77, s[0:1]
	v_mul_f32_e32 v76, 0x37800000, v19
	v_cndmask_b32_e32 v19, v19, v76, vcc
	v_cmp_class_f32_e32 vcc, v18, v206
	s_nop 1
	v_cndmask_b32_e32 v76, v19, v18, vcc
	v_div_scale_f32 v77, s[0:1], v76, v76, 1.0
	v_rcp_f32_e32 v102, v77
	v_and_or_b32 v19, v105, s67, v114
	v_and_or_b32 v18, v104, s67, v113
	global_store_dwordx4 v[74:75], v[16:19], off
	s_nop 1
	v_fma_f32 v16, -v77, v102, 1.0
	v_fmac_f32_e32 v102, v16, v102
	v_div_scale_f32 v16, vcc, 1.0, v76, 1.0
	v_mul_f32_e32 v17, v16, v102
	v_fma_f32 v18, -v77, v17, v16
	v_fmac_f32_e32 v17, v18, v102
	v_fma_f32 v16, -v77, v17, v16
	v_div_fmas_f32 v16, v16, v102, v17
	v_div_fixup_f32 v16, v16, v76, 1.0
	v_pk_mul_f32 v[12:13], v[16:17], v[12:13] op_sel_hi:[0,1]
	v_pk_mul_f32 v[18:19], v[16:17], v[20:21] op_sel_hi:[0,1]
	v_pk_mul_f32 v[20:21], v[16:17], v[98:99] op_sel_hi:[0,1]
	v_pk_mul_f32 v[16:17], v[16:17], v[100:101] op_sel_hi:[0,1]
	v_pk_mul_f32 v[18:19], v[22:23], v[18:19]
	v_pk_mul_f32 v[14:15], v[14:15], v[16:17]
	v_pk_mul_f32 v[20:21], v[108:109], v[20:21]
	v_mov_b32_dpp v22, v18 row_ror:8 row_mask:0xf bank_mask:0xf bound_ctrl:1
	v_mov_b32_dpp v23, v19 row_ror:8 row_mask:0xf bank_mask:0xf bound_ctrl:1
	v_pk_mul_f32 v[18:19], v[62:63], v[18:19]
	v_mov_b32_dpp v16, v14 row_ror:8 row_mask:0xf bank_mask:0xf bound_ctrl:1
	v_mov_b32_dpp v17, v15 row_ror:8 row_mask:0xf bank_mask:0xf bound_ctrl:1
	v_pk_mul_f32 v[12:13], v[110:111], v[12:13]
	v_pk_fma_f32 v[18:19], v[66:67], v[22:23], v[18:19]
	v_mov_b32_dpp v22, v20 row_ror:8 row_mask:0xf bank_mask:0xf bound_ctrl:1
	v_mov_b32_dpp v23, v21 row_ror:8 row_mask:0xf bank_mask:0xf bound_ctrl:1
	v_pk_mul_f32 v[16:17], v[68:69], v[16:17]
	v_mov_b32_dpp v76, v12 row_ror:8 row_mask:0xf bank_mask:0xf bound_ctrl:1
	v_mov_b32_dpp v77, v13 row_ror:8 row_mask:0xf bank_mask:0xf bound_ctrl:1
	v_pk_mul_f32 v[12:13], v[58:59], v[12:13]
	v_pk_mul_f32 v[22:23], v[72:73], v[22:23]
	v_pk_fma_f32 v[14:15], v[60:61], v[14:15], v[16:17]
	v_pk_fma_f32 v[12:13], v[70:71], v[76:77], v[12:13]
	v_pk_fma_f32 v[20:21], v[52:53], v[20:21], v[22:23]
	v_cvt_pk_bf16_f32 v12, v12, v18
	v_cvt_pk_bf16_f32 v13, v13, v19
	v_cvt_pk_bf16_f32 v15, v21, v15
	v_cvt_pk_bf16_f32 v14, v20, v14
	global_store_dwordx4 v[74:75], v[12:15], off offset:1024
	global_load_dwordx4 v[16:19], v[28:29], off
	s_nop 0
	global_load_dwordx4 v[12:15], v[28:29], off offset:16
	global_load_dwordx4 v[20:23], v[64:65], off offset:2048
	v_lshlrev_b32_e32 v75, 16, v9
	v_lshlrev_b32_e32 v74, 16, v8
	v_and_b32_e32 v9, 0xffff0000, v9
	v_and_b32_e32 v8, 0xffff0000, v8
	v_pk_mul_f32 v[76:77], v[74:75], v[74:75]
	v_pk_mul_f32 v[98:99], v[8:9], v[8:9]
	v_lshlrev_b32_e32 v100, 16, v10
	v_and_b32_e32 v10, 0xffff0000, v10
	v_add_f32_e32 v76, v76, v98
	v_mov_b32_e32 v102, v10
	v_mov_b32_e32 v103, v100
	v_add_f32_e32 v76, v77, v76
	v_lshlrev_b32_e32 v101, 16, v11
	v_and_b32_e32 v11, 0xffff0000, v11
	v_pk_mul_f32 v[102:103], v[102:103], v[102:103]
	v_add_f32_e32 v76, v99, v76
	v_mov_b32_e32 v104, v11
	v_mov_b32_e32 v105, v101
	v_add_f32_e32 v76, v103, v76
	v_pk_mul_f32 v[104:105], v[104:105], v[104:105]
	v_add_f32_e32 v76, v102, v76
	v_add_f32_e32 v76, v105, v76
	v_add_f32_e32 v76, v104, v76
	s_nop 1
	v_add_f32_dpp v76, v76, v76 row_ror:8 row_mask:0xf bank_mask:0xf bound_ctrl:1
	s_nop 1
	v_add_f32_dpp v76, v76, v76 row_ror:4 row_mask:0xf bank_mask:0xf bound_ctrl:1
	s_nop 1
	v_add_f32_dpp v76, v76, v76 quad_perm:[2,3,0,1] row_mask:0xf bank_mask:0xf bound_ctrl:1
	s_nop 1
	v_add_f32_dpp v76, v76, v76 quad_perm:[1,0,3,2] row_mask:0xf bank_mask:0xf bound_ctrl:1
	v_fmamk_f32 v76, v76, 0x3c000000, v205
	v_mul_f32_e32 v77, 0x4f800000, v76
	v_cmp_gt_f32_e32 vcc, s8, v76
	s_nop 1
	v_cndmask_b32_e32 v76, v76, v77, vcc
	v_sqrt_f32_e32 v77, v76
	s_nop 0
	v_add_u32_e32 v98, -1, v77
	v_fma_f32 v99, -v98, v77, v76
	v_cmp_ge_f32_e64 s[0:1], 0, v99
	v_add_u32_e32 v99, 1, v77
	s_nop 0
	v_cndmask_b32_e64 v98, v77, v98, s[0:1]
	v_fma_f32 v77, -v99, v77, v76
	v_cmp_lt_f32_e64 s[0:1], 0, v77
	s_nop 1
	v_cndmask_b32_e64 v77, v98, v99, s[0:1]
	v_mul_f32_e32 v98, 0x37800000, v77
	v_cndmask_b32_e32 v77, v77, v98, vcc
	v_cmp_class_f32_e32 vcc, v76, v206
	s_nop 1
	v_cndmask_b32_e32 v98, v77, v76, vcc
	v_div_scale_f32 v99, s[0:1], v98, v98, 1.0
	v_rcp_f32_e32 v102, v99
	s_waitcnt vmcnt(2)
; __device__ __forceinline__ unsigned pk2(float lo, float hi) { return f2bf(lo) | (f2bf(hi) << 16); }
; template <int CTRL> __device__ __forceinline__ float dpp_f(float v) { return __builtin_bit_cast(float, __builtin_amdgcn_update_dpp(0, __builtin_bit_cast(int, v), CTRL, 0xF, 0xF, true)); }
; __device__ __forceinline__ float row16_sum(float v) { v += dpp_f<0x128>(v); v += dpp_f<0x124>(v); v += dpp_f<0x4E>(v); v += dpp_f<0xB1>(v); return v; }
; template <int NIT, bool F8>
; __device__ __forceinline__ void post_segment(bf16_t* seg, const float* gain, const float (&cs)[8], const float (&sn)[8], int c, int grp, unsigned char* k8 = nullptr) {
;     ...
;     for (int it = 0; it < NIT; ++it) {
;         const unsigned w[4] = {raw[it].x, raw[it].y, raw[it].z, raw[it].w}; float x[8];
; #pragma unroll
;         for (int i = 0; i < 4; ++i) { x[2 * i] = bf2f(w[i] & 0xffffu); x[2 * i + 1] = __builtin_bit_cast(float, w[i] & 0xffff0000u); }
;         float ss = 0.f;
; #pragma unroll
;         for (int e = 0; e < 8; ++e) ss += x[e] * x[e];
;         ss = row16_sum(ss); const float r = 1.f / sqrtf(ss * (1.f / 128.f) + EPS);
;         float o[8];
; #pragma unroll
;         for (int e = 0; e < 8; ++e) { const float y = x[e] * r * g[e]; const float py = dpp_f<0x128>(y); o[e] = y * cs[e] + py * sn[e]; }
;         u32x4 ow; ow.x = pk2(o[0], o[1]); ow.y = pk2(o[2], o[3]); ow.z = pk2(o[4], o[5]); ow.w = pk2(o[6], o[7]);
;         if constexpr (F8) *(u32x2*)(k8 + (it * 4 + grp) * 128 + c * 8) = to_fp8x8(o);
;         else *(u32x4*)(seg + (it * 4 + grp) * 128 + c * 8) = ow;
	v_mov_b32_e32 v76, v16
	v_fma_f32 v16, -v99, v102, 1.0
	v_fmac_f32_e32 v102, v16, v102
	v_div_scale_f32 v16, vcc, 1.0, v98, 1.0
	v_mov_b32_e32 v77, v18
	v_mov_b32_e32 v18, v17
	v_mul_f32_e32 v17, v16, v102
	v_fma_f32 v103, -v99, v17, v16
	v_fmac_f32_e32 v17, v103, v102
	v_fma_f32 v16, -v99, v17, v16
	v_div_fmas_f32 v16, v16, v102, v17
	v_div_fixup_f32 v16, v16, v98, 1.0
	v_pk_mul_f32 v[74:75], v[16:17], v[74:75] op_sel_hi:[0,1]
	v_pk_mul_f32 v[8:9], v[16:17], v[8:9] op_sel_hi:[0,1]
	v_pk_mul_f32 v[98:99], v[16:17], v[100:101] op_sel_hi:[0,1]
	v_pk_mul_f32 v[10:11], v[16:17], v[10:11] op_sel_hi:[0,1]
	v_pk_mul_f32 v[16:17], v[76:77], v[74:75]
	v_pk_mul_f32 v[8:9], v[18:19], v[8:9]
	s_nop 0
	v_mov_b32_dpp v74, v16 row_ror:8 row_mask:0xf bank_mask:0xf bound_ctrl:1
	v_mov_b32_dpp v75, v17 row_ror:8 row_mask:0xf bank_mask:0xf bound_ctrl:1
	v_pk_mul_f32 v[16:17], v[58:59], v[16:17]
	v_mov_b32_dpp v100, v8 row_ror:8 row_mask:0xf bank_mask:0xf bound_ctrl:1
	v_pk_fma_f32 v[16:17], v[70:71], v[74:75], v[16:17]
	s_waitcnt vmcnt(1)
	v_mov_b32_e32 v75, v14
	v_mov_b32_e32 v14, v13
	v_mov_b32_dpp v101, v9 row_ror:8 row_mask:0xf bank_mask:0xf bound_ctrl:1
	v_pk_mul_f32 v[8:9], v[62:63], v[8:9]
	v_mov_b32_e32 v74, v12
	v_pk_mul_f32 v[10:11], v[14:15], v[10:11]
	v_pk_fma_f32 v[8:9], v[66:67], v[100:101], v[8:9]
	v_pk_mul_f32 v[98:99], v[74:75], v[98:99]
	v_mov_b32_dpp v100, v10 row_ror:8 row_mask:0xf bank_mask:0xf bound_ctrl:1
	v_mov_b32_dpp v101, v11 row_ror:8 row_mask:0xf bank_mask:0xf bound_ctrl:1
	v_pk_mul_f32 v[10:11], v[60:61], v[10:11]
	v_mov_b32_dpp v12, v98 row_ror:8 row_mask:0xf bank_mask:0xf bound_ctrl:1
	v_mov_b32_dpp v13, v99 row_ror:8 row_mask:0xf bank_mask:0xf bound_ctrl:1
	v_pk_mul_f32 v[98:99], v[52:53], v[98:99]
	v_pk_fma_f32 v[10:11], v[68:69], v[100:101], v[10:11]
	v_pk_fma_f32 v[12:13], v[72:73], v[12:13], v[98:99]
	v_bfe_u32 v98, v11, 16, 1
	v_bfe_u32 v99, v10, 16, 1
	v_bfe_u32 v100, v9, 16, 1
	v_bfe_u32 v101, v8, 16, 1
	v_add3_u32 v102, v8, v101, s33
	v_add3_u32 v103, v9, v100, s33
	v_add3_u32 v104, v10, v99, s33
	v_add3_u32 v105, v11, v98, s33
	v_bfe_u32 v8, v16, 16, 1
	v_bfe_u32 v9, v17, 16, 1
	v_bfe_u32 v10, v12, 16, 1
	v_bfe_u32 v11, v13, 16, 1
	v_add3_u32 v106, v13, v11, s33
	v_add3_u32 v10, v12, v10, s33
	v_add3_u32 v9, v17, v9, s33
	v_add3_u32 v8, v16, v8, s33
	s_waitcnt vmcnt(0)
	v_lshlrev_b32_e32 v13, 16, v21
	v_lshlrev_b32_e32 v12, 16, v20
	v_and_b32_e32 v17, 0xffff0000, v21
	v_and_b32_e32 v16, 0xffff0000, v20
	v_lshrrev_b32_e32 v107, 16, v8
	v_lshrrev_b32_e32 v108, 16, v9
	v_lshrrev_b32_e32 v109, 16, v10
	v_pk_mul_f32 v[8:9], v[12:13], v[12:13]
	v_pk_mul_f32 v[10:11], v[16:17], v[16:17]
	v_lshlrev_b32_e32 v20, 16, v22
	v_and_b32_e32 v22, 0xffff0000, v22
	v_add_f32_e32 v8, v8, v10
	v_mov_b32_e32 v98, v22
	v_mov_b32_e32 v99, v20
	v_add_f32_e32 v8, v9, v8
	v_lshlrev_b32_e32 v21, 16, v23
	v_and_b32_e32 v23, 0xffff0000, v23
	v_pk_mul_f32 v[98:99], v[98:99], v[98:99]
	v_add_f32_e32 v8, v11, v8
	v_mov_b32_e32 v100, v23
	v_mov_b32_e32 v101, v21
	v_add_f32_e32 v8, v99, v8
	v_pk_mul_f32 v[100:101], v[100:101], v[100:101]
	v_add_f32_e32 v8, v98, v8
	v_add_f32_e32 v8, v101, v8
	v_add_f32_e32 v8, v100, v8
	v_lshrrev_b32_e32 v10, 16, v106
	v_and_or_b32 v11, v105, s67, v10
	v_add_f32_dpp v8, v8, v8 row_ror:8 row_mask:0xf bank_mask:0xf bound_ctrl:1
	v_and_or_b32 v10, v104, s67, v109
	s_nop 0
	v_add_f32_dpp v8, v8, v8 row_ror:4 row_mask:0xf bank_mask:0xf bound_ctrl:1
	s_nop 1
	v_add_f32_dpp v8, v8, v8 quad_perm:[2,3,0,1] row_mask:0xf bank_mask:0xf bound_ctrl:1
	s_nop 1
	v_add_f32_dpp v8, v8, v8 quad_perm:[1,0,3,2] row_mask:0xf bank_mask:0xf bound_ctrl:1
	v_fmamk_f32 v8, v8, 0x3c000000, v205
	v_mul_f32_e32 v9, 0x4f800000, v8
	v_cmp_gt_f32_e32 vcc, s8, v8
	s_nop 1
	v_cndmask_b32_e32 v8, v8, v9, vcc
	v_sqrt_f32_e32 v9, v8
	s_nop 0
	v_add_u32_e32 v98, -1, v9
	v_fma_f32 v99, -v98, v9, v8
	v_cmp_ge_f32_e64 s[0:1], 0, v99
	v_add_u32_e32 v99, 1, v9
	s_nop 0
	v_cndmask_b32_e64 v98, v9, v98, s[0:1]
	v_fma_f32 v9, -v99, v9, v8
	v_cmp_lt_f32_e64 s[0:1], 0, v9
	s_nop 1
	v_cndmask_b32_e64 v9, v98, v99, s[0:1]
	v_mul_f32_e32 v98, 0x37800000, v9
	v_cndmask_b32_e32 v9, v9, v98, vcc
	v_cmp_class_f32_e32 vcc, v8, v206
	s_nop 1
	v_cndmask_b32_e32 v98, v9, v8, vcc
	v_div_scale_f32 v99, s[0:1], v98, v98, 1.0
	v_rcp_f32_e32 v100, v99
	v_and_or_b32 v9, v103, s67, v108
	v_and_or_b32 v8, v102, s67, v107
	global_store_dwordx4 v[64:65], v[8:11], off offset:1024
	s_mov_b32 s0, 0x3af00000
	s_nop 0
	v_fma_f32 v8, -v99, v100, 1.0
	v_fmac_f32_e32 v100, v8, v100
	v_div_scale_f32 v8, vcc, 1.0, v98, 1.0
	v_mul_f32_e32 v9, v8, v100
	v_fma_f32 v10, -v99, v9, v8
	v_fmac_f32_e32 v9, v10, v100
	v_fma_f32 v8, -v99, v9, v8
	v_div_fmas_f32 v8, v8, v100, v9
	v_div_fixup_f32 v8, v8, v98, 1.0
	v_pk_mul_f32 v[10:11], v[8:9], v[12:13] op_sel_hi:[0,1]
	v_pk_mul_f32 v[12:13], v[8:9], v[16:17] op_sel_hi:[0,1]
	v_pk_mul_f32 v[16:17], v[8:9], v[20:21] op_sel_hi:[0,1]
	v_pk_mul_f32 v[8:9], v[8:9], v[22:23] op_sel_hi:[0,1]
	v_pk_mul_f32 v[12:13], v[18:19], v[12:13]
	v_pk_mul_f32 v[8:9], v[14:15], v[8:9]
	v_pk_mul_f32 v[16:17], v[74:75], v[16:17]
	v_mov_b32_dpp v18, v12 row_ror:8 row_mask:0xf bank_mask:0xf bound_ctrl:1
	v_mov_b32_dpp v19, v13 row_ror:8 row_mask:0xf bank_mask:0xf bound_ctrl:1
	v_pk_mul_f32 v[12:13], v[62:63], v[12:13]
	v_mov_b32_dpp v14, v8 row_ror:8 row_mask:0xf bank_mask:0xf bound_ctrl:1
	v_mov_b32_dpp v15, v9 row_ror:8 row_mask:0xf bank_mask:0xf bound_ctrl:1
	v_pk_mul_f32 v[10:11], v[76:77], v[10:11]
	v_pk_fma_f32 v[12:13], v[66:67], v[18:19], v[12:13]
	v_mov_b32_dpp v18, v16 row_ror:8 row_mask:0xf bank_mask:0xf bound_ctrl:1
	v_mov_b32_dpp v19, v17 row_ror:8 row_mask:0xf bank_mask:0xf bound_ctrl:1
; __device__ __forceinline__ unsigned pk2(float lo, float hi) { return f2bf(lo) | (f2bf(hi) << 16); }
; template <int CTRL> __device__ __forceinline__ float dpp_f(float v) { return __builtin_bit_cast(float, __builtin_amdgcn_update_dpp(0, __builtin_bit_cast(int, v), CTRL, 0xF, 0xF, true)); }
; __device__ __forceinline__ float row16_sum(float v) { v += dpp_f<0x128>(v); v += dpp_f<0x124>(v); v += dpp_f<0x4E>(v); v += dpp_f<0xB1>(v); return v; }
; template <int NIT, bool F8>
; __device__ __forceinline__ void post_segment(bf16_t* seg, const float* gain, const float (&cs)[8], const float (&sn)[8], int c, int grp, unsigned char* k8 = nullptr) {
;     ...
;         ss = row16_sum(ss); const float r = 1.f / sqrtf(ss * (1.f / 128.f) + EPS);
;         float o[8];
; #pragma unroll
;         for (int e = 0; e < 8; ++e) { const float y = x[e] * r * g[e]; const float py = dpp_f<0x128>(y); o[e] = y * cs[e] + py * sn[e]; }
;         u32x4 ow; ow.x = pk2(o[0], o[1]); ow.y = pk2(o[2], o[3]); ow.z = pk2(o[4], o[5]); ow.w = pk2(o[6], o[7]);
;         if constexpr (F8) *(u32x2*)(k8 + (it * 4 + grp) * 128 + c * 8) = to_fp8x8(o);
;         else *(u32x4*)(seg + (it * 4 + grp) * 128 + c * 8) = ow;
; __device__ __forceinline__ void post_token(int pos, const float* gaq, const float* gak, const float* gbq, const float* gbk, const float* gik, ...
;     ...
;     f32x4 xi[4];
; #pragma unroll
;     for (int it = 0; it < 4; ++it) xi[it] = *(const f32x4*)(irow + (it * 4 + grp) * 64 + 4 * c);
;     const f32x4 xk = *(const f32x4*)(irow + 1024 + 4 * c);
	v_pk_mul_f32 v[14:15], v[68:69], v[14:15]
	v_mov_b32_dpp v20, v10 row_ror:8 row_mask:0xf bank_mask:0xf bound_ctrl:1
	v_mov_b32_dpp v21, v11 row_ror:8 row_mask:0xf bank_mask:0xf bound_ctrl:1
	v_pk_mul_f32 v[10:11], v[58:59], v[10:11]
	v_pk_mul_f32 v[18:19], v[72:73], v[18:19]
	v_pk_fma_f32 v[8:9], v[60:61], v[8:9], v[14:15]
	v_pk_fma_f32 v[10:11], v[70:71], v[20:21], v[10:11]
	v_pk_fma_f32 v[16:17], v[52:53], v[16:17], v[18:19]
	v_bfe_u32 v18, v9, 16, 1
	v_bfe_u32 v19, v8, 16, 1
	v_add3_u32 v19, v8, v19, s33
	v_add3_u32 v18, v9, v18, s33
	v_cvt_pk_bf16_f32 v8, v10, v12
	v_cvt_pk_bf16_f32 v9, v11, v13
	v_bfe_u32 v12, v16, 16, 1
	v_bfe_u32 v13, v17, 16, 1
	v_add3_u32 v13, v17, v13, s33
	v_add3_u32 v12, v16, v12, s33
	v_lshrrev_b32_e32 v12, 16, v12
	v_lshrrev_b32_e32 v13, 16, v13
	v_and_or_b32 v11, v18, s67, v13
	v_and_or_b32 v10, v19, s67, v12
	global_store_dwordx4 v[64:65], v[8:11], off offset:2048
	global_load_dwordx4 v[8:11], v[30:31], off
	s_nop 0
	global_load_dwordx4 v[12:15], v[30:31], off offset:16
	v_div_fixup_f32 v16, v97, v94, 1.0
	v_mul_f32_e32 v18, v16, v78
	v_mul_f32_e32 v19, v16, v79
	v_mul_f32_e32 v20, v16, v80
	v_mul_f32_e32 v21, v16, v81
	v_mul_f32_e32 v64, v16, v82
	v_mul_f32_e32 v65, v16, v83
	v_mul_f32_e32 v70, v16, v84
	v_div_fixup_f32 v22, v96, v95, 1.0
	v_mul_f32_e32 v72, v22, v86
	v_mul_f32_e32 v73, v22, v87
	v_mul_f32_e32 v74, v22, v88
	v_mul_f32_e32 v75, v22, v89
	v_mul_f32_e32 v76, v22, v90
	v_mul_f32_e32 v77, v22, v91
	v_mul_f32_e32 v78, v22, v92
	v_mul_f32_e32 v71, v16, v85
	v_mul_f32_e32 v79, v22, v93
	v_lshl_add_u64 v[16:17], s[90:91], 0, v[44:45]
	v_lshl_add_u64 v[22:23], s[90:91], 0, v[46:47]
	s_waitcnt vmcnt(1)
	v_mul_f32_e32 v18, v8, v18
	s_nop 1
	v_mov_b32_dpp v80, v18 row_ror:8 row_mask:0xf bank_mask:0xf bound_ctrl:1
	v_mul_f32_e32 v81, v58, v18
	v_mul_f32_e32 v18, v9, v19
	v_fmac_f32_e32 v81, v54, v80
	v_mul_f32_e32 v80, v62, v18
	v_mov_b32_dpp v19, v18 row_ror:8 row_mask:0xf bank_mask:0xf bound_ctrl:1
	v_mul_f32_e32 v18, v10, v20
	v_fmac_f32_e32 v80, v66, v19
	v_mul_f32_e32 v20, v59, v18
	v_mov_b32_dpp v19, v18 row_ror:8 row_mask:0xf bank_mask:0xf bound_ctrl:1
	v_mul_f32_e32 v18, v11, v21
	v_fmac_f32_e32 v20, v56, v19
	v_mul_f32_e32 v21, v63, v18
	v_mov_b32_dpp v19, v18 row_ror:8 row_mask:0xf bank_mask:0xf bound_ctrl:1
	s_waitcnt vmcnt(0)
	v_mul_f32_e32 v18, v12, v64
	v_fmac_f32_e32 v21, v67, v19
	v_mul_f32_e32 v64, v52, v18
	v_mov_b32_dpp v19, v18 row_ror:8 row_mask:0xf bank_mask:0xf bound_ctrl:1
	v_mul_f32_e32 v18, v13, v65
	v_fmac_f32_e32 v64, v55, v19
	v_mul_f32_e32 v65, v60, v18
	v_mov_b32_dpp v19, v18 row_ror:8 row_mask:0xf bank_mask:0xf bound_ctrl:1
	v_mul_f32_e32 v18, v14, v70
	v_fmac_f32_e32 v65, v68, v19
	v_mul_f32_e32 v70, v53, v18
	v_mov_b32_dpp v19, v18 row_ror:8 row_mask:0xf bank_mask:0xf bound_ctrl:1
	v_mov_b32_e32 v18, 0
	v_cvt_pk_fp8_f32 v18, v81, v80
	v_mul_f32_e32 v8, v8, v72
	v_fmac_f32_e32 v70, v57, v19
	v_mov_b32_e32 v19, 0
	v_cvt_pk_fp8_f32 v18, v20, v21 op_sel:[0,0,1]
	v_mov_b32_dpp v20, v8 row_ror:8 row_mask:0xf bank_mask:0xf bound_ctrl:1
	v_mul_f32_e32 v21, v58, v8
	v_mul_f32_e32 v8, v9, v73
	v_fmac_f32_e32 v21, v54, v20
	v_mul_f32_e32 v20, v62, v8
	v_mov_b32_dpp v9, v8 row_ror:8 row_mask:0xf bank_mask:0xf bound_ctrl:1
	v_mul_f32_e32 v8, v10, v74
	v_fmac_f32_e32 v20, v66, v9
	v_mul_f32_e32 v10, v59, v8
	v_mov_b32_dpp v9, v8 row_ror:8 row_mask:0xf bank_mask:0xf bound_ctrl:1
	v_mul_f32_e32 v8, v11, v75
	v_fmac_f32_e32 v10, v56, v9
	v_mul_f32_e32 v11, v63, v8
	v_mov_b32_dpp v9, v8 row_ror:8 row_mask:0xf bank_mask:0xf bound_ctrl:1
	v_mul_f32_e32 v8, v12, v76
	v_fmac_f32_e32 v11, v67, v9
	v_mul_f32_e32 v12, v52, v8
	v_mov_b32_dpp v9, v8 row_ror:8 row_mask:0xf bank_mask:0xf bound_ctrl:1
	v_mul_f32_e32 v8, v13, v77
	v_fmac_f32_e32 v12, v55, v9
	v_mul_f32_e32 v13, v60, v8
	v_mov_b32_dpp v9, v8 row_ror:8 row_mask:0xf bank_mask:0xf bound_ctrl:1
	v_mul_f32_e32 v8, v14, v78
	v_cvt_pk_fp8_f32 v19, v64, v65
	v_fmac_f32_e32 v13, v68, v9
	v_mul_f32_dpp v14, v8, v57 row_ror:8 row_mask:0xf bank_mask:0xf bound_ctrl:1
	v_fmac_f32_e32 v14, v53, v8
	v_mov_b32_e32 v8, 0
	v_mov_b32_e32 v9, 0
	v_mul_f32_e32 v71, v15, v71
	v_cvt_pk_fp8_f32 v8, v21, v20
	v_cvt_pk_fp8_f32 v9, v12, v13
	v_mov_b32_dpp v82, v71 row_ror:8 row_mask:0xf bank_mask:0xf bound_ctrl:1
	v_mul_f32_e32 v64, v61, v71
	v_mul_f32_e32 v15, v15, v79
	v_fmac_f32_e32 v64, v69, v82
	v_cvt_pk_fp8_f32 v19, v70, v64 op_sel:[0,0,1]
	v_mul_f32_dpp v12, v15, v69 row_ror:8 row_mask:0xf bank_mask:0xf bound_ctrl:1
	v_fmac_f32_e32 v12, v61, v15
	v_cvt_pk_fp8_f32 v8, v10, v11 op_sel:[0,0,1]
	v_cvt_pk_fp8_f32 v9, v14, v12 op_sel:[0,0,1]
	v_add_co_u32_e32 v10, vcc, s0, v16
	s_nop 1
	v_addc_co_u32_e32 v11, vcc, 0, v17, vcc
	global_store_dwordx2 v[10:11], v[18:19], off
	global_store_dwordx2 v[10:11], v[8:9], off offset:512
	global_load_dwordx4 v[10:13], v[22:23], off offset:-2048
	s_nop 0
	global_load_dwordx4 v[14:17], v[22:23], off offset:-1024
	global_load_dwordx4 v[18:21], v[22:23], off
	global_load_dwordx4 v[60:63], v[22:23], off offset:1024
	v_lshl_add_u64 v[8:9], s[90:91], 0, v[48:49]
	global_load_dwordx4 v[64:67], v[8:9], off
	v_mov_b32_e32 v9, v52
	v_mov_b32_e32 v52, v59
	v_mov_b32_e32 v8, v58
	v_lshl_add_u64 v[22:23], s[90:91], 0, v[42:43]
	s_waitcnt vmcnt(4)
; __device__ __forceinline__ unsigned pk2(float lo, float hi) { return f2bf(lo) | (f2bf(hi) << 16); }
; template <int CTRL> __device__ __forceinline__ float dpp_f(float v) { return __builtin_bit_cast(float, __builtin_amdgcn_update_dpp(0, __builtin_bit_cast(int, v), CTRL, 0xF, 0xF, true)); }
; __device__ __forceinline__ void post_token(int pos, const float* gaq, const float* gak, const float* gbq, const float* gbk, const float* gik, ...
;     ...
;     for (int it = 0; it < 4; ++it) { float o[4];
; #pragma unroll
;         for (int e = 0; e < 4; ++e) { const float x = xi[it][e]; const float px = dpp_f<0x128>(x); o[e] = x * ci[e] + px * si[e]; }
;         u32x2 ow; ow.x = pk2(o[0], o[1]); ow.y = pk2(o[2], o[3]); *(u32x2*)(iq + (it * 4 + grp) * 64 + 4 * c) = ow; }
	v_mov_b32_dpp v70, v11 row_ror:8 row_mask:0xf bank_mask:0xf bound_ctrl:1
	v_mov_b32_dpp v71, v13 row_ror:8 row_mask:0xf bank_mask:0xf bound_ctrl:1
	v_mov_b32_dpp v68, v10 row_ror:8 row_mask:0xf bank_mask:0xf bound_ctrl:1
	v_mov_b32_dpp v69, v12 row_ror:8 row_mask:0xf bank_mask:0xf bound_ctrl:1
	v_mov_b32_e32 v72, v10
	v_mov_b32_e32 v73, v12
	v_mov_b32_e32 v12, v11
	v_pk_mul_f32 v[10:11], v[56:57], v[70:71]
	v_pk_mul_f32 v[68:69], v[54:55], v[68:69]
	v_pk_fma_f32 v[10:11], v[12:13], v[52:53], v[10:11]
	v_pk_fma_f32 v[68:69], v[72:73], v[8:9], v[68:69]
	v_and_b32_sdwa v58, v11, v207 dst_sel:DWORD dst_unused:UNUSED_PAD src0_sel:WORD_1 src1_sel:DWORD
	v_and_b32_sdwa v59, v10, v207 dst_sel:DWORD dst_unused:UNUSED_PAD src0_sel:WORD_1 src1_sel:DWORD
	v_and_b32_sdwa v12, v69, v207 dst_sel:DWORD dst_unused:UNUSED_PAD src0_sel:WORD_1 src1_sel:DWORD
	v_and_b32_sdwa v13, v68, v207 dst_sel:DWORD dst_unused:UNUSED_PAD src0_sel:WORD_1 src1_sel:DWORD
	v_add3_u32 v11, v11, v58, s33
	v_add3_u32 v10, v10, v59, s33
	v_add3_u32 v13, v68, v13, s33
	v_add3_u32 v12, v69, v12, s33
	v_and_b32_e32 v11, 0xffff0000, v11
	v_and_b32_e32 v10, 0xffff0000, v10
	v_or_b32_sdwa v11, v11, v12 dst_sel:DWORD dst_unused:UNUSED_PAD src0_sel:DWORD src1_sel:WORD_1
	v_or_b32_sdwa v10, v10, v13 dst_sel:DWORD dst_unused:UNUSED_PAD src0_sel:DWORD src1_sel:WORD_1
	global_store_dwordx2 v[22:23], v[10:11], off offset:-1024
	s_waitcnt vmcnt(4)
	v_mov_b32_dpp v11, v16 row_ror:8 row_mask:0xf bank_mask:0xf bound_ctrl:1
	v_mov_b32_dpp v10, v14 row_ror:8 row_mask:0xf bank_mask:0xf bound_ctrl:1
	v_mov_b32_dpp v12, v15 row_ror:8 row_mask:0xf bank_mask:0xf bound_ctrl:1
	v_mov_b32_dpp v13, v17 row_ror:8 row_mask:0xf bank_mask:0xf bound_ctrl:1
	v_mov_b32_e32 v58, v14
	v_mov_b32_e32 v59, v16
	v_pk_mul_f32 v[10:11], v[54:55], v[10:11]
	v_mov_b32_e32 v16, v15
	v_pk_fma_f32 v[10:11], v[58:59], v[8:9], v[10:11]
	v_pk_mul_f32 v[12:13], v[56:57], v[12:13]
	v_and_b32_sdwa v14, v11, v207 dst_sel:DWORD dst_unused:UNUSED_PAD src0_sel:WORD_1 src1_sel:DWORD
	v_pk_fma_f32 v[12:13], v[16:17], v[52:53], v[12:13]
	v_and_b32_sdwa v15, v10, v207 dst_sel:DWORD dst_unused:UNUSED_PAD src0_sel:WORD_1 src1_sel:DWORD
	v_add3_u32 v10, v10, v15, s33
	v_add3_u32 v11, v11, v14, s33
	v_and_b32_sdwa v14, v13, v207 dst_sel:DWORD dst_unused:UNUSED_PAD src0_sel:WORD_1 src1_sel:DWORD
	v_and_b32_sdwa v15, v12, v207 dst_sel:DWORD dst_unused:UNUSED_PAD src0_sel:WORD_1 src1_sel:DWORD
	v_add3_u32 v13, v13, v14, s33
	v_add3_u32 v12, v12, v15, s33
	v_and_b32_e32 v13, 0xffff0000, v13
	v_and_b32_e32 v12, 0xffff0000, v12
	v_or_b32_sdwa v11, v13, v11 dst_sel:DWORD dst_unused:UNUSED_PAD src0_sel:DWORD src1_sel:WORD_1
	v_or_b32_sdwa v10, v12, v10 dst_sel:DWORD dst_unused:UNUSED_PAD src0_sel:DWORD src1_sel:WORD_1
	global_store_dwordx2 v[22:23], v[10:11], off offset:-512
	s_waitcnt vmcnt(4)
	v_mov_b32_dpp v11, v20 row_ror:8 row_mask:0xf bank_mask:0xf bound_ctrl:1
	v_mov_b32_dpp v10, v18 row_ror:8 row_mask:0xf bank_mask:0xf bound_ctrl:1
	v_mov_b32_dpp v12, v19 row_ror:8 row_mask:0xf bank_mask:0xf bound_ctrl:1
	v_mov_b32_dpp v13, v21 row_ror:8 row_mask:0xf bank_mask:0xf bound_ctrl:1
	v_mov_b32_e32 v14, v18
	v_mov_b32_e32 v15, v20
	v_pk_mul_f32 v[10:11], v[54:55], v[10:11]
	v_mov_b32_e32 v20, v19
	v_pk_fma_f32 v[10:11], v[8:9], v[14:15], v[10:11]
	v_pk_mul_f32 v[12:13], v[56:57], v[12:13]
	v_and_b32_sdwa v14, v11, v207 dst_sel:DWORD dst_unused:UNUSED_PAD src0_sel:WORD_1 src1_sel:DWORD
	v_pk_fma_f32 v[12:13], v[20:21], v[52:53], v[12:13]
	v_and_b32_sdwa v15, v10, v207 dst_sel:DWORD dst_unused:UNUSED_PAD src0_sel:WORD_1 src1_sel:DWORD
	v_add3_u32 v10, v10, v15, s33
	v_add3_u32 v11, v11, v14, s33
	v_and_b32_sdwa v14, v13, v207 dst_sel:DWORD dst_unused:UNUSED_PAD src0_sel:WORD_1 src1_sel:DWORD
	v_and_b32_sdwa v15, v12, v207 dst_sel:DWORD dst_unused:UNUSED_PAD src0_sel:WORD_1 src1_sel:DWORD
	v_add3_u32 v13, v13, v14, s33
	v_add3_u32 v12, v12, v15, s33
	v_and_b32_e32 v13, 0xffff0000, v13
	v_and_b32_e32 v12, 0xffff0000, v12
	v_or_b32_sdwa v11, v13, v11 dst_sel:DWORD dst_unused:UNUSED_PAD src0_sel:DWORD src1_sel:WORD_1
	v_or_b32_sdwa v10, v12, v10 dst_sel:DWORD dst_unused:UNUSED_PAD src0_sel:DWORD src1_sel:WORD_1
	global_store_dwordx2 v[22:23], v[10:11], off
	s_waitcnt vmcnt(4)
; __device__ __forceinline__ unsigned pk2(float lo, float hi) { return f2bf(lo) | (f2bf(hi) << 16); }
; template <int CTRL> __device__ __forceinline__ float dpp_f(float v) { return __builtin_bit_cast(float, __builtin_amdgcn_update_dpp(0, __builtin_bit_cast(int, v), CTRL, 0xF, 0xF, true)); }
; __device__ __forceinline__ float row16_sum(float v) { v += dpp_f<0x128>(v); v += dpp_f<0x124>(v); v += dpp_f<0x4E>(v); v += dpp_f<0xB1>(v); return v; }
; __device__ __forceinline__ void post_token(int pos, const float* gaq, const float* gak, const float* gbq, const float* gbk, const float* gik, ...
;     ...
;     for (int it = 0; it < 4; ++it) { float o[4];
; #pragma unroll
;         for (int e = 0; e < 4; ++e) { const float x = xi[it][e]; const float px = dpp_f<0x128>(x); o[e] = x * ci[e] + px * si[e]; }
;         u32x2 ow; ow.x = pk2(o[0], o[1]); ow.y = pk2(o[2], o[3]); *(u32x2*)(iq + (it * 4 + grp) * 64 + 4 * c) = ow; }
;     { const f32x4 gk = *(const f32x4*)(gik + 4 * c);
;       float ss = (xk[0] * xk[0] + xk[1] * xk[1]) + (xk[2] * xk[2] + xk[3] * xk[3]); ss = row16_sum(ss); const float r = 1.f / sqrtf(ss * (1.f / 64.f) + EPS);
;       float o[4];
; #pragma unroll
;       for (int e = 0; e < 4; ++e) { const float y = xk[e] * r * gk[e]; const float py = dpp_f<0x128>(y); o[e] = y * ci[e] + py * si[e]; }
;       if (grp == 0) { u32x2 ow; ow.x = pk2(o[0], o[1]); ow.y = pk2(o[2], o[3]); *(u32x2*)(ik + 4 * c) = ow; } }
;     if (lane < 16) iw[lane] = irow[1088 + lane] * 0.25f;
	v_mov_b32_dpp v11, v62 row_ror:8 row_mask:0xf bank_mask:0xf bound_ctrl:1
	v_mov_b32_dpp v10, v60 row_ror:8 row_mask:0xf bank_mask:0xf bound_ctrl:1
	v_mov_b32_dpp v12, v61 row_ror:8 row_mask:0xf bank_mask:0xf bound_ctrl:1
	v_mov_b32_dpp v13, v63 row_ror:8 row_mask:0xf bank_mask:0xf bound_ctrl:1
	v_mov_b32_e32 v14, v60
	v_mov_b32_e32 v15, v62
	v_pk_mul_f32 v[10:11], v[54:55], v[10:11]
	v_mov_b32_e32 v62, v61
	v_pk_fma_f32 v[10:11], v[8:9], v[14:15], v[10:11]
	v_pk_mul_f32 v[12:13], v[56:57], v[12:13]
	v_and_b32_sdwa v14, v11, v207 dst_sel:DWORD dst_unused:UNUSED_PAD src0_sel:WORD_1 src1_sel:DWORD
	v_pk_fma_f32 v[12:13], v[52:53], v[62:63], v[12:13]
	v_and_b32_sdwa v15, v10, v207 dst_sel:DWORD dst_unused:UNUSED_PAD src0_sel:WORD_1 src1_sel:DWORD
	v_add3_u32 v10, v10, v15, s33
	v_add3_u32 v11, v11, v14, s33
	v_and_b32_sdwa v14, v13, v207 dst_sel:DWORD dst_unused:UNUSED_PAD src0_sel:WORD_1 src1_sel:DWORD
	v_and_b32_sdwa v15, v12, v207 dst_sel:DWORD dst_unused:UNUSED_PAD src0_sel:WORD_1 src1_sel:DWORD
	v_add3_u32 v13, v13, v14, s33
	v_add3_u32 v12, v12, v15, s33
	v_and_b32_e32 v13, 0xffff0000, v13
	v_and_b32_e32 v12, 0xffff0000, v12
	v_or_b32_sdwa v11, v13, v11 dst_sel:DWORD dst_unused:UNUSED_PAD src0_sel:DWORD src1_sel:WORD_1
	v_or_b32_sdwa v10, v12, v10 dst_sel:DWORD dst_unused:UNUSED_PAD src0_sel:DWORD src1_sel:WORD_1
	global_store_dwordx2 v[22:23], v[10:11], off offset:512
	global_load_dwordx4 v[14:17], v[32:33], off
	s_waitcnt vmcnt(5)
	v_pk_mul_f32 v[10:11], v[66:67], v[66:67]
	v_pk_mul_f32 v[12:13], v[64:65], v[64:65]
	s_nop 0
	v_pk_mov_b32 v[18:19], v[12:13], v[10:11] op_sel:[1,0]
	v_mov_b32_e32 v13, v11
	v_pk_add_f32 v[10:11], v[18:19], v[12:13]
	s_nop 0
	v_add_f32_e32 v10, v10, v11
	s_nop 1
	v_add_f32_dpp v10, v10, v10 row_ror:8 row_mask:0xf bank_mask:0xf bound_ctrl:1
	s_nop 1
	v_add_f32_dpp v10, v10, v10 row_ror:4 row_mask:0xf bank_mask:0xf bound_ctrl:1
	s_nop 1
	v_add_f32_dpp v10, v10, v10 quad_perm:[2,3,0,1] row_mask:0xf bank_mask:0xf bound_ctrl:1
	s_nop 1
	v_add_f32_dpp v10, v10, v10 quad_perm:[1,0,3,2] row_mask:0xf bank_mask:0xf bound_ctrl:1
	v_fmamk_f32 v10, v10, 0x3c800000, v205
	v_mul_f32_e32 v11, 0x4f800000, v10
	v_cmp_gt_f32_e32 vcc, s8, v10
	s_nop 1
	v_cndmask_b32_e32 v10, v10, v11, vcc
	v_sqrt_f32_e32 v11, v10
	s_nop 0
	v_add_u32_e32 v12, -1, v11
	v_fma_f32 v13, -v12, v11, v10
	v_cmp_ge_f32_e64 s[0:1], 0, v13
	v_add_u32_e32 v13, 1, v11
	s_nop 0
	v_cndmask_b32_e64 v12, v11, v12, s[0:1]
	v_fma_f32 v11, -v13, v11, v10
	v_cmp_lt_f32_e64 s[0:1], 0, v11
	s_nop 1
	v_cndmask_b32_e64 v11, v12, v13, s[0:1]
	v_mul_f32_e32 v12, 0x37800000, v11
	v_cndmask_b32_e32 v11, v11, v12, vcc
	v_cmp_class_f32_e32 vcc, v10, v206
	s_nop 1
	v_cndmask_b32_e32 v10, v11, v10, vcc
	v_div_scale_f32 v11, s[0:1], v10, v10, 1.0
	v_rcp_f32_e32 v12, v11
	s_nop 0
	v_fma_f32 v13, -v11, v12, 1.0
	v_fmac_f32_e32 v12, v13, v12
	v_div_scale_f32 v13, vcc, 1.0, v10, 1.0
	v_mul_f32_e32 v18, v13, v12
	v_fma_f32 v19, -v11, v18, v13
	v_fmac_f32_e32 v18, v19, v12
	v_fma_f32 v11, -v11, v18, v13
	v_div_fmas_f32 v11, v11, v12, v18
	v_div_fixup_f32 v18, v11, v10, 1.0
	v_mov_b32_e32 v10, v64
	v_mov_b32_e32 v11, v66
	v_mov_b32_e32 v66, v65
	v_pk_mul_f32 v[10:11], v[10:11], v[18:19] op_sel_hi:[1,0]
	v_pk_mul_f32 v[18:19], v[66:67], v[18:19] op_sel_hi:[1,0]
	s_waitcnt vmcnt(0)
	v_mov_b32_e32 v12, v14
	v_mov_b32_e32 v13, v16
	v_mov_b32_e32 v16, v15
	v_pk_mul_f32 v[12:13], v[12:13], v[10:11]
	v_pk_mul_f32 v[16:17], v[16:17], v[18:19]
	s_nop 0
	v_mov_b32_dpp v10, v12 row_ror:8 row_mask:0xf bank_mask:0xf bound_ctrl:1
	v_mov_b32_dpp v14, v16 row_ror:8 row_mask:0xf bank_mask:0xf bound_ctrl:1
	v_mov_b32_dpp v11, v13 row_ror:8 row_mask:0xf bank_mask:0xf bound_ctrl:1
	v_mov_b32_dpp v15, v17 row_ror:8 row_mask:0xf bank_mask:0xf bound_ctrl:1
	s_and_saveexec_b64 s[0:1], s[38:39]
	s_cbranch_execz .LBB0_1007
	v_pk_mul_f32 v[8:9], v[8:9], v[12:13]
	v_pk_mul_f32 v[16:17], v[52:53], v[16:17]
	v_pk_fma_f32 v[8:9], v[54:55], v[10:11], v[8:9]
	v_pk_fma_f32 v[12:13], v[56:57], v[14:15], v[16:17]
	v_and_b32_sdwa v10, v9, v207 dst_sel:DWORD dst_unused:UNUSED_PAD src0_sel:WORD_1 src1_sel:DWORD
	v_and_b32_sdwa v11, v8, v207 dst_sel:DWORD dst_unused:UNUSED_PAD src0_sel:WORD_1 src1_sel:DWORD
	v_add3_u32 v8, v8, v11, s33
	v_add3_u32 v9, v9, v10, s33
	v_and_b32_sdwa v10, v13, v207 dst_sel:DWORD dst_unused:UNUSED_PAD src0_sel:WORD_1 src1_sel:DWORD
	v_and_b32_sdwa v11, v12, v207 dst_sel:DWORD dst_unused:UNUSED_PAD src0_sel:WORD_1 src1_sel:DWORD
	v_add3_u32 v10, v13, v10, s33
	v_add3_u32 v11, v12, v11, s33
	v_and_b32_e32 v10, 0xffff0000, v10
	v_and_b32_e32 v11, 0xffff0000, v11
	v_or_b32_sdwa v9, v10, v9 dst_sel:DWORD dst_unused:UNUSED_PAD src0_sel:DWORD src1_sel:WORD_1
	v_or_b32_sdwa v8, v11, v8 dst_sel:DWORD dst_unused:UNUSED_PAD src0_sel:DWORD src1_sel:WORD_1
	v_lshl_add_u64 v[10:11], s[90:91], 0, v[38:39]
	global_store_dwordx2 v[10:11], v[8:9], off
	v_lshl_add_u64 v[8:9], s[90:91], 0, v[50:51]
	global_load_dword v10, v[8:9], off
	v_lshl_add_u64 v[8:9], s[90:91], 0, v[36:37]
	s_waitcnt vmcnt(0)
	v_mul_f32_e32 v10, 0x3e800000, v10
	global_store_dword v[8:9], v10, off
	s_branch .LBB0_1007

; __device__ __forceinline__ unsigned pk2(float lo, float hi) { return f2bf(lo) | (f2bf(hi) << 16); }
;     __device__ __forceinline__ void operator()(const f32x4 (&acc)[2][2][4][2], const pg8::Unit& u, int wr, int wc, int fr, int fq) const {
;     ...
;                 const size_t row = (size_t)(row0 + ai * 128 + m * 16);
;                 float ssq = 0.f, rstd = 1.f;
;                 if constexpr (MODE == 8) rstd = 1.f / sqrtf(rs[row] * (1.f / DM) + EPS);
; #pragma unroll
;                 for (int bj = 0; bj < 2; ++bj) {
;                     const int col = col0 + bj * 128;
;                     f32x4 v0 = acc[ai][bj][m][0], v1 = acc[ai][bj][m][1];
;                     if constexpr (MODE == 0 || MODE == 1) { v0 = v0 * scale; v1 = v1 * scale; }
;                     if constexpr (MODE == 6) { float* p = of + row * IDXW + col; *(f32x4*)p = v0; *(f32x4*)(p + 4) = v1; }
;                     else if constexpr (MODE == 0) {
;                         if (u.pn >= COL_BV / 256) {
;                             const float x8[8] = {v0[0], v0[1], v0[2], v0[3], v1[0], v1[1], v1[2], v1[3]};
;                             *(u32x2*)((unsigned char*)aux + row * 1024 + (col - COL_BV)) = to_fp8x8(x8);
;                         } else { u32x4 w; w.x = pk2(v0[0], v0[1]); w.y = pk2(v0[2], v0[3]); w.z = pk2(v1[0], v1[1]); w.w = pk2(v1[2], v1[3]);
;                             *(u32x4*)(ob + row * QKVW + col) = w; }
.LBB0_1025:
	v_lshl_add_u32 v2, s35, 8, v214
	s_movk_i32 s11, 0x3c00
	s_cmp_lt_i32 s34, 26
	v_lshl_or_b32 v160, s34, 8, v216
	v_mad_i64_i32 v[0:1], s[40:41], v2, s11, 0
	s_cselect_b64 s[44:45], -1, 0
	v_pk_mul_f32 v[8:9], v[158:159], s[18:19] op_sel_hi:[1,0]
	v_pk_mul_f32 v[12:13], v[156:157], s[18:19] op_sel_hi:[1,0]
	v_pk_mul_f32 v[10:11], v[154:155], s[18:19] op_sel_hi:[1,0]
	v_pk_mul_f32 v[14:15], v[152:153], s[18:19] op_sel_hi:[1,0]
	s_mov_b64 s[40:41], -1
	s_and_b64 vcc, exec, s[44:45]
	v_lshl_add_u64 v[4:5], s[20:21], 0, v[0:1]
	v_ashrrev_i32_e32 v1, 31, v160
	s_nop 15
	s_nop 15
	s_cbranch_vccz .LBB0_1027
	v_cvt_pk_bf16_f32 v16, v12, v13
	v_cvt_pk_bf16_f32 v17, v8, v9
	v_cvt_pk_bf16_f32 v18, v14, v15
	v_cvt_pk_bf16_f32 v19, v10, v11
	v_mov_b32_e32 v0, v160
	v_lshl_add_u64 v[6:7], v[0:1], 1, v[4:5]
	global_store_dwordx4 v[6:7], v[16:19], off
	s_mov_b64 s[40:41], 0

; __device__ __forceinline__ unsigned pk2(float lo, float hi) { return f2bf(lo) | (f2bf(hi) << 16); }
;     __device__ __forceinline__ void operator()(const f32x4 (&acc)[2][2][4][2], const pg8::Unit& u, int wr, int wc, int fr, int fq) const {
;     ...
;                 const size_t row = (size_t)(row0 + ai * 128 + m * 16);
;                 float ssq = 0.f, rstd = 1.f;
;                 if constexpr (MODE == 8) rstd = 1.f / sqrtf(rs[row] * (1.f / DM) + EPS);
; #pragma unroll
;                 for (int bj = 0; bj < 2; ++bj) {
;                     const int col = col0 + bj * 128;
;                     f32x4 v0 = acc[ai][bj][m][0], v1 = acc[ai][bj][m][1];
;                     if constexpr (MODE == 0 || MODE == 1) { v0 = v0 * scale; v1 = v1 * scale; }
;                     if constexpr (MODE == 6) { float* p = of + row * IDXW + col; *(f32x4*)p = v0; *(f32x4*)(p + 4) = v1; }
;                     else if constexpr (MODE == 0) {
;                         if (u.pn >= COL_BV / 256) {
;                             const float x8[8] = {v0[0], v0[1], v0[2], v0[3], v1[0], v1[1], v1[2], v1[3]};
;                             *(u32x2*)((unsigned char*)aux + row * 1024 + (col - COL_BV)) = to_fp8x8(x8);
;                         } else { u32x4 w; w.x = pk2(v0[0], v0[1]); w.y = pk2(v0[2], v0[3]); w.z = pk2(v1[0], v1[1]); w.w = pk2(v1[2], v1[3]);
;                             *(u32x4*)(ob + row * QKVW + col) = w; }
.LBB0_1029:
	v_cndmask_b32_e64 v0, 0, 1, s[44:45]
	v_pk_mul_f32 v[8:9], v[150:151], s[18:19] op_sel_hi:[1,0]
	v_pk_mul_f32 v[12:13], v[148:149], s[18:19] op_sel_hi:[1,0]
	v_pk_mul_f32 v[10:11], v[146:147], s[18:19] op_sel_hi:[1,0]
	v_pk_mul_f32 v[14:15], v[144:145], s[18:19] op_sel_hi:[1,0]
	v_cmp_ne_u32_e64 s[40:41], 1, v0
	s_andn2_b64 vcc, exec, s[44:45]
	s_mov_b64 s[34:35], -1
	s_cbranch_vccnz .LBB0_1031
	v_cvt_pk_bf16_f32 v16, v12, v13
	v_cvt_pk_bf16_f32 v17, v8, v9
	v_cvt_pk_bf16_f32 v18, v14, v15
	v_cvt_pk_bf16_f32 v19, v10, v11
	v_mov_b32_e32 v0, v160
	v_lshl_add_u64 v[4:5], v[0:1], 1, v[4:5]
	s_mov_b64 s[34:35], 0
	global_store_dwordx4 v[4:5], v[16:19], off offset:256

; __device__ __forceinline__ unsigned pk2(float lo, float hi) { return f2bf(lo) | (f2bf(hi) << 16); }
;     __device__ __forceinline__ void operator()(const f32x4 (&acc)[2][2][4][2], const pg8::Unit& u, int wr, int wc, int fr, int fq) const {
;     ...
;                 const size_t row = (size_t)(row0 + ai * 128 + m * 16);
;                 float ssq = 0.f, rstd = 1.f;
;                 if constexpr (MODE == 8) rstd = 1.f / sqrtf(rs[row] * (1.f / DM) + EPS);
; #pragma unroll
;                 for (int bj = 0; bj < 2; ++bj) {
;                     const int col = col0 + bj * 128;
;                     f32x4 v0 = acc[ai][bj][m][0], v1 = acc[ai][bj][m][1];
;                     if constexpr (MODE == 0 || MODE == 1) { v0 = v0 * scale; v1 = v1 * scale; }
;                     if constexpr (MODE == 6) { float* p = of + row * IDXW + col; *(f32x4*)p = v0; *(f32x4*)(p + 4) = v1; }
;                     else if constexpr (MODE == 0) {
;                         if (u.pn >= COL_BV / 256) {
;                             const float x8[8] = {v0[0], v0[1], v0[2], v0[3], v1[0], v1[1], v1[2], v1[3]};
;                             *(u32x2*)((unsigned char*)aux + row * 1024 + (col - COL_BV)) = to_fp8x8(x8);
;                         } else { u32x4 w; w.x = pk2(v0[0], v0[1]); w.y = pk2(v0[2], v0[3]); w.z = pk2(v1[0], v1[1]); w.w = pk2(v1[2], v1[3]);
;                             *(u32x4*)(ob + row * QKVW + col) = w; }
.LBB0_1033:
	v_or_b32_e32 v6, 16, v2
	v_mad_i64_i32 v[4:5], s[34:35], v6, s11, 0
	v_pk_mul_f32 v[8:9], v[142:143], s[18:19] op_sel_hi:[1,0]
	v_pk_mul_f32 v[12:13], v[140:141], s[18:19] op_sel_hi:[1,0]
	v_pk_mul_f32 v[10:11], v[138:139], s[18:19] op_sel_hi:[1,0]
	v_pk_mul_f32 v[14:15], v[136:137], s[18:19] op_sel_hi:[1,0]
	s_mov_b64 s[44:45], -1
	s_and_b64 vcc, exec, s[40:41]
	v_lshl_add_u64 v[4:5], s[20:21], 0, v[4:5]
	s_cbranch_vccnz .LBB0_1035
	v_cvt_pk_bf16_f32 v16, v12, v13
	v_cvt_pk_bf16_f32 v17, v8, v9
	v_cvt_pk_bf16_f32 v18, v14, v15
	v_cvt_pk_bf16_f32 v19, v10, v11
	v_mov_b32_e32 v0, v160
	v_lshl_add_u64 v[20:21], v[0:1], 1, v[4:5]
	s_mov_b64 s[44:45], 0
	global_store_dwordx4 v[20:21], v[16:19], off

; __device__ __forceinline__ unsigned pk2(float lo, float hi) { return f2bf(lo) | (f2bf(hi) << 16); }
;     __device__ __forceinline__ void operator()(const f32x4 (&acc)[2][2][4][2], const pg8::Unit& u, int wr, int wc, int fr, int fq) const {
;     ...
;                 const size_t row = (size_t)(row0 + ai * 128 + m * 16);
;                 float ssq = 0.f, rstd = 1.f;
;                 if constexpr (MODE == 8) rstd = 1.f / sqrtf(rs[row] * (1.f / DM) + EPS);
; #pragma unroll
;                 for (int bj = 0; bj < 2; ++bj) {
;                     const int col = col0 + bj * 128;
;                     f32x4 v0 = acc[ai][bj][m][0], v1 = acc[ai][bj][m][1];
;                     if constexpr (MODE == 0 || MODE == 1) { v0 = v0 * scale; v1 = v1 * scale; }
;                     if constexpr (MODE == 6) { float* p = of + row * IDXW + col; *(f32x4*)p = v0; *(f32x4*)(p + 4) = v1; }
;                     else if constexpr (MODE == 0) {
;                         if (u.pn >= COL_BV / 256) {
;                             const float x8[8] = {v0[0], v0[1], v0[2], v0[3], v1[0], v1[1], v1[2], v1[3]};
;                             *(u32x2*)((unsigned char*)aux + row * 1024 + (col - COL_BV)) = to_fp8x8(x8);
;                         } else { u32x4 w; w.x = pk2(v0[0], v0[1]); w.y = pk2(v0[2], v0[3]); w.z = pk2(v1[0], v1[1]); w.w = pk2(v1[2], v1[3]);
;                             *(u32x4*)(ob + row * QKVW + col) = w; }
.LBB0_1037:
	v_pk_mul_f32 v[8:9], v[134:135], s[18:19] op_sel_hi:[1,0]
	v_pk_mul_f32 v[12:13], v[132:133], s[18:19] op_sel_hi:[1,0]
	v_pk_mul_f32 v[10:11], v[130:131], s[18:19] op_sel_hi:[1,0]
	v_pk_mul_f32 v[14:15], v[128:129], s[18:19] op_sel_hi:[1,0]
	s_and_b64 vcc, exec, s[40:41]
	s_mov_b64 s[34:35], -1
	s_cbranch_vccnz .LBB0_1039
	v_cvt_pk_bf16_f32 v16, v12, v13
	v_cvt_pk_bf16_f32 v17, v8, v9
	v_cvt_pk_bf16_f32 v18, v14, v15
	v_cvt_pk_bf16_f32 v19, v10, v11
	v_mov_b32_e32 v0, v160
	v_lshl_add_u64 v[4:5], v[0:1], 1, v[4:5]
	s_mov_b64 s[34:35], 0
	global_store_dwordx4 v[4:5], v[16:19], off offset:256

; __device__ __forceinline__ unsigned pk2(float lo, float hi) { return f2bf(lo) | (f2bf(hi) << 16); }
;     __device__ __forceinline__ void operator()(const f32x4 (&acc)[2][2][4][2], const pg8::Unit& u, int wr, int wc, int fr, int fq) const {
;     ...
;                 const size_t row = (size_t)(row0 + ai * 128 + m * 16);
;                 float ssq = 0.f, rstd = 1.f;
;                 if constexpr (MODE == 8) rstd = 1.f / sqrtf(rs[row] * (1.f / DM) + EPS);
; #pragma unroll
;                 for (int bj = 0; bj < 2; ++bj) {
;                     const int col = col0 + bj * 128;
;                     f32x4 v0 = acc[ai][bj][m][0], v1 = acc[ai][bj][m][1];
;                     if constexpr (MODE == 0 || MODE == 1) { v0 = v0 * scale; v1 = v1 * scale; }
;                     if constexpr (MODE == 6) { float* p = of + row * IDXW + col; *(f32x4*)p = v0; *(f32x4*)(p + 4) = v1; }
;                     else if constexpr (MODE == 0) {
;                         if (u.pn >= COL_BV / 256) {
;                             const float x8[8] = {v0[0], v0[1], v0[2], v0[3], v1[0], v1[1], v1[2], v1[3]};
;                             *(u32x2*)((unsigned char*)aux + row * 1024 + (col - COL_BV)) = to_fp8x8(x8);
;                         } else { u32x4 w; w.x = pk2(v0[0], v0[1]); w.y = pk2(v0[2], v0[3]); w.z = pk2(v1[0], v1[1]); w.w = pk2(v1[2], v1[3]);
;                             *(u32x4*)(ob + row * QKVW + col) = w; }
.LBB0_1041:
	v_or_b32_e32 v6, 32, v2
	v_mad_i64_i32 v[4:5], s[34:35], v6, s11, 0
	v_pk_mul_f32 v[8:9], v[126:127], s[18:19] op_sel_hi:[1,0]
	v_pk_mul_f32 v[12:13], v[124:125], s[18:19] op_sel_hi:[1,0]
	v_pk_mul_f32 v[10:11], v[122:123], s[18:19] op_sel_hi:[1,0]
	v_pk_mul_f32 v[14:15], v[120:121], s[18:19] op_sel_hi:[1,0]
	s_mov_b64 s[44:45], -1
	s_and_b64 vcc, exec, s[40:41]
	v_lshl_add_u64 v[4:5], s[20:21], 0, v[4:5]
	s_cbranch_vccnz .LBB0_1043
	v_cvt_pk_bf16_f32 v16, v12, v13
	v_cvt_pk_bf16_f32 v17, v8, v9
	v_cvt_pk_bf16_f32 v18, v14, v15
	v_cvt_pk_bf16_f32 v19, v10, v11
	v_mov_b32_e32 v0, v160
	v_lshl_add_u64 v[20:21], v[0:1], 1, v[4:5]
	s_mov_b64 s[44:45], 0
	global_store_dwordx4 v[20:21], v[16:19], off

; __device__ __forceinline__ unsigned pk2(float lo, float hi) { return f2bf(lo) | (f2bf(hi) << 16); }
;     __device__ __forceinline__ void operator()(const f32x4 (&acc)[2][2][4][2], const pg8::Unit& u, int wr, int wc, int fr, int fq) const {
;     ...
;                 const size_t row = (size_t)(row0 + ai * 128 + m * 16);
;                 float ssq = 0.f, rstd = 1.f;
;                 if constexpr (MODE == 8) rstd = 1.f / sqrtf(rs[row] * (1.f / DM) + EPS);
; #pragma unroll
;                 for (int bj = 0; bj < 2; ++bj) {
;                     const int col = col0 + bj * 128;
;                     f32x4 v0 = acc[ai][bj][m][0], v1 = acc[ai][bj][m][1];
;                     if constexpr (MODE == 0 || MODE == 1) { v0 = v0 * scale; v1 = v1 * scale; }
;                     if constexpr (MODE == 6) { float* p = of + row * IDXW + col; *(f32x4*)p = v0; *(f32x4*)(p + 4) = v1; }
;                     else if constexpr (MODE == 0) {
;                         if (u.pn >= COL_BV / 256) {
;                             const float x8[8] = {v0[0], v0[1], v0[2], v0[3], v1[0], v1[1], v1[2], v1[3]};
;                             *(u32x2*)((unsigned char*)aux + row * 1024 + (col - COL_BV)) = to_fp8x8(x8);
;                         } else { u32x4 w; w.x = pk2(v0[0], v0[1]); w.y = pk2(v0[2], v0[3]); w.z = pk2(v1[0], v1[1]); w.w = pk2(v1[2], v1[3]);
;                             *(u32x4*)(ob + row * QKVW + col) = w; }
.LBB0_1045:
	v_pk_mul_f32 v[8:9], v[118:119], s[18:19] op_sel_hi:[1,0]
	v_pk_mul_f32 v[12:13], v[116:117], s[18:19] op_sel_hi:[1,0]
	v_pk_mul_f32 v[10:11], v[114:115], s[18:19] op_sel_hi:[1,0]
	v_pk_mul_f32 v[14:15], v[112:113], s[18:19] op_sel_hi:[1,0]
	s_and_b64 vcc, exec, s[40:41]
	s_mov_b64 s[34:35], -1
	s_cbranch_vccnz .LBB0_1047
	v_cvt_pk_bf16_f32 v16, v12, v13
	v_cvt_pk_bf16_f32 v17, v8, v9
	v_cvt_pk_bf16_f32 v18, v14, v15
	v_cvt_pk_bf16_f32 v19, v10, v11
	v_mov_b32_e32 v0, v160
	v_lshl_add_u64 v[4:5], v[0:1], 1, v[4:5]
	s_mov_b64 s[34:35], 0
	global_store_dwordx4 v[4:5], v[16:19], off offset:256

; __device__ __forceinline__ unsigned pk2(float lo, float hi) { return f2bf(lo) | (f2bf(hi) << 16); }
;     __device__ __forceinline__ void operator()(const f32x4 (&acc)[2][2][4][2], const pg8::Unit& u, int wr, int wc, int fr, int fq) const {
;     ...
;                 const size_t row = (size_t)(row0 + ai * 128 + m * 16);
;                 float ssq = 0.f, rstd = 1.f;
;                 if constexpr (MODE == 8) rstd = 1.f / sqrtf(rs[row] * (1.f / DM) + EPS);
; #pragma unroll
;                 for (int bj = 0; bj < 2; ++bj) {
;                     const int col = col0 + bj * 128;
;                     f32x4 v0 = acc[ai][bj][m][0], v1 = acc[ai][bj][m][1];
;                     if constexpr (MODE == 0 || MODE == 1) { v0 = v0 * scale; v1 = v1 * scale; }
;                     if constexpr (MODE == 6) { float* p = of + row * IDXW + col; *(f32x4*)p = v0; *(f32x4*)(p + 4) = v1; }
;                     else if constexpr (MODE == 0) {
;                         if (u.pn >= COL_BV / 256) {
;                             const float x8[8] = {v0[0], v0[1], v0[2], v0[3], v1[0], v1[1], v1[2], v1[3]};
;                             *(u32x2*)((unsigned char*)aux + row * 1024 + (col - COL_BV)) = to_fp8x8(x8);
;                         } else { u32x4 w; w.x = pk2(v0[0], v0[1]); w.y = pk2(v0[2], v0[3]); w.z = pk2(v1[0], v1[1]); w.w = pk2(v1[2], v1[3]);
;                             *(u32x4*)(ob + row * QKVW + col) = w; }
.LBB0_1049:
	v_or_b32_e32 v6, 48, v2
	v_mad_i64_i32 v[4:5], s[34:35], v6, s11, 0
	v_pk_mul_f32 v[8:9], v[110:111], s[18:19] op_sel_hi:[1,0]
	v_pk_mul_f32 v[12:13], v[108:109], s[18:19] op_sel_hi:[1,0]
	v_pk_mul_f32 v[10:11], v[106:107], s[18:19] op_sel_hi:[1,0]
	v_pk_mul_f32 v[14:15], v[104:105], s[18:19] op_sel_hi:[1,0]
	s_mov_b64 s[44:45], -1
	s_and_b64 vcc, exec, s[40:41]
	v_lshl_add_u64 v[4:5], s[20:21], 0, v[4:5]
	s_cbranch_vccnz .LBB0_1051
	v_cvt_pk_bf16_f32 v16, v12, v13
	v_cvt_pk_bf16_f32 v17, v8, v9
	v_cvt_pk_bf16_f32 v18, v14, v15
	v_cvt_pk_bf16_f32 v19, v10, v11
	v_mov_b32_e32 v0, v160
	v_lshl_add_u64 v[20:21], v[0:1], 1, v[4:5]
	s_mov_b64 s[44:45], 0
	global_store_dwordx4 v[20:21], v[16:19], off

; __device__ __forceinline__ unsigned pk2(float lo, float hi) { return f2bf(lo) | (f2bf(hi) << 16); }
;     __device__ __forceinline__ void operator()(const f32x4 (&acc)[2][2][4][2], const pg8::Unit& u, int wr, int wc, int fr, int fq) const {
;     ...
;                 const size_t row = (size_t)(row0 + ai * 128 + m * 16);
;                 float ssq = 0.f, rstd = 1.f;
;                 if constexpr (MODE == 8) rstd = 1.f / sqrtf(rs[row] * (1.f / DM) + EPS);
; #pragma unroll
;                 for (int bj = 0; bj < 2; ++bj) {
;                     const int col = col0 + bj * 128;
;                     f32x4 v0 = acc[ai][bj][m][0], v1 = acc[ai][bj][m][1];
;                     if constexpr (MODE == 0 || MODE == 1) { v0 = v0 * scale; v1 = v1 * scale; }
;                     if constexpr (MODE == 6) { float* p = of + row * IDXW + col; *(f32x4*)p = v0; *(f32x4*)(p + 4) = v1; }
;                     else if constexpr (MODE == 0) {
;                         if (u.pn >= COL_BV / 256) {
;                             const float x8[8] = {v0[0], v0[1], v0[2], v0[3], v1[0], v1[1], v1[2], v1[3]};
;                             *(u32x2*)((unsigned char*)aux + row * 1024 + (col - COL_BV)) = to_fp8x8(x8);
;                         } else { u32x4 w; w.x = pk2(v0[0], v0[1]); w.y = pk2(v0[2], v0[3]); w.z = pk2(v1[0], v1[1]); w.w = pk2(v1[2], v1[3]);
;                             *(u32x4*)(ob + row * QKVW + col) = w; }
.LBB0_1053:
	v_pk_mul_f32 v[8:9], v[102:103], s[18:19] op_sel_hi:[1,0]
	v_pk_mul_f32 v[12:13], v[100:101], s[18:19] op_sel_hi:[1,0]
	v_pk_mul_f32 v[10:11], v[98:99], s[18:19] op_sel_hi:[1,0]
	v_pk_mul_f32 v[14:15], v[96:97], s[18:19] op_sel_hi:[1,0]
	s_and_b64 vcc, exec, s[40:41]
	s_mov_b64 s[34:35], -1
	s_cbranch_vccnz .LBB0_1055
	v_cvt_pk_bf16_f32 v16, v12, v13
	v_cvt_pk_bf16_f32 v17, v8, v9
	v_cvt_pk_bf16_f32 v18, v14, v15
	v_cvt_pk_bf16_f32 v19, v10, v11
	v_mov_b32_e32 v0, v160
	v_lshl_add_u64 v[4:5], v[0:1], 1, v[4:5]
	s_mov_b64 s[34:35], 0
	global_store_dwordx4 v[4:5], v[16:19], off offset:256

; __device__ __forceinline__ unsigned pk2(float lo, float hi) { return f2bf(lo) | (f2bf(hi) << 16); }
;     __device__ __forceinline__ void operator()(const f32x4 (&acc)[2][2][4][2], const pg8::Unit& u, int wr, int wc, int fr, int fq) const {
;     ...
;                 const size_t row = (size_t)(row0 + ai * 128 + m * 16);
;                 float ssq = 0.f, rstd = 1.f;
;                 if constexpr (MODE == 8) rstd = 1.f / sqrtf(rs[row] * (1.f / DM) + EPS);
; #pragma unroll
;                 for (int bj = 0; bj < 2; ++bj) {
;                     const int col = col0 + bj * 128;
;                     f32x4 v0 = acc[ai][bj][m][0], v1 = acc[ai][bj][m][1];
;                     if constexpr (MODE == 0 || MODE == 1) { v0 = v0 * scale; v1 = v1 * scale; }
;                     if constexpr (MODE == 6) { float* p = of + row * IDXW + col; *(f32x4*)p = v0; *(f32x4*)(p + 4) = v1; }
;                     else if constexpr (MODE == 0) {
;                         if (u.pn >= COL_BV / 256) {
;                             const float x8[8] = {v0[0], v0[1], v0[2], v0[3], v1[0], v1[1], v1[2], v1[3]};
;                             *(u32x2*)((unsigned char*)aux + row * 1024 + (col - COL_BV)) = to_fp8x8(x8);
;                         } else { u32x4 w; w.x = pk2(v0[0], v0[1]); w.y = pk2(v0[2], v0[3]); w.z = pk2(v1[0], v1[1]); w.w = pk2(v1[2], v1[3]);
;                             *(u32x4*)(ob + row * QKVW + col) = w; }
.LBB0_1057:
	v_add_u32_e32 v6, 0x80, v2
	v_mad_i64_i32 v[4:5], s[34:35], v6, s11, 0
	v_pk_mul_f32 v[8:9], v[94:95], s[18:19] op_sel_hi:[1,0]
	v_pk_mul_f32 v[12:13], v[92:93], s[18:19] op_sel_hi:[1,0]
	v_pk_mul_f32 v[10:11], v[90:91], s[18:19] op_sel_hi:[1,0]
	v_pk_mul_f32 v[14:15], v[88:89], s[18:19] op_sel_hi:[1,0]
	s_mov_b64 s[44:45], -1
	s_and_b64 vcc, exec, s[40:41]
	v_lshl_add_u64 v[4:5], s[20:21], 0, v[4:5]
	s_cbranch_vccnz .LBB0_1059
	v_cvt_pk_bf16_f32 v16, v12, v13
	v_cvt_pk_bf16_f32 v17, v8, v9
	v_cvt_pk_bf16_f32 v18, v14, v15
	v_cvt_pk_bf16_f32 v19, v10, v11
	v_mov_b32_e32 v0, v160
	v_lshl_add_u64 v[20:21], v[0:1], 1, v[4:5]
	s_mov_b64 s[44:45], 0
	global_store_dwordx4 v[20:21], v[16:19], off

; __device__ __forceinline__ unsigned pk2(float lo, float hi) { return f2bf(lo) | (f2bf(hi) << 16); }
;     __device__ __forceinline__ void operator()(const f32x4 (&acc)[2][2][4][2], const pg8::Unit& u, int wr, int wc, int fr, int fq) const {
;     ...
;                 const size_t row = (size_t)(row0 + ai * 128 + m * 16);
;                 float ssq = 0.f, rstd = 1.f;
;                 if constexpr (MODE == 8) rstd = 1.f / sqrtf(rs[row] * (1.f / DM) + EPS);
; #pragma unroll
;                 for (int bj = 0; bj < 2; ++bj) {
;                     const int col = col0 + bj * 128;
;                     f32x4 v0 = acc[ai][bj][m][0], v1 = acc[ai][bj][m][1];
;                     if constexpr (MODE == 0 || MODE == 1) { v0 = v0 * scale; v1 = v1 * scale; }
;                     if constexpr (MODE == 6) { float* p = of + row * IDXW + col; *(f32x4*)p = v0; *(f32x4*)(p + 4) = v1; }
;                     else if constexpr (MODE == 0) {
;                         if (u.pn >= COL_BV / 256) {
;                             const float x8[8] = {v0[0], v0[1], v0[2], v0[3], v1[0], v1[1], v1[2], v1[3]};
;                             *(u32x2*)((unsigned char*)aux + row * 1024 + (col - COL_BV)) = to_fp8x8(x8);
;                         } else { u32x4 w; w.x = pk2(v0[0], v0[1]); w.y = pk2(v0[2], v0[3]); w.z = pk2(v1[0], v1[1]); w.w = pk2(v1[2], v1[3]);
;                             *(u32x4*)(ob + row * QKVW + col) = w; }
.LBB0_1061:
	v_pk_mul_f32 v[8:9], v[86:87], s[18:19] op_sel_hi:[1,0]
	v_pk_mul_f32 v[12:13], v[84:85], s[18:19] op_sel_hi:[1,0]
	v_pk_mul_f32 v[10:11], v[82:83], s[18:19] op_sel_hi:[1,0]
	v_pk_mul_f32 v[14:15], v[80:81], s[18:19] op_sel_hi:[1,0]
	s_and_b64 vcc, exec, s[40:41]
	s_mov_b64 s[34:35], -1
	s_cbranch_vccnz .LBB0_1063
	v_cvt_pk_bf16_f32 v16, v12, v13
	v_cvt_pk_bf16_f32 v17, v8, v9
	v_cvt_pk_bf16_f32 v18, v14, v15
	v_cvt_pk_bf16_f32 v19, v10, v11
	v_mov_b32_e32 v0, v160
	v_lshl_add_u64 v[4:5], v[0:1], 1, v[4:5]
	s_mov_b64 s[34:35], 0
	global_store_dwordx4 v[4:5], v[16:19], off offset:256

; __device__ __forceinline__ unsigned pk2(float lo, float hi) { return f2bf(lo) | (f2bf(hi) << 16); }
;     __device__ __forceinline__ void operator()(const f32x4 (&acc)[2][2][4][2], const pg8::Unit& u, int wr, int wc, int fr, int fq) const {
;     ...
;                 const size_t row = (size_t)(row0 + ai * 128 + m * 16);
;                 float ssq = 0.f, rstd = 1.f;
;                 if constexpr (MODE == 8) rstd = 1.f / sqrtf(rs[row] * (1.f / DM) + EPS);
; #pragma unroll
;                 for (int bj = 0; bj < 2; ++bj) {
;                     const int col = col0 + bj * 128;
;                     f32x4 v0 = acc[ai][bj][m][0], v1 = acc[ai][bj][m][1];
;                     if constexpr (MODE == 0 || MODE == 1) { v0 = v0 * scale; v1 = v1 * scale; }
;                     if constexpr (MODE == 6) { float* p = of + row * IDXW + col; *(f32x4*)p = v0; *(f32x4*)(p + 4) = v1; }
;                     else if constexpr (MODE == 0) {
;                         if (u.pn >= COL_BV / 256) {
;                             const float x8[8] = {v0[0], v0[1], v0[2], v0[3], v1[0], v1[1], v1[2], v1[3]};
;                             *(u32x2*)((unsigned char*)aux + row * 1024 + (col - COL_BV)) = to_fp8x8(x8);
;                         } else { u32x4 w; w.x = pk2(v0[0], v0[1]); w.y = pk2(v0[2], v0[3]); w.z = pk2(v1[0], v1[1]); w.w = pk2(v1[2], v1[3]);
;                             *(u32x4*)(ob + row * QKVW + col) = w; }
.LBB0_1065:
	v_add_u32_e32 v6, 0x90, v2
	v_mad_i64_i32 v[4:5], s[34:35], v6, s11, 0
	v_pk_mul_f32 v[8:9], v[78:79], s[18:19] op_sel_hi:[1,0]
	v_pk_mul_f32 v[12:13], v[76:77], s[18:19] op_sel_hi:[1,0]
	v_pk_mul_f32 v[10:11], v[74:75], s[18:19] op_sel_hi:[1,0]
	v_pk_mul_f32 v[14:15], v[72:73], s[18:19] op_sel_hi:[1,0]
	s_mov_b64 s[44:45], -1
	s_and_b64 vcc, exec, s[40:41]
	v_lshl_add_u64 v[4:5], s[20:21], 0, v[4:5]
	s_cbranch_vccnz .LBB0_1067
	v_cvt_pk_bf16_f32 v16, v12, v13
	v_cvt_pk_bf16_f32 v17, v8, v9
	v_cvt_pk_bf16_f32 v18, v14, v15
	v_cvt_pk_bf16_f32 v19, v10, v11
	v_mov_b32_e32 v0, v160
	v_lshl_add_u64 v[20:21], v[0:1], 1, v[4:5]
	s_mov_b64 s[44:45], 0
	global_store_dwordx4 v[20:21], v[16:19], off

; __device__ __forceinline__ unsigned pk2(float lo, float hi) { return f2bf(lo) | (f2bf(hi) << 16); }
;     __device__ __forceinline__ void operator()(const f32x4 (&acc)[2][2][4][2], const pg8::Unit& u, int wr, int wc, int fr, int fq) const {
;     ...
;                 const size_t row = (size_t)(row0 + ai * 128 + m * 16);
;                 float ssq = 0.f, rstd = 1.f;
;                 if constexpr (MODE == 8) rstd = 1.f / sqrtf(rs[row] * (1.f / DM) + EPS);
; #pragma unroll
;                 for (int bj = 0; bj < 2; ++bj) {
;                     const int col = col0 + bj * 128;
;                     f32x4 v0 = acc[ai][bj][m][0], v1 = acc[ai][bj][m][1];
;                     if constexpr (MODE == 0 || MODE == 1) { v0 = v0 * scale; v1 = v1 * scale; }
;                     if constexpr (MODE == 6) { float* p = of + row * IDXW + col; *(f32x4*)p = v0; *(f32x4*)(p + 4) = v1; }
;                     else if constexpr (MODE == 0) {
;                         if (u.pn >= COL_BV / 256) {
;                             const float x8[8] = {v0[0], v0[1], v0[2], v0[3], v1[0], v1[1], v1[2], v1[3]};
;                             *(u32x2*)((unsigned char*)aux + row * 1024 + (col - COL_BV)) = to_fp8x8(x8);
;                         } else { u32x4 w; w.x = pk2(v0[0], v0[1]); w.y = pk2(v0[2], v0[3]); w.z = pk2(v1[0], v1[1]); w.w = pk2(v1[2], v1[3]);
;                             *(u32x4*)(ob + row * QKVW + col) = w; }
.LBB0_1069:
	v_pk_mul_f32 v[8:9], v[70:71], s[18:19] op_sel_hi:[1,0]
	v_pk_mul_f32 v[12:13], v[68:69], s[18:19] op_sel_hi:[1,0]
	v_pk_mul_f32 v[10:11], v[66:67], s[18:19] op_sel_hi:[1,0]
	v_pk_mul_f32 v[14:15], v[64:65], s[18:19] op_sel_hi:[1,0]
	s_and_b64 vcc, exec, s[40:41]
	s_mov_b64 s[34:35], -1
	s_cbranch_vccnz .LBB0_1071
	v_cvt_pk_bf16_f32 v16, v12, v13
	v_cvt_pk_bf16_f32 v17, v8, v9
	v_cvt_pk_bf16_f32 v18, v14, v15
	v_cvt_pk_bf16_f32 v19, v10, v11
	v_mov_b32_e32 v0, v160
	v_lshl_add_u64 v[4:5], v[0:1], 1, v[4:5]
	s_mov_b64 s[34:35], 0
	global_store_dwordx4 v[4:5], v[16:19], off offset:256

; __device__ __forceinline__ unsigned pk2(float lo, float hi) { return f2bf(lo) | (f2bf(hi) << 16); }
;     __device__ __forceinline__ void operator()(const f32x4 (&acc)[2][2][4][2], const pg8::Unit& u, int wr, int wc, int fr, int fq) const {
;     ...
;                 const size_t row = (size_t)(row0 + ai * 128 + m * 16);
;                 float ssq = 0.f, rstd = 1.f;
;                 if constexpr (MODE == 8) rstd = 1.f / sqrtf(rs[row] * (1.f / DM) + EPS);
; #pragma unroll
;                 for (int bj = 0; bj < 2; ++bj) {
;                     const int col = col0 + bj * 128;
;                     f32x4 v0 = acc[ai][bj][m][0], v1 = acc[ai][bj][m][1];
;                     if constexpr (MODE == 0 || MODE == 1) { v0 = v0 * scale; v1 = v1 * scale; }
;                     if constexpr (MODE == 6) { float* p = of + row * IDXW + col; *(f32x4*)p = v0; *(f32x4*)(p + 4) = v1; }
;                     else if constexpr (MODE == 0) {
;                         if (u.pn >= COL_BV / 256) {
;                             const float x8[8] = {v0[0], v0[1], v0[2], v0[3], v1[0], v1[1], v1[2], v1[3]};
;                             *(u32x2*)((unsigned char*)aux + row * 1024 + (col - COL_BV)) = to_fp8x8(x8);
;                         } else { u32x4 w; w.x = pk2(v0[0], v0[1]); w.y = pk2(v0[2], v0[3]); w.z = pk2(v1[0], v1[1]); w.w = pk2(v1[2], v1[3]);
;                             *(u32x4*)(ob + row * QKVW + col) = w; }
.LBB0_1073:
	v_add_u32_e32 v6, 0xa0, v2
	v_mad_i64_i32 v[4:5], s[34:35], v6, s11, 0
	v_pk_mul_f32 v[8:9], v[62:63], s[18:19] op_sel_hi:[1,0]
	v_pk_mul_f32 v[12:13], v[60:61], s[18:19] op_sel_hi:[1,0]
	v_pk_mul_f32 v[10:11], v[58:59], s[18:19] op_sel_hi:[1,0]
	v_pk_mul_f32 v[14:15], v[56:57], s[18:19] op_sel_hi:[1,0]
	s_mov_b64 s[44:45], -1
	s_and_b64 vcc, exec, s[40:41]
	v_lshl_add_u64 v[4:5], s[20:21], 0, v[4:5]
	s_cbranch_vccnz .LBB0_1075
	v_cvt_pk_bf16_f32 v16, v12, v13
	v_cvt_pk_bf16_f32 v17, v8, v9
	v_cvt_pk_bf16_f32 v18, v14, v15
	v_cvt_pk_bf16_f32 v19, v10, v11
	v_mov_b32_e32 v0, v160
	v_lshl_add_u64 v[20:21], v[0:1], 1, v[4:5]
	s_mov_b64 s[44:45], 0
	global_store_dwordx4 v[20:21], v[16:19], off

; __device__ __forceinline__ unsigned pk2(float lo, float hi) { return f2bf(lo) | (f2bf(hi) << 16); }
;     __device__ __forceinline__ void operator()(const f32x4 (&acc)[2][2][4][2], const pg8::Unit& u, int wr, int wc, int fr, int fq) const {
;     ...
;                 const size_t row = (size_t)(row0 + ai * 128 + m * 16);
;                 float ssq = 0.f, rstd = 1.f;
;                 if constexpr (MODE == 8) rstd = 1.f / sqrtf(rs[row] * (1.f / DM) + EPS);
; #pragma unroll
;                 for (int bj = 0; bj < 2; ++bj) {
;                     const int col = col0 + bj * 128;
;                     f32x4 v0 = acc[ai][bj][m][0], v1 = acc[ai][bj][m][1];
;                     if constexpr (MODE == 0 || MODE == 1) { v0 = v0 * scale; v1 = v1 * scale; }
;                     if constexpr (MODE == 6) { float* p = of + row * IDXW + col; *(f32x4*)p = v0; *(f32x4*)(p + 4) = v1; }
;                     else if constexpr (MODE == 0) {
;                         if (u.pn >= COL_BV / 256) {
;                             const float x8[8] = {v0[0], v0[1], v0[2], v0[3], v1[0], v1[1], v1[2], v1[3]};
;                             *(u32x2*)((unsigned char*)aux + row * 1024 + (col - COL_BV)) = to_fp8x8(x8);
;                         } else { u32x4 w; w.x = pk2(v0[0], v0[1]); w.y = pk2(v0[2], v0[3]); w.z = pk2(v1[0], v1[1]); w.w = pk2(v1[2], v1[3]);
;                             *(u32x4*)(ob + row * QKVW + col) = w; }
.LBB0_1077:
	v_pk_mul_f32 v[8:9], v[54:55], s[18:19] op_sel_hi:[1,0]
	v_pk_mul_f32 v[12:13], v[52:53], s[18:19] op_sel_hi:[1,0]
	v_pk_mul_f32 v[10:11], v[50:51], s[18:19] op_sel_hi:[1,0]
	v_pk_mul_f32 v[14:15], v[48:49], s[18:19] op_sel_hi:[1,0]
	s_and_b64 vcc, exec, s[40:41]
	s_mov_b64 s[34:35], -1
	s_cbranch_vccnz .LBB0_1079
	v_cvt_pk_bf16_f32 v16, v12, v13
	v_cvt_pk_bf16_f32 v17, v8, v9
	v_cvt_pk_bf16_f32 v18, v14, v15
	v_cvt_pk_bf16_f32 v19, v10, v11
	v_mov_b32_e32 v0, v160
	v_lshl_add_u64 v[4:5], v[0:1], 1, v[4:5]
	s_mov_b64 s[34:35], 0
	global_store_dwordx4 v[4:5], v[16:19], off offset:256

; __device__ __forceinline__ unsigned pk2(float lo, float hi) { return f2bf(lo) | (f2bf(hi) << 16); }
;     __device__ __forceinline__ void operator()(const f32x4 (&acc)[2][2][4][2], const pg8::Unit& u, int wr, int wc, int fr, int fq) const {
;     ...
;                 const size_t row = (size_t)(row0 + ai * 128 + m * 16);
;                 float ssq = 0.f, rstd = 1.f;
;                 if constexpr (MODE == 8) rstd = 1.f / sqrtf(rs[row] * (1.f / DM) + EPS);
; #pragma unroll
;                 for (int bj = 0; bj < 2; ++bj) {
;                     const int col = col0 + bj * 128;
;                     f32x4 v0 = acc[ai][bj][m][0], v1 = acc[ai][bj][m][1];
;                     if constexpr (MODE == 0 || MODE == 1) { v0 = v0 * scale; v1 = v1 * scale; }
;                     if constexpr (MODE == 6) { float* p = of + row * IDXW + col; *(f32x4*)p = v0; *(f32x4*)(p + 4) = v1; }
;                     else if constexpr (MODE == 0) {
;                         if (u.pn >= COL_BV / 256) {
;                             const float x8[8] = {v0[0], v0[1], v0[2], v0[3], v1[0], v1[1], v1[2], v1[3]};
;                             *(u32x2*)((unsigned char*)aux + row * 1024 + (col - COL_BV)) = to_fp8x8(x8);
;                         } else { u32x4 w; w.x = pk2(v0[0], v0[1]); w.y = pk2(v0[2], v0[3]); w.z = pk2(v1[0], v1[1]); w.w = pk2(v1[2], v1[3]);
;                             *(u32x4*)(ob + row * QKVW + col) = w; }
.LBB0_1081:
	v_add_u32_e32 v4, 0xb0, v2
	v_mad_i64_i32 v[2:3], s[34:35], v4, s11, 0
	v_pk_mul_f32 v[6:7], v[46:47], s[18:19] op_sel_hi:[1,0]
	v_pk_mul_f32 v[10:11], v[44:45], s[18:19] op_sel_hi:[1,0]
	v_pk_mul_f32 v[8:9], v[42:43], s[18:19] op_sel_hi:[1,0]
	v_pk_mul_f32 v[12:13], v[40:41], s[18:19] op_sel_hi:[1,0]
	s_mov_b64 s[44:45], -1
	s_and_b64 vcc, exec, s[40:41]
	v_lshl_add_u64 v[2:3], s[20:21], 0, v[2:3]
	s_cbranch_vccnz .LBB0_1083
	v_cvt_pk_bf16_f32 v14, v10, v11
	v_cvt_pk_bf16_f32 v15, v6, v7
	v_cvt_pk_bf16_f32 v16, v12, v13
	v_cvt_pk_bf16_f32 v17, v8, v9
	v_mov_b32_e32 v0, v160
	v_lshl_add_u64 v[18:19], v[0:1], 1, v[2:3]
	s_mov_b64 s[44:45], 0
	global_store_dwordx4 v[18:19], v[14:17], off

; __device__ __forceinline__ unsigned pk2(float lo, float hi) { return f2bf(lo) | (f2bf(hi) << 16); }
;     __device__ __forceinline__ void operator()(const f32x4 (&acc)[2][2][4][2], const pg8::Unit& u, int wr, int wc, int fr, int fq) const {
;     ...
;                 const size_t row = (size_t)(row0 + ai * 128 + m * 16);
;                 float ssq = 0.f, rstd = 1.f;
;                 if constexpr (MODE == 8) rstd = 1.f / sqrtf(rs[row] * (1.f / DM) + EPS);
; #pragma unroll
;                 for (int bj = 0; bj < 2; ++bj) {
;                     const int col = col0 + bj * 128;
;                     f32x4 v0 = acc[ai][bj][m][0], v1 = acc[ai][bj][m][1];
;                     if constexpr (MODE == 0 || MODE == 1) { v0 = v0 * scale; v1 = v1 * scale; }
;                     if constexpr (MODE == 6) { float* p = of + row * IDXW + col; *(f32x4*)p = v0; *(f32x4*)(p + 4) = v1; }
;                     else if constexpr (MODE == 0) {
;                         if (u.pn >= COL_BV / 256) {
;                             const float x8[8] = {v0[0], v0[1], v0[2], v0[3], v1[0], v1[1], v1[2], v1[3]};
;                             *(u32x2*)((unsigned char*)aux + row * 1024 + (col - COL_BV)) = to_fp8x8(x8);
;                         } else { u32x4 w; w.x = pk2(v0[0], v0[1]); w.y = pk2(v0[2], v0[3]); w.z = pk2(v1[0], v1[1]); w.w = pk2(v1[2], v1[3]);
;                             *(u32x4*)(ob + row * QKVW + col) = w; }
.LBB0_1085:
	v_pk_mul_f32 v[6:7], v[38:39], s[18:19] op_sel_hi:[1,0]
	v_pk_mul_f32 v[10:11], v[36:37], s[18:19] op_sel_hi:[1,0]
	v_pk_mul_f32 v[8:9], v[34:35], s[18:19] op_sel_hi:[1,0]
	v_pk_mul_f32 v[12:13], v[32:33], s[18:19] op_sel_hi:[1,0]
	s_and_b64 vcc, exec, s[40:41]
	s_mov_b64 s[34:35], -1
	s_cbranch_vccnz .LBB0_1088
	v_cvt_pk_bf16_f32 v14, v10, v11
	v_cvt_pk_bf16_f32 v15, v6, v7
	v_cvt_pk_bf16_f32 v16, v12, v13
	v_cvt_pk_bf16_f32 v17, v8, v9
	v_mov_b32_e32 v0, v160
	v_lshl_add_u64 v[0:1], v[0:1], 1, v[2:3]
	global_store_dwordx4 v[0:1], v[14:17], off offset:256
	s_cbranch_execz .LBB0_1089

; __device__ __forceinline__ unsigned pk2(float lo, float hi) { return f2bf(lo) | (f2bf(hi) << 16); }
;     __device__ __forceinline__ void operator()(const f32x4 (&acc)[2][2][4][2], const pg8::Unit& u, int wr, int wc, int fr, int fq) const {
;     ...
;                     } else if constexpr (MODE == 1) {
;                         const f32x4 b0 = *(const f32x4*)(vec + col), b1 = *(const f32x4*)(vec + col + 4);
;                         float r[8];
; #pragma unroll
;                         for (int i = 0; i < 4; ++i) { r[i] = 1.f / (1.f + __expf(-(v0[i] + b0[i]))); r[4 + i] = 1.f / (1.f + __expf(-(v1[i] + b1[i]))); }
;                         u32x4 w; w.x = pk2(r[0], r[1]); w.y = pk2(r[2], r[3]); w.z = pk2(r[4], r[5]); w.w = pk2(r[6], r[7]);
;                         *(u32x4*)(ob + row * 4096 + col) = w;
.LBB0_1125:
	v_lshl_or_b32 v2, s8, 8, v214
	v_ashrrev_i32_e32 v3, 31, v2
	v_lshl_add_u64 v[0:1], v[2:3], 2, s[4:5]
	s_nop 15
	s_nop 15
	global_load_dwordx4 v[10:13], v[0:1], off offset:16
	global_load_dwordx4 v[14:17], v[0:1], off
	v_lshl_add_u32 v4, s9, 8, v203
	v_ashrrev_i32_e32 v5, 31, v4
	v_lshlrev_b64 v[6:7], 13, v[4:5]
	s_mov_b64 s[10:11], -1
	s_waitcnt vmcnt(0)
	v_fmac_f32_e32 v13, 0x3c800000, v155
	v_fmamk_f32 v5, v156, 0x3c800000, v14
	v_mul_f32_e32 v5, 0xbfb8aa3b, v5
	v_exp_f32_e32 v14, v5
	v_fmamk_f32 v5, v152, 0x3c800000, v10
	v_mul_f32_e32 v5, 0xbfb8aa3b, v5
	v_exp_f32_e32 v10, v5
	v_fmamk_f32 v5, v157, 0x3c800000, v15
	v_mul_f32_e32 v5, 0xbfb8aa3b, v5
	v_exp_f32_e32 v18, v5
	v_fmamk_f32 v5, v153, 0x3c800000, v11
	v_mul_f32_e32 v5, 0xbfb8aa3b, v5
	v_exp_f32_e32 v8, v5
	v_fmamk_f32 v5, v158, 0x3c800000, v16
	v_mul_f32_e32 v5, 0xbfb8aa3b, v5
	v_exp_f32_e32 v15, v5
	v_fmamk_f32 v5, v154, 0x3c800000, v12
	v_mul_f32_e32 v5, 0xbfb8aa3b, v5
	v_fmac_f32_e32 v17, 0x3c800000, v159
	v_exp_f32_e32 v11, v5
	v_mul_f32_e32 v5, 0xbfb8aa3b, v17
	v_exp_f32_e32 v19, v5
	v_mul_f32_e32 v5, 0xbfb8aa3b, v13
	v_pk_add_f32 v[12:13], v[14:15], 1.0 op_sel_hi:[1,0]
	v_exp_f32_e32 v9, v5
	v_pk_add_f32 v[10:11], v[10:11], 1.0 op_sel_hi:[1,0]
	v_pk_add_f32 v[8:9], v[8:9], 1.0 op_sel_hi:[1,0]
	v_rcp_f32_e32 v5, v13
	s_nop 0
	v_pk_add_f32 v[14:15], v[18:19], 1.0 op_sel_hi:[1,0]
	v_rcp_f32_e32 v12, v12
	s_nop 0
	v_rcp_f32_e32 v13, v14
	s_nop 0
	v_rcp_f32_e32 v14, v15
	s_nop 0
	v_rcp_f32_e32 v11, v11
	s_nop 0
	v_rcp_f32_e32 v10, v10
	s_nop 0
	v_rcp_f32_e32 v8, v8
	s_nop 0
	v_rcp_f32_e32 v9, v9
	v_cvt_pk_bf16_f32 v10, v10, v8
	v_cvt_pk_bf16_f32 v8, v12, v13
	v_lshl_add_u64 v[12:13], s[24:25], 0, v[6:7]
	v_lshlrev_b64 v[6:7], 1, v[2:3]
	v_cvt_pk_bf16_f32 v11, v11, v9
	v_cvt_pk_bf16_f32 v9, v5, v14
	v_lshl_add_u64 v[2:3], v[12:13], 0, v[6:7]
	global_store_dwordx4 v[2:3], v[8:11], off
	global_load_dwordx4 v[10:13], v[0:1], off offset:528
	s_nop 0
	global_load_dwordx4 v[14:17], v[0:1], off offset:512
	s_waitcnt vmcnt(1)
	v_fmac_f32_e32 v13, 0x3c800000, v147
	s_waitcnt vmcnt(0)
	v_fmamk_f32 v5, v148, 0x3c800000, v14
	v_mul_f32_e32 v5, 0xbfb8aa3b, v5
	v_exp_f32_e32 v14, v5
	v_fmamk_f32 v5, v144, 0x3c800000, v10
	v_mul_f32_e32 v5, 0xbfb8aa3b, v5
	v_exp_f32_e32 v10, v5
	v_fmamk_f32 v5, v149, 0x3c800000, v15
	v_mul_f32_e32 v5, 0xbfb8aa3b, v5
	v_exp_f32_e32 v18, v5
	v_fmamk_f32 v5, v145, 0x3c800000, v11
	v_mul_f32_e32 v5, 0xbfb8aa3b, v5
	v_exp_f32_e32 v8, v5
	v_fmamk_f32 v5, v150, 0x3c800000, v16
	v_mul_f32_e32 v5, 0xbfb8aa3b, v5
	v_exp_f32_e32 v15, v5
	v_fmamk_f32 v5, v146, 0x3c800000, v12
	v_mul_f32_e32 v5, 0xbfb8aa3b, v5
	v_fmac_f32_e32 v17, 0x3c800000, v151
	v_exp_f32_e32 v11, v5
	v_mul_f32_e32 v5, 0xbfb8aa3b, v17
	v_exp_f32_e32 v19, v5
	v_mul_f32_e32 v5, 0xbfb8aa3b, v13
	v_pk_add_f32 v[12:13], v[14:15], 1.0 op_sel_hi:[1,0]
	v_exp_f32_e32 v9, v5
	v_pk_add_f32 v[10:11], v[10:11], 1.0 op_sel_hi:[1,0]
	v_pk_add_f32 v[8:9], v[8:9], 1.0 op_sel_hi:[1,0]
	v_rcp_f32_e32 v5, v13
	s_nop 0
	v_rcp_f32_e32 v14, v12
	v_pk_add_f32 v[12:13], v[18:19], 1.0 op_sel_hi:[1,0]
	s_nop 0
	s_nop 0
	v_rcp_f32_e32 v12, v12
	s_nop 0
	v_rcp_f32_e32 v13, v13
	s_nop 0
	v_rcp_f32_e32 v11, v11
	s_nop 0
	v_rcp_f32_e32 v10, v10
	s_nop 0
	v_rcp_f32_e32 v8, v8
	s_nop 0
	v_rcp_f32_e32 v9, v9
	s_nop 0
	v_cvt_pk_bf16_f32 v11, v11, v9
	v_cvt_pk_bf16_f32 v10, v10, v8
	v_cvt_pk_bf16_f32 v9, v5, v13
	v_cvt_pk_bf16_f32 v8, v14, v12
	global_store_dwordx4 v[2:3], v[8:11], off offset:256
	global_load_dwordx4 v[10:13], v[0:1], off offset:16
	s_nop 0
	global_load_dwordx4 v[14:17], v[0:1], off
	v_or_b32_e32 v8, 16, v4
	v_ashrrev_i32_e32 v9, 31, v8
	v_lshlrev_b64 v[8:9], 13, v[8:9]
	v_lshl_add_u64 v[8:9], s[24:25], 0, v[8:9]
	v_lshl_add_u64 v[8:9], v[8:9], 0, v[6:7]
	s_waitcnt vmcnt(1)
	v_fmac_f32_e32 v13, 0x3c800000, v139
	s_waitcnt vmcnt(0)
	v_fmamk_f32 v5, v140, 0x3c800000, v14
	v_mul_f32_e32 v5, 0xbfb8aa3b, v5
	v_exp_f32_e32 v14, v5
	v_fmamk_f32 v5, v136, 0x3c800000, v10
	v_mul_f32_e32 v5, 0xbfb8aa3b, v5
	v_exp_f32_e32 v18, v5
	v_fmamk_f32 v5, v141, 0x3c800000, v15
	v_mul_f32_e32 v5, 0xbfb8aa3b, v5
	v_exp_f32_e32 v20, v5
	v_fmamk_f32 v5, v137, 0x3c800000, v11
	v_mul_f32_e32 v5, 0xbfb8aa3b, v5
	v_exp_f32_e32 v10, v5
	v_fmamk_f32 v5, v142, 0x3c800000, v16
	v_mul_f32_e32 v5, 0xbfb8aa3b, v5
	v_exp_f32_e32 v15, v5
	v_fmamk_f32 v5, v138, 0x3c800000, v12
	v_mul_f32_e32 v5, 0xbfb8aa3b, v5
	v_fmac_f32_e32 v17, 0x3c800000, v143
	v_exp_f32_e32 v19, v5
	v_mul_f32_e32 v5, 0xbfb8aa3b, v17
	v_exp_f32_e32 v21, v5
	v_mul_f32_e32 v5, 0xbfb8aa3b, v13
	v_pk_add_f32 v[12:13], v[14:15], 1.0 op_sel_hi:[1,0]
	v_exp_f32_e32 v11, v5
	s_nop 0
	v_pk_add_f32 v[10:11], v[10:11], 1.0 op_sel_hi:[1,0]
	v_rcp_f32_e32 v5, v13
	s_nop 0
	v_rcp_f32_e32 v14, v12
	v_pk_add_f32 v[12:13], v[20:21], 1.0 op_sel_hi:[1,0]
	s_nop 0
	s_nop 0
	v_rcp_f32_e32 v15, v12
	s_nop 0
	v_rcp_f32_e32 v16, v13
	v_pk_add_f32 v[12:13], v[18:19], 1.0 op_sel_hi:[1,0]
	s_nop 0
	s_nop 0
	v_rcp_f32_e32 v13, v13
	s_nop 0
	v_rcp_f32_e32 v12, v12
	s_nop 0
	v_rcp_f32_e32 v10, v10
	s_nop 0
	v_rcp_f32_e32 v11, v11
	s_nop 0
	v_cvt_pk_bf16_f32 v13, v13, v11
	v_cvt_pk_bf16_f32 v12, v12, v10
	v_cvt_pk_bf16_f32 v11, v5, v16
	v_cvt_pk_bf16_f32 v10, v14, v15
	global_store_dwordx4 v[8:9], v[10:13], off
	global_load_dwordx4 v[10:13], v[0:1], off offset:528
	s_nop 0
	global_load_dwordx4 v[14:17], v[0:1], off offset:512
	s_waitcnt vmcnt(1)
	v_fmac_f32_e32 v13, 0x3c800000, v131
	s_waitcnt vmcnt(0)
; __device__ __forceinline__ unsigned pk2(float lo, float hi) { return f2bf(lo) | (f2bf(hi) << 16); }
;     __device__ __forceinline__ void operator()(const f32x4 (&acc)[2][2][4][2], const pg8::Unit& u, int wr, int wc, int fr, int fq) const {
;     ...
;                     } else if constexpr (MODE == 1) {
;                         const f32x4 b0 = *(const f32x4*)(vec + col), b1 = *(const f32x4*)(vec + col + 4);
;                         float r[8];
; #pragma unroll
;                         for (int i = 0; i < 4; ++i) { r[i] = 1.f / (1.f + __expf(-(v0[i] + b0[i]))); r[4 + i] = 1.f / (1.f + __expf(-(v1[i] + b1[i]))); }
;                         u32x4 w; w.x = pk2(r[0], r[1]); w.y = pk2(r[2], r[3]); w.z = pk2(r[4], r[5]); w.w = pk2(r[6], r[7]);
;                         *(u32x4*)(ob + row * 4096 + col) = w;
	v_fmamk_f32 v5, v132, 0x3c800000, v14
	v_mul_f32_e32 v5, 0xbfb8aa3b, v5
	v_exp_f32_e32 v14, v5
	v_fmamk_f32 v5, v128, 0x3c800000, v10
	v_mul_f32_e32 v5, 0xbfb8aa3b, v5
	v_exp_f32_e32 v18, v5
	v_fmamk_f32 v5, v133, 0x3c800000, v15
	v_mul_f32_e32 v5, 0xbfb8aa3b, v5
	v_exp_f32_e32 v20, v5
	v_fmamk_f32 v5, v129, 0x3c800000, v11
	v_mul_f32_e32 v5, 0xbfb8aa3b, v5
	v_exp_f32_e32 v10, v5
	v_fmamk_f32 v5, v134, 0x3c800000, v16
	v_mul_f32_e32 v5, 0xbfb8aa3b, v5
	v_exp_f32_e32 v15, v5
	v_fmamk_f32 v5, v130, 0x3c800000, v12
	v_mul_f32_e32 v5, 0xbfb8aa3b, v5
	v_fmac_f32_e32 v17, 0x3c800000, v135
	v_exp_f32_e32 v19, v5
	v_mul_f32_e32 v5, 0xbfb8aa3b, v17
	v_exp_f32_e32 v21, v5
	v_mul_f32_e32 v5, 0xbfb8aa3b, v13
	v_pk_add_f32 v[12:13], v[14:15], 1.0 op_sel_hi:[1,0]
	v_exp_f32_e32 v11, v5
	s_nop 0
	v_pk_add_f32 v[10:11], v[10:11], 1.0 op_sel_hi:[1,0]
	v_rcp_f32_e32 v5, v13
	s_nop 0
	v_rcp_f32_e32 v14, v12
	v_pk_add_f32 v[12:13], v[20:21], 1.0 op_sel_hi:[1,0]
	s_nop 0
	s_nop 0
	v_rcp_f32_e32 v15, v12
	s_nop 0
	v_rcp_f32_e32 v16, v13
	v_pk_add_f32 v[12:13], v[18:19], 1.0 op_sel_hi:[1,0]
	s_nop 0
	s_nop 0
	v_rcp_f32_e32 v13, v13
	s_nop 0
	v_rcp_f32_e32 v12, v12
	s_nop 0
	v_rcp_f32_e32 v10, v10
	s_nop 0
	v_rcp_f32_e32 v11, v11
	s_nop 0
	v_cvt_pk_bf16_f32 v13, v13, v11
	v_cvt_pk_bf16_f32 v12, v12, v10
	v_cvt_pk_bf16_f32 v11, v5, v16
	v_cvt_pk_bf16_f32 v10, v14, v15
	global_store_dwordx4 v[8:9], v[10:13], off offset:256
	global_load_dwordx4 v[10:13], v[0:1], off offset:16
	s_nop 0
	global_load_dwordx4 v[14:17], v[0:1], off
	v_or_b32_e32 v8, 32, v4
	v_ashrrev_i32_e32 v9, 31, v8
	v_lshlrev_b64 v[8:9], 13, v[8:9]
	v_lshl_add_u64 v[8:9], s[24:25], 0, v[8:9]
	v_lshl_add_u64 v[8:9], v[8:9], 0, v[6:7]
	v_or_b32_e32 v4, 48, v4
	s_waitcnt vmcnt(1)
	v_fmac_f32_e32 v13, 0x3c800000, v123
	s_waitcnt vmcnt(0)
	v_fmamk_f32 v5, v124, 0x3c800000, v14
	v_mul_f32_e32 v5, 0xbfb8aa3b, v5
	v_exp_f32_e32 v14, v5
	v_fmamk_f32 v5, v120, 0x3c800000, v10
	v_mul_f32_e32 v5, 0xbfb8aa3b, v5
	v_exp_f32_e32 v18, v5
	v_fmamk_f32 v5, v125, 0x3c800000, v15
	v_mul_f32_e32 v5, 0xbfb8aa3b, v5
	v_exp_f32_e32 v20, v5
	v_fmamk_f32 v5, v121, 0x3c800000, v11
	v_mul_f32_e32 v5, 0xbfb8aa3b, v5
	v_exp_f32_e32 v10, v5
	v_fmamk_f32 v5, v126, 0x3c800000, v16
	v_mul_f32_e32 v5, 0xbfb8aa3b, v5
	v_exp_f32_e32 v15, v5
	v_fmamk_f32 v5, v122, 0x3c800000, v12
	v_mul_f32_e32 v5, 0xbfb8aa3b, v5
	v_fmac_f32_e32 v17, 0x3c800000, v127
	v_exp_f32_e32 v19, v5
	v_mul_f32_e32 v5, 0xbfb8aa3b, v17
	v_exp_f32_e32 v21, v5
	v_mul_f32_e32 v5, 0xbfb8aa3b, v13
	v_pk_add_f32 v[12:13], v[14:15], 1.0 op_sel_hi:[1,0]
	v_exp_f32_e32 v11, v5
	s_nop 0
	v_pk_add_f32 v[10:11], v[10:11], 1.0 op_sel_hi:[1,0]
	v_rcp_f32_e32 v5, v13
	s_nop 0
	v_rcp_f32_e32 v14, v12
	v_pk_add_f32 v[12:13], v[20:21], 1.0 op_sel_hi:[1,0]
	s_nop 0
	s_nop 0
	v_rcp_f32_e32 v15, v12
	s_nop 0
	v_rcp_f32_e32 v16, v13
	v_pk_add_f32 v[12:13], v[18:19], 1.0 op_sel_hi:[1,0]
	s_nop 0
	s_nop 0
	v_rcp_f32_e32 v13, v13
	s_nop 0
	v_rcp_f32_e32 v12, v12
	s_nop 0
	v_rcp_f32_e32 v10, v10
	s_nop 0
	v_rcp_f32_e32 v11, v11
	s_nop 0
	v_cvt_pk_bf16_f32 v13, v13, v11
	v_cvt_pk_bf16_f32 v12, v12, v10
	v_cvt_pk_bf16_f32 v11, v5, v16
	v_cvt_pk_bf16_f32 v10, v14, v15
	global_store_dwordx4 v[8:9], v[10:13], off
	global_load_dwordx4 v[10:13], v[0:1], off offset:528
	s_nop 0
	global_load_dwordx4 v[14:17], v[0:1], off offset:512
	s_waitcnt vmcnt(1)
	v_fmac_f32_e32 v13, 0x3c800000, v115
	s_waitcnt vmcnt(0)
	v_fmamk_f32 v5, v116, 0x3c800000, v14
	v_mul_f32_e32 v5, 0xbfb8aa3b, v5
	v_exp_f32_e32 v14, v5
	v_fmamk_f32 v5, v112, 0x3c800000, v10
	v_mul_f32_e32 v5, 0xbfb8aa3b, v5
	v_exp_f32_e32 v18, v5
	v_fmamk_f32 v5, v117, 0x3c800000, v15
	v_mul_f32_e32 v5, 0xbfb8aa3b, v5
	v_exp_f32_e32 v20, v5
	v_fmamk_f32 v5, v113, 0x3c800000, v11
	v_mul_f32_e32 v5, 0xbfb8aa3b, v5
	v_exp_f32_e32 v10, v5
	v_fmamk_f32 v5, v118, 0x3c800000, v16
	v_mul_f32_e32 v5, 0xbfb8aa3b, v5
	v_exp_f32_e32 v15, v5
	v_fmamk_f32 v5, v114, 0x3c800000, v12
	v_mul_f32_e32 v5, 0xbfb8aa3b, v5
	v_fmac_f32_e32 v17, 0x3c800000, v119
	v_exp_f32_e32 v19, v5
	v_mul_f32_e32 v5, 0xbfb8aa3b, v17
	v_exp_f32_e32 v21, v5
	v_mul_f32_e32 v5, 0xbfb8aa3b, v13
	v_pk_add_f32 v[12:13], v[14:15], 1.0 op_sel_hi:[1,0]
	v_exp_f32_e32 v11, v5
	s_nop 0
	v_pk_add_f32 v[10:11], v[10:11], 1.0 op_sel_hi:[1,0]
	v_rcp_f32_e32 v5, v13
	s_nop 0
	v_rcp_f32_e32 v14, v12
	v_pk_add_f32 v[12:13], v[20:21], 1.0 op_sel_hi:[1,0]
	s_nop 0
	s_nop 0
	v_rcp_f32_e32 v15, v12
	s_nop 0
	v_rcp_f32_e32 v16, v13
	v_pk_add_f32 v[12:13], v[18:19], 1.0 op_sel_hi:[1,0]
	s_nop 0
	s_nop 0
	v_rcp_f32_e32 v13, v13
	s_nop 0
	v_rcp_f32_e32 v12, v12
	s_nop 0
	v_rcp_f32_e32 v10, v10
	v_div_scale_f32 v17, s[8:9], v11, v11, 1.0
	v_rcp_f32_e32 v18, v17
	s_nop 0
	v_fma_f32 v19, -v17, v18, 1.0
	v_fmac_f32_e32 v18, v19, v18
	v_div_scale_f32 v19, vcc, 1.0, v11, 1.0
	v_mul_f32_e32 v20, v19, v18
	v_fma_f32 v21, -v17, v20, v19
	v_rcp_f32_e32 v11, v11
	s_nop 0
	v_cvt_pk_bf16_f32 v13, v13, v11
	v_cvt_pk_bf16_f32 v12, v12, v10
	v_cvt_pk_bf16_f32 v11, v5, v16
	v_cvt_pk_bf16_f32 v10, v14, v15
	global_store_dwordx4 v[8:9], v[10:13], off offset:256
	global_load_dwordx4 v[8:11], v[0:1], off offset:16
	s_nop 0
	global_load_dwordx4 v[12:15], v[0:1], off
	v_ashrrev_i32_e32 v5, 31, v4
	v_lshlrev_b64 v[4:5], 13, v[4:5]
	v_lshl_add_u64 v[4:5], s[24:25], 0, v[4:5]
	v_lshl_add_u64 v[4:5], v[4:5], 0, v[6:7]
	s_waitcnt vmcnt(1)
	v_fmamk_f32 v8, v104, 0x3c800000, v8
	v_mul_f32_e32 v8, 0xbfb8aa3b, v8
	v_exp_f32_e32 v16, v8
	s_waitcnt vmcnt(0)
; __device__ __forceinline__ unsigned pk2(float lo, float hi) { return f2bf(lo) | (f2bf(hi) << 16); }
;     __device__ __forceinline__ void operator()(const f32x4 (&acc)[2][2][4][2], const pg8::Unit& u, int wr, int wc, int fr, int fq) const {
;     ...
;                     f32x4 v0 = acc[ai][bj][m][0], v1 = acc[ai][bj][m][1];
;                     if constexpr (MODE == 0 || MODE == 1) { v0 = v0 * scale; v1 = v1 * scale; }
;                     if constexpr (MODE == 6) { float* p = of + row * IDXW + col; *(f32x4*)p = v0; *(f32x4*)(p + 4) = v1; }
;                     else if constexpr (MODE == 0) {
;                         if (u.pn >= COL_BV / 256) {
;                             const float x8[8] = {v0[0], v0[1], v0[2], v0[3], v1[0], v1[1], v1[2], v1[3]};
;                             *(u32x2*)((unsigned char*)aux + row * 1024 + (col - COL_BV)) = to_fp8x8(x8);
;                         } else { u32x4 w; w.x = pk2(v0[0], v0[1]); w.y = pk2(v0[2], v0[3]); w.z = pk2(v1[0], v1[1]); w.w = pk2(v1[2], v1[3]);
;                             *(u32x4*)(ob + row * QKVW + col) = w; }
;                     } else if constexpr (MODE == 1) {
;                         const f32x4 b0 = *(const f32x4*)(vec + col), b1 = *(const f32x4*)(vec + col + 4);
;                         float r[8];
; #pragma unroll
;                         for (int i = 0; i < 4; ++i) { r[i] = 1.f / (1.f + __expf(-(v0[i] + b0[i]))); r[4 + i] = 1.f / (1.f + __expf(-(v1[i] + b1[i]))); }
;                         u32x4 w; w.x = pk2(r[0], r[1]); w.y = pk2(r[2], r[3]); w.z = pk2(r[4], r[5]); w.w = pk2(r[6], r[7]);
;                         *(u32x4*)(ob + row * 4096 + col) = w;
	v_fmamk_f32 v8, v109, 0x3c800000, v13
	v_mul_f32_e32 v8, 0xbfb8aa3b, v8
	v_fmamk_f32 v12, v108, 0x3c800000, v12
	v_exp_f32_e32 v18, v8
	v_fmamk_f32 v8, v105, 0x3c800000, v9
	v_fmamk_f32 v9, v110, 0x3c800000, v14
	v_mul_f32_e32 v12, 0xbfb8aa3b, v12
	v_mul_f32_e32 v9, 0xbfb8aa3b, v9
	v_exp_f32_e32 v12, v12
	v_exp_f32_e32 v13, v9
	v_fmamk_f32 v9, v106, 0x3c800000, v10
	v_mul_f32_e32 v9, 0xbfb8aa3b, v9
	v_fmac_f32_e32 v15, 0x3c800000, v111
	v_exp_f32_e32 v17, v9
	v_mul_f32_e32 v9, 0xbfb8aa3b, v15
	v_fmac_f32_e32 v11, 0x3c800000, v107
	v_exp_f32_e32 v19, v9
	v_mul_f32_e32 v9, 0xbfb8aa3b, v11
	v_pk_add_f32 v[10:11], v[12:13], 1.0 op_sel_hi:[1,0]
	v_mul_f32_e32 v8, 0xbfb8aa3b, v8
	v_exp_f32_e32 v8, v8
	v_exp_f32_e32 v9, v9
	v_rcp_f32_e32 v12, v11
	v_pk_add_f32 v[8:9], v[8:9], 1.0 op_sel_hi:[1,0]
	v_rcp_f32_e32 v13, v10
	v_pk_add_f32 v[10:11], v[18:19], 1.0 op_sel_hi:[1,0]
	s_nop 0
	s_nop 0
	v_rcp_f32_e32 v14, v10
	s_nop 0
	v_rcp_f32_e32 v15, v11
	v_pk_add_f32 v[10:11], v[16:17], 1.0 op_sel_hi:[1,0]
	s_nop 0
	s_nop 0
	v_rcp_f32_e32 v11, v11
	s_nop 0
	v_rcp_f32_e32 v10, v10
	s_nop 0
	v_rcp_f32_e32 v8, v8
	v_div_scale_f32 v16, s[8:9], v9, v9, 1.0
	v_rcp_f32_e32 v17, v16
	s_nop 0
	v_fma_f32 v18, -v16, v17, 1.0
	v_fmac_f32_e32 v17, v18, v17
	v_div_scale_f32 v18, vcc, 1.0, v9, 1.0
	v_mul_f32_e32 v19, v18, v17
	v_fma_f32 v20, -v16, v19, v18
	v_fmac_f32_e32 v19, v20, v17
	v_rcp_f32_e32 v9, v9
	s_nop 0
	v_cvt_pk_bf16_f32 v11, v11, v9
	v_cvt_pk_bf16_f32 v10, v10, v8
	v_cvt_pk_bf16_f32 v9, v12, v15
	v_cvt_pk_bf16_f32 v8, v13, v14
	global_store_dwordx4 v[4:5], v[8:11], off
	global_load_dwordx4 v[6:9], v[0:1], off offset:528
	s_nop 0
	global_load_dwordx4 v[10:13], v[0:1], off offset:512
	s_waitcnt vmcnt(1)
	v_fmamk_f32 v6, v96, 0x3c800000, v6
	v_mul_f32_e32 v6, 0xbfb8aa3b, v6
	v_exp_f32_e32 v14, v6
	s_waitcnt vmcnt(0)
	v_fmamk_f32 v6, v101, 0x3c800000, v11
	v_mul_f32_e32 v6, 0xbfb8aa3b, v6
	v_fmamk_f32 v10, v100, 0x3c800000, v10
	v_exp_f32_e32 v16, v6
	v_fmamk_f32 v6, v97, 0x3c800000, v7
	v_fmamk_f32 v7, v102, 0x3c800000, v12
	v_mul_f32_e32 v10, 0xbfb8aa3b, v10
	v_mul_f32_e32 v7, 0xbfb8aa3b, v7
	v_exp_f32_e32 v10, v10
	v_exp_f32_e32 v11, v7
	v_fmamk_f32 v7, v98, 0x3c800000, v8
	v_mul_f32_e32 v7, 0xbfb8aa3b, v7
	v_fmac_f32_e32 v13, 0x3c800000, v103
	v_exp_f32_e32 v15, v7
	v_mul_f32_e32 v7, 0xbfb8aa3b, v13
	v_fmac_f32_e32 v9, 0x3c800000, v99
	v_exp_f32_e32 v17, v7
	v_mul_f32_e32 v7, 0xbfb8aa3b, v9
	v_pk_add_f32 v[8:9], v[10:11], 1.0 op_sel_hi:[1,0]
	v_mul_f32_e32 v6, 0xbfb8aa3b, v6
	v_exp_f32_e32 v6, v6
	v_exp_f32_e32 v7, v7
	v_rcp_f32_e32 v10, v9
	v_pk_add_f32 v[6:7], v[6:7], 1.0 op_sel_hi:[1,0]
	v_rcp_f32_e32 v11, v8
	v_pk_add_f32 v[8:9], v[16:17], 1.0 op_sel_hi:[1,0]
	s_nop 0
	s_nop 0
	v_rcp_f32_e32 v12, v8
	s_nop 0
	v_rcp_f32_e32 v13, v9
	v_pk_add_f32 v[8:9], v[14:15], 1.0 op_sel_hi:[1,0]
	s_nop 0
	s_nop 0
	v_rcp_f32_e32 v9, v9
	s_nop 0
	v_rcp_f32_e32 v8, v8
	s_nop 0
	v_rcp_f32_e32 v6, v6
	s_nop 0
	v_rcp_f32_e32 v7, v7
	s_nop 0
	v_cvt_pk_bf16_f32 v9, v9, v7
	v_cvt_pk_bf16_f32 v8, v8, v6
	v_cvt_pk_bf16_f32 v7, v10, v13
	v_cvt_pk_bf16_f32 v6, v11, v12
	global_store_dwordx4 v[4:5], v[6:9], off offset:256
	global_load_dwordx4 v[4:7], v[0:1], off offset:16
	s_nop 0
	global_load_dwordx4 v[8:11], v[0:1], off
	s_waitcnt vmcnt(1)
	v_fmamk_f32 v4, v88, 0x3c800000, v4
	v_mul_f32_e32 v4, 0xbfb8aa3b, v4
	v_exp_f32_e32 v12, v4
	s_waitcnt vmcnt(0)
	v_fmamk_f32 v4, v93, 0x3c800000, v9
	v_mul_f32_e32 v4, 0xbfb8aa3b, v4
	v_fmamk_f32 v8, v92, 0x3c800000, v8
	v_exp_f32_e32 v14, v4
	v_fmamk_f32 v4, v89, 0x3c800000, v5
	v_fmamk_f32 v5, v94, 0x3c800000, v10
	v_mul_f32_e32 v8, 0xbfb8aa3b, v8
	v_mul_f32_e32 v5, 0xbfb8aa3b, v5
	v_exp_f32_e32 v8, v8
	v_exp_f32_e32 v9, v5
	v_fmamk_f32 v5, v90, 0x3c800000, v6
	v_mul_f32_e32 v5, 0xbfb8aa3b, v5
	v_fmac_f32_e32 v11, 0x3c800000, v95
	v_exp_f32_e32 v13, v5
	v_mul_f32_e32 v5, 0xbfb8aa3b, v11
	v_fmac_f32_e32 v7, 0x3c800000, v91
	v_exp_f32_e32 v15, v5
	v_mul_f32_e32 v5, 0xbfb8aa3b, v7
	v_pk_add_f32 v[6:7], v[8:9], 1.0 op_sel_hi:[1,0]
	v_mul_f32_e32 v4, 0xbfb8aa3b, v4
	v_exp_f32_e32 v4, v4
	v_exp_f32_e32 v5, v5
	v_rcp_f32_e32 v8, v7
	v_pk_add_f32 v[4:5], v[4:5], 1.0 op_sel_hi:[1,0]
	v_rcp_f32_e32 v9, v6
	v_pk_add_f32 v[6:7], v[14:15], 1.0 op_sel_hi:[1,0]
	s_nop 0
	s_nop 0
	v_rcp_f32_e32 v10, v6
	s_nop 0
	v_rcp_f32_e32 v11, v7
	v_pk_add_f32 v[6:7], v[12:13], 1.0 op_sel_hi:[1,0]
	s_nop 0
	s_nop 0
	v_rcp_f32_e32 v7, v7
	s_nop 0
	v_rcp_f32_e32 v6, v6
	s_nop 0
	v_rcp_f32_e32 v4, v4
	s_mov_b64 s[8:9], 0x100000
	v_rcp_f32_e32 v5, v5
	v_bfe_u32 v14, v11, 16, 1
	v_bfe_u32 v15, v10, 16, 1
	v_add3_u32 v10, v10, v15, s33
	v_add3_u32 v11, v11, v14, s33
	v_bfe_u32 v12, v9, 16, 1
	v_bfe_u32 v13, v8, 16, 1
	v_add3_u32 v8, v8, v13, s33
	v_add3_u32 v9, v9, v12, s33
	v_lshrrev_b32_e32 v12, 16, v9
	v_lshrrev_b32_e32 v13, 16, v8
	v_cvt_pk_bf16_f32 v9, v7, v5
	v_cvt_pk_bf16_f32 v8, v6, v4
	v_lshl_add_u64 v[4:5], v[2:3], 0, s[8:9]
	s_mov_b32 s8, 0x100000
	v_and_or_b32 v6, v10, s67, v12
	v_add_co_u32_e32 v10, vcc, s8, v2
	v_and_or_b32 v7, v11, s67, v13
	s_nop 0
	v_addc_co_u32_e32 v11, vcc, 0, v3, vcc
	global_store_dwordx4 v[10:11], v[6:9], off
	global_load_dwordx4 v[6:9], v[0:1], off offset:528
	s_nop 0
	global_load_dwordx4 v[10:13], v[0:1], off offset:512
	s_waitcnt vmcnt(1)
	v_fmamk_f32 v6, v80, 0x3c800000, v6
	v_mul_f32_e32 v6, 0xbfb8aa3b, v6
	v_exp_f32_e32 v14, v6
	s_waitcnt vmcnt(0)
; __device__ __forceinline__ unsigned pk2(float lo, float hi) { return f2bf(lo) | (f2bf(hi) << 16); }
;     __device__ __forceinline__ void operator()(const f32x4 (&acc)[2][2][4][2], const pg8::Unit& u, int wr, int wc, int fr, int fq) const {
;     ...
;                     f32x4 v0 = acc[ai][bj][m][0], v1 = acc[ai][bj][m][1];
;                     if constexpr (MODE == 0 || MODE == 1) { v0 = v0 * scale; v1 = v1 * scale; }
;                     if constexpr (MODE == 6) { float* p = of + row * IDXW + col; *(f32x4*)p = v0; *(f32x4*)(p + 4) = v1; }
;                     else if constexpr (MODE == 0) {
;                         if (u.pn >= COL_BV / 256) {
;                             const float x8[8] = {v0[0], v0[1], v0[2], v0[3], v1[0], v1[1], v1[2], v1[3]};
;                             *(u32x2*)((unsigned char*)aux + row * 1024 + (col - COL_BV)) = to_fp8x8(x8);
;                         } else { u32x4 w; w.x = pk2(v0[0], v0[1]); w.y = pk2(v0[2], v0[3]); w.z = pk2(v1[0], v1[1]); w.w = pk2(v1[2], v1[3]);
;                             *(u32x4*)(ob + row * QKVW + col) = w; }
;                     } else if constexpr (MODE == 1) {
;                         const f32x4 b0 = *(const f32x4*)(vec + col), b1 = *(const f32x4*)(vec + col + 4);
;                         float r[8];
; #pragma unroll
;                         for (int i = 0; i < 4; ++i) { r[i] = 1.f / (1.f + __expf(-(v0[i] + b0[i]))); r[4 + i] = 1.f / (1.f + __expf(-(v1[i] + b1[i]))); }
;                         u32x4 w; w.x = pk2(r[0], r[1]); w.y = pk2(r[2], r[3]); w.z = pk2(r[4], r[5]); w.w = pk2(r[6], r[7]);
;                         *(u32x4*)(ob + row * 4096 + col) = w;
	v_fmamk_f32 v6, v85, 0x3c800000, v11
	v_mul_f32_e32 v6, 0xbfb8aa3b, v6
	v_fmamk_f32 v10, v84, 0x3c800000, v10
	v_exp_f32_e32 v16, v6
	v_fmamk_f32 v6, v81, 0x3c800000, v7
	v_fmamk_f32 v7, v86, 0x3c800000, v12
	v_mul_f32_e32 v10, 0xbfb8aa3b, v10
	v_mul_f32_e32 v7, 0xbfb8aa3b, v7
	v_exp_f32_e32 v10, v10
	v_exp_f32_e32 v11, v7
	v_fmamk_f32 v7, v82, 0x3c800000, v8
	v_mul_f32_e32 v7, 0xbfb8aa3b, v7
	v_fmac_f32_e32 v13, 0x3c800000, v87
	v_exp_f32_e32 v15, v7
	v_mul_f32_e32 v7, 0xbfb8aa3b, v13
	v_fmac_f32_e32 v9, 0x3c800000, v83
	v_exp_f32_e32 v17, v7
	v_mul_f32_e32 v7, 0xbfb8aa3b, v9
	v_pk_add_f32 v[8:9], v[10:11], 1.0 op_sel_hi:[1,0]
	v_mul_f32_e32 v6, 0xbfb8aa3b, v6
	v_exp_f32_e32 v6, v6
	v_exp_f32_e32 v7, v7
	v_rcp_f32_e32 v10, v9
	v_pk_add_f32 v[6:7], v[6:7], 1.0 op_sel_hi:[1,0]
	v_rcp_f32_e32 v11, v8
	v_pk_add_f32 v[8:9], v[16:17], 1.0 op_sel_hi:[1,0]
	s_nop 0
	s_nop 0
	v_rcp_f32_e32 v12, v8
	s_nop 0
	v_rcp_f32_e32 v13, v9
	v_pk_add_f32 v[8:9], v[14:15], 1.0 op_sel_hi:[1,0]
	s_nop 0
	s_nop 0
	v_rcp_f32_e32 v9, v9
	s_nop 0
	v_rcp_f32_e32 v8, v8
	s_nop 0
	v_rcp_f32_e32 v6, v6
	s_nop 0
	v_rcp_f32_e32 v7, v7
	s_nop 0
	v_cvt_pk_bf16_f32 v9, v9, v7
	v_cvt_pk_bf16_f32 v8, v8, v6
	v_cvt_pk_bf16_f32 v7, v10, v13
	v_cvt_pk_bf16_f32 v6, v11, v12
	global_store_dwordx4 v[4:5], v[6:9], off offset:256
	global_load_dwordx4 v[4:7], v[0:1], off offset:16
	s_nop 0
	global_load_dwordx4 v[8:11], v[0:1], off
	s_waitcnt vmcnt(1)
	v_fmamk_f32 v4, v72, 0x3c800000, v4
	v_mul_f32_e32 v4, 0xbfb8aa3b, v4
	v_exp_f32_e32 v12, v4
	s_waitcnt vmcnt(0)
	v_fmamk_f32 v4, v77, 0x3c800000, v9
	v_mul_f32_e32 v4, 0xbfb8aa3b, v4
	v_fmamk_f32 v8, v76, 0x3c800000, v8
	v_exp_f32_e32 v14, v4
	v_fmamk_f32 v4, v73, 0x3c800000, v5
	v_fmamk_f32 v5, v78, 0x3c800000, v10
	v_mul_f32_e32 v8, 0xbfb8aa3b, v8
	v_mul_f32_e32 v5, 0xbfb8aa3b, v5
	v_exp_f32_e32 v8, v8
	v_exp_f32_e32 v9, v5
	v_fmamk_f32 v5, v74, 0x3c800000, v6
	v_mul_f32_e32 v5, 0xbfb8aa3b, v5
	v_fmac_f32_e32 v11, 0x3c800000, v79
	v_exp_f32_e32 v13, v5
	v_mul_f32_e32 v5, 0xbfb8aa3b, v11
	v_fmac_f32_e32 v7, 0x3c800000, v75
	v_exp_f32_e32 v15, v5
	v_mul_f32_e32 v5, 0xbfb8aa3b, v7
	v_pk_add_f32 v[6:7], v[8:9], 1.0 op_sel_hi:[1,0]
	v_mul_f32_e32 v4, 0xbfb8aa3b, v4
	v_exp_f32_e32 v4, v4
	v_exp_f32_e32 v5, v5
	v_rcp_f32_e32 v8, v7
	v_pk_add_f32 v[4:5], v[4:5], 1.0 op_sel_hi:[1,0]
	v_rcp_f32_e32 v9, v6
	v_pk_add_f32 v[6:7], v[14:15], 1.0 op_sel_hi:[1,0]
	s_nop 0
	s_nop 0
	v_rcp_f32_e32 v10, v6
	s_nop 0
	v_rcp_f32_e32 v11, v7
	v_pk_add_f32 v[6:7], v[12:13], 1.0 op_sel_hi:[1,0]
	s_nop 0
	s_nop 0
	v_rcp_f32_e32 v7, v7
	s_nop 0
	v_rcp_f32_e32 v6, v6
	s_nop 0
	v_rcp_f32_e32 v4, v4
	s_mov_b64 s[8:9], 0x120000
	v_rcp_f32_e32 v5, v5
	v_bfe_u32 v14, v11, 16, 1
	v_bfe_u32 v15, v10, 16, 1
	v_add3_u32 v10, v10, v15, s33
	v_add3_u32 v11, v11, v14, s33
	v_bfe_u32 v12, v9, 16, 1
	v_bfe_u32 v13, v8, 16, 1
	v_add3_u32 v8, v8, v13, s33
	v_add3_u32 v9, v9, v12, s33
	v_lshrrev_b32_e32 v12, 16, v9
	v_lshrrev_b32_e32 v13, 16, v8
	v_cvt_pk_bf16_f32 v9, v7, v5
	v_cvt_pk_bf16_f32 v8, v6, v4
	v_lshl_add_u64 v[4:5], v[2:3], 0, s[8:9]
	s_mov_b32 s8, 0x120000
	v_and_or_b32 v6, v10, s67, v12
	v_add_co_u32_e32 v10, vcc, s8, v2
	v_and_or_b32 v7, v11, s67, v13
	s_nop 0
	v_addc_co_u32_e32 v11, vcc, 0, v3, vcc
	global_store_dwordx4 v[10:11], v[6:9], off
	global_load_dwordx4 v[6:9], v[0:1], off offset:528
	s_nop 0
	global_load_dwordx4 v[10:13], v[0:1], off offset:512
	s_waitcnt vmcnt(1)
	v_fmamk_f32 v6, v64, 0x3c800000, v6
	v_mul_f32_e32 v6, 0xbfb8aa3b, v6
	v_exp_f32_e32 v14, v6
	s_waitcnt vmcnt(0)
	v_fmamk_f32 v6, v69, 0x3c800000, v11
	v_mul_f32_e32 v6, 0xbfb8aa3b, v6
	v_fmamk_f32 v10, v68, 0x3c800000, v10
	v_exp_f32_e32 v16, v6
	v_fmamk_f32 v6, v65, 0x3c800000, v7
	v_fmamk_f32 v7, v70, 0x3c800000, v12
	v_mul_f32_e32 v10, 0xbfb8aa3b, v10
	v_mul_f32_e32 v7, 0xbfb8aa3b, v7
	v_exp_f32_e32 v10, v10
	v_exp_f32_e32 v11, v7
	v_fmamk_f32 v7, v66, 0x3c800000, v8
	v_mul_f32_e32 v7, 0xbfb8aa3b, v7
	v_fmac_f32_e32 v13, 0x3c800000, v71
	v_exp_f32_e32 v15, v7
	v_mul_f32_e32 v7, 0xbfb8aa3b, v13
	v_fmac_f32_e32 v9, 0x3c800000, v67
	v_exp_f32_e32 v17, v7
	v_mul_f32_e32 v7, 0xbfb8aa3b, v9
	v_pk_add_f32 v[8:9], v[10:11], 1.0 op_sel_hi:[1,0]
	v_mul_f32_e32 v6, 0xbfb8aa3b, v6
	v_exp_f32_e32 v6, v6
	v_exp_f32_e32 v7, v7
	v_rcp_f32_e32 v10, v9
	v_pk_add_f32 v[6:7], v[6:7], 1.0 op_sel_hi:[1,0]
	v_rcp_f32_e32 v11, v8
	v_pk_add_f32 v[8:9], v[16:17], 1.0 op_sel_hi:[1,0]
	s_nop 0
	s_nop 0
	v_rcp_f32_e32 v12, v8
	s_nop 0
	v_rcp_f32_e32 v13, v9
	v_pk_add_f32 v[8:9], v[14:15], 1.0 op_sel_hi:[1,0]
	s_nop 0
	s_nop 0
	v_rcp_f32_e32 v9, v9
	s_nop 0
	v_rcp_f32_e32 v8, v8
	s_nop 0
	v_rcp_f32_e32 v6, v6
	s_nop 0
	v_rcp_f32_e32 v7, v7
	s_nop 0
	v_cvt_pk_bf16_f32 v9, v9, v7
	v_cvt_pk_bf16_f32 v8, v8, v6
	v_cvt_pk_bf16_f32 v7, v10, v13
	v_cvt_pk_bf16_f32 v6, v11, v12
	global_store_dwordx4 v[4:5], v[6:9], off offset:256
	global_load_dwordx4 v[4:7], v[0:1], off offset:16
	s_nop 0
	global_load_dwordx4 v[8:11], v[0:1], off
	s_waitcnt vmcnt(1)
	v_fmamk_f32 v4, v56, 0x3c800000, v4
	v_mul_f32_e32 v4, 0xbfb8aa3b, v4
	v_exp_f32_e32 v12, v4
	s_waitcnt vmcnt(0)
; __device__ __forceinline__ unsigned pk2(float lo, float hi) { return f2bf(lo) | (f2bf(hi) << 16); }
;     __device__ __forceinline__ void operator()(const f32x4 (&acc)[2][2][4][2], const pg8::Unit& u, int wr, int wc, int fr, int fq) const {
;     ...
;                     f32x4 v0 = acc[ai][bj][m][0], v1 = acc[ai][bj][m][1];
;                     if constexpr (MODE == 0 || MODE == 1) { v0 = v0 * scale; v1 = v1 * scale; }
;                     if constexpr (MODE == 6) { float* p = of + row * IDXW + col; *(f32x4*)p = v0; *(f32x4*)(p + 4) = v1; }
;                     else if constexpr (MODE == 0) {
;                         if (u.pn >= COL_BV / 256) {
;                             const float x8[8] = {v0[0], v0[1], v0[2], v0[3], v1[0], v1[1], v1[2], v1[3]};
;                             *(u32x2*)((unsigned char*)aux + row * 1024 + (col - COL_BV)) = to_fp8x8(x8);
;                         } else { u32x4 w; w.x = pk2(v0[0], v0[1]); w.y = pk2(v0[2], v0[3]); w.z = pk2(v1[0], v1[1]); w.w = pk2(v1[2], v1[3]);
;                             *(u32x4*)(ob + row * QKVW + col) = w; }
;                     } else if constexpr (MODE == 1) {
;                         const f32x4 b0 = *(const f32x4*)(vec + col), b1 = *(const f32x4*)(vec + col + 4);
;                         float r[8];
; #pragma unroll
;                         for (int i = 0; i < 4; ++i) { r[i] = 1.f / (1.f + __expf(-(v0[i] + b0[i]))); r[4 + i] = 1.f / (1.f + __expf(-(v1[i] + b1[i]))); }
;                         u32x4 w; w.x = pk2(r[0], r[1]); w.y = pk2(r[2], r[3]); w.z = pk2(r[4], r[5]); w.w = pk2(r[6], r[7]);
;                         *(u32x4*)(ob + row * 4096 + col) = w;
	v_fmamk_f32 v4, v61, 0x3c800000, v9
	v_mul_f32_e32 v4, 0xbfb8aa3b, v4
	v_fmamk_f32 v8, v60, 0x3c800000, v8
	v_exp_f32_e32 v14, v4
	v_fmamk_f32 v4, v57, 0x3c800000, v5
	v_fmamk_f32 v5, v62, 0x3c800000, v10
	v_mul_f32_e32 v8, 0xbfb8aa3b, v8
	v_mul_f32_e32 v5, 0xbfb8aa3b, v5
	v_exp_f32_e32 v8, v8
	v_exp_f32_e32 v9, v5
	v_fmamk_f32 v5, v58, 0x3c800000, v6
	v_mul_f32_e32 v5, 0xbfb8aa3b, v5
	v_fmac_f32_e32 v11, 0x3c800000, v63
	v_exp_f32_e32 v13, v5
	v_mul_f32_e32 v5, 0xbfb8aa3b, v11
	v_fmac_f32_e32 v7, 0x3c800000, v59
	v_exp_f32_e32 v15, v5
	v_mul_f32_e32 v5, 0xbfb8aa3b, v7
	v_pk_add_f32 v[6:7], v[8:9], 1.0 op_sel_hi:[1,0]
	v_mul_f32_e32 v4, 0xbfb8aa3b, v4
	v_exp_f32_e32 v4, v4
	v_exp_f32_e32 v5, v5
	v_rcp_f32_e32 v8, v7
	v_pk_add_f32 v[4:5], v[4:5], 1.0 op_sel_hi:[1,0]
	v_rcp_f32_e32 v9, v6
	v_pk_add_f32 v[6:7], v[14:15], 1.0 op_sel_hi:[1,0]
	s_nop 0
	s_nop 0
	v_rcp_f32_e32 v10, v6
	s_nop 0
	v_rcp_f32_e32 v11, v7
	v_pk_add_f32 v[6:7], v[12:13], 1.0 op_sel_hi:[1,0]
	s_nop 0
	s_nop 0
	v_rcp_f32_e32 v7, v7
	s_nop 0
	v_rcp_f32_e32 v6, v6
	s_nop 0
	v_rcp_f32_e32 v4, v4
	s_mov_b64 s[8:9], 0x140000
	v_rcp_f32_e32 v5, v5
	v_bfe_u32 v14, v11, 16, 1
	v_bfe_u32 v15, v10, 16, 1
	v_add3_u32 v10, v10, v15, s33
	v_add3_u32 v11, v11, v14, s33
	v_bfe_u32 v12, v9, 16, 1
	v_bfe_u32 v13, v8, 16, 1
	v_add3_u32 v8, v8, v13, s33
	v_add3_u32 v9, v9, v12, s33
	v_lshrrev_b32_e32 v12, 16, v9
	v_lshrrev_b32_e32 v13, 16, v8
	v_cvt_pk_bf16_f32 v9, v7, v5
	v_cvt_pk_bf16_f32 v8, v6, v4
	v_lshl_add_u64 v[4:5], v[2:3], 0, s[8:9]
	s_mov_b32 s8, 0x140000
	v_and_or_b32 v6, v10, s67, v12
	v_add_co_u32_e32 v10, vcc, s8, v2
	v_and_or_b32 v7, v11, s67, v13
	s_nop 0
	v_addc_co_u32_e32 v11, vcc, 0, v3, vcc
	global_store_dwordx4 v[10:11], v[6:9], off
	global_load_dwordx4 v[6:9], v[0:1], off offset:528
	s_nop 0
	global_load_dwordx4 v[10:13], v[0:1], off offset:512
	s_waitcnt vmcnt(1)
	v_fmamk_f32 v6, v48, 0x3c800000, v6
	v_mul_f32_e32 v6, 0xbfb8aa3b, v6
	v_exp_f32_e32 v14, v6
	s_waitcnt vmcnt(0)
	v_fmamk_f32 v6, v53, 0x3c800000, v11
	v_mul_f32_e32 v6, 0xbfb8aa3b, v6
	v_fmamk_f32 v10, v52, 0x3c800000, v10
	v_exp_f32_e32 v16, v6
	v_fmamk_f32 v6, v49, 0x3c800000, v7
	v_fmamk_f32 v7, v54, 0x3c800000, v12
	v_mul_f32_e32 v10, 0xbfb8aa3b, v10
	v_mul_f32_e32 v7, 0xbfb8aa3b, v7
	v_exp_f32_e32 v10, v10
	v_exp_f32_e32 v11, v7
	v_fmamk_f32 v7, v50, 0x3c800000, v8
	v_mul_f32_e32 v7, 0xbfb8aa3b, v7
	v_fmac_f32_e32 v13, 0x3c800000, v55
	v_exp_f32_e32 v15, v7
	v_mul_f32_e32 v7, 0xbfb8aa3b, v13
	v_fmac_f32_e32 v9, 0x3c800000, v51
	v_exp_f32_e32 v17, v7
	v_mul_f32_e32 v7, 0xbfb8aa3b, v9
	v_pk_add_f32 v[8:9], v[10:11], 1.0 op_sel_hi:[1,0]
	v_mul_f32_e32 v6, 0xbfb8aa3b, v6
	v_exp_f32_e32 v6, v6
	v_exp_f32_e32 v7, v7
	v_rcp_f32_e32 v10, v9
	v_pk_add_f32 v[6:7], v[6:7], 1.0 op_sel_hi:[1,0]
	v_rcp_f32_e32 v11, v8
	v_pk_add_f32 v[8:9], v[16:17], 1.0 op_sel_hi:[1,0]
	s_nop 0
	s_nop 0
	v_rcp_f32_e32 v12, v8
	s_nop 0
	v_rcp_f32_e32 v13, v9
	v_pk_add_f32 v[8:9], v[14:15], 1.0 op_sel_hi:[1,0]
	s_nop 0
	s_nop 0
	v_rcp_f32_e32 v9, v9
	s_nop 0
	v_rcp_f32_e32 v8, v8
	s_nop 0
	v_rcp_f32_e32 v6, v6
	v_div_scale_f32 v14, s[8:9], v7, v7, 1.0
	v_rcp_f32_e32 v15, v14
	s_nop 0
	v_fma_f32 v16, -v14, v15, 1.0
	v_fmac_f32_e32 v15, v16, v15
	v_div_scale_f32 v16, vcc, 1.0, v7, 1.0
	v_mul_f32_e32 v17, v16, v15
	v_fma_f32 v18, -v14, v17, v16
	v_fmac_f32_e32 v17, v18, v15
	v_rcp_f32_e32 v7, v7
	s_nop 0
	v_cvt_pk_bf16_f32 v9, v9, v7
	v_cvt_pk_bf16_f32 v8, v8, v6
	v_cvt_pk_bf16_f32 v7, v10, v13
	v_cvt_pk_bf16_f32 v6, v11, v12
	global_store_dwordx4 v[4:5], v[6:9], off offset:256
	global_load_dwordx4 v[4:7], v[0:1], off offset:16
	s_nop 0
	global_load_dwordx4 v[8:11], v[0:1], off
	s_waitcnt vmcnt(1)
	v_fmamk_f32 v4, v40, 0x3c800000, v4
	v_mul_f32_e32 v4, 0xbfb8aa3b, v4
	v_exp_f32_e32 v12, v4
	s_waitcnt vmcnt(0)
; template <class Epi, class Sched, bool ALIGN_EPI = false, bool SP2 = false, bool F8 = false>
; __device__ __forceinline__ void gemm_phase(PG8_LAS unsigned char* lds, const Gemm g, const Sched& S, const Epi& E) {
;     ...
;         if constexpr (ALIGN_EPI) { if (wr == 0) PG8_BAR; }
;         if constexpr (F8) asm volatile("s_nop 15\n\ts_nop 15" : "+v"(acc[1][1][0][0]), "+v"(acc[1][1][0][1]), "+v"(acc[1][1][1][0]), "+v"(acc[1][1][1][1]), "+v"(acc[1][1][2][0]), "+v"(acc[1][1][2][1]), "+v"(acc[1][1][3][0]), "+v"(acc[1][1][3][1]));
;         if constexpr (!Epi::AFTER_DRAIN) { E(acc, cur, wr, wc, fr, fq); S.done(cur); }
;         if (!has_next) break;
; #pragma unroll
;         for (int a = 0; a < 2; ++a)
; #pragma unroll
;             for (int b = 0; b < 2; ++b)
; #pragma unroll
;                 for (int m = 0; m < 4; ++m)
; #pragma unroll
;     __device__ __forceinline__ void operator()(const f32x4 (&acc)[2][2][4][2], const pg8::Unit& u, int wr, int wc, int fr, int fq) const {
;     ...
;                     f32x4 v0 = acc[ai][bj][m][0], v1 = acc[ai][bj][m][1];
;                     if constexpr (MODE == 0 || MODE == 1) { v0 = v0 * scale; v1 = v1 * scale; }
;                     if constexpr (MODE == 6) { float* p = of + row * IDXW + col; *(f32x4*)p = v0; *(f32x4*)(p + 4) = v1; }
;                     else if constexpr (MODE == 0) {
;                         if (u.pn >= COL_BV / 256) {
;                             const float x8[8] = {v0[0], v0[1], v0[2], v0[3], v1[0], v1[1], v1[2], v1[3]};
;                             *(u32x2*)((unsigned char*)aux + row * 1024 + (col - COL_BV)) = to_fp8x8(x8);
;                         } else { u32x4 w; w.x = pk2(v0[0], v0[1]); w.y = pk2(v0[2], v0[3]); w.z = pk2(v1[0], v1[1]); w.w = pk2(v1[2], v1[3]);
;                             *(u32x4*)(ob + row * QKVW + col) = w; }
;                     } else if constexpr (MODE == 1) {
;                         const f32x4 b0 = *(const f32x4*)(vec + col), b1 = *(const f32x4*)(vec + col + 4);
;                         float r[8];
; #pragma unroll
;                         for (int i = 0; i < 4; ++i) { r[i] = 1.f / (1.f + __expf(-(v0[i] + b0[i]))); r[4 + i] = 1.f / (1.f + __expf(-(v1[i] + b1[i]))); }
;                         u32x4 w; w.x = pk2(r[0], r[1]); w.y = pk2(r[2], r[3]); w.z = pk2(r[4], r[5]); w.w = pk2(r[6], r[7]);
;                         *(u32x4*)(ob + row * 4096 + col) = w;
	v_fmamk_f32 v4, v45, 0x3c800000, v9
	v_mul_f32_e32 v4, 0xbfb8aa3b, v4
	v_fmamk_f32 v8, v44, 0x3c800000, v8
	v_exp_f32_e32 v14, v4
	v_fmamk_f32 v4, v41, 0x3c800000, v5
	v_fmamk_f32 v5, v46, 0x3c800000, v10
	v_mul_f32_e32 v8, 0xbfb8aa3b, v8
	v_mul_f32_e32 v5, 0xbfb8aa3b, v5
	v_exp_f32_e32 v8, v8
	v_exp_f32_e32 v9, v5
	v_fmamk_f32 v5, v42, 0x3c800000, v6
	v_mul_f32_e32 v5, 0xbfb8aa3b, v5
	v_fmac_f32_e32 v11, 0x3c800000, v47
	v_exp_f32_e32 v13, v5
	v_mul_f32_e32 v5, 0xbfb8aa3b, v11
	v_fmac_f32_e32 v7, 0x3c800000, v43
	v_exp_f32_e32 v15, v5
	v_mul_f32_e32 v5, 0xbfb8aa3b, v7
	v_pk_add_f32 v[6:7], v[8:9], 1.0 op_sel_hi:[1,0]
	v_mul_f32_e32 v4, 0xbfb8aa3b, v4
	v_exp_f32_e32 v4, v4
	v_exp_f32_e32 v5, v5
	v_rcp_f32_e32 v8, v7
	v_pk_add_f32 v[4:5], v[4:5], 1.0 op_sel_hi:[1,0]
	v_rcp_f32_e32 v9, v6
	v_pk_add_f32 v[6:7], v[14:15], 1.0 op_sel_hi:[1,0]
	s_nop 0
	s_nop 0
	v_rcp_f32_e32 v10, v6
	s_nop 0
	v_rcp_f32_e32 v11, v7
	v_pk_add_f32 v[6:7], v[12:13], 1.0 op_sel_hi:[1,0]
	s_nop 0
	s_nop 0
	v_rcp_f32_e32 v7, v7
	s_nop 0
	v_rcp_f32_e32 v6, v6
	s_nop 0
	v_rcp_f32_e32 v4, v4
	v_div_scale_f32 v12, s[8:9], v5, v5, 1.0
	v_rcp_f32_e32 v13, v12
	s_mov_b64 s[8:9], 0x160000
	v_fma_f32 v14, -v12, v13, 1.0
	v_fmac_f32_e32 v13, v14, v13
	v_div_scale_f32 v14, vcc, 1.0, v5, 1.0
	v_mul_f32_e32 v15, v14, v13
	v_fma_f32 v16, -v12, v15, v14
	v_rcp_f32_e32 v5, v5
	v_bfe_u32 v14, v11, 16, 1
	v_bfe_u32 v15, v10, 16, 1
	v_add3_u32 v10, v10, v15, s33
	v_add3_u32 v11, v11, v14, s33
	v_bfe_u32 v12, v9, 16, 1
	v_bfe_u32 v13, v8, 16, 1
	v_add3_u32 v8, v8, v13, s33
	v_add3_u32 v9, v9, v12, s33
	v_lshrrev_b32_e32 v12, 16, v9
	v_lshrrev_b32_e32 v13, 16, v8
	v_cvt_pk_bf16_f32 v9, v7, v5
	v_cvt_pk_bf16_f32 v8, v6, v4
	v_lshl_add_u64 v[4:5], v[2:3], 0, s[8:9]
	s_mov_b32 s8, 0x160000
	v_add_co_u32_e32 v2, vcc, s8, v2
	v_and_or_b32 v7, v11, s67, v13
	v_and_or_b32 v6, v10, s67, v12
	v_addc_co_u32_e32 v3, vcc, 0, v3, vcc
	global_store_dwordx4 v[2:3], v[6:9], off
	global_load_dwordx4 v[6:9], v[0:1], off offset:528
	s_nop 0
	global_load_dwordx4 v[0:3], v[0:1], off offset:512
	s_waitcnt vmcnt(1)
	v_fmac_f32_e32 v9, 0x3c800000, v35
	s_waitcnt vmcnt(0)
	v_fmamk_f32 v0, v36, 0x3c800000, v0
	v_mul_f32_e32 v0, 0xbfb8aa3b, v0
	v_exp_f32_e32 v10, v0
	v_fmamk_f32 v0, v32, 0x3c800000, v6
	v_mul_f32_e32 v0, 0xbfb8aa3b, v0
	v_exp_f32_e32 v6, v0
	v_fmamk_f32 v0, v37, 0x3c800000, v1
	v_fmamk_f32 v1, v38, 0x3c800000, v2
	v_mul_f32_e32 v1, 0xbfb8aa3b, v1
	v_exp_f32_e32 v11, v1
	v_fmamk_f32 v1, v34, 0x3c800000, v8
	v_mul_f32_e32 v0, 0xbfb8aa3b, v0
	v_mul_f32_e32 v1, 0xbfb8aa3b, v1
	v_fmac_f32_e32 v3, 0x3c800000, v39
	v_exp_f32_e32 v12, v0
	v_fmamk_f32 v0, v33, 0x3c800000, v7
	v_exp_f32_e32 v7, v1
	v_mul_f32_e32 v1, 0xbfb8aa3b, v3
	v_pk_add_f32 v[2:3], v[10:11], 1.0 op_sel_hi:[1,0]
	v_exp_f32_e32 v13, v1
	v_mul_f32_e32 v1, 0xbfb8aa3b, v9
	v_mul_f32_e32 v0, 0xbfb8aa3b, v0
	v_exp_f32_e32 v0, v0
	v_exp_f32_e32 v1, v1
	v_rcp_f32_e32 v8, v3
	v_pk_add_f32 v[0:1], v[0:1], 1.0 op_sel_hi:[1,0]
	v_rcp_f32_e32 v9, v2
	v_pk_add_f32 v[2:3], v[12:13], 1.0 op_sel_hi:[1,0]
	s_nop 0
	s_nop 0
	v_rcp_f32_e32 v10, v2
	s_nop 0
	v_rcp_f32_e32 v11, v3
	v_pk_add_f32 v[2:3], v[6:7], 1.0 op_sel_hi:[1,0]
	s_nop 0
	s_nop 0
	v_rcp_f32_e32 v3, v3
	s_nop 0
	v_rcp_f32_e32 v2, v2
	s_nop 0
	v_rcp_f32_e32 v0, v0
	v_div_scale_f32 v6, s[8:9], v1, v1, 1.0
	v_rcp_f32_e32 v7, v6
	s_nop 0
	v_fma_f32 v12, -v6, v7, 1.0
	v_fmac_f32_e32 v7, v12, v7
	v_div_scale_f32 v12, vcc, 1.0, v1, 1.0
	v_mul_f32_e32 v13, v12, v7
	v_fma_f32 v14, -v6, v13, v12
	v_fmac_f32_e32 v13, v14, v7
	v_fma_f32 v6, -v6, v13, v12
	v_div_fmas_f32 v6, v6, v7, v13
	v_rcp_f32_e32 v1, v1
	s_nop 0
	v_cvt_pk_bf16_f32 v3, v3, v1
	v_cvt_pk_bf16_f32 v2, v2, v0
	v_cvt_pk_bf16_f32 v1, v8, v11
	v_cvt_pk_bf16_f32 v0, v9, v10
	s_andn2_b64 vcc, exec, s[38:39]
	global_store_dwordx4 v[4:5], v[0:3], off offset:256
	s_cbranch_vccnz .LBB0_1114
	s_andn2_b64 vcc, exec, s[0:1]
	s_cbranch_vccnz .LBB0_1113
	s_barrier
	s_branch .LBB0_1113

; #define LAS __attribute__((address_space(3)))
; template <bool F8>
; __device__ __forceinline__ void transpose_item(const float* W, int ldw, int K, int N, int Npad, void* WTv, LAS float* scr, int item, int lane) {
;     ...
;     for (int i = 0; i < 8; ++i) { const int kk = 8 * i + (lane >> 3); tv[i] = ok ? *(const f32x4*)(W + (size_t)(k0 + kk) * ldw + n0 + c4) : (f32x4){0.f, 0.f, 0.f, 0.f}; }
; #pragma unroll
;     for (int i = 0; i < 8; ++i) { const int kk = 8 * i + (lane >> 3); LAS float* d = scr + kk * 33 + c4; d[0] = tv[i][0]; d[1] = tv[i][1]; d[2] = tv[i][2]; d[3] = tv[i][3]; }
;     asm volatile("s_waitcnt lgkmcnt(0)" ::: "memory");
;     const int c = lane & 7;
; #pragma unroll
;     for (int j = 0; j < 4; ++j) { const int n = (lane >> 3) + 8 * j; const LAS float* s = scr + (8 * c) * 33 + n;
;         if constexpr (F8) { const float x[8] = {s[0] * W8_SCALE, s[33] * W8_SCALE, s[66] * W8_SCALE, s[99] * W8_SCALE, s[132] * W8_SCALE, s[165] * W8_SCALE, s[198] * W8_SCALE, s[231] * W8_SCALE};
;             *(u32x2*)((unsigned char*)WTv + (size_t)(n0 + n) * K + k0 + 8 * c) = to_fp8x8(x); }
;         else { u32x4 o; o.x = pk2(s[0 * 33], s[1 * 33]); o.y = pk2(s[2 * 33], s[3 * 33]); o.z = pk2(s[4 * 33], s[5 * 33]); o.w = pk2(s[6 * 33], s[7 * 33]);
;             *(u32x4*)((bf16_t*)WTv + (size_t)(n0 + n) * K + k0 + 8 * c) = o; } }
; __global__ void __launch_bounds__(NTHREADS, 2) mega(Args a) {
;     ...
;                 const int l = it / PER_LAYER; int r = it % PER_LAYER; unsigned char* wl = ws + WS_W + (size_t)l * W_LAYER;
;                 const float* win = a.in[I_WIN] + (size_t)l * DM * NIN;
;                 if (r < I_IN8) { transpose_item<true>(win, NIN, DM, QKVW, QKVW, wl + W_IN8, scr, r, lane); continue; } r -= I_IN8;
;                 if (r < I_I16) { transpose_item<false>(win + QKVW, NIN, DM, NIN - QKVW, IDXW, wl + W_I16, scr, r, lane); continue; } r -= I_I16;
;                 if (r < I_G8) { transpose_item<true>(a.in[I_WG] + (size_t)l * DM * 4096, 4096, DM, 4096, 4096, wl + W_G8, scr, r, lane); continue; } r -= I_G8;
;                 if (r < I_PA) { transpose_item<false>(a.in[I_WPA] + (size_t)l * 512 * DM, DM, 512, DM, DM, wl + W_PA, scr, r, lane); continue; } r -= I_PA;
;                 if (r < I_PB) { transpose_item<false>(a.in[I_WPB] + (size_t)l * 1024 * DM, DM, 1024, DM, DM, wl + W_PB, scr, r, lane); continue; } r -= I_PB;
.LBB0_1188:
	s_mul_hi_i32 s0, s12, 0xfe03f81
	s_lshr_b32 s1, s0, 31
	s_ashr_i32 s0, s0, 11
	s_add_i32 s4, s0, s1
	s_mul_i32 s0, s4, 0xffff7f00
	s_add_i32 s17, s12, s0
	s_mul_i32 s1, s4, 0x7100000
	s_mul_hi_i32 s0, s4, 0x7100000
	s_add_u32 s10, s36, s1
	v_readlane_b32 s1, v251, 26
	s_addc_u32 s11, s1, s0
	s_mul_i32 s1, s4, 0x44a0000
	s_mul_hi_i32 s0, s4, 0x44a0000
	s_add_u32 s13, s78, s1
	s_addc_u32 s16, s79, s0
	s_cmpk_gt_i32 s17, 0x1dff
	s_mov_b64 s[0:1], -1
	s_cbranch_scc0 .LBB0_1230
	s_cmpk_gt_u32 s17, 0x22ff
	s_cbranch_scc0 .LBB0_1211
	s_ashr_i32 s5, s4, 31
	s_cmpk_gt_u32 s17, 0x32ff
	s_cbranch_scc0 .LBB0_1208
	s_cmpk_gt_u32 s17, 0x34ff
	s_cbranch_scc0 .LBB0_1205
	s_cmpk_gt_u32 s17, 0x38ff
	s_cbranch_scc0 .LBB0_1202
	s_cmpk_gt_u32 s17, 0x40ff
	s_cbranch_scc0 .LBB0_1199
	s_lshl_b64 s[0:1], s[4:5], 26
	s_cmpk_gt_u32 s17, 0x60ff
	s_mov_b64 s[6:7], -1
	s_cbranch_scc0 .LBB0_1196
	s_add_u32 s7, s86, s0
	s_addc_u32 s19, s87, s1
	s_add_i32 s6, s17, 0x9f00
	s_and_b32 s28, s6, 0xffc0
	s_lshl_b32 s6, s17, 5
	s_and_b32 s6, s6, 0x7e0
	s_lshl_b32 s22, s6, 2
	s_add_u32 s22, s7, s22
	v_or_b32_e32 v2, s28, v33
	s_addc_u32 s23, s19, 0
	v_lshlrev_b32_e32 v160, 2, v32
	v_lshl_add_u64 v[0:1], s[22:23], 0, v[160:161]
	v_lshlrev_b32_e32 v160, 13, v2
	v_lshl_add_u64 v[28:29], v[0:1], 0, v[160:161]
	s_mov_b32 s7, 0x10000
	v_add_co_u32_e32 v4, vcc, s7, v28
	s_mov_b32 s7, 0x20000
	s_nop 0
	v_addc_co_u32_e32 v5, vcc, 0, v29, vcc
	v_add_co_u32_e32 v8, vcc, s7, v28
	s_mov_b32 s7, 0x30000
	s_nop 0
	v_addc_co_u32_e32 v9, vcc, 0, v29, vcc
	v_add_co_u32_e32 v12, vcc, s7, v28
	s_mov_b32 s7, 0x40000
	s_nop 0
	v_addc_co_u32_e32 v13, vcc, 0, v29, vcc
	v_add_co_u32_e32 v16, vcc, s7, v28
	s_mov_b32 s7, 0x50000
	s_nop 0
	v_addc_co_u32_e32 v17, vcc, 0, v29, vcc
	v_add_co_u32_e32 v20, vcc, s7, v28
	global_load_dwordx4 v[0:3], v[28:29], off
	s_nop 0
	global_load_dwordx4 v[4:7], v[4:5], off
	v_addc_co_u32_e32 v21, vcc, 0, v29, vcc
	global_load_dwordx4 v[8:11], v[8:9], off
	s_nop 0
	global_load_dwordx4 v[12:15], v[12:13], off
	s_nop 0
	global_load_dwordx4 v[16:19], v[16:17], off
	s_nop 0
	global_load_dwordx4 v[20:23], v[20:21], off
	s_mov_b32 s7, 0x60000
	v_add_co_u32_e32 v24, vcc, s7, v28
	s_mov_b32 s7, 0x70000
	s_nop 0
	v_addc_co_u32_e32 v25, vcc, 0, v29, vcc
	global_load_dwordx4 v[24:27], v[24:25], off
	v_add_co_u32_e32 v28, vcc, s7, v28
	v_add_u32_e32 v38, v40, v41
	s_nop 0
	v_addc_co_u32_e32 v29, vcc, 0, v29, vcc
	global_load_dwordx4 v[28:31], v[28:29], off
	v_add_u32_e32 v39, 0x420, v38
	v_add_u32_e32 v46, 0x428, v38
	v_add_u32_e32 v47, 0x840, v38
	v_add_u32_e32 v48, 0x848, v38
	v_add_u32_e32 v49, 0xc60, v38
	v_add_u32_e32 v50, 0xc68, v38
	v_add_u32_e32 v51, 0x1080, v38
	v_add_u32_e32 v52, 0x1088, v38
	v_add_u32_e32 v53, 0x14a0, v38
	v_add_u32_e32 v54, 0x14a8, v38
	v_add_u32_e32 v55, 0x18c0, v38
	v_add_u32_e32 v56, 0x18c8, v38
	v_add_u32_e32 v57, 0x1ce0, v38
	v_add_u32_e32 v58, 0x1ce8, v38
	s_lshl_b32 s7, s28, 1
	s_add_u32 s22, s10, s7
	s_addc_u32 s23, s11, 0
	v_lshlrev_b32_e32 v160, 1, v34
	v_lshl_add_u64 v[36:37], s[22:23], 0, v[160:161]
	s_mov_b64 s[22:23], 0x5100000
	s_waitcnt vmcnt(7)
	ds_write2_b32 v38, v0, v1 offset1:1
	ds_write2_b32 v38, v2, v3 offset0:2 offset1:3
	s_waitcnt vmcnt(6)
	ds_write2_b32 v39, v4, v5 offset1:1
	ds_write2_b32 v46, v6, v7 offset1:1
	s_waitcnt vmcnt(5)
	ds_write2_b32 v47, v8, v9 offset1:1
	ds_write2_b32 v48, v10, v11 offset1:1
	s_waitcnt vmcnt(4)
	ds_write2_b32 v49, v12, v13 offset1:1
	ds_write2_b32 v50, v14, v15 offset1:1
	s_waitcnt vmcnt(3)
	ds_write2_b32 v51, v16, v17 offset1:1
	ds_write2_b32 v52, v18, v19 offset1:1
	s_waitcnt vmcnt(2)
	ds_write2_b32 v53, v20, v21 offset1:1
	ds_write2_b32 v54, v22, v23 offset1:1
	s_waitcnt vmcnt(1)
	ds_write2_b32 v55, v24, v25 offset1:1
	ds_write2_b32 v56, v26, v27 offset1:1
	s_waitcnt vmcnt(0)
	ds_write2_b32 v57, v28, v29 offset1:1
	ds_write2_b32 v58, v30, v31 offset1:1
	s_waitcnt lgkmcnt(0)
	ds_read2_b32 v[4:5], v45 offset1:8
	ds_read2_b32 v[6:7], v45 offset0:33 offset1:41
	ds_read2_b32 v[8:9], v45 offset0:66 offset1:74
	ds_read2_b32 v[12:13], v45 offset0:99 offset1:107
	ds_read2_b32 v[14:15], v45 offset0:132 offset1:140
	s_waitcnt lgkmcnt(4)
	s_waitcnt lgkmcnt(3)
	ds_read2_b32 v[16:17], v45 offset0:165 offset1:173
	s_waitcnt lgkmcnt(3)
	v_cvt_pk_bf16_f32 v0, v4, v6
	s_waitcnt lgkmcnt(2)
	ds_read2_b32 v[18:19], v45 offset0:198 offset1:206
	ds_read2_b32 v[20:21], v45 offset0:231 offset1:239
	v_cvt_pk_bf16_f32 v1, v8, v12
	s_waitcnt lgkmcnt(3)
	s_waitcnt lgkmcnt(2)
	v_cvt_pk_bf16_f32 v2, v14, v16
	s_waitcnt lgkmcnt(1)
	s_waitcnt lgkmcnt(0)
	v_cvt_pk_bf16_f32 v3, v18, v20
	v_or_b32_e32 v4, s6, v33
	v_lshl_add_u64 v[10:11], v[36:37], 0, s[22:23]
	v_lshlrev_b32_e32 v160, 14, v4
	v_lshl_add_u64 v[22:23], v[10:11], 0, v[160:161]
	global_store_dwordx4 v[22:23], v[0:3], off
	v_or_b32_e32 v6, s6, v42
	s_nop 0
	v_cvt_pk_bf16_f32 v0, v5, v7
	v_cvt_pk_bf16_f32 v1, v9, v13
	v_cvt_pk_bf16_f32 v2, v15, v17
	v_lshlrev_b32_e32 v160, 14, v6
	v_cvt_pk_bf16_f32 v3, v19, v21
	ds_read2_b32 v[4:5], v45 offset0:16 offset1:24
	v_lshl_add_u64 v[6:7], v[10:11], 0, v[160:161]
	global_store_dwordx4 v[6:7], v[0:3], off
	ds_read2_b32 v[6:7], v45 offset0:49 offset1:57
	ds_read2_b32 v[8:9], v45 offset0:82 offset1:90
	ds_read2_b32 v[12:13], v45 offset0:115 offset1:123
	s_waitcnt lgkmcnt(3)
	s_waitcnt lgkmcnt(2)
	ds_read2_b32 v[14:15], v45 offset0:148 offset1:156
	ds_read2_b32 v[16:17], v45 offset0:181 offset1:189
	v_cvt_pk_bf16_f32 v0, v4, v6
	s_waitcnt lgkmcnt(3)
	s_waitcnt lgkmcnt(2)
	ds_read2_b32 v[18:19], v45 offset0:214 offset1:222
	ds_read2_b32 v[20:21], v45 offset0:247 offset1:255
	v_cvt_pk_bf16_f32 v1, v8, v12
	s_waitcnt lgkmcnt(3)
	s_waitcnt lgkmcnt(2)
	v_cvt_pk_bf16_f32 v2, v14, v16
	s_waitcnt lgkmcnt(1)
	s_waitcnt lgkmcnt(0)
	v_cvt_pk_bf16_f32 v3, v18, v20
	v_or_b32_e32 v4, s6, v43
	v_lshlrev_b32_e32 v160, 14, v4
	v_lshl_add_u64 v[22:23], v[10:11], 0, v[160:161]
	global_store_dwordx4 v[22:23], v[0:3], off
	s_nop 1
	v_cvt_pk_bf16_f32 v0, v5, v7
	s_nop 0
	v_cvt_pk_bf16_f32 v1, v9, v13
	v_cvt_pk_bf16_f32 v2, v15, v17
	v_cvt_pk_bf16_f32 v3, v19, v21
	v_or_b32_e32 v4, s6, v44
	v_lshlrev_b32_e32 v160, 14, v4
	v_lshl_add_u64 v[4:5], v[10:11], 0, v[160:161]
	global_store_dwordx4 v[4:5], v[0:3], off
	s_waitcnt lgkmcnt(0)
	s_mov_b64 s[6:7], 0
; #define LAS __attribute__((address_space(3)))
; __device__ __forceinline__ unsigned pk2(float lo, float hi) { return f2bf(lo) | (f2bf(hi) << 16); }
; template <bool F8>
; __device__ __forceinline__ void transpose_item(const float* W, int ldw, int K, int N, int Npad, void* WTv, LAS float* scr, int item, int lane) {
;     ...
;     for (int i = 0; i < 8; ++i) { const int kk = 8 * i + (lane >> 3); tv[i] = ok ? *(const f32x4*)(W + (size_t)(k0 + kk) * ldw + n0 + c4) : (f32x4){0.f, 0.f, 0.f, 0.f}; }
; #pragma unroll
;     for (int i = 0; i < 8; ++i) { const int kk = 8 * i + (lane >> 3); LAS float* d = scr + kk * 33 + c4; d[0] = tv[i][0]; d[1] = tv[i][1]; d[2] = tv[i][2]; d[3] = tv[i][3]; }
;     asm volatile("s_waitcnt lgkmcnt(0)" ::: "memory");
;     const int c = lane & 7;
; #pragma unroll
;     for (int j = 0; j < 4; ++j) { const int n = (lane >> 3) + 8 * j; const LAS float* s = scr + (8 * c) * 33 + n;
;         if constexpr (F8) { const float x[8] = {s[0] * W8_SCALE, s[33] * W8_SCALE, s[66] * W8_SCALE, s[99] * W8_SCALE, s[132] * W8_SCALE, s[165] * W8_SCALE, s[198] * W8_SCALE, s[231] * W8_SCALE};
;             *(u32x2*)((unsigned char*)WTv + (size_t)(n0 + n) * K + k0 + 8 * c) = to_fp8x8(x); }
;         else { u32x4 o; o.x = pk2(s[0 * 33], s[1 * 33]); o.y = pk2(s[2 * 33], s[3 * 33]); o.z = pk2(s[4 * 33], s[5 * 33]); o.w = pk2(s[6 * 33], s[7 * 33]);
;             *(u32x4*)((bf16_t*)WTv + (size_t)(n0 + n) * K + k0 + 8 * c) = o; } }
; __global__ void __launch_bounds__(NTHREADS, 2) mega(Args a) {
;     ...
;                 if (r < I_UP) { transpose_item<false>(a.in[I_WUP] + (size_t)l * DM * HIDN, HIDN, DM, HIDN, HIDN, wl + W_UP, scr, r, lane); continue; } r -= I_UP;
.LBB0_1196:
	s_andn2_b64 vcc, exec, s[6:7]
	s_cbranch_vccnz .LBB0_1198
	s_add_u32 s6, s84, s0
	s_addc_u32 s1, s85, s1
	s_add_i32 s0, s17, 0xbf00
	s_bfe_u32 s19, s0, 0x80008
	s_lshl_b32 s0, s17, 5
	s_and_b32 s0, s0, 0x1fe0
	s_lshl_b32 s7, s0, 2
	s_add_u32 s6, s6, s7
	v_lshl_or_b32 v2, s19, 6, v33
	s_addc_u32 s7, s1, 0
	v_lshlrev_b32_e32 v160, 2, v32
	v_lshl_add_u64 v[0:1], s[6:7], 0, v[160:161]
	v_lshlrev_b32_e32 v160, 15, v2
	v_lshl_add_u64 v[28:29], v[0:1], 0, v[160:161]
	s_mov_b32 s1, 0x40000
	v_add_co_u32_e32 v4, vcc, s1, v28
	s_mov_b32 s1, 0x80000
	s_nop 0
	v_addc_co_u32_e32 v5, vcc, 0, v29, vcc
	v_add_co_u32_e32 v8, vcc, s1, v28
	s_mov_b32 s1, 0xc0000
	s_nop 0
	v_addc_co_u32_e32 v9, vcc, 0, v29, vcc
	v_add_co_u32_e32 v12, vcc, s1, v28
	s_mov_b32 s1, 0x100000
	s_nop 0
	v_addc_co_u32_e32 v13, vcc, 0, v29, vcc
	v_add_co_u32_e32 v16, vcc, s1, v28
	s_mov_b32 s1, 0x140000
	s_nop 0
	v_addc_co_u32_e32 v17, vcc, 0, v29, vcc
	v_add_co_u32_e32 v20, vcc, s1, v28
	global_load_dwordx4 v[0:3], v[28:29], off
	s_nop 0
	global_load_dwordx4 v[4:7], v[4:5], off
	v_addc_co_u32_e32 v21, vcc, 0, v29, vcc
	global_load_dwordx4 v[8:11], v[8:9], off
	s_nop 0
	global_load_dwordx4 v[12:15], v[12:13], off
	s_nop 0
	global_load_dwordx4 v[16:19], v[16:17], off
	s_nop 0
	global_load_dwordx4 v[20:23], v[20:21], off
	s_mov_b32 s1, 0x180000
	v_add_co_u32_e32 v24, vcc, s1, v28
	s_mov_b32 s1, 0x1c0000
	s_nop 0
	v_addc_co_u32_e32 v25, vcc, 0, v29, vcc
	global_load_dwordx4 v[24:27], v[24:25], off
	v_add_co_u32_e32 v28, vcc, s1, v28
	v_add_u32_e32 v38, v40, v41
	s_nop 0
	v_addc_co_u32_e32 v29, vcc, 0, v29, vcc
	global_load_dwordx4 v[28:31], v[28:29], off
	v_add_u32_e32 v39, 0x420, v38
	v_add_u32_e32 v46, 0x428, v38
	v_add_u32_e32 v47, 0x840, v38
	v_add_u32_e32 v48, 0x848, v38
	v_add_u32_e32 v49, 0xc60, v38
	v_add_u32_e32 v50, 0xc68, v38
	v_add_u32_e32 v51, 0x1080, v38
	v_add_u32_e32 v52, 0x1088, v38
	v_add_u32_e32 v53, 0x14a0, v38
	v_add_u32_e32 v54, 0x14a8, v38
	v_add_u32_e32 v55, 0x18c0, v38
	v_add_u32_e32 v56, 0x18c8, v38
	v_add_u32_e32 v57, 0x1ce0, v38
	v_add_u32_e32 v58, 0x1ce8, v38
	s_lshl_b32 s1, s19, 7
	s_add_u32 s6, s10, s1
	s_addc_u32 s7, s11, 0
	v_lshlrev_b32_e32 v160, 1, v34
	v_lshl_add_u64 v[36:37], s[6:7], 0, v[160:161]
	s_mov_b64 s[6:7], 0x3100000
	s_waitcnt vmcnt(7)
	ds_write2_b32 v38, v0, v1 offset1:1
	ds_write2_b32 v38, v2, v3 offset0:2 offset1:3
	s_waitcnt vmcnt(6)
	ds_write2_b32 v39, v4, v5 offset1:1
	ds_write2_b32 v46, v6, v7 offset1:1
	s_waitcnt vmcnt(5)
	ds_write2_b32 v47, v8, v9 offset1:1
	ds_write2_b32 v48, v10, v11 offset1:1
	s_waitcnt vmcnt(4)
	ds_write2_b32 v49, v12, v13 offset1:1
	ds_write2_b32 v50, v14, v15 offset1:1
	s_waitcnt vmcnt(3)
	ds_write2_b32 v51, v16, v17 offset1:1
	ds_write2_b32 v52, v18, v19 offset1:1
	s_waitcnt vmcnt(2)
	ds_write2_b32 v53, v20, v21 offset1:1
	ds_write2_b32 v54, v22, v23 offset1:1
	s_waitcnt vmcnt(1)
	ds_write2_b32 v55, v24, v25 offset1:1
	ds_write2_b32 v56, v26, v27 offset1:1
	s_waitcnt vmcnt(0)
	ds_write2_b32 v57, v28, v29 offset1:1
	ds_write2_b32 v58, v30, v31 offset1:1
	s_waitcnt lgkmcnt(0)
	ds_read2_b32 v[4:5], v45 offset1:8
	ds_read2_b32 v[6:7], v45 offset0:33 offset1:41
	ds_read2_b32 v[8:9], v45 offset0:66 offset1:74
	ds_read2_b32 v[12:13], v45 offset0:99 offset1:107
	ds_read2_b32 v[14:15], v45 offset0:132 offset1:140
	s_waitcnt lgkmcnt(4)
	s_waitcnt lgkmcnt(3)
	ds_read2_b32 v[16:17], v45 offset0:165 offset1:173
	s_waitcnt lgkmcnt(3)
	v_cvt_pk_bf16_f32 v0, v4, v6
	s_waitcnt lgkmcnt(2)
	ds_read2_b32 v[18:19], v45 offset0:198 offset1:206
	ds_read2_b32 v[20:21], v45 offset0:231 offset1:239
	v_cvt_pk_bf16_f32 v1, v8, v12
	s_waitcnt lgkmcnt(3)
	s_waitcnt lgkmcnt(2)
	v_cvt_pk_bf16_f32 v2, v14, v16
	s_waitcnt lgkmcnt(1)
	s_waitcnt lgkmcnt(0)
	v_cvt_pk_bf16_f32 v3, v18, v20
	v_or_b32_e32 v4, s0, v33
	v_lshl_add_u64 v[10:11], v[36:37], 0, s[6:7]
	v_lshlrev_b32_e32 v160, 12, v4
	v_lshl_add_u64 v[22:23], v[10:11], 0, v[160:161]
	global_store_dwordx4 v[22:23], v[0:3], off
	v_or_b32_e32 v6, s0, v42
	s_nop 0
	v_cvt_pk_bf16_f32 v0, v5, v7
	v_cvt_pk_bf16_f32 v1, v9, v13
	v_cvt_pk_bf16_f32 v2, v15, v17
	v_lshlrev_b32_e32 v160, 12, v6
	v_cvt_pk_bf16_f32 v3, v19, v21
	ds_read2_b32 v[4:5], v45 offset0:16 offset1:24
	v_lshl_add_u64 v[6:7], v[10:11], 0, v[160:161]
	global_store_dwordx4 v[6:7], v[0:3], off
	ds_read2_b32 v[6:7], v45 offset0:49 offset1:57
	ds_read2_b32 v[8:9], v45 offset0:82 offset1:90
	ds_read2_b32 v[12:13], v45 offset0:115 offset1:123
	s_waitcnt lgkmcnt(3)
	s_waitcnt lgkmcnt(2)
	ds_read2_b32 v[14:15], v45 offset0:148 offset1:156
	ds_read2_b32 v[16:17], v45 offset0:181 offset1:189
	v_cvt_pk_bf16_f32 v0, v4, v6
	s_waitcnt lgkmcnt(3)
	s_waitcnt lgkmcnt(2)
	ds_read2_b32 v[18:19], v45 offset0:214 offset1:222
	ds_read2_b32 v[20:21], v45 offset0:247 offset1:255
	v_cvt_pk_bf16_f32 v1, v8, v12
	s_waitcnt lgkmcnt(3)
	s_waitcnt lgkmcnt(2)
	v_cvt_pk_bf16_f32 v2, v14, v16
	s_waitcnt lgkmcnt(1)
	s_waitcnt lgkmcnt(0)
	v_cvt_pk_bf16_f32 v3, v18, v20
	v_or_b32_e32 v4, s0, v43
	v_lshlrev_b32_e32 v160, 12, v4
	v_lshl_add_u64 v[22:23], v[10:11], 0, v[160:161]
	global_store_dwordx4 v[22:23], v[0:3], off
	s_nop 1
	v_cvt_pk_bf16_f32 v0, v5, v7
	s_nop 0
	v_cvt_pk_bf16_f32 v1, v9, v13
	v_cvt_pk_bf16_f32 v2, v15, v17
	v_cvt_pk_bf16_f32 v3, v19, v21
	v_or_b32_e32 v4, s0, v44
	v_lshlrev_b32_e32 v160, 12, v4
	v_lshl_add_u64 v[4:5], v[10:11], 0, v[160:161]
	global_store_dwordx4 v[4:5], v[0:3], off
	s_waitcnt lgkmcnt(0)

; #define LAS __attribute__((address_space(3)))
; __device__ __forceinline__ unsigned pk2(float lo, float hi) { return f2bf(lo) | (f2bf(hi) << 16); }
; template <bool F8>
; __device__ __forceinline__ void transpose_item(const float* W, int ldw, int K, int N, int Npad, void* WTv, LAS float* scr, int item, int lane) {
;     ...
;     for (int i = 0; i < 8; ++i) { const int kk = 8 * i + (lane >> 3); tv[i] = ok ? *(const f32x4*)(W + (size_t)(k0 + kk) * ldw + n0 + c4) : (f32x4){0.f, 0.f, 0.f, 0.f}; }
; #pragma unroll
;     for (int i = 0; i < 8; ++i) { const int kk = 8 * i + (lane >> 3); LAS float* d = scr + kk * 33 + c4; d[0] = tv[i][0]; d[1] = tv[i][1]; d[2] = tv[i][2]; d[3] = tv[i][3]; }
;     asm volatile("s_waitcnt lgkmcnt(0)" ::: "memory");
;     const int c = lane & 7;
; #pragma unroll
;     for (int j = 0; j < 4; ++j) { const int n = (lane >> 3) + 8 * j; const LAS float* s = scr + (8 * c) * 33 + n;
;         if constexpr (F8) { const float x[8] = {s[0] * W8_SCALE, s[33] * W8_SCALE, s[66] * W8_SCALE, s[99] * W8_SCALE, s[132] * W8_SCALE, s[165] * W8_SCALE, s[198] * W8_SCALE, s[231] * W8_SCALE};
;             *(u32x2*)((unsigned char*)WTv + (size_t)(n0 + n) * K + k0 + 8 * c) = to_fp8x8(x); }
;         else { u32x4 o; o.x = pk2(s[0 * 33], s[1 * 33]); o.y = pk2(s[2 * 33], s[3 * 33]); o.z = pk2(s[4 * 33], s[5 * 33]); o.w = pk2(s[6 * 33], s[7 * 33]);
;             *(u32x4*)((bf16_t*)WTv + (size_t)(n0 + n) * K + k0 + 8 * c) = o; } }
; __global__ void __launch_bounds__(NTHREADS, 2) mega(Args a) {
;     ...
;                 if (r < I_O) { transpose_item<false>(a.in[I_WO] + (size_t)l * DM * DM, DM, DM, DM, DM, wl + W_O, scr, r, lane); continue; } r -= I_O;
.LBB0_1199:
	s_andn2_b64 vcc, exec, s[0:1]
	s_cbranch_vccnz .LBB0_1201
	v_readlane_b32 s40, v254, 42
	s_lshl_b64 s[0:1], s[4:5], 24
	v_readlane_b32 s54, v254, 56
	v_readlane_b32 s55, v254, 57
	s_add_u32 s6, s54, s0
	s_addc_u32 s1, s55, s1
	s_add_i32 s0, s17, 0xc700
	s_and_b32 s19, s0, 0xffc0
	s_lshl_b32 s0, s17, 5
	s_and_b32 s0, s0, 0x7e0
	s_lshl_b32 s7, s0, 2
	s_add_u32 s6, s6, s7
	v_or_b32_e32 v2, s19, v33
	s_addc_u32 s7, s1, 0
	v_lshlrev_b32_e32 v160, 2, v32
	v_lshl_add_u64 v[0:1], s[6:7], 0, v[160:161]
	v_lshlrev_b32_e32 v160, 13, v2
	v_lshl_add_u64 v[28:29], v[0:1], 0, v[160:161]
	s_mov_b32 s1, 0x10000
	v_add_co_u32_e32 v4, vcc, s1, v28
	s_mov_b32 s1, 0x20000
	s_nop 0
	v_addc_co_u32_e32 v5, vcc, 0, v29, vcc
	v_add_co_u32_e32 v8, vcc, s1, v28
	s_mov_b32 s1, 0x30000
	s_nop 0
	v_addc_co_u32_e32 v9, vcc, 0, v29, vcc
	v_add_co_u32_e32 v12, vcc, s1, v28
	s_mov_b32 s1, 0x40000
	s_nop 0
	v_addc_co_u32_e32 v13, vcc, 0, v29, vcc
	v_add_co_u32_e32 v16, vcc, s1, v28
	s_mov_b32 s1, 0x50000
	s_nop 0
	v_addc_co_u32_e32 v17, vcc, 0, v29, vcc
	v_add_co_u32_e32 v20, vcc, s1, v28
	global_load_dwordx4 v[0:3], v[28:29], off
	s_nop 0
	global_load_dwordx4 v[4:7], v[4:5], off
	v_addc_co_u32_e32 v21, vcc, 0, v29, vcc
	global_load_dwordx4 v[8:11], v[8:9], off
	s_nop 0
	global_load_dwordx4 v[12:15], v[12:13], off
	s_nop 0
	global_load_dwordx4 v[16:19], v[16:17], off
	s_nop 0
	global_load_dwordx4 v[20:23], v[20:21], off
	s_mov_b32 s1, 0x60000
	v_add_co_u32_e32 v24, vcc, s1, v28
	s_mov_b32 s1, 0x70000
	s_nop 0
	v_addc_co_u32_e32 v25, vcc, 0, v29, vcc
	global_load_dwordx4 v[24:27], v[24:25], off
	v_add_co_u32_e32 v28, vcc, s1, v28
	v_add_u32_e32 v38, v40, v41
	s_nop 0
	v_addc_co_u32_e32 v29, vcc, 0, v29, vcc
	global_load_dwordx4 v[28:31], v[28:29], off
	v_add_u32_e32 v39, 0x420, v38
	v_add_u32_e32 v46, 0x428, v38
	v_add_u32_e32 v47, 0x840, v38
	v_add_u32_e32 v48, 0x848, v38
	v_add_u32_e32 v49, 0xc60, v38
	v_add_u32_e32 v50, 0xc68, v38
	v_add_u32_e32 v51, 0x1080, v38
	v_add_u32_e32 v52, 0x1088, v38
	v_add_u32_e32 v53, 0x14a0, v38
	v_add_u32_e32 v54, 0x14a8, v38
	v_add_u32_e32 v55, 0x18c0, v38
	v_add_u32_e32 v56, 0x18c8, v38
	v_add_u32_e32 v57, 0x1ce0, v38
	v_add_u32_e32 v58, 0x1ce8, v38
	s_lshl_b32 s1, s19, 1
	s_add_u32 s6, s10, s1
	s_addc_u32 s7, s11, 0
	v_lshlrev_b32_e32 v160, 1, v34
	v_lshl_add_u64 v[36:37], s[6:7], 0, v[160:161]
	s_mov_b64 s[6:7], 0x2900000
	v_readlane_b32 s41, v254, 43
	v_readlane_b32 s42, v254, 44
	v_readlane_b32 s43, v254, 45
	v_readlane_b32 s44, v254, 46
	v_readlane_b32 s45, v254, 47
	v_readlane_b32 s46, v254, 48
	v_readlane_b32 s47, v254, 49
	v_readlane_b32 s48, v254, 50
	v_readlane_b32 s49, v254, 51
	v_readlane_b32 s50, v254, 52
	v_readlane_b32 s51, v254, 53
	v_readlane_b32 s52, v254, 54
	v_readlane_b32 s53, v254, 55
	s_waitcnt vmcnt(7)
	ds_write2_b32 v38, v0, v1 offset1:1
	ds_write2_b32 v38, v2, v3 offset0:2 offset1:3
	s_waitcnt vmcnt(6)
	ds_write2_b32 v39, v4, v5 offset1:1
	ds_write2_b32 v46, v6, v7 offset1:1
	s_waitcnt vmcnt(5)
	ds_write2_b32 v47, v8, v9 offset1:1
	ds_write2_b32 v48, v10, v11 offset1:1
	s_waitcnt vmcnt(4)
	ds_write2_b32 v49, v12, v13 offset1:1
	ds_write2_b32 v50, v14, v15 offset1:1
	s_waitcnt vmcnt(3)
	ds_write2_b32 v51, v16, v17 offset1:1
	ds_write2_b32 v52, v18, v19 offset1:1
	s_waitcnt vmcnt(2)
	ds_write2_b32 v53, v20, v21 offset1:1
	ds_write2_b32 v54, v22, v23 offset1:1
	s_waitcnt vmcnt(1)
	ds_write2_b32 v55, v24, v25 offset1:1
	ds_write2_b32 v56, v26, v27 offset1:1
	s_waitcnt vmcnt(0)
	ds_write2_b32 v57, v28, v29 offset1:1
	ds_write2_b32 v58, v30, v31 offset1:1
	s_waitcnt lgkmcnt(0)
	ds_read2_b32 v[4:5], v45 offset1:8
	ds_read2_b32 v[6:7], v45 offset0:33 offset1:41
	ds_read2_b32 v[8:9], v45 offset0:66 offset1:74
	ds_read2_b32 v[12:13], v45 offset0:99 offset1:107
	ds_read2_b32 v[14:15], v45 offset0:132 offset1:140
	s_waitcnt lgkmcnt(4)
	s_waitcnt lgkmcnt(3)
	ds_read2_b32 v[16:17], v45 offset0:165 offset1:173
	s_waitcnt lgkmcnt(3)
	v_cvt_pk_bf16_f32 v0, v4, v6
	s_waitcnt lgkmcnt(2)
	ds_read2_b32 v[18:19], v45 offset0:198 offset1:206
	ds_read2_b32 v[20:21], v45 offset0:231 offset1:239
	v_cvt_pk_bf16_f32 v1, v8, v12
	s_waitcnt lgkmcnt(3)
	s_waitcnt lgkmcnt(2)
	v_cvt_pk_bf16_f32 v2, v14, v16
	s_waitcnt lgkmcnt(1)
	s_waitcnt lgkmcnt(0)
	v_cvt_pk_bf16_f32 v3, v18, v20
	v_or_b32_e32 v4, s0, v33
	v_lshl_add_u64 v[10:11], v[36:37], 0, s[6:7]
	v_lshlrev_b32_e32 v160, 12, v4
	v_lshl_add_u64 v[22:23], v[10:11], 0, v[160:161]
	global_store_dwordx4 v[22:23], v[0:3], off
	v_or_b32_e32 v6, s0, v42
	s_nop 0
	v_cvt_pk_bf16_f32 v0, v5, v7
	v_cvt_pk_bf16_f32 v1, v9, v13
	v_cvt_pk_bf16_f32 v2, v15, v17
	v_lshlrev_b32_e32 v160, 12, v6
	v_cvt_pk_bf16_f32 v3, v19, v21
	ds_read2_b32 v[4:5], v45 offset0:16 offset1:24
	v_lshl_add_u64 v[6:7], v[10:11], 0, v[160:161]
	global_store_dwordx4 v[6:7], v[0:3], off
	ds_read2_b32 v[6:7], v45 offset0:49 offset1:57
	ds_read2_b32 v[8:9], v45 offset0:82 offset1:90
	ds_read2_b32 v[12:13], v45 offset0:115 offset1:123
	s_waitcnt lgkmcnt(3)
	s_waitcnt lgkmcnt(2)
	ds_read2_b32 v[14:15], v45 offset0:148 offset1:156
	ds_read2_b32 v[16:17], v45 offset0:181 offset1:189
	v_cvt_pk_bf16_f32 v0, v4, v6
	s_waitcnt lgkmcnt(3)
	s_waitcnt lgkmcnt(2)
	ds_read2_b32 v[18:19], v45 offset0:214 offset1:222
	ds_read2_b32 v[20:21], v45 offset0:247 offset1:255
	v_cvt_pk_bf16_f32 v1, v8, v12
	s_waitcnt lgkmcnt(3)
	s_waitcnt lgkmcnt(2)
	v_cvt_pk_bf16_f32 v2, v14, v16
	s_waitcnt lgkmcnt(1)
	s_waitcnt lgkmcnt(0)
	v_cvt_pk_bf16_f32 v3, v18, v20
	v_or_b32_e32 v4, s0, v43
	v_lshlrev_b32_e32 v160, 12, v4
	v_lshl_add_u64 v[22:23], v[10:11], 0, v[160:161]
	global_store_dwordx4 v[22:23], v[0:3], off
	s_nop 1
	v_cvt_pk_bf16_f32 v0, v5, v7
	s_nop 0
	v_cvt_pk_bf16_f32 v1, v9, v13
	v_cvt_pk_bf16_f32 v2, v15, v17
	v_cvt_pk_bf16_f32 v3, v19, v21
	v_or_b32_e32 v4, s0, v44
	v_lshlrev_b32_e32 v160, 12, v4
	v_lshl_add_u64 v[4:5], v[10:11], 0, v[160:161]
	global_store_dwordx4 v[4:5], v[0:3], off
	s_waitcnt lgkmcnt(0)

; #define LAS __attribute__((address_space(3)))
; __device__ __forceinline__ unsigned pk2(float lo, float hi) { return f2bf(lo) | (f2bf(hi) << 16); }
; template <bool F8>
; __device__ __forceinline__ void transpose_item(const float* W, int ldw, int K, int N, int Npad, void* WTv, LAS float* scr, int item, int lane) {
;     ...
;     for (int i = 0; i < 8; ++i) { const int kk = 8 * i + (lane >> 3); tv[i] = ok ? *(const f32x4*)(W + (size_t)(k0 + kk) * ldw + n0 + c4) : (f32x4){0.f, 0.f, 0.f, 0.f}; }
; #pragma unroll
;     for (int i = 0; i < 8; ++i) { const int kk = 8 * i + (lane >> 3); LAS float* d = scr + kk * 33 + c4; d[0] = tv[i][0]; d[1] = tv[i][1]; d[2] = tv[i][2]; d[3] = tv[i][3]; }
;     asm volatile("s_waitcnt lgkmcnt(0)" ::: "memory");
;     const int c = lane & 7;
; #pragma unroll
;     for (int j = 0; j < 4; ++j) { const int n = (lane >> 3) + 8 * j; const LAS float* s = scr + (8 * c) * 33 + n;
;         if constexpr (F8) { const float x[8] = {s[0] * W8_SCALE, s[33] * W8_SCALE, s[66] * W8_SCALE, s[99] * W8_SCALE, s[132] * W8_SCALE, s[165] * W8_SCALE, s[198] * W8_SCALE, s[231] * W8_SCALE};
;             *(u32x2*)((unsigned char*)WTv + (size_t)(n0 + n) * K + k0 + 8 * c) = to_fp8x8(x); }
;         else { u32x4 o; o.x = pk2(s[0 * 33], s[1 * 33]); o.y = pk2(s[2 * 33], s[3 * 33]); o.z = pk2(s[4 * 33], s[5 * 33]); o.w = pk2(s[6 * 33], s[7 * 33]);
;             *(u32x4*)((bf16_t*)WTv + (size_t)(n0 + n) * K + k0 + 8 * c) = o; } }
; __global__ void __launch_bounds__(NTHREADS, 2) mega(Args a) {
;     ...
;                 if (r < I_PB) { transpose_item<false>(a.in[I_WPB] + (size_t)l * 1024 * DM, DM, 1024, DM, DM, wl + W_PB, scr, r, lane); continue; } r -= I_PB;
.LBB0_1202:
	s_andn2_b64 vcc, exec, s[0:1]
	s_cbranch_vccnz .LBB0_1204
	v_readlane_b32 s40, v254, 42
	s_lshl_b64 s[0:1], s[4:5], 23
	v_readlane_b32 s52, v254, 54
	v_readlane_b32 s53, v254, 55
	s_add_u32 s6, s52, s0
	s_addc_u32 s1, s53, s1
	s_add_i32 s0, s17, 0xcb00
	s_and_b32 s19, s0, 0xffc0
	s_lshl_b32 s0, s17, 5
	s_and_b32 s0, s0, 0x7e0
	s_lshl_b32 s7, s0, 2
	s_add_u32 s6, s6, s7
	v_or_b32_e32 v2, s19, v33
	s_addc_u32 s7, s1, 0
	v_lshlrev_b32_e32 v160, 2, v32
	v_lshl_add_u64 v[0:1], s[6:7], 0, v[160:161]
	v_lshlrev_b32_e32 v160, 13, v2
	v_lshl_add_u64 v[28:29], v[0:1], 0, v[160:161]
	s_mov_b32 s1, 0x10000
	v_add_co_u32_e32 v4, vcc, s1, v28
	s_mov_b32 s1, 0x20000
	s_nop 0
	v_addc_co_u32_e32 v5, vcc, 0, v29, vcc
	v_add_co_u32_e32 v8, vcc, s1, v28
	s_mov_b32 s1, 0x30000
	s_nop 0
	v_addc_co_u32_e32 v9, vcc, 0, v29, vcc
	v_add_co_u32_e32 v12, vcc, s1, v28
	s_mov_b32 s1, 0x40000
	s_nop 0
	v_addc_co_u32_e32 v13, vcc, 0, v29, vcc
	v_add_co_u32_e32 v16, vcc, s1, v28
	s_mov_b32 s1, 0x50000
	s_nop 0
	v_addc_co_u32_e32 v17, vcc, 0, v29, vcc
	v_add_co_u32_e32 v20, vcc, s1, v28
	global_load_dwordx4 v[0:3], v[28:29], off
	s_nop 0
	global_load_dwordx4 v[4:7], v[4:5], off
	v_addc_co_u32_e32 v21, vcc, 0, v29, vcc
	global_load_dwordx4 v[8:11], v[8:9], off
	s_nop 0
	global_load_dwordx4 v[12:15], v[12:13], off
	s_nop 0
	global_load_dwordx4 v[16:19], v[16:17], off
	s_nop 0
	global_load_dwordx4 v[20:23], v[20:21], off
	s_mov_b32 s1, 0x60000
	v_add_co_u32_e32 v24, vcc, s1, v28
	s_mov_b32 s1, 0x70000
	s_nop 0
	v_addc_co_u32_e32 v25, vcc, 0, v29, vcc
	global_load_dwordx4 v[24:27], v[24:25], off
	v_add_co_u32_e32 v28, vcc, s1, v28
	v_add_u32_e32 v38, v40, v41
	s_nop 0
	v_addc_co_u32_e32 v29, vcc, 0, v29, vcc
	global_load_dwordx4 v[28:31], v[28:29], off
	v_add_u32_e32 v39, 0x420, v38
	v_add_u32_e32 v46, 0x428, v38
	v_add_u32_e32 v47, 0x840, v38
	v_add_u32_e32 v48, 0x848, v38
	v_add_u32_e32 v49, 0xc60, v38
	v_add_u32_e32 v50, 0xc68, v38
	v_add_u32_e32 v51, 0x1080, v38
	v_add_u32_e32 v52, 0x1088, v38
	v_add_u32_e32 v53, 0x14a0, v38
	v_add_u32_e32 v54, 0x14a8, v38
	v_add_u32_e32 v55, 0x18c0, v38
	v_add_u32_e32 v56, 0x18c8, v38
	v_add_u32_e32 v57, 0x1ce0, v38
	v_add_u32_e32 v58, 0x1ce8, v38
	s_lshl_b32 s1, s19, 1
	s_add_u32 s6, s10, s1
	s_addc_u32 s7, s11, 0
	v_lshlrev_b32_e32 v160, 1, v34
	v_lshl_add_u64 v[36:37], s[6:7], 0, v[160:161]
	s_mov_b64 s[6:7], 0x2500000
	v_readlane_b32 s41, v254, 43
	v_readlane_b32 s42, v254, 44
	v_readlane_b32 s43, v254, 45
	v_readlane_b32 s44, v254, 46
	v_readlane_b32 s45, v254, 47
	v_readlane_b32 s46, v254, 48
	v_readlane_b32 s47, v254, 49
	v_readlane_b32 s48, v254, 50
	v_readlane_b32 s49, v254, 51
	v_readlane_b32 s50, v254, 52
	v_readlane_b32 s51, v254, 53
	v_readlane_b32 s54, v254, 56
	v_readlane_b32 s55, v254, 57
	s_waitcnt vmcnt(7)
	ds_write2_b32 v38, v0, v1 offset1:1
	ds_write2_b32 v38, v2, v3 offset0:2 offset1:3
	s_waitcnt vmcnt(6)
	ds_write2_b32 v39, v4, v5 offset1:1
	ds_write2_b32 v46, v6, v7 offset1:1
	s_waitcnt vmcnt(5)
	ds_write2_b32 v47, v8, v9 offset1:1
	ds_write2_b32 v48, v10, v11 offset1:1
	s_waitcnt vmcnt(4)
	ds_write2_b32 v49, v12, v13 offset1:1
	ds_write2_b32 v50, v14, v15 offset1:1
	s_waitcnt vmcnt(3)
	ds_write2_b32 v51, v16, v17 offset1:1
	ds_write2_b32 v52, v18, v19 offset1:1
	s_waitcnt vmcnt(2)
	ds_write2_b32 v53, v20, v21 offset1:1
	ds_write2_b32 v54, v22, v23 offset1:1
	s_waitcnt vmcnt(1)
	ds_write2_b32 v55, v24, v25 offset1:1
	ds_write2_b32 v56, v26, v27 offset1:1
	s_waitcnt vmcnt(0)
	ds_write2_b32 v57, v28, v29 offset1:1
	ds_write2_b32 v58, v30, v31 offset1:1
	s_waitcnt lgkmcnt(0)
	ds_read2_b32 v[4:5], v45 offset1:8
	ds_read2_b32 v[6:7], v45 offset0:33 offset1:41
	ds_read2_b32 v[8:9], v45 offset0:66 offset1:74
	ds_read2_b32 v[12:13], v45 offset0:99 offset1:107
	ds_read2_b32 v[14:15], v45 offset0:132 offset1:140
	s_waitcnt lgkmcnt(4)
	s_waitcnt lgkmcnt(3)
	ds_read2_b32 v[16:17], v45 offset0:165 offset1:173
	s_waitcnt lgkmcnt(3)
	v_cvt_pk_bf16_f32 v0, v4, v6
	s_waitcnt lgkmcnt(2)
	ds_read2_b32 v[18:19], v45 offset0:198 offset1:206
	ds_read2_b32 v[20:21], v45 offset0:231 offset1:239
	v_cvt_pk_bf16_f32 v1, v8, v12
	s_waitcnt lgkmcnt(3)
	s_waitcnt lgkmcnt(2)
	v_cvt_pk_bf16_f32 v2, v14, v16
	s_waitcnt lgkmcnt(1)
	s_waitcnt lgkmcnt(0)
	v_cvt_pk_bf16_f32 v3, v18, v20
	v_or_b32_e32 v4, s0, v33
	v_lshl_add_u64 v[10:11], v[36:37], 0, s[6:7]
	v_lshlrev_b32_e32 v160, 11, v4
	v_lshl_add_u64 v[22:23], v[10:11], 0, v[160:161]
	global_store_dwordx4 v[22:23], v[0:3], off
	v_or_b32_e32 v6, s0, v42
	s_nop 0
	v_cvt_pk_bf16_f32 v0, v5, v7
	v_cvt_pk_bf16_f32 v1, v9, v13
	v_cvt_pk_bf16_f32 v2, v15, v17
	v_lshlrev_b32_e32 v160, 11, v6
	v_cvt_pk_bf16_f32 v3, v19, v21
	ds_read2_b32 v[4:5], v45 offset0:16 offset1:24
	v_lshl_add_u64 v[6:7], v[10:11], 0, v[160:161]
	global_store_dwordx4 v[6:7], v[0:3], off
	ds_read2_b32 v[6:7], v45 offset0:49 offset1:57
	ds_read2_b32 v[8:9], v45 offset0:82 offset1:90
	ds_read2_b32 v[12:13], v45 offset0:115 offset1:123
	s_waitcnt lgkmcnt(3)
	s_waitcnt lgkmcnt(2)
	ds_read2_b32 v[14:15], v45 offset0:148 offset1:156
	ds_read2_b32 v[16:17], v45 offset0:181 offset1:189
	v_cvt_pk_bf16_f32 v0, v4, v6
	s_waitcnt lgkmcnt(3)
	s_waitcnt lgkmcnt(2)
	ds_read2_b32 v[18:19], v45 offset0:214 offset1:222
	ds_read2_b32 v[20:21], v45 offset0:247 offset1:255
	v_cvt_pk_bf16_f32 v1, v8, v12
	s_waitcnt lgkmcnt(3)
	s_waitcnt lgkmcnt(2)
	v_cvt_pk_bf16_f32 v2, v14, v16
	s_waitcnt lgkmcnt(1)
	s_waitcnt lgkmcnt(0)
	v_cvt_pk_bf16_f32 v3, v18, v20
	v_or_b32_e32 v4, s0, v43
	v_lshlrev_b32_e32 v160, 11, v4
	v_lshl_add_u64 v[22:23], v[10:11], 0, v[160:161]
	global_store_dwordx4 v[22:23], v[0:3], off
	s_nop 1
	v_cvt_pk_bf16_f32 v0, v5, v7
	s_nop 0
	v_cvt_pk_bf16_f32 v1, v9, v13
	v_cvt_pk_bf16_f32 v2, v15, v17
	v_cvt_pk_bf16_f32 v3, v19, v21
	v_or_b32_e32 v4, s0, v44
	v_lshlrev_b32_e32 v160, 11, v4
	v_lshl_add_u64 v[4:5], v[10:11], 0, v[160:161]
	global_store_dwordx4 v[4:5], v[0:3], off
	s_waitcnt lgkmcnt(0)

; #define LAS __attribute__((address_space(3)))
; __device__ __forceinline__ unsigned pk2(float lo, float hi) { return f2bf(lo) | (f2bf(hi) << 16); }
; template <bool F8>
; __device__ __forceinline__ void transpose_item(const float* W, int ldw, int K, int N, int Npad, void* WTv, LAS float* scr, int item, int lane) {
;     ...
;     for (int i = 0; i < 8; ++i) { const int kk = 8 * i + (lane >> 3); tv[i] = ok ? *(const f32x4*)(W + (size_t)(k0 + kk) * ldw + n0 + c4) : (f32x4){0.f, 0.f, 0.f, 0.f}; }
; #pragma unroll
;     for (int i = 0; i < 8; ++i) { const int kk = 8 * i + (lane >> 3); LAS float* d = scr + kk * 33 + c4; d[0] = tv[i][0]; d[1] = tv[i][1]; d[2] = tv[i][2]; d[3] = tv[i][3]; }
;     asm volatile("s_waitcnt lgkmcnt(0)" ::: "memory");
;     const int c = lane & 7;
; #pragma unroll
;     for (int j = 0; j < 4; ++j) { const int n = (lane >> 3) + 8 * j; const LAS float* s = scr + (8 * c) * 33 + n;
;         if constexpr (F8) { const float x[8] = {s[0] * W8_SCALE, s[33] * W8_SCALE, s[66] * W8_SCALE, s[99] * W8_SCALE, s[132] * W8_SCALE, s[165] * W8_SCALE, s[198] * W8_SCALE, s[231] * W8_SCALE};
;             *(u32x2*)((unsigned char*)WTv + (size_t)(n0 + n) * K + k0 + 8 * c) = to_fp8x8(x); }
;         else { u32x4 o; o.x = pk2(s[0 * 33], s[1 * 33]); o.y = pk2(s[2 * 33], s[3 * 33]); o.z = pk2(s[4 * 33], s[5 * 33]); o.w = pk2(s[6 * 33], s[7 * 33]);
;             *(u32x4*)((bf16_t*)WTv + (size_t)(n0 + n) * K + k0 + 8 * c) = o; } }
; __global__ void __launch_bounds__(NTHREADS, 2) mega(Args a) {
;     ...
;                 if (r < I_PA) { transpose_item<false>(a.in[I_WPA] + (size_t)l * 512 * DM, DM, 512, DM, DM, wl + W_PA, scr, r, lane); continue; } r -= I_PA;
.LBB0_1205:
	s_andn2_b64 vcc, exec, s[0:1]
	s_cbranch_vccnz .LBB0_1207
	v_readlane_b32 s40, v254, 42
	s_lshl_b64 s[0:1], s[4:5], 22
	v_readlane_b32 s50, v254, 52
	v_readlane_b32 s51, v254, 53
	s_add_u32 s6, s50, s0
	s_addc_u32 s1, s51, s1
	s_add_i32 s0, s17, 0xcd00
	s_and_b32 s19, s0, 0xffc0
	s_lshl_b32 s0, s17, 5
	s_and_b32 s0, s0, 0x7e0
	s_lshl_b32 s7, s0, 2
	s_add_u32 s6, s6, s7
	v_or_b32_e32 v2, s19, v33
	s_addc_u32 s7, s1, 0
	v_lshlrev_b32_e32 v160, 2, v32
	v_lshl_add_u64 v[0:1], s[6:7], 0, v[160:161]
	v_lshlrev_b32_e32 v160, 13, v2
	v_lshl_add_u64 v[28:29], v[0:1], 0, v[160:161]
	s_mov_b32 s1, 0x10000
	v_add_co_u32_e32 v4, vcc, s1, v28
	s_mov_b32 s1, 0x20000
	s_nop 0
	v_addc_co_u32_e32 v5, vcc, 0, v29, vcc
	v_add_co_u32_e32 v8, vcc, s1, v28
	s_mov_b32 s1, 0x30000
	s_nop 0
	v_addc_co_u32_e32 v9, vcc, 0, v29, vcc
	v_add_co_u32_e32 v12, vcc, s1, v28
	s_mov_b32 s1, 0x40000
	s_nop 0
	v_addc_co_u32_e32 v13, vcc, 0, v29, vcc
	v_add_co_u32_e32 v16, vcc, s1, v28
	s_mov_b32 s1, 0x50000
	s_nop 0
	v_addc_co_u32_e32 v17, vcc, 0, v29, vcc
	v_add_co_u32_e32 v20, vcc, s1, v28
	global_load_dwordx4 v[0:3], v[28:29], off
	s_nop 0
	global_load_dwordx4 v[4:7], v[4:5], off
	v_addc_co_u32_e32 v21, vcc, 0, v29, vcc
	global_load_dwordx4 v[8:11], v[8:9], off
	s_nop 0
	global_load_dwordx4 v[12:15], v[12:13], off
	s_nop 0
	global_load_dwordx4 v[16:19], v[16:17], off
	s_nop 0
	global_load_dwordx4 v[20:23], v[20:21], off
	s_mov_b32 s1, 0x60000
	v_add_co_u32_e32 v24, vcc, s1, v28
	s_mov_b32 s1, 0x70000
	s_nop 0
	v_addc_co_u32_e32 v25, vcc, 0, v29, vcc
	global_load_dwordx4 v[24:27], v[24:25], off
	v_add_co_u32_e32 v28, vcc, s1, v28
	v_add_u32_e32 v38, v40, v41
	s_nop 0
	v_addc_co_u32_e32 v29, vcc, 0, v29, vcc
	global_load_dwordx4 v[28:31], v[28:29], off
	v_add_u32_e32 v39, 0x420, v38
	v_add_u32_e32 v46, 0x428, v38
	v_add_u32_e32 v47, 0x840, v38
	v_add_u32_e32 v48, 0x848, v38
	v_add_u32_e32 v49, 0xc60, v38
	v_add_u32_e32 v50, 0xc68, v38
	v_add_u32_e32 v51, 0x1080, v38
	v_add_u32_e32 v52, 0x1088, v38
	v_add_u32_e32 v53, 0x14a0, v38
	v_add_u32_e32 v54, 0x14a8, v38
	v_add_u32_e32 v55, 0x18c0, v38
	v_add_u32_e32 v56, 0x18c8, v38
	v_add_u32_e32 v57, 0x1ce0, v38
	v_add_u32_e32 v58, 0x1ce8, v38
	s_lshl_b32 s1, s19, 1
	s_add_u32 s6, s10, s1
	s_addc_u32 s7, s11, 0
	v_lshlrev_b32_e32 v160, 1, v34
	v_lshl_add_u64 v[36:37], s[6:7], 0, v[160:161]
	s_mov_b64 s[6:7], 0x2300000
	v_readlane_b32 s41, v254, 43
	v_readlane_b32 s42, v254, 44
	v_readlane_b32 s43, v254, 45
	v_readlane_b32 s44, v254, 46
	v_readlane_b32 s45, v254, 47
	v_readlane_b32 s46, v254, 48
	v_readlane_b32 s47, v254, 49
	v_readlane_b32 s48, v254, 50
	v_readlane_b32 s49, v254, 51
	v_readlane_b32 s52, v254, 54
	v_readlane_b32 s53, v254, 55
	v_readlane_b32 s54, v254, 56
	v_readlane_b32 s55, v254, 57
	s_waitcnt vmcnt(7)
	ds_write2_b32 v38, v0, v1 offset1:1
	ds_write2_b32 v38, v2, v3 offset0:2 offset1:3
	s_waitcnt vmcnt(6)
	ds_write2_b32 v39, v4, v5 offset1:1
	ds_write2_b32 v46, v6, v7 offset1:1
	s_waitcnt vmcnt(5)
	ds_write2_b32 v47, v8, v9 offset1:1
	ds_write2_b32 v48, v10, v11 offset1:1
	s_waitcnt vmcnt(4)
	ds_write2_b32 v49, v12, v13 offset1:1
	ds_write2_b32 v50, v14, v15 offset1:1
	s_waitcnt vmcnt(3)
	ds_write2_b32 v51, v16, v17 offset1:1
	ds_write2_b32 v52, v18, v19 offset1:1
	s_waitcnt vmcnt(2)
	ds_write2_b32 v53, v20, v21 offset1:1
	ds_write2_b32 v54, v22, v23 offset1:1
	s_waitcnt vmcnt(1)
	ds_write2_b32 v55, v24, v25 offset1:1
	ds_write2_b32 v56, v26, v27 offset1:1
	s_waitcnt vmcnt(0)
	ds_write2_b32 v57, v28, v29 offset1:1
	ds_write2_b32 v58, v30, v31 offset1:1
	s_waitcnt lgkmcnt(0)
	ds_read2_b32 v[4:5], v45 offset1:8
	ds_read2_b32 v[6:7], v45 offset0:33 offset1:41
	ds_read2_b32 v[8:9], v45 offset0:66 offset1:74
	ds_read2_b32 v[12:13], v45 offset0:99 offset1:107
	ds_read2_b32 v[14:15], v45 offset0:132 offset1:140
	s_waitcnt lgkmcnt(4)
	s_waitcnt lgkmcnt(3)
	ds_read2_b32 v[16:17], v45 offset0:165 offset1:173
	s_waitcnt lgkmcnt(3)
	v_cvt_pk_bf16_f32 v0, v4, v6
	s_waitcnt lgkmcnt(2)
	ds_read2_b32 v[18:19], v45 offset0:198 offset1:206
	ds_read2_b32 v[20:21], v45 offset0:231 offset1:239
	v_cvt_pk_bf16_f32 v1, v8, v12
	s_waitcnt lgkmcnt(3)
	s_waitcnt lgkmcnt(2)
	v_cvt_pk_bf16_f32 v2, v14, v16
	s_waitcnt lgkmcnt(1)
	s_waitcnt lgkmcnt(0)
	v_cvt_pk_bf16_f32 v3, v18, v20
	v_or_b32_e32 v4, s0, v33
	v_lshl_add_u64 v[10:11], v[36:37], 0, s[6:7]
	v_lshlrev_b32_e32 v160, 10, v4
	v_lshl_add_u64 v[22:23], v[10:11], 0, v[160:161]
	global_store_dwordx4 v[22:23], v[0:3], off
	v_or_b32_e32 v6, s0, v42
	s_nop 0
	v_cvt_pk_bf16_f32 v0, v5, v7
	v_cvt_pk_bf16_f32 v1, v9, v13
	v_cvt_pk_bf16_f32 v2, v15, v17
	v_lshlrev_b32_e32 v160, 10, v6
	v_cvt_pk_bf16_f32 v3, v19, v21
	ds_read2_b32 v[4:5], v45 offset0:16 offset1:24
	v_lshl_add_u64 v[6:7], v[10:11], 0, v[160:161]
	global_store_dwordx4 v[6:7], v[0:3], off
	ds_read2_b32 v[6:7], v45 offset0:49 offset1:57
	ds_read2_b32 v[8:9], v45 offset0:82 offset1:90
	ds_read2_b32 v[12:13], v45 offset0:115 offset1:123
	s_waitcnt lgkmcnt(3)
	s_waitcnt lgkmcnt(2)
	ds_read2_b32 v[14:15], v45 offset0:148 offset1:156
	ds_read2_b32 v[16:17], v45 offset0:181 offset1:189
	v_cvt_pk_bf16_f32 v0, v4, v6
	s_waitcnt lgkmcnt(3)
	s_waitcnt lgkmcnt(2)
	ds_read2_b32 v[18:19], v45 offset0:214 offset1:222
	ds_read2_b32 v[20:21], v45 offset0:247 offset1:255
	v_cvt_pk_bf16_f32 v1, v8, v12
	s_waitcnt lgkmcnt(3)
	s_waitcnt lgkmcnt(2)
	v_cvt_pk_bf16_f32 v2, v14, v16
	s_waitcnt lgkmcnt(1)
	s_waitcnt lgkmcnt(0)
	v_cvt_pk_bf16_f32 v3, v18, v20
	v_or_b32_e32 v4, s0, v43
	v_lshlrev_b32_e32 v160, 10, v4
	v_lshl_add_u64 v[22:23], v[10:11], 0, v[160:161]
	global_store_dwordx4 v[22:23], v[0:3], off
	s_nop 1
	v_cvt_pk_bf16_f32 v0, v5, v7
	s_nop 0
	v_cvt_pk_bf16_f32 v1, v9, v13
	v_cvt_pk_bf16_f32 v2, v15, v17
	v_cvt_pk_bf16_f32 v3, v19, v21
	v_or_b32_e32 v4, s0, v44
	v_lshlrev_b32_e32 v160, 10, v4
	v_lshl_add_u64 v[4:5], v[10:11], 0, v[160:161]
	global_store_dwordx4 v[4:5], v[0:3], off
	s_waitcnt lgkmcnt(0)

; #define LAS __attribute__((address_space(3)))
; __device__ __forceinline__ unsigned pk2(float lo, float hi) { return f2bf(lo) | (f2bf(hi) << 16); }
; template <bool F8>
; __device__ __forceinline__ void transpose_item(const float* W, int ldw, int K, int N, int Npad, void* WTv, LAS float* scr, int item, int lane) {
;     ...
;     for (int i = 0; i < 8; ++i) { const int kk = 8 * i + (lane >> 3); tv[i] = ok ? *(const f32x4*)(W + (size_t)(k0 + kk) * ldw + n0 + c4) : (f32x4){0.f, 0.f, 0.f, 0.f}; }
; #pragma unroll
;     for (int i = 0; i < 8; ++i) { const int kk = 8 * i + (lane >> 3); LAS float* d = scr + kk * 33 + c4; d[0] = tv[i][0]; d[1] = tv[i][1]; d[2] = tv[i][2]; d[3] = tv[i][3]; }
;     asm volatile("s_waitcnt lgkmcnt(0)" ::: "memory");
;     const int c = lane & 7;
; #pragma unroll
;     for (int j = 0; j < 4; ++j) { const int n = (lane >> 3) + 8 * j; const LAS float* s = scr + (8 * c) * 33 + n;
;         if constexpr (F8) { const float x[8] = {s[0] * W8_SCALE, s[33] * W8_SCALE, s[66] * W8_SCALE, s[99] * W8_SCALE, s[132] * W8_SCALE, s[165] * W8_SCALE, s[198] * W8_SCALE, s[231] * W8_SCALE};
;             *(u32x2*)((unsigned char*)WTv + (size_t)(n0 + n) * K + k0 + 8 * c) = to_fp8x8(x); }
;         else { u32x4 o; o.x = pk2(s[0 * 33], s[1 * 33]); o.y = pk2(s[2 * 33], s[3 * 33]); o.z = pk2(s[4 * 33], s[5 * 33]); o.w = pk2(s[6 * 33], s[7 * 33]);
;             *(u32x4*)((bf16_t*)WTv + (size_t)(n0 + n) * K + k0 + 8 * c) = o; } }
; __global__ void __launch_bounds__(NTHREADS, 2) mega(Args a) {
;     ...
;                 if (r < I_I16) { transpose_item<false>(win + QKVW, NIN, DM, NIN - QKVW, IDXW, wl + W_I16, scr, r, lane); continue; } r -= I_I16;
.LBB0_1228:
	s_or_b64 exec, exec, s[6:7]
	v_add_u32_e32 v36, v40, v41
	s_waitcnt vmcnt(0)
	ds_write2_b32 v36, v0, v1 offset1:1
	ds_write2_b32 v36, v2, v3 offset0:2 offset1:3
	v_add_u32_e32 v0, 0x420, v36
	ds_write2_b32 v0, v4, v5 offset1:1
	v_add_u32_e32 v0, 0x428, v36
	ds_write2_b32 v0, v6, v7 offset1:1
	v_add_u32_e32 v0, 0x840, v36
	ds_write2_b32 v0, v12, v13 offset1:1
	v_add_u32_e32 v0, 0x848, v36
	ds_write2_b32 v0, v14, v15 offset1:1
	v_add_u32_e32 v0, 0xc60, v36
	ds_write2_b32 v0, v8, v9 offset1:1
	v_add_u32_e32 v0, 0xc68, v36
	ds_write2_b32 v0, v10, v11 offset1:1
	v_add_u32_e32 v0, 0x1080, v36
	ds_write2_b32 v0, v20, v21 offset1:1
	v_add_u32_e32 v0, 0x1088, v36
	ds_write2_b32 v0, v22, v23 offset1:1
	v_add_u32_e32 v0, 0x14a0, v36
	ds_write2_b32 v0, v16, v17 offset1:1
	v_add_u32_e32 v0, 0x14a8, v36
	ds_write2_b32 v0, v18, v19 offset1:1
	v_add_u32_e32 v0, 0x18c0, v36
	ds_write2_b32 v0, v28, v29 offset1:1
	v_add_u32_e32 v0, 0x18c8, v36
	ds_write2_b32 v0, v30, v31 offset1:1
	v_add_u32_e32 v0, 0x1ce0, v36
	ds_write2_b32 v0, v24, v25 offset1:1
	v_add_u32_e32 v0, 0x1ce8, v36
	ds_write2_b32 v0, v26, v27 offset1:1
	s_waitcnt lgkmcnt(0)
	ds_read2_b32 v[4:5], v45 offset1:8
	ds_read2_b32 v[8:9], v45 offset0:33 offset1:41
	ds_read2_b32 v[10:11], v45 offset0:66 offset1:74
	ds_read2_b32 v[12:13], v45 offset0:99 offset1:107
	ds_read2_b32 v[14:15], v45 offset0:132 offset1:140
	s_waitcnt lgkmcnt(4)
	s_waitcnt lgkmcnt(3)
	ds_read2_b32 v[16:17], v45 offset0:165 offset1:173
	v_cvt_pk_bf16_f32 v0, v4, v8
	s_waitcnt lgkmcnt(3)
	s_waitcnt lgkmcnt(2)
	ds_read2_b32 v[18:19], v45 offset0:198 offset1:206
	ds_read2_b32 v[20:21], v45 offset0:231 offset1:239
	v_cvt_pk_bf16_f32 v1, v10, v12
	s_waitcnt lgkmcnt(3)
	s_waitcnt lgkmcnt(2)
	v_cvt_pk_bf16_f32 v2, v14, v16
	s_waitcnt lgkmcnt(1)
	s_lshl_b32 s0, s19, 1
	s_waitcnt lgkmcnt(0)
	s_add_u32 s0, s10, s0
	s_addc_u32 s1, s11, 0
	v_lshlrev_b32_e32 v160, 1, v34
	v_cvt_pk_bf16_f32 v3, v18, v20
	v_or_b32_e32 v4, s5, v33
	v_lshl_add_u64 v[6:7], s[0:1], 0, v[160:161]
	v_lshlrev_b32_e32 v160, 12, v4
	v_lshl_add_u64 v[22:23], v[6:7], 0, v[160:161]
	global_store_dwordx4 v[22:23], v[0:3], off
	v_or_b32_e32 v8, s5, v42
	s_nop 0
	v_cvt_pk_bf16_f32 v0, v5, v9
	v_cvt_pk_bf16_f32 v1, v11, v13
	v_cvt_pk_bf16_f32 v2, v15, v17
	v_lshlrev_b32_e32 v160, 12, v8
	v_cvt_pk_bf16_f32 v3, v19, v21
	ds_read2_b32 v[4:5], v45 offset0:16 offset1:24
	v_lshl_add_u64 v[8:9], v[6:7], 0, v[160:161]
	global_store_dwordx4 v[8:9], v[0:3], off
	ds_read2_b32 v[8:9], v45 offset0:49 offset1:57
	ds_read2_b32 v[10:11], v45 offset0:82 offset1:90
	ds_read2_b32 v[12:13], v45 offset0:115 offset1:123
	s_waitcnt lgkmcnt(3)
	s_waitcnt lgkmcnt(2)
	ds_read2_b32 v[14:15], v45 offset0:148 offset1:156
	ds_read2_b32 v[16:17], v45 offset0:181 offset1:189
	v_cvt_pk_bf16_f32 v0, v4, v8
	s_waitcnt lgkmcnt(3)
	s_waitcnt lgkmcnt(2)
	ds_read2_b32 v[18:19], v45 offset0:214 offset1:222
	ds_read2_b32 v[20:21], v45 offset0:247 offset1:255
	v_cvt_pk_bf16_f32 v1, v10, v12
	s_waitcnt lgkmcnt(3)
	s_waitcnt lgkmcnt(2)
	v_cvt_pk_bf16_f32 v2, v14, v16
	s_waitcnt lgkmcnt(1)
	s_waitcnt lgkmcnt(0)
	v_cvt_pk_bf16_f32 v3, v18, v20
	v_or_b32_e32 v4, s5, v43
	v_lshlrev_b32_e32 v160, 12, v4
	v_lshl_add_u64 v[22:23], v[6:7], 0, v[160:161]
	global_store_dwordx4 v[22:23], v[0:3], off
	s_nop 1
	v_cvt_pk_bf16_f32 v0, v5, v9
	s_nop 0
	v_cvt_pk_bf16_f32 v1, v11, v13
	v_cvt_pk_bf16_f32 v2, v15, v17
	v_cvt_pk_bf16_f32 v3, v19, v21
	v_or_b32_e32 v4, s5, v44
	v_lshlrev_b32_e32 v160, 12, v4
	v_lshl_add_u64 v[4:5], v[6:7], 0, v[160:161]
	global_store_dwordx4 v[4:5], v[0:3], off
	s_waitcnt lgkmcnt(0)
